# all flat_load/flat_store/flat_atomic instructions (global addresses only) issued as global_* so they do not occupy the LDS path
# baseline (speedup 1.0000x reference)
; __device__ __forceinline__ int ltid() { int t = threadIdx.x; asm volatile("" : "+v"(t)); return t; }
; __device__ __forceinline__ int lbid() { int t = blockIdx.x; asm volatile("" : "+s"(t)); return t; }
; __device__ __forceinline__ float wave_sum(float v) { for (int o = 32; o > 0; o >>= 1) v += __shfl_xor(v, o); return v; }
; __device__ __forceinline__ void unpack8(u32x4 w, float* f) { f[0] = bflo(w.x); f[1] = bfhi(w.x); f[2] = bflo(w.y); f[3] = bfhi(w.y); f[4] = bflo(w.z); f[5] = bfhi(w.z); f[6] = bflo(w.w); f[7] = bfhi(w.w); }
; __device__ __forceinline__ void final_phase(const bf16_t* __restrict__ H, const float* __restrict__ g, float* __restrict__ outf) {
;     const int tid = ltid(), wid = tid >> 6, lane = tid & 63;
;     for (int row = lbid() * 8 + wid; row < S_; row += gridDim.x * 8) {
;         float v[32]; float ssq = 0.f;
; #pragma unroll
;         for (int i = 0; i < 4; ++i) { float f[8]; unpack8(*(const u32x4*)(H + (size_t)row * DM + (i * 64 + lane) * 8), f);
; #pragma unroll
;             for (int k = 0; k < 8; ++k) { v[i * 8 + k] = f[k]; ssq += f[k] * f[k]; } }
;         ssq = wave_sum(ssq);
;         const float rstd = rsqrtf(ssq * (1.f / DM) + EPS_);
; #pragma unroll
;         for (int i = 0; i < 4; ++i) { const int col = (i * 64 + lane) * 8;
; #pragma unroll
;             for (int q = 0; q < 2; ++q) { const f32x4 gv = *(const f32x4*)(g + col + q * 4); f32x4 y;
; #pragma unroll
;                 for (int k = 0; k < 4; ++k) y[k] = v[i * 8 + q * 4 + k] * rstd * gv[k];
;                 *(f32x4*)(outf + (size_t)row * DM + col + q * 4) = y; } }
;     }
; }
.LBB0_87:
	v_ashrrev_i32_e32 v33, 31, v32
	v_lshlrev_b64 v[40:41], 12, v[32:33]
	v_lshl_add_u64 v[40:41], v[34:35], 0, v[40:41]
	global_load_dwordx4 v[50:53], v[40:41], off
	global_load_dwordx4 v[54:57], v[40:41], off offset:1024
	global_load_dwordx4 v[58:61], v[40:41], off offset:2048
	global_load_dwordx4 v[62:65], v[40:41], off offset:3072
	s_waitcnt vmcnt(0) lgkmcnt(0)
	v_lshlrev_b32_e32 v40, 16, v50
	v_and_b32_e32 v41, 0xffff0000, v50
	v_lshlrev_b32_e32 v42, 16, v51
	v_and_b32_e32 v43, 0xffff0000, v51
	v_pk_mul_f32 v[78:79], v[40:41], v[40:41]
	v_pk_mul_f32 v[80:81], v[42:43], v[42:43]
	v_add_f32_e32 v37, v78, v79
	v_lshlrev_b32_e32 v50, 16, v52
	v_and_b32_e32 v51, 0xffff0000, v52
	v_add_f32_e32 v37, v80, v37
	v_pk_mul_f32 v[82:83], v[50:51], v[50:51]
	v_add_f32_e32 v37, v81, v37
	v_lshlrev_b32_e32 v52, 16, v53
	v_and_b32_e32 v53, 0xffff0000, v53
	v_add_f32_e32 v37, v82, v37
	v_pk_mul_f32 v[84:85], v[52:53], v[52:53]
	v_add_f32_e32 v37, v83, v37
	v_lshlrev_b32_e32 v66, 16, v54
	v_and_b32_e32 v67, 0xffff0000, v54
	v_add_f32_e32 v37, v84, v37
	v_pk_mul_f32 v[86:87], v[66:67], v[66:67]
	v_add_f32_e32 v37, v85, v37
	v_lshlrev_b32_e32 v54, 16, v55
	v_and_b32_e32 v55, 0xffff0000, v55
	v_add_f32_e32 v37, v86, v37
	v_pk_mul_f32 v[88:89], v[54:55], v[54:55]
	v_add_f32_e32 v37, v87, v37
	v_lshlrev_b32_e32 v68, 16, v56
	v_and_b32_e32 v69, 0xffff0000, v56
	v_add_f32_e32 v37, v88, v37
	v_pk_mul_f32 v[90:91], v[68:69], v[68:69]
	v_add_f32_e32 v37, v89, v37
	v_lshlrev_b32_e32 v56, 16, v57
	v_and_b32_e32 v57, 0xffff0000, v57
	v_add_f32_e32 v37, v90, v37
	v_pk_mul_f32 v[92:93], v[56:57], v[56:57]
	v_add_f32_e32 v37, v91, v37
	v_lshlrev_b32_e32 v70, 16, v58
	v_and_b32_e32 v71, 0xffff0000, v58
	v_add_f32_e32 v37, v92, v37
	v_pk_mul_f32 v[94:95], v[70:71], v[70:71]
	v_add_f32_e32 v37, v93, v37
	v_lshlrev_b32_e32 v58, 16, v59
	v_and_b32_e32 v59, 0xffff0000, v59
	v_add_f32_e32 v37, v94, v37
	v_pk_mul_f32 v[96:97], v[58:59], v[58:59]
	v_add_f32_e32 v37, v95, v37
	v_lshlrev_b32_e32 v72, 16, v60
	v_and_b32_e32 v73, 0xffff0000, v60
	v_add_f32_e32 v37, v96, v37
	v_pk_mul_f32 v[98:99], v[72:73], v[72:73]
	v_add_f32_e32 v37, v97, v37
	v_lshlrev_b32_e32 v60, 16, v61
	v_and_b32_e32 v61, 0xffff0000, v61
	v_add_f32_e32 v37, v98, v37
	v_pk_mul_f32 v[100:101], v[60:61], v[60:61]
	v_add_f32_e32 v37, v99, v37
	v_lshlrev_b32_e32 v74, 16, v62
	v_and_b32_e32 v75, 0xffff0000, v62
	v_add_f32_e32 v37, v100, v37
	v_pk_mul_f32 v[102:103], v[74:75], v[74:75]
	v_add_f32_e32 v37, v101, v37
	v_lshlrev_b32_e32 v62, 16, v63
	v_and_b32_e32 v63, 0xffff0000, v63
	v_add_f32_e32 v37, v102, v37
	v_pk_mul_f32 v[104:105], v[62:63], v[62:63]
	v_add_f32_e32 v37, v103, v37
	v_lshlrev_b32_e32 v76, 16, v64
	v_and_b32_e32 v77, 0xffff0000, v64
	v_add_f32_e32 v37, v104, v37
	v_pk_mul_f32 v[106:107], v[76:77], v[76:77]
	v_add_f32_e32 v37, v105, v37
	v_lshlrev_b32_e32 v64, 16, v65
	v_and_b32_e32 v65, 0xffff0000, v65
	v_add_f32_e32 v37, v106, v37
	v_pk_mul_f32 v[108:109], v[64:65], v[64:65]
	v_add_f32_e32 v37, v107, v37
	v_add_f32_e32 v37, v108, v37
	v_add_f32_e32 v37, v109, v37
	ds_bpermute_b32 v39, v44, v37
	v_lshlrev_b64 v[78:79], 13, v[32:33]
	v_lshl_add_u64 v[78:79], s[10:11], 0, v[78:79]
	v_add_u32_e32 v32, s12, v32
	v_cmp_lt_i32_e32 vcc, s14, v32
	s_waitcnt lgkmcnt(0)
	v_add_f32_e32 v37, v37, v39
	ds_bpermute_b32 v39, v45, v37
	s_or_b64 s[6:7], vcc, s[6:7]
	s_waitcnt lgkmcnt(0)
	v_add_f32_e32 v37, v37, v39
	ds_bpermute_b32 v39, v46, v37
	s_waitcnt lgkmcnt(0)
	v_add_f32_e32 v37, v37, v39
	ds_bpermute_b32 v39, v47, v37
	s_waitcnt lgkmcnt(0)
	v_add_f32_e32 v80, v37, v39
	ds_bpermute_b32 v81, v48, v80
	v_mov_b32_e32 v37, v195
	v_mov_b32_e32 v39, v195
	s_waitcnt lgkmcnt(0)
	v_add_f32_e32 v33, v80, v81
	ds_bpermute_b32 v82, v49, v33
	v_lshl_add_u64 v[80:81], v[78:79], 0, v[194:195]
	s_waitcnt lgkmcnt(0)
	v_add_f32_e32 v33, v33, v82
	v_fmamk_f32 v33, v33, 0x3a000000, v242
	v_mul_f32_e32 v82, 0x4b800000, v33
	v_cmp_gt_f32_e64 s[0:1], s13, v33
	s_nop 1
	v_cndmask_b32_e64 v33, v33, v82, s[0:1]
	v_rsq_f32_e32 v33, v33
	v_lshl_add_u64 v[82:83], v[78:79], 0, v[36:37]
	v_lshl_add_u64 v[78:79], v[78:79], 0, v[38:39]
	v_mul_f32_e32 v37, 0x45800000, v33
	v_cndmask_b32_e64 v84, v33, v37, s[0:1]
	v_pk_mul_f32 v[40:41], v[84:85], v[40:41] op_sel_hi:[0,1]
	v_pk_mul_f32 v[42:43], v[84:85], v[42:43] op_sel_hi:[0,1]
	v_pk_mul_f32 v[50:51], v[84:85], v[50:51] op_sel_hi:[0,1]
	v_pk_mul_f32 v[52:53], v[84:85], v[52:53] op_sel_hi:[0,1]
	v_pk_mul_f32 v[66:67], v[84:85], v[66:67] op_sel_hi:[0,1]
	v_pk_mul_f32 v[54:55], v[84:85], v[54:55] op_sel_hi:[0,1]
	v_pk_mul_f32 v[68:69], v[84:85], v[68:69] op_sel_hi:[0,1]
	v_pk_mul_f32 v[86:87], v[84:85], v[56:57] op_sel_hi:[0,1]
	v_pk_mul_f32 v[70:71], v[84:85], v[70:71] op_sel_hi:[0,1]
	v_pk_mul_f32 v[88:89], v[84:85], v[58:59] op_sel_hi:[0,1]
	v_pk_mul_f32 v[72:73], v[84:85], v[72:73] op_sel_hi:[0,1]
	v_pk_mul_f32 v[90:91], v[84:85], v[60:61] op_sel_hi:[0,1]
	v_pk_mul_f32 v[74:75], v[84:85], v[74:75] op_sel_hi:[0,1]
	v_pk_mul_f32 v[92:93], v[84:85], v[62:63] op_sel_hi:[0,1]
	v_pk_mul_f32 v[94:95], v[84:85], v[76:77] op_sel_hi:[0,1]
	v_pk_mul_f32 v[76:77], v[84:85], v[64:65] op_sel_hi:[0,1]
	v_pk_mul_f32 v[42:43], v[6:7], v[42:43]
	v_pk_mul_f32 v[40:41], v[4:5], v[40:41]
	v_pk_mul_f32 v[52:53], v[2:3], v[52:53]
	v_pk_mul_f32 v[50:51], v[0:1], v[50:51]
	v_pk_mul_f32 v[56:57], v[14:15], v[54:55]
	v_pk_mul_f32 v[54:55], v[12:13], v[66:67]
	v_pk_mul_f32 v[60:61], v[10:11], v[86:87]
	v_pk_mul_f32 v[58:59], v[8:9], v[68:69]
	v_pk_mul_f32 v[64:65], v[22:23], v[88:89]
	v_pk_mul_f32 v[62:63], v[20:21], v[70:71]
	v_pk_mul_f32 v[68:69], v[18:19], v[90:91]
	v_pk_mul_f32 v[66:67], v[16:17], v[72:73]
	v_pk_mul_f32 v[72:73], v[30:31], v[92:93]
	v_pk_mul_f32 v[70:71], v[28:29], v[74:75]
	v_pk_mul_f32 v[76:77], v[26:27], v[76:77]
	v_pk_mul_f32 v[74:75], v[24:25], v[94:95]
	global_store_dwordx4 v[80:81], v[40:43], off
	global_store_dwordx4 v[80:81], v[50:53], off offset:16
	global_store_dwordx4 v[80:81], v[54:57], off offset:2048
	global_store_dwordx4 v[80:81], v[58:61], off offset:2064
	global_store_dwordx4 v[82:83], v[62:65], off
	global_store_dwordx4 v[82:83], v[66:69], off offset:16
	global_store_dwordx4 v[78:79], v[70:73], off
	global_store_dwordx4 v[78:79], v[74:77], off offset:16
	s_andn2_b64 exec, exec, s[6:7]
	s_cbranch_execnz .LBB0_87

; #define LAS __attribute__((address_space(3)))
; __device__ __forceinline__ void unpack8(u32x4 w, float* f) { f[0] = bflo(w.x); f[1] = bfhi(w.x); f[2] = bflo(w.y); f[3] = bfhi(w.y); f[4] = bflo(w.z); f[5] = bfhi(w.z); f[6] = bflo(w.w); f[7] = bfhi(w.w); }
; __device__ __forceinline__ u32x4 pack8(const float* f) { u32x4 w; w.x = cvt_pk_bf16(f[0], f[1]); w.y = cvt_pk_bf16(f[2], f[3]); w.z = cvt_pk_bf16(f[4], f[5]); w.w = cvt_pk_bf16(f[6], f[7]); return w; }
;     __device__ __forceinline__ void operator()(const f32x4 (&acc)[2][2][4][2], const Unit& u, int wr, int wc, int fr, int fq, LAS unsigned char* lds, int par, int npm, int tid) const {
;         const int row0 = u.pm * BM + wr * 64 + fr, col0 = u.pn * BM + wc * 32 + 8 * fq;
;         u32x4 old[2][4][2];
; #pragma unroll
;         for (int ai = 0; ai < 2; ++ai)
; #pragma unroll
;             for (int m = 0; m < 4; ++m)
; #pragma unroll
;                 for (int bj = 0; bj < 2; ++bj) old[ai][m][bj] = *(const u32x4*)(Hb + (size_t)(row0 + ai * HALF + m * 16) * ldc + col0 + bj * HALF);
; #pragma unroll
;         for (int ai = 0; ai < 2; ++ai)
; #pragma unroll
;             for (int m = 0; m < 4; ++m) { const int row = row0 + ai * HALF + m * 16; bf16_t* hp = Hb + (size_t)row * ldc + col0;
;                 float part = 0.f;
; #pragma unroll
;                 for (int bj = 0; bj < 2; ++bj) { float o[8]; unpack8(old[ai][m][bj], o);
;                     const f32x4 a0 = acc[ai][bj][m][0], a1 = acc[ai][bj][m][1];
;                     float v[8] = {o[0] + a0[0], o[1] + a0[1], o[2] + a0[2], o[3] + a0[3], o[4] + a1[0], o[5] + a1[1], o[6] + a1[2], o[7] + a1[3]};
; #pragma unroll
;                     for (int k = 0; k < 8; ++k) part += v[k] * v[k];
;                     *(u32x4*)(hp + bj * HALF) = pack8(v); }
;                 part += __shfl_xor(part, 16); part += __shfl_xor(part, 32);
;                 if (fq == 0) atomicAdd(ssq + row, (unsigned long long)(part * 1048576.f)); }
.LBB0_120:
	v_lshl_or_b32 v212, s38, 8, v246
	v_lshl_add_u32 v228, s37, 8, v201
	v_ashrrev_i32_e32 v213, 31, v212
	v_readlane_b32 s14, v254, 8
	v_lshlrev_b64 v[230:231], 1, v[212:213]
	v_readlane_b32 s15, v254, 9
	v_ashrrev_i32_e32 v229, 31, v228
	v_lshlrev_b64 v[232:233], 12, v[228:229]
	v_lshl_add_u64 v[132:133], s[14:15], 0, v[230:231]
	v_lshl_add_u64 v[128:129], v[132:133], 0, v[232:233]
	global_load_dwordx4 v[188:191], v[128:129], off
	global_load_dwordx4 v[184:187], v[128:129], off offset:256
	v_or_b32_e32 v226, 16, v228
	v_ashrrev_i32_e32 v227, 31, v226
	v_lshlrev_b64 v[128:129], 12, v[226:227]
	v_or_b32_e32 v224, 32, v228
	v_lshl_add_u64 v[128:129], v[132:133], 0, v[128:129]
	v_ashrrev_i32_e32 v225, 31, v224
	global_load_dwordx4 v[180:183], v[128:129], off
	global_load_dwordx4 v[176:179], v[128:129], off offset:256
	v_lshlrev_b64 v[128:129], 12, v[224:225]
	v_or_b32_e32 v222, 48, v228
	v_lshl_add_u64 v[128:129], v[132:133], 0, v[128:129]
	v_ashrrev_i32_e32 v223, 31, v222
	global_load_dwordx4 v[172:175], v[128:129], off
	global_load_dwordx4 v[168:171], v[128:129], off offset:256
	v_lshlrev_b64 v[128:129], 12, v[222:223]
	v_add_u32_e32 v220, 0x80, v228
	v_lshl_add_u64 v[128:129], v[132:133], 0, v[128:129]
	v_ashrrev_i32_e32 v221, 31, v220
	global_load_dwordx4 v[164:167], v[128:129], off
	global_load_dwordx4 v[160:163], v[128:129], off offset:256
	v_lshlrev_b64 v[128:129], 12, v[220:221]
	v_add_u32_e32 v218, 0x90, v228
	v_lshl_add_u64 v[128:129], v[132:133], 0, v[128:129]
	v_ashrrev_i32_e32 v219, 31, v218
	global_load_dwordx4 v[156:159], v[128:129], off
	global_load_dwordx4 v[152:155], v[128:129], off offset:256
	v_lshlrev_b64 v[128:129], 12, v[218:219]
	v_add_u32_e32 v216, 0xa0, v228
	v_add_u32_e32 v214, 0xb0, v228
	v_lshl_add_u64 v[128:129], v[132:133], 0, v[128:129]
	v_ashrrev_i32_e32 v217, 31, v216
	v_ashrrev_i32_e32 v215, 31, v214
	global_load_dwordx4 v[148:151], v[128:129], off
	global_load_dwordx4 v[144:147], v[128:129], off offset:256
	v_lshlrev_b64 v[128:129], 12, v[216:217]
	v_lshlrev_b64 v[134:135], 12, v[214:215]
	v_lshl_add_u64 v[128:129], v[132:133], 0, v[128:129]
	v_lshl_add_u64 v[132:133], v[132:133], 0, v[134:135]
	global_load_dwordx4 v[136:139], v[128:129], off
	s_nop 0
	global_load_dwordx4 v[128:131], v[128:129], off offset:256
	s_nop 0
	global_load_dwordx4 v[140:143], v[132:133], off
	s_nop 0
	global_load_dwordx4 v[132:135], v[132:133], off offset:256
	v_lshl_add_u64 v[232:233], s[14:15], 0, v[232:233]
	v_lshl_add_u64 v[230:231], v[232:233], 0, v[230:231]
	s_waitcnt vmcnt(0) lgkmcnt(0)
	v_lshlrev_b32_e32 v193, 16, v188
	v_and_b32_e32 v188, 0xffff0000, v188
	v_lshlrev_b32_e32 v239, 16, v191
	v_and_b32_e32 v191, 0xffff0000, v191
	v_add_f32_e32 v125, v125, v188
	v_lshlrev_b32_e32 v232, 16, v189
	v_add_f32_e32 v124, v124, v193
	v_add_f32_e32 v123, v123, v191
	v_mul_f32_e32 v191, v125, v125
	v_and_b32_e32 v189, 0xffff0000, v189
	v_add_f32_e32 v126, v126, v232
	v_fmac_f32_e32 v191, v124, v124
	v_lshlrev_b32_e32 v233, 16, v190
	v_add_f32_e32 v127, v127, v189
	v_fmac_f32_e32 v191, v126, v126
	v_and_b32_e32 v190, 0xffff0000, v190
	v_add_f32_e32 v188, v120, v233
	v_fmac_f32_e32 v191, v127, v127
	v_add_f32_e32 v189, v121, v190
	v_fmac_f32_e32 v191, v188, v188
	v_add_f32_e32 v190, v122, v239
	v_fmac_f32_e32 v191, v189, v189
	v_fmac_f32_e32 v191, v190, v190
	v_cvt_pk_bf16_f32 v120, v124, v125
	v_fmac_f32_e32 v191, v123, v123
	v_cvt_pk_bf16_f32 v121, v126, v127
	v_cvt_pk_bf16_f32 v122, v188, v189
	v_cvt_pk_bf16_f32 v123, v190, v123
	global_store_dwordx4 v[230:231], v[120:123], off
	v_lshlrev_b32_e32 v124, 16, v186
	v_and_b32_e32 v125, 0xffff0000, v186
	v_lshlrev_b32_e32 v120, 16, v184
	v_and_b32_e32 v121, 0xffff0000, v184
	v_add_f32_e32 v116, v116, v120
	v_lshlrev_b32_e32 v122, 16, v185
	v_add_f32_e32 v117, v117, v121
	v_fmac_f32_e32 v191, v116, v116
	v_and_b32_e32 v123, 0xffff0000, v185
	v_add_f32_e32 v118, v118, v122
	v_fmac_f32_e32 v191, v117, v117
	v_add_f32_e32 v119, v119, v123
	v_fmac_f32_e32 v191, v118, v118
	v_add_f32_e32 v120, v112, v124
	v_fmac_f32_e32 v191, v119, v119
	v_lshlrev_b32_e32 v126, 16, v187
	v_add_f32_e32 v121, v113, v125
	v_fmac_f32_e32 v191, v120, v120
	v_and_b32_e32 v127, 0xffff0000, v187
	v_add_f32_e32 v122, v114, v126
	v_fmac_f32_e32 v191, v121, v121
	v_add_f32_e32 v115, v115, v127
	v_fmac_f32_e32 v191, v122, v122
	v_cvt_pk_bf16_f32 v112, v116, v117
	v_cvt_pk_bf16_f32 v113, v118, v119
	v_fmac_f32_e32 v191, v115, v115
	v_cvt_pk_bf16_f32 v114, v120, v121
	v_cvt_pk_bf16_f32 v115, v122, v115
	global_store_dwordx4 v[230:231], v[112:115], off offset:256
	s_nop 1
	v_and_b32_e32 v113, 64, v238
	v_xor_b32_e32 v112, 16, v238
	v_add_u32_e32 v113, 64, v113
	v_cmp_lt_i32_e32 vcc, v112, v113
	v_xor_b32_e32 v115, 32, v238
	s_nop 0
	v_cndmask_b32_e32 v112, v238, v112, vcc
	v_lshlrev_b32_e32 v112, 2, v112
	ds_bpermute_b32 v114, v112, v191
	v_cmp_lt_i32_e32 vcc, v115, v113
	s_waitcnt lgkmcnt(0)
	v_add_f32_e32 v114, v191, v114
	v_cndmask_b32_e32 v113, v238, v115, vcc
	v_lshlrev_b32_e32 v113, 2, v113
	ds_bpermute_b32 v115, v113, v114
	s_and_saveexec_b64 s[14:15], s[4:5]
	s_cbranch_execz .LBB0_122
	s_waitcnt lgkmcnt(0)
	v_add_f32_e32 v114, v114, v115
	v_mul_f32_e32 v114, 0x49800000, v114
	v_trunc_f32_e32 v114, v114
	v_mul_f32_e32 v115, 0x2f800000, v114
	v_floor_f32_e32 v115, v115
	v_fmac_f32_e32 v114, 0xcf800000, v115
	v_cvt_u32_f32_e32 v114, v114
	v_cvt_u32_f32_e32 v115, v115
	v_readlane_b32 s16, v254, 37
	v_readlane_b32 s17, v254, 38
	s_nop 1
	v_lshl_add_u64 v[116:117], v[228:229], 3, s[16:17]
	global_atomic_add_x2 v[116:117], v[114:115], off
; __device__ __forceinline__ void unpack8(u32x4 w, float* f) { f[0] = bflo(w.x); f[1] = bfhi(w.x); f[2] = bflo(w.y); f[3] = bfhi(w.y); f[4] = bflo(w.z); f[5] = bfhi(w.z); f[6] = bflo(w.w); f[7] = bfhi(w.w); }
; __device__ __forceinline__ u32x4 pack8(const float* f) { u32x4 w; w.x = cvt_pk_bf16(f[0], f[1]); w.y = cvt_pk_bf16(f[2], f[3]); w.z = cvt_pk_bf16(f[4], f[5]); w.w = cvt_pk_bf16(f[6], f[7]); return w; }
;     __device__ __forceinline__ void operator()(const f32x4 (&acc)[2][2][4][2], const Unit& u, int wr, int wc, int fr, int fq, LAS unsigned char* lds, int par, int npm, int tid) const {
;     ...
;         for (int ai = 0; ai < 2; ++ai)
; #pragma unroll
;             for (int m = 0; m < 4; ++m) { const int row = row0 + ai * HALF + m * 16; bf16_t* hp = Hb + (size_t)row * ldc + col0;
;                 float part = 0.f;
; #pragma unroll
;                 for (int bj = 0; bj < 2; ++bj) { float o[8]; unpack8(old[ai][m][bj], o);
;                     const f32x4 a0 = acc[ai][bj][m][0], a1 = acc[ai][bj][m][1];
;                     float v[8] = {o[0] + a0[0], o[1] + a0[1], o[2] + a0[2], o[3] + a0[3], o[4] + a1[0], o[5] + a1[1], o[6] + a1[2], o[7] + a1[3]};
; #pragma unroll
;                     for (int k = 0; k < 8; ++k) part += v[k] * v[k];
;                     *(u32x4*)(hp + bj * HALF) = pack8(v); }
;                 part += __shfl_xor(part, 16); part += __shfl_xor(part, 32);
;                 if (fq == 0) atomicAdd(ssq + row, (unsigned long long)(part * 1048576.f)); }
.LBB0_122:
	s_or_b64 exec, exec, s[14:15]
	v_and_b32_e32 v117, 0xffff0000, v180
	v_lshlrev_b32_e32 v116, 16, v180
	v_and_b32_e32 v119, 0xffff0000, v181
	v_add_f32_e32 v109, v109, v117
	v_lshlrev_b32_e32 v118, 16, v181
	v_add_f32_e32 v108, v108, v116
	v_add_f32_e32 v111, v111, v119
	v_mul_f32_e32 v119, v109, v109
	v_add_f32_e32 v110, v110, v118
	v_fmac_f32_e32 v119, v108, v108
	v_lshlrev_b32_e32 v120, 16, v182
	v_fmac_f32_e32 v119, v110, v110
	v_and_b32_e32 v121, 0xffff0000, v182
	v_add_f32_e32 v116, v104, v120
	v_fmac_f32_e32 v119, v111, v111
	v_lshlrev_b32_e32 v122, 16, v183
	v_add_f32_e32 v117, v105, v121
	v_fmac_f32_e32 v119, v116, v116
	v_and_b32_e32 v123, 0xffff0000, v183
	v_add_f32_e32 v118, v106, v122
	v_fmac_f32_e32 v119, v117, v117
	v_add_f32_e32 v107, v107, v123
	v_fmac_f32_e32 v119, v118, v118
	v_lshlrev_b32_e32 v106, 16, v176
	v_fmac_f32_e32 v119, v107, v107
	v_cvt_pk_bf16_f32 v104, v108, v109
	v_and_b32_e32 v108, 0xffff0000, v176
	v_add_f32_e32 v100, v100, v106
	v_lshlrev_b32_e32 v109, 16, v177
	v_add_f32_e32 v101, v101, v108
	v_fmac_f32_e32 v119, v100, v100
	v_cvt_pk_bf16_f32 v105, v110, v111
	v_and_b32_e32 v110, 0xffff0000, v177
	v_add_f32_e32 v102, v102, v109
	v_fmac_f32_e32 v119, v101, v101
	v_lshlrev_b32_e32 v111, 16, v178
	v_add_f32_e32 v103, v103, v110
	v_fmac_f32_e32 v119, v102, v102
	v_and_b32_e32 v120, 0xffff0000, v178
	v_add_f32_e32 v108, v96, v111
	v_fmac_f32_e32 v119, v103, v103
	v_lshlrev_b32_e32 v121, 16, v179
	v_add_f32_e32 v109, v97, v120
	v_fmac_f32_e32 v119, v108, v108
	v_and_b32_e32 v122, 0xffff0000, v179
	v_add_f32_e32 v110, v98, v121
	v_fmac_f32_e32 v119, v109, v109
	v_add_f32_e32 v111, v99, v122
	v_fmac_f32_e32 v119, v110, v110
	v_fmac_f32_e32 v119, v111, v111
	ds_bpermute_b32 v96, v112, v119
	v_readlane_b32 s14, v254, 8
	s_waitcnt lgkmcnt(0)
	v_lshlrev_b64 v[114:115], 11, v[226:227]
	v_readlane_b32 s15, v254, 9
	v_cvt_pk_bf16_f32 v106, v116, v117
	v_add_f32_e32 v96, v119, v96
	ds_bpermute_b32 v97, v113, v96
	v_lshl_add_u64 v[114:115], v[114:115], 1, s[14:15]
	v_lshl_add_u64 v[114:115], v[212:213], 1, v[114:115]
	v_cvt_pk_bf16_f32 v107, v118, v107
	global_store_dwordx4 v[114:115], v[104:107], off
	v_cvt_pk_bf16_f32 v98, v100, v101
	v_cvt_pk_bf16_f32 v99, v102, v103
	v_cvt_pk_bf16_f32 v100, v108, v109
	v_cvt_pk_bf16_f32 v101, v110, v111
	global_store_dwordx4 v[114:115], v[98:101], off offset:256
	s_and_saveexec_b64 s[14:15], s[4:5]
	s_cbranch_execz .LBB0_124
	s_waitcnt lgkmcnt(0)
	v_add_f32_e32 v96, v96, v97
	v_mul_f32_e32 v96, 0x49800000, v96
	v_trunc_f32_e32 v96, v96
	v_mul_f32_e32 v97, 0x2f800000, v96
	v_floor_f32_e32 v97, v97
	v_fmac_f32_e32 v96, 0xcf800000, v97
	v_cvt_u32_f32_e32 v96, v96
	v_cvt_u32_f32_e32 v97, v97
	v_readlane_b32 s16, v254, 37
	v_readlane_b32 s17, v254, 38
	s_nop 1
	v_lshl_add_u64 v[98:99], v[226:227], 3, s[16:17]
	global_atomic_add_x2 v[98:99], v[96:97], off
.LBB0_124:
	s_or_b64 exec, exec, s[14:15]
	v_and_b32_e32 v99, 0xffff0000, v172
	v_lshlrev_b32_e32 v98, 16, v172
	v_and_b32_e32 v101, 0xffff0000, v173
	v_add_f32_e32 v93, v93, v99
	v_lshlrev_b32_e32 v100, 16, v173
	v_add_f32_e32 v92, v92, v98
	v_add_f32_e32 v95, v95, v101
	v_mul_f32_e32 v101, v93, v93
	v_add_f32_e32 v94, v94, v100
	v_fmac_f32_e32 v101, v92, v92
	v_lshlrev_b32_e32 v102, 16, v174
	v_fmac_f32_e32 v101, v94, v94
	v_and_b32_e32 v103, 0xffff0000, v174
	v_add_f32_e32 v98, v88, v102
	v_fmac_f32_e32 v101, v95, v95
	v_lshlrev_b32_e32 v104, 16, v175
	v_add_f32_e32 v99, v89, v103
	v_fmac_f32_e32 v101, v98, v98
	v_and_b32_e32 v105, 0xffff0000, v175
	v_add_f32_e32 v100, v90, v104
	v_fmac_f32_e32 v101, v99, v99
	v_add_f32_e32 v91, v91, v105
	v_fmac_f32_e32 v101, v100, v100
	v_lshlrev_b32_e32 v90, 16, v168
	v_fmac_f32_e32 v101, v91, v91
	v_cvt_pk_bf16_f32 v88, v92, v93
	v_and_b32_e32 v92, 0xffff0000, v168
	v_add_f32_e32 v84, v84, v90
	v_lshlrev_b32_e32 v93, 16, v169
	v_add_f32_e32 v85, v85, v92
	v_fmac_f32_e32 v101, v84, v84
	v_cvt_pk_bf16_f32 v89, v94, v95
	v_and_b32_e32 v94, 0xffff0000, v169
	v_add_f32_e32 v86, v86, v93
	v_fmac_f32_e32 v101, v85, v85
	v_lshlrev_b32_e32 v95, 16, v170
	v_add_f32_e32 v87, v87, v94
	v_fmac_f32_e32 v101, v86, v86
	v_and_b32_e32 v102, 0xffff0000, v170
	v_add_f32_e32 v92, v80, v95
	v_fmac_f32_e32 v101, v87, v87
	v_lshlrev_b32_e32 v103, 16, v171
	v_add_f32_e32 v93, v81, v102
	v_fmac_f32_e32 v101, v92, v92
	v_and_b32_e32 v104, 0xffff0000, v171
	v_add_f32_e32 v94, v82, v103
	v_fmac_f32_e32 v101, v93, v93
	v_add_f32_e32 v95, v83, v104
	v_fmac_f32_e32 v101, v94, v94
	v_fmac_f32_e32 v101, v95, v95
	ds_bpermute_b32 v80, v112, v101
	v_readlane_b32 s14, v254, 8
	s_waitcnt lgkmcnt(0)
	v_lshlrev_b64 v[96:97], 11, v[224:225]
	v_readlane_b32 s15, v254, 9
	v_cvt_pk_bf16_f32 v90, v98, v99
	v_add_f32_e32 v80, v101, v80
	ds_bpermute_b32 v81, v113, v80
	v_lshl_add_u64 v[96:97], v[96:97], 1, s[14:15]
	v_lshl_add_u64 v[96:97], v[212:213], 1, v[96:97]
	v_cvt_pk_bf16_f32 v91, v100, v91
	global_store_dwordx4 v[96:97], v[88:91], off
	v_cvt_pk_bf16_f32 v82, v84, v85
	v_cvt_pk_bf16_f32 v83, v86, v87
	v_cvt_pk_bf16_f32 v84, v92, v93
	v_cvt_pk_bf16_f32 v85, v94, v95
	global_store_dwordx4 v[96:97], v[82:85], off offset:256
	s_and_saveexec_b64 s[14:15], s[4:5]
	s_cbranch_execz .LBB0_126
	s_waitcnt lgkmcnt(0)
	v_add_f32_e32 v80, v80, v81
	v_mul_f32_e32 v80, 0x49800000, v80
	v_trunc_f32_e32 v80, v80
	v_mul_f32_e32 v81, 0x2f800000, v80
	v_floor_f32_e32 v81, v81
	v_fmac_f32_e32 v80, 0xcf800000, v81
	v_cvt_u32_f32_e32 v80, v80
	v_cvt_u32_f32_e32 v81, v81
	v_readlane_b32 s16, v254, 37
	v_readlane_b32 s17, v254, 38
	s_nop 1
	v_lshl_add_u64 v[82:83], v[224:225], 3, s[16:17]
	global_atomic_add_x2 v[82:83], v[80:81], off
; __device__ __forceinline__ void unpack8(u32x4 w, float* f) { f[0] = bflo(w.x); f[1] = bfhi(w.x); f[2] = bflo(w.y); f[3] = bfhi(w.y); f[4] = bflo(w.z); f[5] = bfhi(w.z); f[6] = bflo(w.w); f[7] = bfhi(w.w); }
; __device__ __forceinline__ u32x4 pack8(const float* f) { u32x4 w; w.x = cvt_pk_bf16(f[0], f[1]); w.y = cvt_pk_bf16(f[2], f[3]); w.z = cvt_pk_bf16(f[4], f[5]); w.w = cvt_pk_bf16(f[6], f[7]); return w; }
;     __device__ __forceinline__ void operator()(const f32x4 (&acc)[2][2][4][2], const Unit& u, int wr, int wc, int fr, int fq, LAS unsigned char* lds, int par, int npm, int tid) const {
;     ...
;         for (int ai = 0; ai < 2; ++ai)
; #pragma unroll
;             for (int m = 0; m < 4; ++m) { const int row = row0 + ai * HALF + m * 16; bf16_t* hp = Hb + (size_t)row * ldc + col0;
;                 float part = 0.f;
; #pragma unroll
;                 for (int bj = 0; bj < 2; ++bj) { float o[8]; unpack8(old[ai][m][bj], o);
;                     const f32x4 a0 = acc[ai][bj][m][0], a1 = acc[ai][bj][m][1];
;                     float v[8] = {o[0] + a0[0], o[1] + a0[1], o[2] + a0[2], o[3] + a0[3], o[4] + a1[0], o[5] + a1[1], o[6] + a1[2], o[7] + a1[3]};
; #pragma unroll
;                     for (int k = 0; k < 8; ++k) part += v[k] * v[k];
;                     *(u32x4*)(hp + bj * HALF) = pack8(v); }
;                 part += __shfl_xor(part, 16); part += __shfl_xor(part, 32);
;                 if (fq == 0) atomicAdd(ssq + row, (unsigned long long)(part * 1048576.f)); }
.LBB0_126:
	s_or_b64 exec, exec, s[14:15]
	v_and_b32_e32 v83, 0xffff0000, v164
	v_lshlrev_b32_e32 v82, 16, v164
	v_and_b32_e32 v85, 0xffff0000, v165
	v_add_f32_e32 v77, v77, v83
	v_lshlrev_b32_e32 v84, 16, v165
	v_add_f32_e32 v76, v76, v82
	v_add_f32_e32 v79, v79, v85
	v_mul_f32_e32 v85, v77, v77
	v_add_f32_e32 v78, v78, v84
	v_fmac_f32_e32 v85, v76, v76
	v_lshlrev_b32_e32 v86, 16, v166
	v_fmac_f32_e32 v85, v78, v78
	v_and_b32_e32 v87, 0xffff0000, v166
	v_add_f32_e32 v82, v72, v86
	v_fmac_f32_e32 v85, v79, v79
	v_lshlrev_b32_e32 v88, 16, v167
	v_add_f32_e32 v83, v73, v87
	v_fmac_f32_e32 v85, v82, v82
	v_and_b32_e32 v89, 0xffff0000, v167
	v_add_f32_e32 v84, v74, v88
	v_fmac_f32_e32 v85, v83, v83
	v_add_f32_e32 v75, v75, v89
	v_fmac_f32_e32 v85, v84, v84
	v_lshlrev_b32_e32 v74, 16, v160
	v_fmac_f32_e32 v85, v75, v75
	v_cvt_pk_bf16_f32 v72, v76, v77
	v_and_b32_e32 v76, 0xffff0000, v160
	v_add_f32_e32 v68, v68, v74
	v_lshlrev_b32_e32 v77, 16, v161
	v_add_f32_e32 v69, v69, v76
	v_fmac_f32_e32 v85, v68, v68
	v_cvt_pk_bf16_f32 v73, v78, v79
	v_and_b32_e32 v78, 0xffff0000, v161
	v_add_f32_e32 v70, v70, v77
	v_fmac_f32_e32 v85, v69, v69
	v_lshlrev_b32_e32 v79, 16, v162
	v_add_f32_e32 v71, v71, v78
	v_fmac_f32_e32 v85, v70, v70
	v_and_b32_e32 v86, 0xffff0000, v162
	v_add_f32_e32 v76, v64, v79
	v_fmac_f32_e32 v85, v71, v71
	v_lshlrev_b32_e32 v87, 16, v163
	v_add_f32_e32 v77, v65, v86
	v_fmac_f32_e32 v85, v76, v76
	v_and_b32_e32 v88, 0xffff0000, v163
	v_add_f32_e32 v78, v66, v87
	v_fmac_f32_e32 v85, v77, v77
	v_add_f32_e32 v79, v67, v88
	v_fmac_f32_e32 v85, v78, v78
	v_fmac_f32_e32 v85, v79, v79
	ds_bpermute_b32 v64, v112, v85
	v_readlane_b32 s14, v254, 8
	s_waitcnt lgkmcnt(0)
	v_lshlrev_b64 v[80:81], 11, v[222:223]
	v_readlane_b32 s15, v254, 9
	v_cvt_pk_bf16_f32 v74, v82, v83
	v_add_f32_e32 v64, v85, v64
	ds_bpermute_b32 v65, v113, v64
	v_lshl_add_u64 v[80:81], v[80:81], 1, s[14:15]
	v_lshl_add_u64 v[80:81], v[212:213], 1, v[80:81]
	v_cvt_pk_bf16_f32 v75, v84, v75
	global_store_dwordx4 v[80:81], v[72:75], off
	v_cvt_pk_bf16_f32 v66, v68, v69
	v_cvt_pk_bf16_f32 v67, v70, v71
	v_cvt_pk_bf16_f32 v68, v76, v77
	v_cvt_pk_bf16_f32 v69, v78, v79
	global_store_dwordx4 v[80:81], v[66:69], off offset:256
	s_and_saveexec_b64 s[14:15], s[4:5]
	s_cbranch_execz .LBB0_128
	s_waitcnt lgkmcnt(0)
	v_add_f32_e32 v64, v64, v65
	v_mul_f32_e32 v64, 0x49800000, v64
	v_trunc_f32_e32 v64, v64
	v_mul_f32_e32 v65, 0x2f800000, v64
	v_floor_f32_e32 v65, v65
	v_fmac_f32_e32 v64, 0xcf800000, v65
	v_cvt_u32_f32_e32 v64, v64
	v_cvt_u32_f32_e32 v65, v65
	v_readlane_b32 s16, v254, 37
	v_readlane_b32 s17, v254, 38
	s_nop 1
	v_lshl_add_u64 v[66:67], v[222:223], 3, s[16:17]
	global_atomic_add_x2 v[66:67], v[64:65], off
.LBB0_128:
	s_or_b64 exec, exec, s[14:15]
	v_and_b32_e32 v67, 0xffff0000, v156
	v_lshlrev_b32_e32 v66, 16, v156
	v_and_b32_e32 v69, 0xffff0000, v157
	v_add_f32_e32 v61, v61, v67
	v_lshlrev_b32_e32 v68, 16, v157
	v_add_f32_e32 v60, v60, v66
	v_add_f32_e32 v63, v63, v69
	v_mul_f32_e32 v69, v61, v61
	v_add_f32_e32 v62, v62, v68
	v_fmac_f32_e32 v69, v60, v60
	v_lshlrev_b32_e32 v70, 16, v158
	v_fmac_f32_e32 v69, v62, v62
	v_and_b32_e32 v71, 0xffff0000, v158
	v_add_f32_e32 v66, v56, v70
	v_fmac_f32_e32 v69, v63, v63
	v_lshlrev_b32_e32 v72, 16, v159
	v_add_f32_e32 v67, v57, v71
	v_fmac_f32_e32 v69, v66, v66
	v_and_b32_e32 v73, 0xffff0000, v159
	v_add_f32_e32 v68, v58, v72
	v_fmac_f32_e32 v69, v67, v67
	v_add_f32_e32 v59, v59, v73
	v_fmac_f32_e32 v69, v68, v68
	v_lshlrev_b32_e32 v58, 16, v152
	v_fmac_f32_e32 v69, v59, v59
	v_cvt_pk_bf16_f32 v56, v60, v61
	v_and_b32_e32 v60, 0xffff0000, v152
	v_add_f32_e32 v52, v52, v58
	v_lshlrev_b32_e32 v61, 16, v153
	v_add_f32_e32 v53, v53, v60
	v_fmac_f32_e32 v69, v52, v52
	v_cvt_pk_bf16_f32 v57, v62, v63
	v_and_b32_e32 v62, 0xffff0000, v153
	v_add_f32_e32 v54, v54, v61
	v_fmac_f32_e32 v69, v53, v53
	v_lshlrev_b32_e32 v63, 16, v154
	v_add_f32_e32 v55, v55, v62
	v_fmac_f32_e32 v69, v54, v54
	v_and_b32_e32 v70, 0xffff0000, v154
	v_add_f32_e32 v60, v48, v63
	v_fmac_f32_e32 v69, v55, v55
	v_lshlrev_b32_e32 v71, 16, v155
	v_add_f32_e32 v61, v49, v70
	v_fmac_f32_e32 v69, v60, v60
	v_and_b32_e32 v72, 0xffff0000, v155
	v_add_f32_e32 v62, v50, v71
	v_fmac_f32_e32 v69, v61, v61
	v_add_f32_e32 v63, v51, v72
	v_fmac_f32_e32 v69, v62, v62
	v_fmac_f32_e32 v69, v63, v63
	ds_bpermute_b32 v48, v112, v69
	v_readlane_b32 s14, v254, 8
	s_waitcnt lgkmcnt(0)
	v_lshlrev_b64 v[64:65], 11, v[220:221]
	v_readlane_b32 s15, v254, 9
	v_cvt_pk_bf16_f32 v58, v66, v67
	v_add_f32_e32 v48, v69, v48
	ds_bpermute_b32 v49, v113, v48
	v_lshl_add_u64 v[64:65], v[64:65], 1, s[14:15]
	v_lshl_add_u64 v[64:65], v[212:213], 1, v[64:65]
	v_cvt_pk_bf16_f32 v59, v68, v59
	global_store_dwordx4 v[64:65], v[56:59], off
	v_cvt_pk_bf16_f32 v50, v52, v53
	v_cvt_pk_bf16_f32 v51, v54, v55
	v_cvt_pk_bf16_f32 v52, v60, v61
	v_cvt_pk_bf16_f32 v53, v62, v63
	global_store_dwordx4 v[64:65], v[50:53], off offset:256
	s_and_saveexec_b64 s[14:15], s[4:5]
	s_cbranch_execz .LBB0_130
	s_waitcnt lgkmcnt(0)
	v_add_f32_e32 v48, v48, v49
	v_mul_f32_e32 v48, 0x49800000, v48
	v_trunc_f32_e32 v48, v48
	v_mul_f32_e32 v49, 0x2f800000, v48
	v_floor_f32_e32 v49, v49
	v_fmac_f32_e32 v48, 0xcf800000, v49
	v_cvt_u32_f32_e32 v48, v48
	v_cvt_u32_f32_e32 v49, v49
	v_readlane_b32 s16, v254, 37
	v_readlane_b32 s17, v254, 38
	s_nop 1
	v_lshl_add_u64 v[50:51], v[220:221], 3, s[16:17]
	global_atomic_add_x2 v[50:51], v[48:49], off
; __device__ __forceinline__ void unpack8(u32x4 w, float* f) { f[0] = bflo(w.x); f[1] = bfhi(w.x); f[2] = bflo(w.y); f[3] = bfhi(w.y); f[4] = bflo(w.z); f[5] = bfhi(w.z); f[6] = bflo(w.w); f[7] = bfhi(w.w); }
; __device__ __forceinline__ u32x4 pack8(const float* f) { u32x4 w; w.x = cvt_pk_bf16(f[0], f[1]); w.y = cvt_pk_bf16(f[2], f[3]); w.z = cvt_pk_bf16(f[4], f[5]); w.w = cvt_pk_bf16(f[6], f[7]); return w; }
;     __device__ __forceinline__ void operator()(const f32x4 (&acc)[2][2][4][2], const Unit& u, int wr, int wc, int fr, int fq, LAS unsigned char* lds, int par, int npm, int tid) const {
;     ...
;         for (int ai = 0; ai < 2; ++ai)
; #pragma unroll
;             for (int m = 0; m < 4; ++m) { const int row = row0 + ai * HALF + m * 16; bf16_t* hp = Hb + (size_t)row * ldc + col0;
;                 float part = 0.f;
; #pragma unroll
;                 for (int bj = 0; bj < 2; ++bj) { float o[8]; unpack8(old[ai][m][bj], o);
;                     const f32x4 a0 = acc[ai][bj][m][0], a1 = acc[ai][bj][m][1];
;                     float v[8] = {o[0] + a0[0], o[1] + a0[1], o[2] + a0[2], o[3] + a0[3], o[4] + a1[0], o[5] + a1[1], o[6] + a1[2], o[7] + a1[3]};
; #pragma unroll
;                     for (int k = 0; k < 8; ++k) part += v[k] * v[k];
;                     *(u32x4*)(hp + bj * HALF) = pack8(v); }
;                 part += __shfl_xor(part, 16); part += __shfl_xor(part, 32);
;                 if (fq == 0) atomicAdd(ssq + row, (unsigned long long)(part * 1048576.f)); }
.LBB0_130:
	s_or_b64 exec, exec, s[14:15]
	v_and_b32_e32 v51, 0xffff0000, v148
	v_lshlrev_b32_e32 v50, 16, v148
	v_and_b32_e32 v53, 0xffff0000, v149
	v_add_f32_e32 v45, v45, v51
	v_lshlrev_b32_e32 v52, 16, v149
	v_add_f32_e32 v44, v44, v50
	v_add_f32_e32 v47, v47, v53
	v_mul_f32_e32 v53, v45, v45
	v_add_f32_e32 v46, v46, v52
	v_fmac_f32_e32 v53, v44, v44
	v_lshlrev_b32_e32 v54, 16, v150
	v_fmac_f32_e32 v53, v46, v46
	v_and_b32_e32 v55, 0xffff0000, v150
	v_add_f32_e32 v50, v40, v54
	v_fmac_f32_e32 v53, v47, v47
	v_lshlrev_b32_e32 v56, 16, v151
	v_add_f32_e32 v51, v41, v55
	v_fmac_f32_e32 v53, v50, v50
	v_and_b32_e32 v57, 0xffff0000, v151
	v_add_f32_e32 v52, v42, v56
	v_fmac_f32_e32 v53, v51, v51
	v_add_f32_e32 v43, v43, v57
	v_fmac_f32_e32 v53, v52, v52
	v_lshlrev_b32_e32 v42, 16, v144
	v_fmac_f32_e32 v53, v43, v43
	v_cvt_pk_bf16_f32 v40, v44, v45
	v_and_b32_e32 v44, 0xffff0000, v144
	v_add_f32_e32 v36, v36, v42
	v_lshlrev_b32_e32 v45, 16, v145
	v_add_f32_e32 v37, v37, v44
	v_fmac_f32_e32 v53, v36, v36
	v_cvt_pk_bf16_f32 v41, v46, v47
	v_and_b32_e32 v46, 0xffff0000, v145
	v_add_f32_e32 v38, v38, v45
	v_fmac_f32_e32 v53, v37, v37
	v_lshlrev_b32_e32 v47, 16, v146
	v_add_f32_e32 v39, v39, v46
	v_fmac_f32_e32 v53, v38, v38
	v_and_b32_e32 v54, 0xffff0000, v146
	v_add_f32_e32 v44, v32, v47
	v_fmac_f32_e32 v53, v39, v39
	v_lshlrev_b32_e32 v55, 16, v147
	v_add_f32_e32 v45, v33, v54
	v_fmac_f32_e32 v53, v44, v44
	v_and_b32_e32 v56, 0xffff0000, v147
	v_add_f32_e32 v46, v34, v55
	v_fmac_f32_e32 v53, v45, v45
	v_add_f32_e32 v47, v35, v56
	v_fmac_f32_e32 v53, v46, v46
	v_fmac_f32_e32 v53, v47, v47
	ds_bpermute_b32 v32, v112, v53
	v_readlane_b32 s14, v254, 8
	s_waitcnt lgkmcnt(0)
	v_lshlrev_b64 v[48:49], 11, v[218:219]
	v_readlane_b32 s15, v254, 9
	v_cvt_pk_bf16_f32 v42, v50, v51
	v_add_f32_e32 v32, v53, v32
	ds_bpermute_b32 v33, v113, v32
	v_lshl_add_u64 v[48:49], v[48:49], 1, s[14:15]
	v_lshl_add_u64 v[48:49], v[212:213], 1, v[48:49]
	v_cvt_pk_bf16_f32 v43, v52, v43
	global_store_dwordx4 v[48:49], v[40:43], off
	v_cvt_pk_bf16_f32 v34, v36, v37
	v_cvt_pk_bf16_f32 v35, v38, v39
	v_cvt_pk_bf16_f32 v36, v44, v45
	v_cvt_pk_bf16_f32 v37, v46, v47
	global_store_dwordx4 v[48:49], v[34:37], off offset:256
	s_and_saveexec_b64 s[14:15], s[4:5]
	s_cbranch_execz .LBB0_132
	s_waitcnt lgkmcnt(0)
	v_add_f32_e32 v32, v32, v33
	v_mul_f32_e32 v32, 0x49800000, v32
	v_trunc_f32_e32 v32, v32
	v_mul_f32_e32 v33, 0x2f800000, v32
	v_floor_f32_e32 v33, v33
	v_fmac_f32_e32 v32, 0xcf800000, v33
	v_cvt_u32_f32_e32 v32, v32
	v_cvt_u32_f32_e32 v33, v33
	v_readlane_b32 s16, v254, 37
	v_readlane_b32 s17, v254, 38
	s_nop 1
	v_lshl_add_u64 v[34:35], v[218:219], 3, s[16:17]
	global_atomic_add_x2 v[34:35], v[32:33], off
; __device__ __forceinline__ void unpack8(u32x4 w, float* f) { f[0] = bflo(w.x); f[1] = bfhi(w.x); f[2] = bflo(w.y); f[3] = bfhi(w.y); f[4] = bflo(w.z); f[5] = bfhi(w.z); f[6] = bflo(w.w); f[7] = bfhi(w.w); }
; __device__ __forceinline__ u32x4 pack8(const float* f) { u32x4 w; w.x = cvt_pk_bf16(f[0], f[1]); w.y = cvt_pk_bf16(f[2], f[3]); w.z = cvt_pk_bf16(f[4], f[5]); w.w = cvt_pk_bf16(f[6], f[7]); return w; }
;     __device__ __forceinline__ void operator()(const f32x4 (&acc)[2][2][4][2], const Unit& u, int wr, int wc, int fr, int fq, LAS unsigned char* lds, int par, int npm, int tid) const {
;     ...
;         for (int ai = 0; ai < 2; ++ai)
; #pragma unroll
;             for (int m = 0; m < 4; ++m) { const int row = row0 + ai * HALF + m * 16; bf16_t* hp = Hb + (size_t)row * ldc + col0;
;                 float part = 0.f;
; #pragma unroll
;                 for (int bj = 0; bj < 2; ++bj) { float o[8]; unpack8(old[ai][m][bj], o);
;                     const f32x4 a0 = acc[ai][bj][m][0], a1 = acc[ai][bj][m][1];
;                     float v[8] = {o[0] + a0[0], o[1] + a0[1], o[2] + a0[2], o[3] + a0[3], o[4] + a1[0], o[5] + a1[1], o[6] + a1[2], o[7] + a1[3]};
; #pragma unroll
;                     for (int k = 0; k < 8; ++k) part += v[k] * v[k];
;                     *(u32x4*)(hp + bj * HALF) = pack8(v); }
;                 part += __shfl_xor(part, 16); part += __shfl_xor(part, 32);
;                 if (fq == 0) atomicAdd(ssq + row, (unsigned long long)(part * 1048576.f)); }
.LBB0_132:
	s_or_b64 exec, exec, s[14:15]
	v_and_b32_e32 v35, 0xffff0000, v136
	v_lshlrev_b32_e32 v34, 16, v136
	v_and_b32_e32 v37, 0xffff0000, v137
	v_add_f32_e32 v29, v29, v35
	v_lshlrev_b32_e32 v36, 16, v137
	v_add_f32_e32 v28, v28, v34
	v_add_f32_e32 v31, v31, v37
	v_mul_f32_e32 v37, v29, v29
	v_add_f32_e32 v30, v30, v36
	v_fmac_f32_e32 v37, v28, v28
	v_lshlrev_b32_e32 v38, 16, v138
	v_fmac_f32_e32 v37, v30, v30
	v_and_b32_e32 v39, 0xffff0000, v138
	v_add_f32_e32 v34, v24, v38
	v_fmac_f32_e32 v37, v31, v31
	v_lshlrev_b32_e32 v40, 16, v139
	v_add_f32_e32 v35, v25, v39
	v_fmac_f32_e32 v37, v34, v34
	v_and_b32_e32 v41, 0xffff0000, v139
	v_add_f32_e32 v36, v26, v40
	v_fmac_f32_e32 v37, v35, v35
	v_add_f32_e32 v27, v27, v41
	v_fmac_f32_e32 v37, v36, v36
	v_lshlrev_b32_e32 v26, 16, v128
	v_fmac_f32_e32 v37, v27, v27
	v_cvt_pk_bf16_f32 v24, v28, v29
	v_and_b32_e32 v28, 0xffff0000, v128
	v_add_f32_e32 v20, v20, v26
	v_lshlrev_b32_e32 v29, 16, v129
	v_add_f32_e32 v21, v21, v28
	v_fmac_f32_e32 v37, v20, v20
	v_cvt_pk_bf16_f32 v25, v30, v31
	v_and_b32_e32 v30, 0xffff0000, v129
	v_add_f32_e32 v22, v22, v29
	v_fmac_f32_e32 v37, v21, v21
	v_lshlrev_b32_e32 v31, 16, v130
	v_add_f32_e32 v23, v23, v30
	v_fmac_f32_e32 v37, v22, v22
	v_and_b32_e32 v38, 0xffff0000, v130
	v_add_f32_e32 v28, v16, v31
	v_fmac_f32_e32 v37, v23, v23
	v_lshlrev_b32_e32 v39, 16, v131
	v_add_f32_e32 v29, v17, v38
	v_fmac_f32_e32 v37, v28, v28
	v_and_b32_e32 v40, 0xffff0000, v131
	v_add_f32_e32 v30, v18, v39
	v_fmac_f32_e32 v37, v29, v29
	v_add_f32_e32 v31, v19, v40
	v_fmac_f32_e32 v37, v30, v30
	v_fmac_f32_e32 v37, v31, v31
	ds_bpermute_b32 v16, v112, v37
	v_readlane_b32 s14, v254, 8
	s_waitcnt lgkmcnt(0)
	v_lshlrev_b64 v[32:33], 11, v[216:217]
	v_readlane_b32 s15, v254, 9
	v_cvt_pk_bf16_f32 v26, v34, v35
	v_add_f32_e32 v16, v37, v16
	ds_bpermute_b32 v17, v113, v16
	v_lshl_add_u64 v[32:33], v[32:33], 1, s[14:15]
	v_lshl_add_u64 v[32:33], v[212:213], 1, v[32:33]
	v_cvt_pk_bf16_f32 v27, v36, v27
	global_store_dwordx4 v[32:33], v[24:27], off
	v_cvt_pk_bf16_f32 v18, v20, v21
	v_cvt_pk_bf16_f32 v19, v22, v23
	v_cvt_pk_bf16_f32 v20, v28, v29
	v_cvt_pk_bf16_f32 v21, v30, v31
	global_store_dwordx4 v[32:33], v[18:21], off offset:256
	s_and_saveexec_b64 s[14:15], s[4:5]
	s_cbranch_execz .LBB0_134
	s_waitcnt lgkmcnt(0)
	v_add_f32_e32 v16, v16, v17
	v_mul_f32_e32 v16, 0x49800000, v16
	v_trunc_f32_e32 v16, v16
	v_mul_f32_e32 v17, 0x2f800000, v16
	v_floor_f32_e32 v17, v17
	v_fmac_f32_e32 v16, 0xcf800000, v17
	v_cvt_u32_f32_e32 v16, v16
	v_cvt_u32_f32_e32 v17, v17
	v_readlane_b32 s16, v254, 37
	v_readlane_b32 s17, v254, 38
	s_nop 1
	v_lshl_add_u64 v[18:19], v[216:217], 3, s[16:17]
	global_atomic_add_x2 v[18:19], v[16:17], off
.LBB0_134:
	s_or_b64 exec, exec, s[14:15]
	v_and_b32_e32 v19, 0xffff0000, v140
	v_lshlrev_b32_e32 v18, 16, v140
	v_and_b32_e32 v21, 0xffff0000, v141
	v_add_f32_e32 v13, v13, v19
	v_lshlrev_b32_e32 v20, 16, v141
	v_add_f32_e32 v12, v12, v18
	v_add_f32_e32 v15, v15, v21
	v_mul_f32_e32 v21, v13, v13
	v_add_f32_e32 v14, v14, v20
	v_fmac_f32_e32 v21, v12, v12
	v_lshlrev_b32_e32 v22, 16, v142
	v_fmac_f32_e32 v21, v14, v14
	v_and_b32_e32 v23, 0xffff0000, v142
	v_add_f32_e32 v18, v8, v22
	v_fmac_f32_e32 v21, v15, v15
	v_lshlrev_b32_e32 v24, 16, v143
	v_add_f32_e32 v19, v9, v23
	v_fmac_f32_e32 v21, v18, v18
	v_and_b32_e32 v25, 0xffff0000, v143
	v_add_f32_e32 v20, v10, v24
	v_fmac_f32_e32 v21, v19, v19
	v_add_f32_e32 v11, v11, v25
	v_fmac_f32_e32 v21, v20, v20
	v_lshlrev_b32_e32 v10, 16, v132
	v_fmac_f32_e32 v21, v11, v11
	v_cvt_pk_bf16_f32 v8, v12, v13
	v_and_b32_e32 v12, 0xffff0000, v132
	v_add_f32_e32 v4, v4, v10
	v_lshlrev_b32_e32 v13, 16, v133
	v_add_f32_e32 v5, v5, v12
	v_fmac_f32_e32 v21, v4, v4
	v_cvt_pk_bf16_f32 v9, v14, v15
	v_and_b32_e32 v14, 0xffff0000, v133
	v_add_f32_e32 v6, v6, v13
	v_fmac_f32_e32 v21, v5, v5
	v_lshlrev_b32_e32 v15, 16, v134
	v_add_f32_e32 v7, v7, v14
	v_fmac_f32_e32 v21, v6, v6
	v_and_b32_e32 v22, 0xffff0000, v134
	v_add_f32_e32 v12, v0, v15
	v_fmac_f32_e32 v21, v7, v7
	v_lshlrev_b32_e32 v23, 16, v135
	v_add_f32_e32 v13, v1, v22
	v_fmac_f32_e32 v21, v12, v12
	v_and_b32_e32 v24, 0xffff0000, v135
	v_add_f32_e32 v14, v2, v23
	v_fmac_f32_e32 v21, v13, v13
	v_add_f32_e32 v15, v3, v24
	v_fmac_f32_e32 v21, v14, v14
	v_fmac_f32_e32 v21, v15, v15
	ds_bpermute_b32 v0, v112, v21
	v_readlane_b32 s14, v254, 8
	s_waitcnt lgkmcnt(0)
	v_lshlrev_b64 v[16:17], 11, v[214:215]
	v_readlane_b32 s15, v254, 9
	v_cvt_pk_bf16_f32 v10, v18, v19
	v_add_f32_e32 v0, v21, v0
	ds_bpermute_b32 v1, v113, v0
	v_lshl_add_u64 v[16:17], v[16:17], 1, s[14:15]
	v_lshl_add_u64 v[16:17], v[212:213], 1, v[16:17]
	v_cvt_pk_bf16_f32 v11, v20, v11
	global_store_dwordx4 v[16:17], v[8:11], off
	v_cvt_pk_bf16_f32 v2, v4, v5
	v_cvt_pk_bf16_f32 v3, v6, v7
	v_cvt_pk_bf16_f32 v4, v12, v13
	v_cvt_pk_bf16_f32 v5, v14, v15
	global_store_dwordx4 v[16:17], v[2:5], off offset:256
	s_and_saveexec_b64 s[14:15], s[4:5]
	s_cbranch_execz .LBB0_105
	s_waitcnt lgkmcnt(0)
	v_add_f32_e32 v0, v0, v1
	v_mul_f32_e32 v0, 0x49800000, v0
	v_trunc_f32_e32 v0, v0
	v_mul_f32_e32 v1, 0x2f800000, v0
	v_floor_f32_e32 v1, v1
	v_fmac_f32_e32 v0, 0xcf800000, v1
	v_cvt_u32_f32_e32 v0, v0
	v_cvt_u32_f32_e32 v1, v1
	v_readlane_b32 s16, v254, 37
	v_readlane_b32 s17, v254, 38
	s_nop 1
	v_lshl_add_u64 v[2:3], v[214:215], 3, s[16:17]
	global_atomic_add_x2 v[2:3], v[0:1], off
	s_branch .LBB0_105

; #define LAS __attribute__((address_space(3)))
;     __device__ bool next(int i, Unit& u) const {
;         if (i >= icnt) return false; const long L = (long)(i + ioff) * G + c; if (L >= nwg) return false;
;         int wgid = (int)L; { const int q = nwg / NXCD, r = nwg % NXCD, xcd = wgid % NXCD, off = wgid / NXCD; wgid = (xcd < r ? xcd * (q + 1) : r * (q + 1) + (xcd - r) * q) + off; }
;         const int nig = WGM * nN, gid = wgid / nig, fm = gid * WGM, gsz = (nM - fm) < WGM ? (nM - fm) : WGM;
;         u.pm = fm + ((wgid % nig) % gsz); u.pn = (wgid % nig) / gsz; if (u.pn >= skip_lo) u.pn += skip_n; return true;
;     __device__ __forceinline__ void stash(unsigned long long v, LAS unsigned char* lds, int par, int tid) const { if (tid < 256) *(LAS float*)(lds + 131072 + par * 1024 + tid * 4) = rsqrtf((float)v * (1.f / (1048576.f * DM)) + EPS_); }
.LBB0_146:
	s_ashr_i32 s0, s2, 3
	s_add_i32 s0, s4, s0
	s_ashr_i32 s1, s0, 31
	s_lshr_b32 s1, s1, 24
	s_add_i32 s1, s0, s1
	s_ashr_i32 s2, s1, 8
	s_and_b32 s1, s1, 0xff00
	s_sub_i32 s0, s0, s1
	s_sext_i32_i16 s1, s0
	s_bfe_u32 s1, s1, 0x3001c
	s_lshl_b32 s3, s2, 3
	s_add_i32 s2, s0, s1
	s_and_b32 s1, s2, 0xfff8
	s_sub_i32 s0, s0, s1
	s_sext_i32_i16 s0, s0
	s_add_i32 s39, s3, s0
	s_movk_i32 s0, 0x100
	v_cmp_gt_i32_e64 s[4:5], s0, v144
	s_and_saveexec_b64 s[0:1], s[4:5]
	s_cbranch_execz .LBB0_148
	v_lshl_add_u32 v0, s39, 8, v144
	v_readlane_b32 s8, v254, 39
	s_waitcnt lgkmcnt(0)
	v_ashrrev_i32_e32 v1, 31, v0
	v_readlane_b32 s9, v254, 40
	s_mov_b32 s3, 0x800000
	s_nop 0
	v_lshl_add_u64 v[0:1], v[0:1], 3, s[8:9]
	global_load_dwordx2 v[0:1], v[0:1], off
	s_waitcnt vmcnt(0) lgkmcnt(0)
	v_ffbh_u32_e32 v2, v1
	v_min_u32_e32 v2, 32, v2
	v_lshlrev_b64 v[0:1], v2, v[0:1]
	v_min_u32_e32 v0, 1, v0
	v_or_b32_e32 v0, v1, v0
	v_cvt_f32_u32_e32 v0, v0
	v_sub_u32_e32 v1, 32, v2
	v_ldexp_f32 v0, v0, v1
	v_fmamk_f32 v0, v0, 0x30000000, v242
	v_mul_f32_e32 v1, 0x4b800000, v0
	v_cmp_gt_f32_e32 vcc, s3, v0
	s_nop 1
	v_cndmask_b32_e32 v0, v0, v1, vcc
	v_rsq_f32_e32 v0, v0
	v_lshl_add_u32 v1, v144, 2, 0
	v_add_u32_e32 v1, 0x20000, v1
	v_mul_f32_e32 v2, 0x45800000, v0
	v_cndmask_b32_e32 v0, v0, v2, vcc
	ds_write_b32 v1, v0

; #define LAS __attribute__((address_space(3)))
; __device__ __forceinline__ unsigned cvt_pk_bf16(float lo, float hi) { unsigned r; asm volatile("v_cvt_pk_bf16_f32 %0, %1, %2" : "=v"(r) : "v"(lo), "v"(hi)); return r; }
;     __device__ __forceinline__ void stash(unsigned long long v, LAS unsigned char* lds, int par, int tid) const { if (tid < 256) *(LAS float*)(lds + 131072 + par * 1024 + tid * 4) = rsqrtf((float)v * (1.f / (1048576.f * DM)) + EPS_); }
;     __device__ __forceinline__ void operator()(const f32x4 (&acc)[2][2][4][2], const Unit& u, int wr, int wc, int fr, int fq, LAS unsigned char* lds, int par, int npm, int tid) const {
;         const int row0 = u.pm * BM + wr * 64 + fr, col0 = u.pn * BM + wc * 32 + 8 * fq;
;         unsigned long long nx = 0ull; if (npm >= 0) nx = prefetch(npm, tid);
; #pragma unroll
;         for (int ai = 0; ai < 2; ++ai)
; #pragma unroll
;             for (int m = 0; m < 4; ++m) { const int row = row0 + ai * HALF + m * 16; bf16_t* rowp = O + (size_t)row * ldc + col0;
;                 const float rstd = *(const LAS float*)(lds + 131072 + par * 1024 + (wr * 64 + fr + ai * HALF + m * 16) * 4);
; #pragma unroll
;                 for (int bj = 0; bj < 2; ++bj) { f32x4 v0 = acc[ai][bj][m][0] * rstd, v1 = acc[ai][bj][m][1] * rstd;
;                     if (ACT == 1) {
; #pragma unroll
;                         for (int j = 0; j < 4; ++j) { const float a = fmaxf(v0[j], 0.f), b = fmaxf(v1[j], 0.f); v0[j] = a * a; v1[j] = b * b; } }
;                     u32x4 w; w.x = cvt_pk_bf16(v0[0], v0[1]); w.y = cvt_pk_bf16(v0[2], v0[3]); w.z = cvt_pk_bf16(v1[0], v1[1]); w.w = cvt_pk_bf16(v1[2], v1[3]);
;                     *(u32x4*)(rowp + bj * HALF) = w; } }
;         if (npm >= 0) stash(nx, lds, par ^ 1, tid);
.LBB0_166:
	s_and_b64 s[14:15], s[14:15], exec
	s_cselect_b32 s18, s38, -1
	s_cmp_gt_i32 s18, -1
	s_cselect_b64 s[14:15], -1, 0
	s_and_b64 s[14:15], s[4:5], s[14:15]
	v_mov_b32_e32 v151, 0x358637bd
	s_and_saveexec_b64 s[16:17], s[14:15]
	s_cbranch_execz .LBB0_168
	v_lshl_add_u32 v138, s18, 8, v144
	v_readlane_b32 s18, v254, 39
	v_ashrrev_i32_e32 v139, 31, v138
	v_readlane_b32 s19, v254, 40
	s_nop 1
	v_lshl_add_u64 v[138:139], v[138:139], 3, s[18:19]
	global_load_dwordx2 v[138:139], v[138:139], off
	s_waitcnt vmcnt(0) lgkmcnt(0)
	v_ffbh_u32_e32 v140, v139
	v_min_u32_e32 v140, 32, v140
	v_lshlrev_b64 v[138:139], v140, v[138:139]
	v_min_u32_e32 v138, 1, v138
	v_or_b32_e32 v138, v139, v138
	v_cvt_f32_u32_e32 v138, v138
	v_sub_u32_e32 v139, 32, v140
	v_ldexp_f32 v138, v138, v139
	v_fmamk_f32 v151, v138, 0x30000000, v242
.LBB0_168:
	s_or_b64 exec, exec, s[16:17]
	s_lshl_b32 s16, s41, 10
	s_and_b32 s18, s16, 0x400
	v_add_u32_e32 v152, s18, v147
	ds_read_b32 v154, v152
	v_lshl_add_u32 v140, s39, 8, v145
	v_lshl_or_b32 v138, s40, 8, v149
	v_ashrrev_i32_e32 v141, 31, v140
	v_readlane_b32 s16, v254, 23
	s_waitcnt lgkmcnt(0)
	v_pk_mul_f32 v[120:121], v[120:121], v[154:155] op_sel_hi:[1,0]
	v_pk_mul_f32 v[124:125], v[124:125], v[154:155] op_sel_hi:[1,0]
	v_pk_mul_f32 v[122:123], v[122:123], v[154:155] op_sel_hi:[1,0]
	v_max_f32_e32 v120, 0, v120
	v_ashrrev_i32_e32 v139, 31, v138
	v_lshlrev_b64 v[142:143], 14, v[140:141]
	v_readlane_b32 s17, v254, 24
	v_pk_mul_f32 v[126:127], v[126:127], v[154:155] op_sel_hi:[1,0]
	v_mul_f32_e32 v141, v120, v120
	v_max_f32_e32 v120, 0, v125
	v_max_f32_e32 v121, 0, v121
	v_max_f32_e32 v122, 0, v122
	v_lshl_add_u64 v[156:157], s[16:17], 0, v[142:143]
	v_lshlrev_b64 v[142:143], 1, v[138:139]
	v_max_f32_e32 v124, 0, v124
	v_mul_f32_e32 v120, v120, v120
	v_mul_f32_e32 v125, v121, v121
	v_max_f32_e32 v121, 0, v126
	v_mul_f32_e32 v126, v122, v122
	v_max_f32_e32 v122, 0, v127
	v_max_f32_e32 v123, 0, v123
	v_pk_mul_f32 v[114:115], v[114:115], v[154:155] op_sel_hi:[1,0]
	v_pk_mul_f32 v[112:113], v[112:113], v[154:155] op_sel_hi:[1,0]
	v_lshl_add_u64 v[138:139], v[156:157], 0, v[142:143]
	v_mul_f32_e32 v124, v124, v124
	v_mul_f32_e32 v121, v121, v121
	v_mul_f32_e32 v122, v122, v122
	v_mul_f32_e32 v123, v123, v123
	v_cvt_pk_bf16_f32 v120, v124, v120
	v_pk_mul_f32 v[118:119], v[118:119], v[154:155] op_sel_hi:[1,0]
	v_pk_mul_f32 v[116:117], v[116:117], v[154:155] op_sel_hi:[1,0]
	v_max_f32_e32 v112, 0, v112
	v_max_f32_e32 v113, 0, v113
	v_max_f32_e32 v114, 0, v114
	v_cvt_pk_bf16_f32 v121, v121, v122
	v_cvt_pk_bf16_f32 v122, v141, v125
	v_cvt_pk_bf16_f32 v123, v126, v123
	global_store_dwordx4 v[138:139], v[120:123], off
	v_max_f32_e32 v115, 0, v115
	v_max_f32_e32 v116, 0, v116
	v_mul_f32_e32 v120, v112, v112
	v_max_f32_e32 v112, 0, v117
	v_mul_f32_e32 v117, v113, v113
	v_max_f32_e32 v113, 0, v118
	v_mul_f32_e32 v118, v114, v114
	v_max_f32_e32 v114, 0, v119
	v_mul_f32_e32 v112, v112, v112
	v_mul_f32_e32 v113, v113, v113
	v_mul_f32_e32 v114, v114, v114
	v_mul_f32_e32 v115, v115, v115
	v_mul_f32_e32 v116, v116, v116
	v_cvt_pk_bf16_f32 v112, v116, v112
	v_cvt_pk_bf16_f32 v113, v113, v114
	v_cvt_pk_bf16_f32 v114, v120, v117
	v_cvt_pk_bf16_f32 v115, v118, v115
	global_store_dwordx4 v[138:139], v[112:115], off offset:256
	ds_read_b32 v114, v152 offset:64
	s_waitcnt lgkmcnt(0)
	v_pk_mul_f32 v[104:105], v[104:105], v[114:115] op_sel_hi:[1,0]
	v_or_b32_e32 v112, 16, v140
	v_ashrrev_i32_e32 v113, 31, v112
	v_pk_mul_f32 v[108:109], v[108:109], v[114:115] op_sel_hi:[1,0]
	v_pk_mul_f32 v[106:107], v[106:107], v[114:115] op_sel_hi:[1,0]
	v_max_f32_e32 v104, 0, v104
	v_lshlrev_b64 v[112:113], 14, v[112:113]
	v_pk_mul_f32 v[110:111], v[110:111], v[114:115] op_sel_hi:[1,0]
	v_mul_f32_e32 v115, v104, v104
	v_max_f32_e32 v104, 0, v109
	v_max_f32_e32 v105, 0, v105
	v_max_f32_e32 v106, 0, v106
	v_lshl_add_u64 v[112:113], s[16:17], 0, v[112:113]
	v_max_f32_e32 v108, 0, v108
	v_mul_f32_e32 v104, v104, v104
	v_mul_f32_e32 v109, v105, v105
	v_max_f32_e32 v105, 0, v110
	v_mul_f32_e32 v110, v106, v106
	v_max_f32_e32 v106, 0, v111
	v_max_f32_e32 v107, 0, v107
	v_pk_mul_f32 v[98:99], v[98:99], v[114:115] op_sel_hi:[1,0]
	v_pk_mul_f32 v[96:97], v[96:97], v[114:115] op_sel_hi:[1,0]
	v_lshl_add_u64 v[112:113], v[112:113], 0, v[142:143]
	v_mul_f32_e32 v108, v108, v108
	v_mul_f32_e32 v105, v105, v105
	v_mul_f32_e32 v106, v106, v106
	v_mul_f32_e32 v107, v107, v107
	v_cvt_pk_bf16_f32 v104, v108, v104
	v_pk_mul_f32 v[102:103], v[102:103], v[114:115] op_sel_hi:[1,0]
	v_pk_mul_f32 v[100:101], v[100:101], v[114:115] op_sel_hi:[1,0]
	v_max_f32_e32 v96, 0, v96
	v_max_f32_e32 v97, 0, v97
	v_max_f32_e32 v98, 0, v98
	v_cvt_pk_bf16_f32 v105, v105, v106
	v_cvt_pk_bf16_f32 v106, v115, v109
	v_cvt_pk_bf16_f32 v107, v110, v107
	global_store_dwordx4 v[112:113], v[104:107], off
	v_max_f32_e32 v99, 0, v99
	v_max_f32_e32 v100, 0, v100
	v_mul_f32_e32 v104, v96, v96
	v_max_f32_e32 v96, 0, v101
	v_mul_f32_e32 v101, v97, v97
	v_max_f32_e32 v97, 0, v102
	v_mul_f32_e32 v102, v98, v98
	v_max_f32_e32 v98, 0, v103
	v_mul_f32_e32 v96, v96, v96
	v_mul_f32_e32 v97, v97, v97
	v_mul_f32_e32 v98, v98, v98
	v_mul_f32_e32 v99, v99, v99
	v_mul_f32_e32 v100, v100, v100
	v_cvt_pk_bf16_f32 v96, v100, v96
	v_cvt_pk_bf16_f32 v97, v97, v98
	v_cvt_pk_bf16_f32 v98, v104, v101
	v_cvt_pk_bf16_f32 v99, v102, v99
	global_store_dwordx4 v[112:113], v[96:99], off offset:256
	ds_read_b32 v98, v152 offset:128
	s_waitcnt lgkmcnt(0)
; #define LAS __attribute__((address_space(3)))
; __device__ __forceinline__ unsigned cvt_pk_bf16(float lo, float hi) { unsigned r; asm volatile("v_cvt_pk_bf16_f32 %0, %1, %2" : "=v"(r) : "v"(lo), "v"(hi)); return r; }
;     __device__ __forceinline__ void operator()(const f32x4 (&acc)[2][2][4][2], const Unit& u, int wr, int wc, int fr, int fq, LAS unsigned char* lds, int par, int npm, int tid) const {
;     ...
;             for (int m = 0; m < 4; ++m) { const int row = row0 + ai * HALF + m * 16; bf16_t* rowp = O + (size_t)row * ldc + col0;
;                 const float rstd = *(const LAS float*)(lds + 131072 + par * 1024 + (wr * 64 + fr + ai * HALF + m * 16) * 4);
; #pragma unroll
;                 for (int bj = 0; bj < 2; ++bj) { f32x4 v0 = acc[ai][bj][m][0] * rstd, v1 = acc[ai][bj][m][1] * rstd;
;                     if (ACT == 1) {
; #pragma unroll
;                         for (int j = 0; j < 4; ++j) { const float a = fmaxf(v0[j], 0.f), b = fmaxf(v1[j], 0.f); v0[j] = a * a; v1[j] = b * b; } }
;                     u32x4 w; w.x = cvt_pk_bf16(v0[0], v0[1]); w.y = cvt_pk_bf16(v0[2], v0[3]); w.z = cvt_pk_bf16(v1[0], v1[1]); w.w = cvt_pk_bf16(v1[2], v1[3]);
;                     *(u32x4*)(rowp + bj * HALF) = w; } }
	v_pk_mul_f32 v[88:89], v[88:89], v[98:99] op_sel_hi:[1,0]
	v_or_b32_e32 v96, 32, v140
	v_ashrrev_i32_e32 v97, 31, v96
	v_pk_mul_f32 v[92:93], v[92:93], v[98:99] op_sel_hi:[1,0]
	v_pk_mul_f32 v[90:91], v[90:91], v[98:99] op_sel_hi:[1,0]
	v_max_f32_e32 v88, 0, v88
	v_lshlrev_b64 v[96:97], 14, v[96:97]
	v_pk_mul_f32 v[94:95], v[94:95], v[98:99] op_sel_hi:[1,0]
	v_mul_f32_e32 v99, v88, v88
	v_max_f32_e32 v88, 0, v93
	v_max_f32_e32 v89, 0, v89
	v_max_f32_e32 v90, 0, v90
	v_lshl_add_u64 v[96:97], s[16:17], 0, v[96:97]
	v_max_f32_e32 v92, 0, v92
	v_mul_f32_e32 v88, v88, v88
	v_mul_f32_e32 v93, v89, v89
	v_max_f32_e32 v89, 0, v94
	v_mul_f32_e32 v94, v90, v90
	v_max_f32_e32 v90, 0, v95
	v_max_f32_e32 v91, 0, v91
	v_pk_mul_f32 v[82:83], v[82:83], v[98:99] op_sel_hi:[1,0]
	v_pk_mul_f32 v[80:81], v[80:81], v[98:99] op_sel_hi:[1,0]
	v_lshl_add_u64 v[96:97], v[96:97], 0, v[142:143]
	v_mul_f32_e32 v92, v92, v92
	v_mul_f32_e32 v89, v89, v89
	v_mul_f32_e32 v90, v90, v90
	v_mul_f32_e32 v91, v91, v91
	v_cvt_pk_bf16_f32 v88, v92, v88
	v_pk_mul_f32 v[86:87], v[86:87], v[98:99] op_sel_hi:[1,0]
	v_pk_mul_f32 v[84:85], v[84:85], v[98:99] op_sel_hi:[1,0]
	v_max_f32_e32 v80, 0, v80
	v_max_f32_e32 v81, 0, v81
	v_max_f32_e32 v82, 0, v82
	v_cvt_pk_bf16_f32 v89, v89, v90
	v_cvt_pk_bf16_f32 v90, v99, v93
	v_cvt_pk_bf16_f32 v91, v94, v91
	global_store_dwordx4 v[96:97], v[88:91], off
	v_max_f32_e32 v83, 0, v83
	v_max_f32_e32 v84, 0, v84
	v_mul_f32_e32 v88, v80, v80
	v_max_f32_e32 v80, 0, v85
	v_mul_f32_e32 v85, v81, v81
	v_max_f32_e32 v81, 0, v86
	v_mul_f32_e32 v86, v82, v82
	v_max_f32_e32 v82, 0, v87
	v_mul_f32_e32 v80, v80, v80
	v_mul_f32_e32 v81, v81, v81
	v_mul_f32_e32 v82, v82, v82
	v_mul_f32_e32 v83, v83, v83
	v_mul_f32_e32 v84, v84, v84
	v_cvt_pk_bf16_f32 v80, v84, v80
	v_cvt_pk_bf16_f32 v81, v81, v82
	v_cvt_pk_bf16_f32 v82, v88, v85
	v_cvt_pk_bf16_f32 v83, v86, v83
	global_store_dwordx4 v[96:97], v[80:83], off offset:256
	ds_read_b32 v82, v152 offset:192
	s_waitcnt lgkmcnt(0)
	v_pk_mul_f32 v[72:73], v[72:73], v[82:83] op_sel_hi:[1,0]
	v_or_b32_e32 v80, 48, v140
	v_ashrrev_i32_e32 v81, 31, v80
	v_pk_mul_f32 v[76:77], v[76:77], v[82:83] op_sel_hi:[1,0]
	v_pk_mul_f32 v[74:75], v[74:75], v[82:83] op_sel_hi:[1,0]
	v_max_f32_e32 v72, 0, v72
	v_lshlrev_b64 v[80:81], 14, v[80:81]
	v_pk_mul_f32 v[78:79], v[78:79], v[82:83] op_sel_hi:[1,0]
	v_mul_f32_e32 v83, v72, v72
	v_max_f32_e32 v72, 0, v77
	v_max_f32_e32 v73, 0, v73
	v_max_f32_e32 v74, 0, v74
	v_lshl_add_u64 v[80:81], s[16:17], 0, v[80:81]
	v_max_f32_e32 v76, 0, v76
	v_mul_f32_e32 v72, v72, v72
	v_mul_f32_e32 v77, v73, v73
	v_max_f32_e32 v73, 0, v78
	v_mul_f32_e32 v78, v74, v74
	v_max_f32_e32 v74, 0, v79
	v_max_f32_e32 v75, 0, v75
	v_pk_mul_f32 v[66:67], v[66:67], v[82:83] op_sel_hi:[1,0]
	v_pk_mul_f32 v[64:65], v[64:65], v[82:83] op_sel_hi:[1,0]
	v_lshl_add_u64 v[80:81], v[80:81], 0, v[142:143]
	v_mul_f32_e32 v76, v76, v76
	v_mul_f32_e32 v73, v73, v73
	v_mul_f32_e32 v74, v74, v74
	v_mul_f32_e32 v75, v75, v75
	v_cvt_pk_bf16_f32 v72, v76, v72
	v_pk_mul_f32 v[70:71], v[70:71], v[82:83] op_sel_hi:[1,0]
	v_pk_mul_f32 v[68:69], v[68:69], v[82:83] op_sel_hi:[1,0]
	v_max_f32_e32 v64, 0, v64
	v_max_f32_e32 v65, 0, v65
	v_max_f32_e32 v66, 0, v66
	v_cvt_pk_bf16_f32 v73, v73, v74
	v_cvt_pk_bf16_f32 v74, v83, v77
	v_cvt_pk_bf16_f32 v75, v78, v75
	global_store_dwordx4 v[80:81], v[72:75], off
	v_max_f32_e32 v67, 0, v67
	v_max_f32_e32 v68, 0, v68
	v_mul_f32_e32 v72, v64, v64
	v_max_f32_e32 v64, 0, v69
	v_mul_f32_e32 v69, v65, v65
	v_max_f32_e32 v65, 0, v70
	v_mul_f32_e32 v70, v66, v66
	v_max_f32_e32 v66, 0, v71
	v_mul_f32_e32 v64, v64, v64
	v_mul_f32_e32 v65, v65, v65
	v_mul_f32_e32 v66, v66, v66
	v_mul_f32_e32 v67, v67, v67
	v_mul_f32_e32 v68, v68, v68
	v_cvt_pk_bf16_f32 v64, v68, v64
	v_cvt_pk_bf16_f32 v65, v65, v66
	v_cvt_pk_bf16_f32 v66, v72, v69
	v_cvt_pk_bf16_f32 v67, v70, v67
	global_store_dwordx4 v[80:81], v[64:67], off offset:256
	ds_read_b32 v64, v152 offset:512
	s_mov_b64 s[16:17], 0x200000
	v_lshl_add_u64 v[66:67], v[138:139], 0, s[16:17]
	s_mov_b32 s16, 0x200000
	s_waitcnt lgkmcnt(0)
	v_pk_mul_f32 v[56:57], v[56:57], v[64:65] op_sel_hi:[1,0]
	v_pk_mul_f32 v[60:61], v[60:61], v[64:65] op_sel_hi:[1,0]
	v_pk_mul_f32 v[58:59], v[58:59], v[64:65] op_sel_hi:[1,0]
	v_max_f32_e32 v56, 0, v56
	v_pk_mul_f32 v[62:63], v[62:63], v[64:65] op_sel_hi:[1,0]
	v_max_f32_e32 v60, 0, v60
	v_mul_f32_e32 v65, v56, v56
	v_max_f32_e32 v56, 0, v61
	v_max_f32_e32 v57, 0, v57
	v_max_f32_e32 v58, 0, v58
	v_mul_f32_e32 v60, v60, v60
	v_mul_f32_e32 v56, v56, v56
	v_mul_f32_e32 v61, v57, v57
	v_max_f32_e32 v57, 0, v62
	v_mul_f32_e32 v62, v58, v58
	v_max_f32_e32 v58, 0, v63
	v_mul_f32_e32 v57, v57, v57
	v_max_f32_e32 v59, 0, v59
	v_mul_f32_e32 v58, v58, v58
	v_cvt_pk_bf16_f32 v56, v60, v56
	v_add_co_u32_e32 v60, vcc, s16, v138
	v_pk_mul_f32 v[50:51], v[50:51], v[64:65] op_sel_hi:[1,0]
	v_pk_mul_f32 v[48:49], v[48:49], v[64:65] op_sel_hi:[1,0]
	v_mul_f32_e32 v59, v59, v59
	v_cvt_pk_bf16_f32 v57, v57, v58
	v_cvt_pk_bf16_f32 v58, v65, v61
	v_addc_co_u32_e32 v61, vcc, 0, v139, vcc
	v_pk_mul_f32 v[54:55], v[54:55], v[64:65] op_sel_hi:[1,0]
	v_pk_mul_f32 v[52:53], v[52:53], v[64:65] op_sel_hi:[1,0]
	v_max_f32_e32 v48, 0, v48
	v_max_f32_e32 v49, 0, v49
	v_max_f32_e32 v50, 0, v50
	v_cvt_pk_bf16_f32 v59, v62, v59
	global_store_dwordx4 v[60:61], v[56:59], off
	v_max_f32_e32 v51, 0, v51
	v_max_f32_e32 v52, 0, v52
	v_mul_f32_e32 v56, v48, v48
	v_max_f32_e32 v48, 0, v53
	v_mul_f32_e32 v53, v49, v49
	v_max_f32_e32 v49, 0, v54
	v_mul_f32_e32 v54, v50, v50
	v_max_f32_e32 v50, 0, v55
	v_mul_f32_e32 v48, v48, v48
	v_mul_f32_e32 v49, v49, v49
	v_mul_f32_e32 v50, v50, v50
	v_mul_f32_e32 v51, v51, v51
	v_mul_f32_e32 v52, v52, v52
	v_cvt_pk_bf16_f32 v48, v52, v48
	v_cvt_pk_bf16_f32 v49, v49, v50
	v_cvt_pk_bf16_f32 v50, v56, v53
	v_cvt_pk_bf16_f32 v51, v54, v51
	global_store_dwordx4 v[66:67], v[48:51], off offset:256
	ds_read_b32 v48, v152 offset:576
	s_mov_b64 s[16:17], 0x240000
	v_lshl_add_u64 v[50:51], v[138:139], 0, s[16:17]
	s_mov_b32 s16, 0x240000
	s_waitcnt lgkmcnt(0)
; #define LAS __attribute__((address_space(3)))
; __device__ __forceinline__ unsigned cvt_pk_bf16(float lo, float hi) { unsigned r; asm volatile("v_cvt_pk_bf16_f32 %0, %1, %2" : "=v"(r) : "v"(lo), "v"(hi)); return r; }
;     __device__ __forceinline__ void stash(unsigned long long v, LAS unsigned char* lds, int par, int tid) const { if (tid < 256) *(LAS float*)(lds + 131072 + par * 1024 + tid * 4) = rsqrtf((float)v * (1.f / (1048576.f * DM)) + EPS_); }
;     __device__ __forceinline__ void operator()(const f32x4 (&acc)[2][2][4][2], const Unit& u, int wr, int wc, int fr, int fq, LAS unsigned char* lds, int par, int npm, int tid) const {
;     ...
;             for (int m = 0; m < 4; ++m) { const int row = row0 + ai * HALF + m * 16; bf16_t* rowp = O + (size_t)row * ldc + col0;
;                 const float rstd = *(const LAS float*)(lds + 131072 + par * 1024 + (wr * 64 + fr + ai * HALF + m * 16) * 4);
; #pragma unroll
;                 for (int bj = 0; bj < 2; ++bj) { f32x4 v0 = acc[ai][bj][m][0] * rstd, v1 = acc[ai][bj][m][1] * rstd;
;                     if (ACT == 1) {
; #pragma unroll
;                         for (int j = 0; j < 4; ++j) { const float a = fmaxf(v0[j], 0.f), b = fmaxf(v1[j], 0.f); v0[j] = a * a; v1[j] = b * b; } }
;                     u32x4 w; w.x = cvt_pk_bf16(v0[0], v0[1]); w.y = cvt_pk_bf16(v0[2], v0[3]); w.z = cvt_pk_bf16(v1[0], v1[1]); w.w = cvt_pk_bf16(v1[2], v1[3]);
;                     *(u32x4*)(rowp + bj * HALF) = w; } }
;         if (npm >= 0) stash(nx, lds, par ^ 1, tid);
	v_pk_mul_f32 v[40:41], v[40:41], v[48:49] op_sel_hi:[1,0]
	v_pk_mul_f32 v[44:45], v[44:45], v[48:49] op_sel_hi:[1,0]
	v_pk_mul_f32 v[42:43], v[42:43], v[48:49] op_sel_hi:[1,0]
	v_max_f32_e32 v40, 0, v40
	v_pk_mul_f32 v[46:47], v[46:47], v[48:49] op_sel_hi:[1,0]
	v_max_f32_e32 v44, 0, v44
	v_mul_f32_e32 v49, v40, v40
	v_max_f32_e32 v40, 0, v45
	v_max_f32_e32 v41, 0, v41
	v_max_f32_e32 v42, 0, v42
	v_mul_f32_e32 v44, v44, v44
	v_mul_f32_e32 v40, v40, v40
	v_mul_f32_e32 v45, v41, v41
	v_max_f32_e32 v41, 0, v46
	v_mul_f32_e32 v46, v42, v42
	v_max_f32_e32 v42, 0, v47
	v_mul_f32_e32 v41, v41, v41
	v_max_f32_e32 v43, 0, v43
	v_mul_f32_e32 v42, v42, v42
	v_cvt_pk_bf16_f32 v40, v44, v40
	v_add_co_u32_e32 v44, vcc, s16, v138
	v_pk_mul_f32 v[34:35], v[34:35], v[48:49] op_sel_hi:[1,0]
	v_pk_mul_f32 v[32:33], v[32:33], v[48:49] op_sel_hi:[1,0]
	v_mul_f32_e32 v43, v43, v43
	v_cvt_pk_bf16_f32 v41, v41, v42
	v_cvt_pk_bf16_f32 v42, v49, v45
	v_addc_co_u32_e32 v45, vcc, 0, v139, vcc
	v_pk_mul_f32 v[38:39], v[38:39], v[48:49] op_sel_hi:[1,0]
	v_pk_mul_f32 v[36:37], v[36:37], v[48:49] op_sel_hi:[1,0]
	v_max_f32_e32 v32, 0, v32
	v_max_f32_e32 v33, 0, v33
	v_max_f32_e32 v34, 0, v34
	v_cvt_pk_bf16_f32 v43, v46, v43
	global_store_dwordx4 v[44:45], v[40:43], off
	v_max_f32_e32 v35, 0, v35
	v_max_f32_e32 v36, 0, v36
	v_mul_f32_e32 v40, v32, v32
	v_max_f32_e32 v32, 0, v37
	v_mul_f32_e32 v37, v33, v33
	v_max_f32_e32 v33, 0, v38
	v_mul_f32_e32 v38, v34, v34
	v_max_f32_e32 v34, 0, v39
	v_mul_f32_e32 v32, v32, v32
	v_mul_f32_e32 v33, v33, v33
	v_mul_f32_e32 v34, v34, v34
	v_mul_f32_e32 v35, v35, v35
	v_mul_f32_e32 v36, v36, v36
	v_cvt_pk_bf16_f32 v32, v36, v32
	v_cvt_pk_bf16_f32 v33, v33, v34
	v_cvt_pk_bf16_f32 v34, v40, v37
	v_cvt_pk_bf16_f32 v35, v38, v35
	global_store_dwordx4 v[50:51], v[32:35], off offset:256
	ds_read_b32 v32, v152 offset:640
	s_mov_b64 s[16:17], 0x280000
	v_lshl_add_u64 v[34:35], v[138:139], 0, s[16:17]
	s_mov_b32 s16, 0x280000
	s_waitcnt lgkmcnt(0)
	v_pk_mul_f32 v[24:25], v[24:25], v[32:33] op_sel_hi:[1,0]
	v_pk_mul_f32 v[28:29], v[28:29], v[32:33] op_sel_hi:[1,0]
	v_pk_mul_f32 v[26:27], v[26:27], v[32:33] op_sel_hi:[1,0]
	v_max_f32_e32 v24, 0, v24
	v_pk_mul_f32 v[30:31], v[30:31], v[32:33] op_sel_hi:[1,0]
	v_max_f32_e32 v28, 0, v28
	v_mul_f32_e32 v33, v24, v24
	v_max_f32_e32 v24, 0, v29
	v_max_f32_e32 v25, 0, v25
	v_max_f32_e32 v26, 0, v26
	v_mul_f32_e32 v28, v28, v28
	v_mul_f32_e32 v24, v24, v24
	v_mul_f32_e32 v29, v25, v25
	v_max_f32_e32 v25, 0, v30
	v_mul_f32_e32 v30, v26, v26
	v_max_f32_e32 v26, 0, v31
	v_mul_f32_e32 v25, v25, v25
	v_max_f32_e32 v27, 0, v27
	v_mul_f32_e32 v26, v26, v26
	v_cvt_pk_bf16_f32 v24, v28, v24
	v_add_co_u32_e32 v28, vcc, s16, v138
	v_pk_mul_f32 v[18:19], v[18:19], v[32:33] op_sel_hi:[1,0]
	v_pk_mul_f32 v[16:17], v[16:17], v[32:33] op_sel_hi:[1,0]
	v_mul_f32_e32 v27, v27, v27
	v_cvt_pk_bf16_f32 v25, v25, v26
	v_cvt_pk_bf16_f32 v26, v33, v29
	v_addc_co_u32_e32 v29, vcc, 0, v139, vcc
	v_pk_mul_f32 v[22:23], v[22:23], v[32:33] op_sel_hi:[1,0]
	v_pk_mul_f32 v[20:21], v[20:21], v[32:33] op_sel_hi:[1,0]
	v_max_f32_e32 v16, 0, v16
	v_max_f32_e32 v17, 0, v17
	v_max_f32_e32 v18, 0, v18
	v_cvt_pk_bf16_f32 v27, v30, v27
	global_store_dwordx4 v[28:29], v[24:27], off
	v_max_f32_e32 v19, 0, v19
	v_max_f32_e32 v20, 0, v20
	v_mul_f32_e32 v24, v16, v16
	v_max_f32_e32 v16, 0, v21
	v_mul_f32_e32 v21, v17, v17
	v_max_f32_e32 v17, 0, v22
	v_mul_f32_e32 v22, v18, v18
	v_max_f32_e32 v18, 0, v23
	v_mul_f32_e32 v16, v16, v16
	v_mul_f32_e32 v17, v17, v17
	v_mul_f32_e32 v18, v18, v18
	v_mul_f32_e32 v19, v19, v19
	v_mul_f32_e32 v20, v20, v20
	v_cvt_pk_bf16_f32 v16, v20, v16
	v_cvt_pk_bf16_f32 v17, v17, v18
	v_cvt_pk_bf16_f32 v18, v24, v21
	v_cvt_pk_bf16_f32 v19, v22, v19
	global_store_dwordx4 v[34:35], v[16:19], off offset:256
	ds_read_b32 v16, v152 offset:704
	s_mov_b64 s[16:17], 0x2c0000
	v_lshl_add_u64 v[18:19], v[138:139], 0, s[16:17]
	s_mov_b32 s16, 0x2c0000
	s_waitcnt lgkmcnt(0)
	v_pk_mul_f32 v[8:9], v[8:9], v[16:17] op_sel_hi:[1,0]
	v_pk_mul_f32 v[12:13], v[12:13], v[16:17] op_sel_hi:[1,0]
	v_pk_mul_f32 v[10:11], v[10:11], v[16:17] op_sel_hi:[1,0]
	v_max_f32_e32 v8, 0, v8
	v_pk_mul_f32 v[14:15], v[14:15], v[16:17] op_sel_hi:[1,0]
	v_max_f32_e32 v12, 0, v12
	v_mul_f32_e32 v17, v8, v8
	v_max_f32_e32 v8, 0, v13
	v_max_f32_e32 v9, 0, v9
	v_max_f32_e32 v10, 0, v10
	v_mul_f32_e32 v12, v12, v12
	v_mul_f32_e32 v8, v8, v8
	v_mul_f32_e32 v13, v9, v9
	v_max_f32_e32 v9, 0, v14
	v_mul_f32_e32 v14, v10, v10
	v_max_f32_e32 v10, 0, v15
	v_mul_f32_e32 v9, v9, v9
	v_max_f32_e32 v11, 0, v11
	v_mul_f32_e32 v10, v10, v10
	v_cvt_pk_bf16_f32 v8, v12, v8
	v_add_co_u32_e32 v12, vcc, s16, v138
	v_pk_mul_f32 v[2:3], v[2:3], v[16:17] op_sel_hi:[1,0]
	v_pk_mul_f32 v[0:1], v[0:1], v[16:17] op_sel_hi:[1,0]
	v_mul_f32_e32 v11, v11, v11
	v_cvt_pk_bf16_f32 v9, v9, v10
	v_cvt_pk_bf16_f32 v10, v17, v13
	v_addc_co_u32_e32 v13, vcc, 0, v139, vcc
	v_pk_mul_f32 v[6:7], v[6:7], v[16:17] op_sel_hi:[1,0]
	v_pk_mul_f32 v[4:5], v[4:5], v[16:17] op_sel_hi:[1,0]
	v_max_f32_e32 v0, 0, v0
	v_max_f32_e32 v1, 0, v1
	v_max_f32_e32 v2, 0, v2
	v_cvt_pk_bf16_f32 v11, v14, v11
	global_store_dwordx4 v[12:13], v[8:11], off
	v_max_f32_e32 v3, 0, v3
	v_max_f32_e32 v4, 0, v4
	v_mul_f32_e32 v8, v0, v0
	v_max_f32_e32 v0, 0, v5
	v_mul_f32_e32 v5, v1, v1
	v_max_f32_e32 v1, 0, v6
	v_mul_f32_e32 v6, v2, v2
	v_max_f32_e32 v2, 0, v7
	v_mul_f32_e32 v0, v0, v0
	v_mul_f32_e32 v1, v1, v1
	v_mul_f32_e32 v2, v2, v2
	v_mul_f32_e32 v3, v3, v3
	v_mul_f32_e32 v4, v4, v4
	v_cvt_pk_bf16_f32 v0, v4, v0
	v_cvt_pk_bf16_f32 v1, v1, v2
	v_cvt_pk_bf16_f32 v2, v8, v5
	v_cvt_pk_bf16_f32 v3, v6, v3
	global_store_dwordx4 v[18:19], v[0:3], off offset:256
	s_and_saveexec_b64 s[16:17], s[14:15]
	s_cbranch_execz .LBB0_151
	s_xor_b32 s14, s18, 0x400
	v_add_u32_e32 v0, s14, v148
	s_mov_b32 s14, 0x800000
	v_cmp_gt_f32_e32 vcc, s14, v151
	v_mul_f32_e32 v1, 0x4b800000, v151
	s_nop 0
	v_cndmask_b32_e32 v1, v151, v1, vcc
	v_rsq_f32_e32 v1, v1
	s_nop 0
	v_mul_f32_e32 v2, 0x45800000, v1
	v_cndmask_b32_e32 v1, v1, v2, vcc
	ds_write_b32 v0, v1
	s_branch .LBB0_151

; __device__ __forceinline__ void unpack8(u32x4 w, float* f) { f[0] = bflo(w.x); f[1] = bfhi(w.x); f[2] = bflo(w.y); f[3] = bfhi(w.y); f[4] = bflo(w.z); f[5] = bfhi(w.z); f[6] = bflo(w.w); f[7] = bfhi(w.w); }
; __device__ __forceinline__ u32x4 pack8(const float* f) { u32x4 w; w.x = cvt_pk_bf16(f[0], f[1]); w.y = cvt_pk_bf16(f[2], f[3]); w.z = cvt_pk_bf16(f[4], f[5]); w.w = cvt_pk_bf16(f[6], f[7]); return w; }
;     __device__ __forceinline__ void operator()(const f32x4 (&acc)[2][2][4][2], const Unit& u, int wr, int wc, int fr, int fq, LAS unsigned char* lds, int par, int npm, int tid) const {
;         const int row0 = u.pm * BM + wr * 64 + fr, col0 = u.pn * BM + wc * 32 + 8 * fq;
;         u32x4 old[2][4][2];
; #pragma unroll
;         for (int ai = 0; ai < 2; ++ai)
; #pragma unroll
;             for (int m = 0; m < 4; ++m)
; #pragma unroll
;                 for (int bj = 0; bj < 2; ++bj) old[ai][m][bj] = *(const u32x4*)(Hb + (size_t)(row0 + ai * HALF + m * 16) * ldc + col0 + bj * HALF);
; #pragma unroll
;         for (int ai = 0; ai < 2; ++ai)
; #pragma unroll
;             for (int m = 0; m < 4; ++m) { const int row = row0 + ai * HALF + m * 16; bf16_t* hp = Hb + (size_t)row * ldc + col0;
;                 float part = 0.f;
; #pragma unroll
;                 for (int bj = 0; bj < 2; ++bj) { float o[8]; unpack8(old[ai][m][bj], o);
;                     const f32x4 a0 = acc[ai][bj][m][0], a1 = acc[ai][bj][m][1];
;                     float v[8] = {o[0] + a0[0], o[1] + a0[1], o[2] + a0[2], o[3] + a0[3], o[4] + a1[0], o[5] + a1[1], o[6] + a1[2], o[7] + a1[3]};
; #pragma unroll
;                     for (int k = 0; k < 8; ++k) part += v[k] * v[k];
;                     *(u32x4*)(hp + bj * HALF) = pack8(v); }
;                 part += __shfl_xor(part, 16); part += __shfl_xor(part, 32);
;                 if (fq == 0) atomicAdd(ssq + row, (unsigned long long)(part * 1048576.f)); }
.LBB0_201:
	v_lshl_or_b32 v212, s38, 8, v246
	v_lshl_add_u32 v228, s37, 8, v201
	v_ashrrev_i32_e32 v213, 31, v212
	v_readlane_b32 s14, v254, 8
	v_lshlrev_b64 v[230:231], 1, v[212:213]
	v_readlane_b32 s15, v254, 9
	v_ashrrev_i32_e32 v229, 31, v228
	v_lshlrev_b64 v[232:233], 12, v[228:229]
	v_lshl_add_u64 v[132:133], s[14:15], 0, v[230:231]
	v_lshl_add_u64 v[128:129], v[132:133], 0, v[232:233]
	global_load_dwordx4 v[188:191], v[128:129], off
	global_load_dwordx4 v[184:187], v[128:129], off offset:256
	v_or_b32_e32 v226, 16, v228
	v_ashrrev_i32_e32 v227, 31, v226
	v_lshlrev_b64 v[128:129], 12, v[226:227]
	v_or_b32_e32 v224, 32, v228
	v_lshl_add_u64 v[128:129], v[132:133], 0, v[128:129]
	v_ashrrev_i32_e32 v225, 31, v224
	global_load_dwordx4 v[180:183], v[128:129], off
	global_load_dwordx4 v[176:179], v[128:129], off offset:256
	v_lshlrev_b64 v[128:129], 12, v[224:225]
	v_or_b32_e32 v222, 48, v228
	v_lshl_add_u64 v[128:129], v[132:133], 0, v[128:129]
	v_ashrrev_i32_e32 v223, 31, v222
	global_load_dwordx4 v[172:175], v[128:129], off
	global_load_dwordx4 v[168:171], v[128:129], off offset:256
	v_lshlrev_b64 v[128:129], 12, v[222:223]
	v_add_u32_e32 v220, 0x80, v228
	v_lshl_add_u64 v[128:129], v[132:133], 0, v[128:129]
	v_ashrrev_i32_e32 v221, 31, v220
	global_load_dwordx4 v[164:167], v[128:129], off
	global_load_dwordx4 v[160:163], v[128:129], off offset:256
	v_lshlrev_b64 v[128:129], 12, v[220:221]
	v_add_u32_e32 v218, 0x90, v228
	v_lshl_add_u64 v[128:129], v[132:133], 0, v[128:129]
	v_ashrrev_i32_e32 v219, 31, v218
	global_load_dwordx4 v[156:159], v[128:129], off
	global_load_dwordx4 v[152:155], v[128:129], off offset:256
	v_lshlrev_b64 v[128:129], 12, v[218:219]
	v_add_u32_e32 v216, 0xa0, v228
	v_add_u32_e32 v214, 0xb0, v228
	v_lshl_add_u64 v[128:129], v[132:133], 0, v[128:129]
	v_ashrrev_i32_e32 v217, 31, v216
	v_ashrrev_i32_e32 v215, 31, v214
	global_load_dwordx4 v[148:151], v[128:129], off
	global_load_dwordx4 v[144:147], v[128:129], off offset:256
	v_lshlrev_b64 v[128:129], 12, v[216:217]
	v_lshlrev_b64 v[134:135], 12, v[214:215]
	v_lshl_add_u64 v[128:129], v[132:133], 0, v[128:129]
	v_lshl_add_u64 v[132:133], v[132:133], 0, v[134:135]
	global_load_dwordx4 v[136:139], v[128:129], off
	s_nop 0
	global_load_dwordx4 v[128:131], v[128:129], off offset:256
	s_nop 0
	global_load_dwordx4 v[140:143], v[132:133], off
	s_nop 0
	global_load_dwordx4 v[132:135], v[132:133], off offset:256
	v_lshl_add_u64 v[232:233], s[14:15], 0, v[232:233]
	v_lshl_add_u64 v[230:231], v[232:233], 0, v[230:231]
	s_waitcnt vmcnt(0) lgkmcnt(0)
	v_lshlrev_b32_e32 v193, 16, v188
	v_and_b32_e32 v188, 0xffff0000, v188
	v_lshlrev_b32_e32 v239, 16, v191
	v_and_b32_e32 v191, 0xffff0000, v191
	v_add_f32_e32 v125, v125, v188
	v_lshlrev_b32_e32 v232, 16, v189
	v_add_f32_e32 v124, v124, v193
	v_add_f32_e32 v123, v123, v191
	v_mul_f32_e32 v191, v125, v125
	v_and_b32_e32 v189, 0xffff0000, v189
	v_add_f32_e32 v126, v126, v232
	v_fmac_f32_e32 v191, v124, v124
	v_lshlrev_b32_e32 v233, 16, v190
	v_add_f32_e32 v127, v127, v189
	v_fmac_f32_e32 v191, v126, v126
	v_and_b32_e32 v190, 0xffff0000, v190
	v_add_f32_e32 v188, v120, v233
	v_fmac_f32_e32 v191, v127, v127
	v_add_f32_e32 v189, v121, v190
	v_fmac_f32_e32 v191, v188, v188
	v_add_f32_e32 v190, v122, v239
	v_fmac_f32_e32 v191, v189, v189
	v_fmac_f32_e32 v191, v190, v190
	v_cvt_pk_bf16_f32 v120, v124, v125
	v_fmac_f32_e32 v191, v123, v123
	v_cvt_pk_bf16_f32 v121, v126, v127
	v_cvt_pk_bf16_f32 v122, v188, v189
	v_cvt_pk_bf16_f32 v123, v190, v123
	global_store_dwordx4 v[230:231], v[120:123], off
	v_lshlrev_b32_e32 v124, 16, v186
	v_and_b32_e32 v125, 0xffff0000, v186
	v_lshlrev_b32_e32 v120, 16, v184
	v_and_b32_e32 v121, 0xffff0000, v184
	v_add_f32_e32 v116, v116, v120
	v_lshlrev_b32_e32 v122, 16, v185
	v_add_f32_e32 v117, v117, v121
	v_fmac_f32_e32 v191, v116, v116
	v_and_b32_e32 v123, 0xffff0000, v185
	v_add_f32_e32 v118, v118, v122
	v_fmac_f32_e32 v191, v117, v117
	v_add_f32_e32 v119, v119, v123
	v_fmac_f32_e32 v191, v118, v118
	v_add_f32_e32 v120, v112, v124
	v_fmac_f32_e32 v191, v119, v119
	v_lshlrev_b32_e32 v126, 16, v187
	v_add_f32_e32 v121, v113, v125
	v_fmac_f32_e32 v191, v120, v120
	v_and_b32_e32 v127, 0xffff0000, v187
	v_add_f32_e32 v122, v114, v126
	v_fmac_f32_e32 v191, v121, v121
	v_add_f32_e32 v115, v115, v127
	v_fmac_f32_e32 v191, v122, v122
	v_cvt_pk_bf16_f32 v112, v116, v117
	v_cvt_pk_bf16_f32 v113, v118, v119
	v_fmac_f32_e32 v191, v115, v115
	v_cvt_pk_bf16_f32 v114, v120, v121
	v_cvt_pk_bf16_f32 v115, v122, v115
	global_store_dwordx4 v[230:231], v[112:115], off offset:256
	s_nop 1
	v_and_b32_e32 v113, 64, v238
	v_xor_b32_e32 v112, 16, v238
	v_add_u32_e32 v113, 64, v113
	v_cmp_lt_i32_e32 vcc, v112, v113
	v_xor_b32_e32 v115, 32, v238
	s_nop 0
	v_cndmask_b32_e32 v112, v238, v112, vcc
	v_lshlrev_b32_e32 v112, 2, v112
	ds_bpermute_b32 v114, v112, v191
	v_cmp_lt_i32_e32 vcc, v115, v113
	s_waitcnt lgkmcnt(0)
	v_add_f32_e32 v114, v191, v114
	v_cndmask_b32_e32 v113, v238, v115, vcc
	v_lshlrev_b32_e32 v113, 2, v113
	ds_bpermute_b32 v115, v113, v114
	s_and_saveexec_b64 s[14:15], s[4:5]
	s_cbranch_execz .LBB0_203
	s_waitcnt lgkmcnt(0)
	v_add_f32_e32 v114, v114, v115
	v_mul_f32_e32 v114, 0x49800000, v114
	v_trunc_f32_e32 v114, v114
	v_mul_f32_e32 v115, 0x2f800000, v114
	v_floor_f32_e32 v115, v115
	v_fmac_f32_e32 v114, 0xcf800000, v115
	v_cvt_u32_f32_e32 v114, v114
	v_cvt_u32_f32_e32 v115, v115
	v_readlane_b32 s16, v254, 39
	v_readlane_b32 s17, v254, 40
	s_nop 1
	v_lshl_add_u64 v[116:117], v[228:229], 3, s[16:17]
	global_atomic_add_x2 v[116:117], v[114:115], off
; __device__ __forceinline__ void unpack8(u32x4 w, float* f) { f[0] = bflo(w.x); f[1] = bfhi(w.x); f[2] = bflo(w.y); f[3] = bfhi(w.y); f[4] = bflo(w.z); f[5] = bfhi(w.z); f[6] = bflo(w.w); f[7] = bfhi(w.w); }
; __device__ __forceinline__ u32x4 pack8(const float* f) { u32x4 w; w.x = cvt_pk_bf16(f[0], f[1]); w.y = cvt_pk_bf16(f[2], f[3]); w.z = cvt_pk_bf16(f[4], f[5]); w.w = cvt_pk_bf16(f[6], f[7]); return w; }
;     __device__ __forceinline__ void operator()(const f32x4 (&acc)[2][2][4][2], const Unit& u, int wr, int wc, int fr, int fq, LAS unsigned char* lds, int par, int npm, int tid) const {
;     ...
;             for (int m = 0; m < 4; ++m) { const int row = row0 + ai * HALF + m * 16; bf16_t* hp = Hb + (size_t)row * ldc + col0;
;                 float part = 0.f;
; #pragma unroll
;                 for (int bj = 0; bj < 2; ++bj) { float o[8]; unpack8(old[ai][m][bj], o);
;                     const f32x4 a0 = acc[ai][bj][m][0], a1 = acc[ai][bj][m][1];
;                     float v[8] = {o[0] + a0[0], o[1] + a0[1], o[2] + a0[2], o[3] + a0[3], o[4] + a1[0], o[5] + a1[1], o[6] + a1[2], o[7] + a1[3]};
; #pragma unroll
;                     for (int k = 0; k < 8; ++k) part += v[k] * v[k];
;                     *(u32x4*)(hp + bj * HALF) = pack8(v); }
;                 part += __shfl_xor(part, 16); part += __shfl_xor(part, 32);
;                 if (fq == 0) atomicAdd(ssq + row, (unsigned long long)(part * 1048576.f)); }
.LBB0_203:
	s_or_b64 exec, exec, s[14:15]
	v_and_b32_e32 v117, 0xffff0000, v180
	v_lshlrev_b32_e32 v116, 16, v180
	v_and_b32_e32 v119, 0xffff0000, v181
	v_add_f32_e32 v109, v109, v117
	v_lshlrev_b32_e32 v118, 16, v181
	v_add_f32_e32 v108, v108, v116
	v_add_f32_e32 v111, v111, v119
	v_mul_f32_e32 v119, v109, v109
	v_add_f32_e32 v110, v110, v118
	v_fmac_f32_e32 v119, v108, v108
	v_lshlrev_b32_e32 v120, 16, v182
	v_fmac_f32_e32 v119, v110, v110
	v_and_b32_e32 v121, 0xffff0000, v182
	v_add_f32_e32 v116, v104, v120
	v_fmac_f32_e32 v119, v111, v111
	v_lshlrev_b32_e32 v122, 16, v183
	v_add_f32_e32 v117, v105, v121
	v_fmac_f32_e32 v119, v116, v116
	v_and_b32_e32 v123, 0xffff0000, v183
	v_add_f32_e32 v118, v106, v122
	v_fmac_f32_e32 v119, v117, v117
	v_add_f32_e32 v107, v107, v123
	v_fmac_f32_e32 v119, v118, v118
	v_lshlrev_b32_e32 v106, 16, v176
	v_fmac_f32_e32 v119, v107, v107
	v_cvt_pk_bf16_f32 v104, v108, v109
	v_and_b32_e32 v108, 0xffff0000, v176
	v_add_f32_e32 v100, v100, v106
	v_lshlrev_b32_e32 v109, 16, v177
	v_add_f32_e32 v101, v101, v108
	v_fmac_f32_e32 v119, v100, v100
	v_cvt_pk_bf16_f32 v105, v110, v111
	v_and_b32_e32 v110, 0xffff0000, v177
	v_add_f32_e32 v102, v102, v109
	v_fmac_f32_e32 v119, v101, v101
	v_lshlrev_b32_e32 v111, 16, v178
	v_add_f32_e32 v103, v103, v110
	v_fmac_f32_e32 v119, v102, v102
	v_and_b32_e32 v120, 0xffff0000, v178
	v_add_f32_e32 v108, v96, v111
	v_fmac_f32_e32 v119, v103, v103
	v_lshlrev_b32_e32 v121, 16, v179
	v_add_f32_e32 v109, v97, v120
	v_fmac_f32_e32 v119, v108, v108
	v_and_b32_e32 v122, 0xffff0000, v179
	v_add_f32_e32 v110, v98, v121
	v_fmac_f32_e32 v119, v109, v109
	v_add_f32_e32 v111, v99, v122
	v_fmac_f32_e32 v119, v110, v110
	v_fmac_f32_e32 v119, v111, v111
	ds_bpermute_b32 v96, v112, v119
	v_readlane_b32 s14, v254, 8
	s_waitcnt lgkmcnt(0)
	v_lshlrev_b64 v[114:115], 11, v[226:227]
	v_readlane_b32 s15, v254, 9
	v_cvt_pk_bf16_f32 v106, v116, v117
	v_add_f32_e32 v96, v119, v96
	ds_bpermute_b32 v97, v113, v96
	v_lshl_add_u64 v[114:115], v[114:115], 1, s[14:15]
	v_lshl_add_u64 v[114:115], v[212:213], 1, v[114:115]
	v_cvt_pk_bf16_f32 v107, v118, v107
	global_store_dwordx4 v[114:115], v[104:107], off
	v_cvt_pk_bf16_f32 v98, v100, v101
	v_cvt_pk_bf16_f32 v99, v102, v103
	v_cvt_pk_bf16_f32 v100, v108, v109
	v_cvt_pk_bf16_f32 v101, v110, v111
	global_store_dwordx4 v[114:115], v[98:101], off offset:256
	s_and_saveexec_b64 s[14:15], s[4:5]
	s_cbranch_execz .LBB0_205
	s_waitcnt lgkmcnt(0)
	v_add_f32_e32 v96, v96, v97
	v_mul_f32_e32 v96, 0x49800000, v96
	v_trunc_f32_e32 v96, v96
	v_mul_f32_e32 v97, 0x2f800000, v96
	v_floor_f32_e32 v97, v97
	v_fmac_f32_e32 v96, 0xcf800000, v97
	v_cvt_u32_f32_e32 v96, v96
	v_cvt_u32_f32_e32 v97, v97
	v_readlane_b32 s16, v254, 39
	v_readlane_b32 s17, v254, 40
	s_nop 1
	v_lshl_add_u64 v[98:99], v[226:227], 3, s[16:17]
	global_atomic_add_x2 v[98:99], v[96:97], off
.LBB0_205:
	s_or_b64 exec, exec, s[14:15]
	v_and_b32_e32 v99, 0xffff0000, v172
	v_lshlrev_b32_e32 v98, 16, v172
	v_and_b32_e32 v101, 0xffff0000, v173
	v_add_f32_e32 v93, v93, v99
	v_lshlrev_b32_e32 v100, 16, v173
	v_add_f32_e32 v92, v92, v98
	v_add_f32_e32 v95, v95, v101
	v_mul_f32_e32 v101, v93, v93
	v_add_f32_e32 v94, v94, v100
	v_fmac_f32_e32 v101, v92, v92
	v_lshlrev_b32_e32 v102, 16, v174
	v_fmac_f32_e32 v101, v94, v94
	v_and_b32_e32 v103, 0xffff0000, v174
	v_add_f32_e32 v98, v88, v102
	v_fmac_f32_e32 v101, v95, v95
	v_lshlrev_b32_e32 v104, 16, v175
	v_add_f32_e32 v99, v89, v103
	v_fmac_f32_e32 v101, v98, v98
	v_and_b32_e32 v105, 0xffff0000, v175
	v_add_f32_e32 v100, v90, v104
	v_fmac_f32_e32 v101, v99, v99
	v_add_f32_e32 v91, v91, v105
	v_fmac_f32_e32 v101, v100, v100
	v_lshlrev_b32_e32 v90, 16, v168
	v_fmac_f32_e32 v101, v91, v91
	v_cvt_pk_bf16_f32 v88, v92, v93
	v_and_b32_e32 v92, 0xffff0000, v168
	v_add_f32_e32 v84, v84, v90
	v_lshlrev_b32_e32 v93, 16, v169
	v_add_f32_e32 v85, v85, v92
	v_fmac_f32_e32 v101, v84, v84
	v_cvt_pk_bf16_f32 v89, v94, v95
	v_and_b32_e32 v94, 0xffff0000, v169
	v_add_f32_e32 v86, v86, v93
	v_fmac_f32_e32 v101, v85, v85
	v_lshlrev_b32_e32 v95, 16, v170
	v_add_f32_e32 v87, v87, v94
	v_fmac_f32_e32 v101, v86, v86
	v_and_b32_e32 v102, 0xffff0000, v170
	v_add_f32_e32 v92, v80, v95
	v_fmac_f32_e32 v101, v87, v87
	v_lshlrev_b32_e32 v103, 16, v171
	v_add_f32_e32 v93, v81, v102
	v_fmac_f32_e32 v101, v92, v92
	v_and_b32_e32 v104, 0xffff0000, v171
	v_add_f32_e32 v94, v82, v103
	v_fmac_f32_e32 v101, v93, v93
	v_add_f32_e32 v95, v83, v104
	v_fmac_f32_e32 v101, v94, v94
	v_fmac_f32_e32 v101, v95, v95
	ds_bpermute_b32 v80, v112, v101
	v_readlane_b32 s14, v254, 8
	s_waitcnt lgkmcnt(0)
	v_lshlrev_b64 v[96:97], 11, v[224:225]
	v_readlane_b32 s15, v254, 9
	v_cvt_pk_bf16_f32 v90, v98, v99
	v_add_f32_e32 v80, v101, v80
	ds_bpermute_b32 v81, v113, v80
	v_lshl_add_u64 v[96:97], v[96:97], 1, s[14:15]
	v_lshl_add_u64 v[96:97], v[212:213], 1, v[96:97]
	v_cvt_pk_bf16_f32 v91, v100, v91
	global_store_dwordx4 v[96:97], v[88:91], off
	v_cvt_pk_bf16_f32 v82, v84, v85
	v_cvt_pk_bf16_f32 v83, v86, v87
	v_cvt_pk_bf16_f32 v84, v92, v93
	v_cvt_pk_bf16_f32 v85, v94, v95
	global_store_dwordx4 v[96:97], v[82:85], off offset:256
	s_and_saveexec_b64 s[14:15], s[4:5]
	s_cbranch_execz .LBB0_207
	s_waitcnt lgkmcnt(0)
	v_add_f32_e32 v80, v80, v81
	v_mul_f32_e32 v80, 0x49800000, v80
	v_trunc_f32_e32 v80, v80
	v_mul_f32_e32 v81, 0x2f800000, v80
	v_floor_f32_e32 v81, v81
	v_fmac_f32_e32 v80, 0xcf800000, v81
	v_cvt_u32_f32_e32 v80, v80
	v_cvt_u32_f32_e32 v81, v81
	v_readlane_b32 s16, v254, 39
	v_readlane_b32 s17, v254, 40
	s_nop 1
	v_lshl_add_u64 v[82:83], v[224:225], 3, s[16:17]
	global_atomic_add_x2 v[82:83], v[80:81], off
; __device__ __forceinline__ void unpack8(u32x4 w, float* f) { f[0] = bflo(w.x); f[1] = bfhi(w.x); f[2] = bflo(w.y); f[3] = bfhi(w.y); f[4] = bflo(w.z); f[5] = bfhi(w.z); f[6] = bflo(w.w); f[7] = bfhi(w.w); }
; __device__ __forceinline__ u32x4 pack8(const float* f) { u32x4 w; w.x = cvt_pk_bf16(f[0], f[1]); w.y = cvt_pk_bf16(f[2], f[3]); w.z = cvt_pk_bf16(f[4], f[5]); w.w = cvt_pk_bf16(f[6], f[7]); return w; }
;     __device__ __forceinline__ void operator()(const f32x4 (&acc)[2][2][4][2], const Unit& u, int wr, int wc, int fr, int fq, LAS unsigned char* lds, int par, int npm, int tid) const {
;     ...
;             for (int m = 0; m < 4; ++m) { const int row = row0 + ai * HALF + m * 16; bf16_t* hp = Hb + (size_t)row * ldc + col0;
;                 float part = 0.f;
; #pragma unroll
;                 for (int bj = 0; bj < 2; ++bj) { float o[8]; unpack8(old[ai][m][bj], o);
;                     const f32x4 a0 = acc[ai][bj][m][0], a1 = acc[ai][bj][m][1];
;                     float v[8] = {o[0] + a0[0], o[1] + a0[1], o[2] + a0[2], o[3] + a0[3], o[4] + a1[0], o[5] + a1[1], o[6] + a1[2], o[7] + a1[3]};
; #pragma unroll
;                     for (int k = 0; k < 8; ++k) part += v[k] * v[k];
;                     *(u32x4*)(hp + bj * HALF) = pack8(v); }
;                 part += __shfl_xor(part, 16); part += __shfl_xor(part, 32);
;                 if (fq == 0) atomicAdd(ssq + row, (unsigned long long)(part * 1048576.f)); }
.LBB0_207:
	s_or_b64 exec, exec, s[14:15]
	v_and_b32_e32 v83, 0xffff0000, v164
	v_lshlrev_b32_e32 v82, 16, v164
	v_and_b32_e32 v85, 0xffff0000, v165
	v_add_f32_e32 v77, v77, v83
	v_lshlrev_b32_e32 v84, 16, v165
	v_add_f32_e32 v76, v76, v82
	v_add_f32_e32 v79, v79, v85
	v_mul_f32_e32 v85, v77, v77
	v_add_f32_e32 v78, v78, v84
	v_fmac_f32_e32 v85, v76, v76
	v_lshlrev_b32_e32 v86, 16, v166
	v_fmac_f32_e32 v85, v78, v78
	v_and_b32_e32 v87, 0xffff0000, v166
	v_add_f32_e32 v82, v72, v86
	v_fmac_f32_e32 v85, v79, v79
	v_lshlrev_b32_e32 v88, 16, v167
	v_add_f32_e32 v83, v73, v87
	v_fmac_f32_e32 v85, v82, v82
	v_and_b32_e32 v89, 0xffff0000, v167
	v_add_f32_e32 v84, v74, v88
	v_fmac_f32_e32 v85, v83, v83
	v_add_f32_e32 v75, v75, v89
	v_fmac_f32_e32 v85, v84, v84
	v_lshlrev_b32_e32 v74, 16, v160
	v_fmac_f32_e32 v85, v75, v75
	v_cvt_pk_bf16_f32 v72, v76, v77
	v_and_b32_e32 v76, 0xffff0000, v160
	v_add_f32_e32 v68, v68, v74
	v_lshlrev_b32_e32 v77, 16, v161
	v_add_f32_e32 v69, v69, v76
	v_fmac_f32_e32 v85, v68, v68
	v_cvt_pk_bf16_f32 v73, v78, v79
	v_and_b32_e32 v78, 0xffff0000, v161
	v_add_f32_e32 v70, v70, v77
	v_fmac_f32_e32 v85, v69, v69
	v_lshlrev_b32_e32 v79, 16, v162
	v_add_f32_e32 v71, v71, v78
	v_fmac_f32_e32 v85, v70, v70
	v_and_b32_e32 v86, 0xffff0000, v162
	v_add_f32_e32 v76, v64, v79
	v_fmac_f32_e32 v85, v71, v71
	v_lshlrev_b32_e32 v87, 16, v163
	v_add_f32_e32 v77, v65, v86
	v_fmac_f32_e32 v85, v76, v76
	v_and_b32_e32 v88, 0xffff0000, v163
	v_add_f32_e32 v78, v66, v87
	v_fmac_f32_e32 v85, v77, v77
	v_add_f32_e32 v79, v67, v88
	v_fmac_f32_e32 v85, v78, v78
	v_fmac_f32_e32 v85, v79, v79
	ds_bpermute_b32 v64, v112, v85
	v_readlane_b32 s14, v254, 8
	s_waitcnt lgkmcnt(0)
	v_lshlrev_b64 v[80:81], 11, v[222:223]
	v_readlane_b32 s15, v254, 9
	v_cvt_pk_bf16_f32 v74, v82, v83
	v_add_f32_e32 v64, v85, v64
	ds_bpermute_b32 v65, v113, v64
	v_lshl_add_u64 v[80:81], v[80:81], 1, s[14:15]
	v_lshl_add_u64 v[80:81], v[212:213], 1, v[80:81]
	v_cvt_pk_bf16_f32 v75, v84, v75
	global_store_dwordx4 v[80:81], v[72:75], off
	v_cvt_pk_bf16_f32 v66, v68, v69
	v_cvt_pk_bf16_f32 v67, v70, v71
	v_cvt_pk_bf16_f32 v68, v76, v77
	v_cvt_pk_bf16_f32 v69, v78, v79
	global_store_dwordx4 v[80:81], v[66:69], off offset:256
	s_and_saveexec_b64 s[14:15], s[4:5]
	s_cbranch_execz .LBB0_209
	s_waitcnt lgkmcnt(0)
	v_add_f32_e32 v64, v64, v65
	v_mul_f32_e32 v64, 0x49800000, v64
	v_trunc_f32_e32 v64, v64
	v_mul_f32_e32 v65, 0x2f800000, v64
	v_floor_f32_e32 v65, v65
	v_fmac_f32_e32 v64, 0xcf800000, v65
	v_cvt_u32_f32_e32 v64, v64
	v_cvt_u32_f32_e32 v65, v65
	v_readlane_b32 s16, v254, 39
	v_readlane_b32 s17, v254, 40
	s_nop 1
	v_lshl_add_u64 v[66:67], v[222:223], 3, s[16:17]
	global_atomic_add_x2 v[66:67], v[64:65], off
.LBB0_209:
	s_or_b64 exec, exec, s[14:15]
	v_and_b32_e32 v67, 0xffff0000, v156
	v_lshlrev_b32_e32 v66, 16, v156
	v_and_b32_e32 v69, 0xffff0000, v157
	v_add_f32_e32 v61, v61, v67
	v_lshlrev_b32_e32 v68, 16, v157
	v_add_f32_e32 v60, v60, v66
	v_add_f32_e32 v63, v63, v69
	v_mul_f32_e32 v69, v61, v61
	v_add_f32_e32 v62, v62, v68
	v_fmac_f32_e32 v69, v60, v60
	v_lshlrev_b32_e32 v70, 16, v158
	v_fmac_f32_e32 v69, v62, v62
	v_and_b32_e32 v71, 0xffff0000, v158
	v_add_f32_e32 v66, v56, v70
	v_fmac_f32_e32 v69, v63, v63
	v_lshlrev_b32_e32 v72, 16, v159
	v_add_f32_e32 v67, v57, v71
	v_fmac_f32_e32 v69, v66, v66
	v_and_b32_e32 v73, 0xffff0000, v159
	v_add_f32_e32 v68, v58, v72
	v_fmac_f32_e32 v69, v67, v67
	v_add_f32_e32 v59, v59, v73
	v_fmac_f32_e32 v69, v68, v68
	v_lshlrev_b32_e32 v58, 16, v152
	v_fmac_f32_e32 v69, v59, v59
	v_cvt_pk_bf16_f32 v56, v60, v61
	v_and_b32_e32 v60, 0xffff0000, v152
	v_add_f32_e32 v52, v52, v58
	v_lshlrev_b32_e32 v61, 16, v153
	v_add_f32_e32 v53, v53, v60
	v_fmac_f32_e32 v69, v52, v52
	v_cvt_pk_bf16_f32 v57, v62, v63
	v_and_b32_e32 v62, 0xffff0000, v153
	v_add_f32_e32 v54, v54, v61
	v_fmac_f32_e32 v69, v53, v53
	v_lshlrev_b32_e32 v63, 16, v154
	v_add_f32_e32 v55, v55, v62
	v_fmac_f32_e32 v69, v54, v54
	v_and_b32_e32 v70, 0xffff0000, v154
	v_add_f32_e32 v60, v48, v63
	v_fmac_f32_e32 v69, v55, v55
	v_lshlrev_b32_e32 v71, 16, v155
	v_add_f32_e32 v61, v49, v70
	v_fmac_f32_e32 v69, v60, v60
	v_and_b32_e32 v72, 0xffff0000, v155
	v_add_f32_e32 v62, v50, v71
	v_fmac_f32_e32 v69, v61, v61
	v_add_f32_e32 v63, v51, v72
	v_fmac_f32_e32 v69, v62, v62
	v_fmac_f32_e32 v69, v63, v63
	ds_bpermute_b32 v48, v112, v69
	v_readlane_b32 s14, v254, 8
	s_waitcnt lgkmcnt(0)
	v_lshlrev_b64 v[64:65], 11, v[220:221]
	v_readlane_b32 s15, v254, 9
	v_cvt_pk_bf16_f32 v58, v66, v67
	v_add_f32_e32 v48, v69, v48
	ds_bpermute_b32 v49, v113, v48
	v_lshl_add_u64 v[64:65], v[64:65], 1, s[14:15]
	v_lshl_add_u64 v[64:65], v[212:213], 1, v[64:65]
	v_cvt_pk_bf16_f32 v59, v68, v59
	global_store_dwordx4 v[64:65], v[56:59], off
	v_cvt_pk_bf16_f32 v50, v52, v53
	v_cvt_pk_bf16_f32 v51, v54, v55
	v_cvt_pk_bf16_f32 v52, v60, v61
	v_cvt_pk_bf16_f32 v53, v62, v63
	global_store_dwordx4 v[64:65], v[50:53], off offset:256
	s_and_saveexec_b64 s[14:15], s[4:5]
	s_cbranch_execz .LBB0_211
	s_waitcnt lgkmcnt(0)
	v_add_f32_e32 v48, v48, v49
	v_mul_f32_e32 v48, 0x49800000, v48
	v_trunc_f32_e32 v48, v48
	v_mul_f32_e32 v49, 0x2f800000, v48
	v_floor_f32_e32 v49, v49
	v_fmac_f32_e32 v48, 0xcf800000, v49
	v_cvt_u32_f32_e32 v48, v48
	v_cvt_u32_f32_e32 v49, v49
	v_readlane_b32 s16, v254, 39
	v_readlane_b32 s17, v254, 40
	s_nop 1
	v_lshl_add_u64 v[50:51], v[220:221], 3, s[16:17]
	global_atomic_add_x2 v[50:51], v[48:49], off
; __device__ __forceinline__ void unpack8(u32x4 w, float* f) { f[0] = bflo(w.x); f[1] = bfhi(w.x); f[2] = bflo(w.y); f[3] = bfhi(w.y); f[4] = bflo(w.z); f[5] = bfhi(w.z); f[6] = bflo(w.w); f[7] = bfhi(w.w); }
; __device__ __forceinline__ u32x4 pack8(const float* f) { u32x4 w; w.x = cvt_pk_bf16(f[0], f[1]); w.y = cvt_pk_bf16(f[2], f[3]); w.z = cvt_pk_bf16(f[4], f[5]); w.w = cvt_pk_bf16(f[6], f[7]); return w; }
;     __device__ __forceinline__ void operator()(const f32x4 (&acc)[2][2][4][2], const Unit& u, int wr, int wc, int fr, int fq, LAS unsigned char* lds, int par, int npm, int tid) const {
;     ...
;             for (int m = 0; m < 4; ++m) { const int row = row0 + ai * HALF + m * 16; bf16_t* hp = Hb + (size_t)row * ldc + col0;
;                 float part = 0.f;
; #pragma unroll
;                 for (int bj = 0; bj < 2; ++bj) { float o[8]; unpack8(old[ai][m][bj], o);
;                     const f32x4 a0 = acc[ai][bj][m][0], a1 = acc[ai][bj][m][1];
;                     float v[8] = {o[0] + a0[0], o[1] + a0[1], o[2] + a0[2], o[3] + a0[3], o[4] + a1[0], o[5] + a1[1], o[6] + a1[2], o[7] + a1[3]};
; #pragma unroll
;                     for (int k = 0; k < 8; ++k) part += v[k] * v[k];
;                     *(u32x4*)(hp + bj * HALF) = pack8(v); }
;                 part += __shfl_xor(part, 16); part += __shfl_xor(part, 32);
;                 if (fq == 0) atomicAdd(ssq + row, (unsigned long long)(part * 1048576.f)); }
.LBB0_211:
	s_or_b64 exec, exec, s[14:15]
	v_and_b32_e32 v51, 0xffff0000, v148
	v_lshlrev_b32_e32 v50, 16, v148
	v_and_b32_e32 v53, 0xffff0000, v149
	v_add_f32_e32 v45, v45, v51
	v_lshlrev_b32_e32 v52, 16, v149
	v_add_f32_e32 v44, v44, v50
	v_add_f32_e32 v47, v47, v53
	v_mul_f32_e32 v53, v45, v45
	v_add_f32_e32 v46, v46, v52
	v_fmac_f32_e32 v53, v44, v44
	v_lshlrev_b32_e32 v54, 16, v150
	v_fmac_f32_e32 v53, v46, v46
	v_and_b32_e32 v55, 0xffff0000, v150
	v_add_f32_e32 v50, v40, v54
	v_fmac_f32_e32 v53, v47, v47
	v_lshlrev_b32_e32 v56, 16, v151
	v_add_f32_e32 v51, v41, v55
	v_fmac_f32_e32 v53, v50, v50
	v_and_b32_e32 v57, 0xffff0000, v151
	v_add_f32_e32 v52, v42, v56
	v_fmac_f32_e32 v53, v51, v51
	v_add_f32_e32 v43, v43, v57
	v_fmac_f32_e32 v53, v52, v52
	v_lshlrev_b32_e32 v42, 16, v144
	v_fmac_f32_e32 v53, v43, v43
	v_cvt_pk_bf16_f32 v40, v44, v45
	v_and_b32_e32 v44, 0xffff0000, v144
	v_add_f32_e32 v36, v36, v42
	v_lshlrev_b32_e32 v45, 16, v145
	v_add_f32_e32 v37, v37, v44
	v_fmac_f32_e32 v53, v36, v36
	v_cvt_pk_bf16_f32 v41, v46, v47
	v_and_b32_e32 v46, 0xffff0000, v145
	v_add_f32_e32 v38, v38, v45
	v_fmac_f32_e32 v53, v37, v37
	v_lshlrev_b32_e32 v47, 16, v146
	v_add_f32_e32 v39, v39, v46
	v_fmac_f32_e32 v53, v38, v38
	v_and_b32_e32 v54, 0xffff0000, v146
	v_add_f32_e32 v44, v32, v47
	v_fmac_f32_e32 v53, v39, v39
	v_lshlrev_b32_e32 v55, 16, v147
	v_add_f32_e32 v45, v33, v54
	v_fmac_f32_e32 v53, v44, v44
	v_and_b32_e32 v56, 0xffff0000, v147
	v_add_f32_e32 v46, v34, v55
	v_fmac_f32_e32 v53, v45, v45
	v_add_f32_e32 v47, v35, v56
	v_fmac_f32_e32 v53, v46, v46
	v_fmac_f32_e32 v53, v47, v47
	ds_bpermute_b32 v32, v112, v53
	v_readlane_b32 s14, v254, 8
	s_waitcnt lgkmcnt(0)
	v_lshlrev_b64 v[48:49], 11, v[218:219]
	v_readlane_b32 s15, v254, 9
	v_cvt_pk_bf16_f32 v42, v50, v51
	v_add_f32_e32 v32, v53, v32
	ds_bpermute_b32 v33, v113, v32
	v_lshl_add_u64 v[48:49], v[48:49], 1, s[14:15]
	v_lshl_add_u64 v[48:49], v[212:213], 1, v[48:49]
	v_cvt_pk_bf16_f32 v43, v52, v43
	global_store_dwordx4 v[48:49], v[40:43], off
	v_cvt_pk_bf16_f32 v34, v36, v37
	v_cvt_pk_bf16_f32 v35, v38, v39
	v_cvt_pk_bf16_f32 v36, v44, v45
	v_cvt_pk_bf16_f32 v37, v46, v47
	global_store_dwordx4 v[48:49], v[34:37], off offset:256
	s_and_saveexec_b64 s[14:15], s[4:5]
	s_cbranch_execz .LBB0_213
	s_waitcnt lgkmcnt(0)
	v_add_f32_e32 v32, v32, v33
	v_mul_f32_e32 v32, 0x49800000, v32
	v_trunc_f32_e32 v32, v32
	v_mul_f32_e32 v33, 0x2f800000, v32
	v_floor_f32_e32 v33, v33
	v_fmac_f32_e32 v32, 0xcf800000, v33
	v_cvt_u32_f32_e32 v32, v32
	v_cvt_u32_f32_e32 v33, v33
	v_readlane_b32 s16, v254, 39
	v_readlane_b32 s17, v254, 40
	s_nop 1
	v_lshl_add_u64 v[34:35], v[218:219], 3, s[16:17]
	global_atomic_add_x2 v[34:35], v[32:33], off
; __device__ __forceinline__ void unpack8(u32x4 w, float* f) { f[0] = bflo(w.x); f[1] = bfhi(w.x); f[2] = bflo(w.y); f[3] = bfhi(w.y); f[4] = bflo(w.z); f[5] = bfhi(w.z); f[6] = bflo(w.w); f[7] = bfhi(w.w); }
; __device__ __forceinline__ u32x4 pack8(const float* f) { u32x4 w; w.x = cvt_pk_bf16(f[0], f[1]); w.y = cvt_pk_bf16(f[2], f[3]); w.z = cvt_pk_bf16(f[4], f[5]); w.w = cvt_pk_bf16(f[6], f[7]); return w; }
;     __device__ __forceinline__ void operator()(const f32x4 (&acc)[2][2][4][2], const Unit& u, int wr, int wc, int fr, int fq, LAS unsigned char* lds, int par, int npm, int tid) const {
;     ...
;             for (int m = 0; m < 4; ++m) { const int row = row0 + ai * HALF + m * 16; bf16_t* hp = Hb + (size_t)row * ldc + col0;
;                 float part = 0.f;
; #pragma unroll
;                 for (int bj = 0; bj < 2; ++bj) { float o[8]; unpack8(old[ai][m][bj], o);
;                     const f32x4 a0 = acc[ai][bj][m][0], a1 = acc[ai][bj][m][1];
;                     float v[8] = {o[0] + a0[0], o[1] + a0[1], o[2] + a0[2], o[3] + a0[3], o[4] + a1[0], o[5] + a1[1], o[6] + a1[2], o[7] + a1[3]};
; #pragma unroll
;                     for (int k = 0; k < 8; ++k) part += v[k] * v[k];
;                     *(u32x4*)(hp + bj * HALF) = pack8(v); }
;                 part += __shfl_xor(part, 16); part += __shfl_xor(part, 32);
;                 if (fq == 0) atomicAdd(ssq + row, (unsigned long long)(part * 1048576.f)); }
.LBB0_213:
	s_or_b64 exec, exec, s[14:15]
	v_and_b32_e32 v35, 0xffff0000, v136
	v_lshlrev_b32_e32 v34, 16, v136
	v_and_b32_e32 v37, 0xffff0000, v137
	v_add_f32_e32 v29, v29, v35
	v_lshlrev_b32_e32 v36, 16, v137
	v_add_f32_e32 v28, v28, v34
	v_add_f32_e32 v31, v31, v37
	v_mul_f32_e32 v37, v29, v29
	v_add_f32_e32 v30, v30, v36
	v_fmac_f32_e32 v37, v28, v28
	v_lshlrev_b32_e32 v38, 16, v138
	v_fmac_f32_e32 v37, v30, v30
	v_and_b32_e32 v39, 0xffff0000, v138
	v_add_f32_e32 v34, v24, v38
	v_fmac_f32_e32 v37, v31, v31
	v_lshlrev_b32_e32 v40, 16, v139
	v_add_f32_e32 v35, v25, v39
	v_fmac_f32_e32 v37, v34, v34
	v_and_b32_e32 v41, 0xffff0000, v139
	v_add_f32_e32 v36, v26, v40
	v_fmac_f32_e32 v37, v35, v35
	v_add_f32_e32 v27, v27, v41
	v_fmac_f32_e32 v37, v36, v36
	v_lshlrev_b32_e32 v26, 16, v128
	v_fmac_f32_e32 v37, v27, v27
	v_cvt_pk_bf16_f32 v24, v28, v29
	v_and_b32_e32 v28, 0xffff0000, v128
	v_add_f32_e32 v20, v20, v26
	v_lshlrev_b32_e32 v29, 16, v129
	v_add_f32_e32 v21, v21, v28
	v_fmac_f32_e32 v37, v20, v20
	v_cvt_pk_bf16_f32 v25, v30, v31
	v_and_b32_e32 v30, 0xffff0000, v129
	v_add_f32_e32 v22, v22, v29
	v_fmac_f32_e32 v37, v21, v21
	v_lshlrev_b32_e32 v31, 16, v130
	v_add_f32_e32 v23, v23, v30
	v_fmac_f32_e32 v37, v22, v22
	v_and_b32_e32 v38, 0xffff0000, v130
	v_add_f32_e32 v28, v16, v31
	v_fmac_f32_e32 v37, v23, v23
	v_lshlrev_b32_e32 v39, 16, v131
	v_add_f32_e32 v29, v17, v38
	v_fmac_f32_e32 v37, v28, v28
	v_and_b32_e32 v40, 0xffff0000, v131
	v_add_f32_e32 v30, v18, v39
	v_fmac_f32_e32 v37, v29, v29
	v_add_f32_e32 v31, v19, v40
	v_fmac_f32_e32 v37, v30, v30
	v_fmac_f32_e32 v37, v31, v31
	ds_bpermute_b32 v16, v112, v37
	v_readlane_b32 s14, v254, 8
	s_waitcnt lgkmcnt(0)
	v_lshlrev_b64 v[32:33], 11, v[216:217]
	v_readlane_b32 s15, v254, 9
	v_cvt_pk_bf16_f32 v26, v34, v35
	v_add_f32_e32 v16, v37, v16
	ds_bpermute_b32 v17, v113, v16
	v_lshl_add_u64 v[32:33], v[32:33], 1, s[14:15]
	v_lshl_add_u64 v[32:33], v[212:213], 1, v[32:33]
	v_cvt_pk_bf16_f32 v27, v36, v27
	global_store_dwordx4 v[32:33], v[24:27], off
	v_cvt_pk_bf16_f32 v18, v20, v21
	v_cvt_pk_bf16_f32 v19, v22, v23
	v_cvt_pk_bf16_f32 v20, v28, v29
	v_cvt_pk_bf16_f32 v21, v30, v31
	global_store_dwordx4 v[32:33], v[18:21], off offset:256
	s_and_saveexec_b64 s[14:15], s[4:5]
	s_cbranch_execz .LBB0_215
	s_waitcnt lgkmcnt(0)
	v_add_f32_e32 v16, v16, v17
	v_mul_f32_e32 v16, 0x49800000, v16
	v_trunc_f32_e32 v16, v16
	v_mul_f32_e32 v17, 0x2f800000, v16
	v_floor_f32_e32 v17, v17
	v_fmac_f32_e32 v16, 0xcf800000, v17
	v_cvt_u32_f32_e32 v16, v16
	v_cvt_u32_f32_e32 v17, v17
	v_readlane_b32 s16, v254, 39
	v_readlane_b32 s17, v254, 40
	s_nop 1
	v_lshl_add_u64 v[18:19], v[216:217], 3, s[16:17]
	global_atomic_add_x2 v[18:19], v[16:17], off
.LBB0_215:
	s_or_b64 exec, exec, s[14:15]
	v_and_b32_e32 v19, 0xffff0000, v140
	v_lshlrev_b32_e32 v18, 16, v140
	v_and_b32_e32 v21, 0xffff0000, v141
	v_add_f32_e32 v13, v13, v19
	v_lshlrev_b32_e32 v20, 16, v141
	v_add_f32_e32 v12, v12, v18
	v_add_f32_e32 v15, v15, v21
	v_mul_f32_e32 v21, v13, v13
	v_add_f32_e32 v14, v14, v20
	v_fmac_f32_e32 v21, v12, v12
	v_lshlrev_b32_e32 v22, 16, v142
	v_fmac_f32_e32 v21, v14, v14
	v_and_b32_e32 v23, 0xffff0000, v142
	v_add_f32_e32 v18, v8, v22
	v_fmac_f32_e32 v21, v15, v15
	v_lshlrev_b32_e32 v24, 16, v143
	v_add_f32_e32 v19, v9, v23
	v_fmac_f32_e32 v21, v18, v18
	v_and_b32_e32 v25, 0xffff0000, v143
	v_add_f32_e32 v20, v10, v24
	v_fmac_f32_e32 v21, v19, v19
	v_add_f32_e32 v11, v11, v25
	v_fmac_f32_e32 v21, v20, v20
	v_lshlrev_b32_e32 v10, 16, v132
	v_fmac_f32_e32 v21, v11, v11
	v_cvt_pk_bf16_f32 v8, v12, v13
	v_and_b32_e32 v12, 0xffff0000, v132
	v_add_f32_e32 v4, v4, v10
	v_lshlrev_b32_e32 v13, 16, v133
	v_add_f32_e32 v5, v5, v12
	v_fmac_f32_e32 v21, v4, v4
	v_cvt_pk_bf16_f32 v9, v14, v15
	v_and_b32_e32 v14, 0xffff0000, v133
	v_add_f32_e32 v6, v6, v13
	v_fmac_f32_e32 v21, v5, v5
	v_lshlrev_b32_e32 v15, 16, v134
	v_add_f32_e32 v7, v7, v14
	v_fmac_f32_e32 v21, v6, v6
	v_and_b32_e32 v22, 0xffff0000, v134
	v_add_f32_e32 v12, v0, v15
	v_fmac_f32_e32 v21, v7, v7
	v_lshlrev_b32_e32 v23, 16, v135
	v_add_f32_e32 v13, v1, v22
	v_fmac_f32_e32 v21, v12, v12
	v_and_b32_e32 v24, 0xffff0000, v135
	v_add_f32_e32 v14, v2, v23
	v_fmac_f32_e32 v21, v13, v13
	v_add_f32_e32 v15, v3, v24
	v_fmac_f32_e32 v21, v14, v14
	v_fmac_f32_e32 v21, v15, v15
	ds_bpermute_b32 v0, v112, v21
	v_readlane_b32 s14, v254, 8
	s_waitcnt lgkmcnt(0)
	v_lshlrev_b64 v[16:17], 11, v[214:215]
	v_readlane_b32 s15, v254, 9
	v_cvt_pk_bf16_f32 v10, v18, v19
	v_add_f32_e32 v0, v21, v0
	ds_bpermute_b32 v1, v113, v0
	v_lshl_add_u64 v[16:17], v[16:17], 1, s[14:15]
	v_lshl_add_u64 v[16:17], v[212:213], 1, v[16:17]
	v_cvt_pk_bf16_f32 v11, v20, v11
	global_store_dwordx4 v[16:17], v[8:11], off
	v_cvt_pk_bf16_f32 v2, v4, v5
	v_cvt_pk_bf16_f32 v3, v6, v7
	v_cvt_pk_bf16_f32 v4, v12, v13
	v_cvt_pk_bf16_f32 v5, v14, v15
	global_store_dwordx4 v[16:17], v[2:5], off offset:256
	s_and_saveexec_b64 s[14:15], s[4:5]
	s_cbranch_execz .LBB0_186
	s_waitcnt lgkmcnt(0)
	v_add_f32_e32 v0, v0, v1
	v_mul_f32_e32 v0, 0x49800000, v0
	v_trunc_f32_e32 v0, v0
	v_mul_f32_e32 v1, 0x2f800000, v0
	v_floor_f32_e32 v1, v1
	v_fmac_f32_e32 v0, 0xcf800000, v1
	v_cvt_u32_f32_e32 v0, v0
	v_cvt_u32_f32_e32 v1, v1
	v_readlane_b32 s16, v254, 39
	v_readlane_b32 s17, v254, 40
	s_nop 1
	v_lshl_add_u64 v[2:3], v[214:215], 3, s[16:17]
	global_atomic_add_x2 v[2:3], v[0:1], off
	s_branch .LBB0_186

; __device__ __forceinline__ void mlstm_out(const Bufs& B, const float* __restrict__ g_out, int item, LAS unsigned char* lds) {
;     ...
;     const float mst0 = B.MST[(0 * 4 + h) * 64 + c], mst1 = B.MST[(1 * 4 + h) * 64 + c];
;     { u32x4 rq[4], rk[4], rv[4], rc[4];
;         ld_N<128, 128>(rq, B.QKML + (size_t)s0 * 1024 + h * 128, 1024, tid);
;         ld_N<128, 128>(rk, B.QKML + (size_t)s0 * 1024 + 512 + h * 128, 1024, tid);
;         ld_T<128>(rv, B.PROJ + (size_t)s0 * NPROJP + PC_MLV + h * 128, NPROJP, tid);
;         ld_N<128, 128>(rc, B.CST + (size_t)((0 * 4 + h) * 64 + c) * 16384, 128, tid);
;         st_N<128, 128>(T0, 136, rq, tid); st_N<128, 128>(T1, 136, rk, tid); st_T<128, false>(T2, 136, rv, vea, tid); st_N<128, 128>(T3, 136, rc, tid); }
.LBB0_224:
	s_and_b32 s14, s0, 3
	s_ashr_i32 s15, s0, 2
	v_writelane_b32 v254, s0, 50
	s_lshl_b32 s0, s14, 6
	s_add_i32 s2, s0, s15
	s_ashr_i32 s3, s2, 31
	s_lshl_b32 s8, s15, 7
	s_lshl_b64 s[0:1], s[2:3], 2
	v_readlane_b32 s6, v254, 35
	v_readlane_b32 s7, v254, 36
	s_add_u32 s0, s6, s0
	s_addc_u32 s1, s7, s1
	v_mov_b32_e32 v72, v192
	s_waitcnt lgkmcnt(0)
	v_mov_b64_e32 v[0:1], s[0:1]
	global_load_dword v75, v[0:1], off
	global_load_dword v76, v[0:1], off offset:1024
	v_ashrrev_i32_e32 v0, 31, v72
	v_add_u32_e32 v38, 0x200, v72
	v_add_u32_e32 v39, 0x400, v72
	v_add_u32_e32 v64, 0x600, v72
	s_ashr_i32 s9, s8, 31
	v_lshrrev_b32_e32 v0, 28, v0
	v_ashrrev_i32_e32 v4, 31, v38
	v_ashrrev_i32_e32 v8, 31, v39
	v_ashrrev_i32_e32 v12, 31, v64
	s_lshl_b64 s[0:1], s[8:9], 11
	v_readlane_b32 s6, v254, 15
	v_add_u32_e32 v0, v72, v0
	v_lshrrev_b32_e32 v4, 28, v4
	v_lshrrev_b32_e32 v8, 28, v8
	v_lshrrev_b32_e32 v12, 28, v12
	v_readlane_b32 s7, v254, 16
	s_add_u32 s0, s6, s0
	v_ashrrev_i32_e32 v56, 4, v0
	v_and_b32_e32 v0, -16, v0
	v_add_u32_e32 v4, v38, v4
	v_add_u32_e32 v8, v39, v8
	v_add_u32_e32 v12, v64, v12
	s_addc_u32 s1, s7, s1
	s_lshl_b32 s4, s14, 8
	v_sub_u32_e32 v77, v72, v0
	v_ashrrev_i32_e32 v58, 4, v4
	v_and_b32_e32 v4, -16, v4
	v_ashrrev_i32_e32 v60, 4, v8
	v_and_b32_e32 v8, -16, v8
	v_ashrrev_i32_e32 v62, 4, v12
	v_and_b32_e32 v12, -16, v12
	s_add_u32 s0, s0, s4
	v_lshlrev_b32_e32 v48, 3, v77
	v_ashrrev_i32_e32 v57, 31, v56
	v_sub_u32_e32 v94, v38, v4
	v_ashrrev_i32_e32 v59, 31, v58
	v_sub_u32_e32 v95, v39, v8
	v_ashrrev_i32_e32 v61, 31, v60
	v_sub_u32_e32 v96, v64, v12
	v_ashrrev_i32_e32 v63, 31, v62
	s_addc_u32 s1, s1, 0
	v_lshlrev_b64 v[0:1], 11, v[56:57]
	v_ashrrev_i32_e32 v49, 31, v48
	v_lshlrev_b32_e32 v50, 3, v94
	v_lshlrev_b64 v[4:5], 11, v[58:59]
	v_lshlrev_b32_e32 v52, 3, v95
	v_lshlrev_b64 v[8:9], 11, v[60:61]
	v_lshlrev_b32_e32 v54, 3, v96
	v_lshlrev_b64 v[12:13], 11, v[62:63]
	v_lshl_add_u64 v[0:1], s[0:1], 0, v[0:1]
	v_lshlrev_b64 v[20:21], 1, v[48:49]
	v_lshl_add_u64 v[4:5], s[0:1], 0, v[4:5]
	v_ashrrev_i32_e32 v51, 31, v50
	v_lshl_add_u64 v[8:9], s[0:1], 0, v[8:9]
	v_ashrrev_i32_e32 v53, 31, v52
	v_lshl_add_u64 v[12:13], s[0:1], 0, v[12:13]
	v_ashrrev_i32_e32 v55, 31, v54
	s_mul_i32 s0, s15, 0x120000
	v_lshl_add_u64 v[16:17], v[0:1], 0, v[20:21]
	v_lshlrev_b64 v[28:29], 1, v[50:51]
	v_lshlrev_b64 v[32:33], 1, v[52:53]
	v_lshlrev_b64 v[36:37], 1, v[54:55]
	s_mul_hi_i32 s1, s8, 0x2400
	s_add_u32 s0, s16, s0
	global_load_dwordx4 v[0:3], v[16:17], off
	v_lshl_add_u64 v[22:23], v[4:5], 0, v[28:29]
	v_lshl_add_u64 v[30:31], v[8:9], 0, v[32:33]
	v_lshl_add_u64 v[34:35], v[12:13], 0, v[36:37]
	s_addc_u32 s1, s17, s1
	global_load_dwordx4 v[4:7], v[22:23], off
	global_load_dwordx4 v[8:11], v[30:31], off
	global_load_dwordx4 v[12:15], v[34:35], off
	s_nop 0
	global_load_dwordx4 v[16:19], v[16:17], off offset:1024
	s_nop 0
	global_load_dwordx4 v[24:27], v[22:23], off offset:1024
	global_load_dwordx4 v[40:43], v[30:31], off offset:1024
	global_load_dwordx4 v[44:47], v[34:35], off offset:1024
	s_add_u32 s0, s0, s4
	v_ashrrev_i32_e32 v30, 4, v72
	s_mov_b32 s6, s8
	s_addc_u32 s1, s1, 0
	v_and_b32_e32 v70, -8, v30
	v_ashrrev_i32_e32 v30, 4, v38
	v_writelane_b32 v254, s6, 52
	v_and_b32_e32 v74, 0x7f, v72
	v_mov_b64_e32 v[22:23], s[0:1]
	v_and_b32_e32 v68, -8, v30
	v_ashrrev_i32_e32 v30, 4, v39
	v_writelane_b32 v254, s7, 53
	v_mad_u64_u32 v[22:23], s[0:1], v74, s5, v[22:23]
	v_and_b32_e32 v66, -8, v30
	v_ashrrev_i32_e32 v30, 4, v64
	v_and_b32_e32 v64, -8, v30
	s_lshl_b64 s[0:1], s[2:3], 15
	v_readlane_b32 s4, v254, 19
	v_ashrrev_i32_e32 v71, 31, v70
	v_ashrrev_i32_e32 v69, 31, v68
	v_ashrrev_i32_e32 v67, 31, v66
	v_ashrrev_i32_e32 v65, 31, v64
	v_readlane_b32 s5, v254, 20
	s_add_u32 s0, s4, s0
	v_lshl_add_u64 v[78:79], v[70:71], 1, v[22:23]
	v_lshl_add_u64 v[82:83], v[68:69], 1, v[22:23]
	v_lshl_add_u64 v[86:87], v[66:67], 1, v[22:23]
	v_lshl_add_u64 v[90:91], v[64:65], 1, v[22:23]
	s_addc_u32 s1, s5, s1
	v_lshlrev_b64 v[22:23], 8, v[56:57]
	v_lshlrev_b64 v[30:31], 8, v[58:59]
	v_lshlrev_b64 v[34:35], 8, v[60:61]
	v_lshlrev_b64 v[38:39], 8, v[62:63]
	v_lshl_add_u64 v[22:23], s[0:1], 0, v[22:23]
	v_lshl_add_u64 v[30:31], s[0:1], 0, v[30:31]
	v_lshl_add_u64 v[34:35], s[0:1], 0, v[34:35]
	v_lshl_add_u64 v[38:39], s[0:1], 0, v[38:39]
	v_lshl_add_u64 v[20:21], v[22:23], 0, v[20:21]
	v_lshl_add_u64 v[28:29], v[30:31], 0, v[28:29]
	v_lshl_add_u64 v[32:33], v[34:35], 0, v[32:33]
	v_lshl_add_u64 v[36:37], v[38:39], 0, v[36:37]
	global_load_dwordx4 v[20:23], v[20:21], off
	s_movk_i32 s0, 0x110
	global_load_dwordx4 v[28:31], v[28:29], off
	v_mul_lo_u32 v65, v56, s0
	global_load_dwordx4 v[32:35], v[32:33], off
	v_lshlrev_b32_e32 v67, 4, v77
	global_load_dwordx4 v[36:39], v[36:37], off
	s_nop 0
	global_load_dwordx4 v[78:81], v[78:79], off offset:2048
	s_nop 0
	global_load_dwordx4 v[82:85], v[82:83], off offset:2048
	s_nop 0
	global_load_dwordx4 v[86:89], v[86:87], off offset:2048
	s_nop 0
	global_load_dwordx4 v[90:93], v[90:91], off offset:2048
	v_add3_u32 v69, 0, v65, v67
	v_readlane_b32 s1, v253, 22
	v_ashrrev_i32_e32 v73, 6, v72
	s_movk_i32 s16, 0x110
	v_cmp_gt_i32_e32 vcc, 2, v73
	s_waitcnt vmcnt(0) lgkmcnt(0)
; __device__ __forceinline__ void mlstm_out(const Bufs& B, const float* __restrict__ g_out, int item, LAS unsigned char* lds) {
;     ...
;         st_N<128, 128>(T0, 136, rq, tid); st_N<128, 128>(T1, 136, rk, tid); st_T<128, false>(T2, 136, rv, vea, tid); st_N<128, 128>(T3, 136, rc, tid); }
;     if (wid < 2) {
	ds_write_b128 v69, v[0:3]
	v_mul_lo_u32 v0, v58, s0
	v_lshlrev_b32_e32 v1, 4, v94
	v_add3_u32 v2, 0, v0, v1
	v_mul_lo_u32 v3, v60, s0
	ds_write_b128 v2, v[4:7]
	v_lshlrev_b32_e32 v4, 4, v95
	v_add3_u32 v5, 0, v3, v4
	v_mul_lo_u32 v6, v62, s0
	v_lshlrev_b32_e32 v7, 4, v96
	ds_write_b128 v5, v[8:11]
	v_add3_u32 v8, 0, v6, v7
	ds_write_b128 v8, v[12:15]
	ds_write_b128 v69, v[16:19] offset:34816
	ds_write_b128 v2, v[24:27] offset:34816
	ds_write_b128 v5, v[40:43] offset:34816
	ds_write_b128 v8, v[44:47] offset:34816
	v_mul_lo_u32 v2, v70, s0
	v_lshlrev_b32_e32 v5, 1, v74
	v_add3_u32 v2, s1, v2, v5
	ds_write_b16 v2, v78
	ds_write_b16_d16_hi v2, v78 offset:272
	ds_write_b16 v2, v79 offset:544
	ds_write_b16_d16_hi v2, v79 offset:816
	ds_write_b16 v2, v80 offset:1088
	ds_write_b16_d16_hi v2, v80 offset:1360
	ds_write_b16 v2, v81 offset:1632
	ds_write_b16_d16_hi v2, v81 offset:1904
	v_mul_lo_u32 v2, v68, s0
	v_add3_u32 v2, s1, v2, v5
	ds_write_b16 v2, v82
	ds_write_b16_d16_hi v2, v82 offset:272
	ds_write_b16 v2, v83 offset:544
	ds_write_b16_d16_hi v2, v83 offset:816
	ds_write_b16 v2, v84 offset:1088
	ds_write_b16_d16_hi v2, v84 offset:1360
	ds_write_b16 v2, v85 offset:1632
	ds_write_b16_d16_hi v2, v85 offset:1904
	v_mul_lo_u32 v2, v66, s0
	v_add3_u32 v2, s1, v2, v5
	ds_write_b16 v2, v86
	ds_write_b16_d16_hi v2, v86 offset:272
	ds_write_b16 v2, v87 offset:544
	ds_write_b16_d16_hi v2, v87 offset:816
	ds_write_b16 v2, v88 offset:1088
	ds_write_b16_d16_hi v2, v88 offset:1360
	ds_write_b16 v2, v89 offset:1632
	ds_write_b16_d16_hi v2, v89 offset:1904
	v_mul_lo_u32 v2, v64, s0
	v_readlane_b32 s0, v253, 23
	v_add3_u32 v2, s1, v2, v5
	ds_write_b16 v2, v90
	ds_write_b16_d16_hi v2, v90 offset:272
	ds_write_b16 v2, v91 offset:544
	ds_write_b16_d16_hi v2, v91 offset:816
	ds_write_b16 v2, v92 offset:1088
	ds_write_b16_d16_hi v2, v92 offset:1360
	ds_write_b16 v2, v93 offset:1632
	ds_write_b16_d16_hi v2, v93 offset:1904
	v_add_u32_e32 v0, s0, v0
	v_add_u32_e32 v116, v0, v1
	v_add_u32_e32 v0, s0, v3
	v_add_u32_e32 v2, s0, v65
	v_add_u32_e32 v117, v0, v4
	v_add_u32_e32 v0, s0, v6
	v_add_u32_e32 v115, v2, v67
	v_add_u32_e32 v118, v0, v7
	ds_write_b128 v115, v[20:23]
	ds_write_b128 v116, v[28:31]
	ds_write_b128 v117, v[32:35]
	ds_write_b128 v118, v[36:39]
	s_and_saveexec_b64 s[12:13], vcc
	s_cbranch_execz .LBB0_227
; __device__ __forceinline__ void mlstm_out(const Bufs& B, const float* __restrict__ g_out, int item, LAS unsigned char* lds) {
;     ...
;         const int dir = wid; const float mst = dir ? mst1 : mst0;
;         const int l0 = 2 * lane, l1 = l0 + 1, p0 = dir ? 127 - l0 : l0, p1 = dir ? 127 - l1 : l1, gi = 8 * dir + h, gf = gi + 4;
;         const float li0 = B.G[(size_t)(s0 + p0) * 16 + gi], lf0 = B.G[(size_t)(s0 + p0) * 16 + gf], li1 = B.G[(size_t)(s0 + p1) * 16 + gi], lf1 = B.G[(size_t)(s0 + p1) * 16 + gf];
;         const float t = lf0 + lf1, incl = scan_add64(t, lane), b0 = incl - t + lf0, b1 = incl;
;         const float a0 = li0 - b0, a1 = li1 - b1, inm = scan_max64(fmaxf(a0, a1), lane);
;         float exm = __shfl_up(inm, 1); if (lane == 0) exm = -3.0e38f;
;         const float A0 = fmaxf(exm, a0), A1 = inm, amax = __shfl(inm, 63), cc = fmaxf(amax, mst);
;         const float M0 = fmaxf(A0, mst), M1 = fmaxf(A1, mst);
;         vea[dir * 128 + p0] = __expf(a0 - cc); vea[dir * 128 + p1] = __expf(a1 - cc);
;         veM[dir * 128 + p0] = __expf(cc - M0) * SC; veM[dir * 128 + p1] = __expf(cc - M1) * SC;
;         vedn[dir * 128 + p0] = __expf(-(b0 + M0)); vedn[dir * 128 + p1] = __expf(-(b1 + M1));
;         if (lane == 0) vsc[dir] = __expf(mst - cc);
;     }
;     if (tid < 256) { const int dir = tid >> 7, d = tid & 127; vn[tid] = B.NST[(size_t)((dir * 4 + h) * 64 + c) * 128 + d]; }
	v_and_b32_e32 v1, 63, v72
	v_lshlrev_b32_e32 v2, 1, v1
	v_cmp_gt_u32_e32 vcc, 64, v72
	v_xor_b32_e32 v4, 0x7f, v2
	v_readlane_b32 s0, v254, 52
	v_cndmask_b32_e32 v6, v4, v2, vcc
	s_mov_b32 s4, s0
	v_or_b32_e32 v3, 1, v2
	v_xor_b32_e32 v2, 0x7e, v2
	v_readlane_b32 s1, v254, 53
	v_or_b32_e32 v4, s4, v6
	v_cndmask_b32_e32 v7, v2, v3, vcc
	v_lshl_or_b32 v2, v73, 3, s14
	v_ashrrev_i32_e32 v5, 31, v4
	v_readlane_b32 s0, v254, 31
	v_ashrrev_i32_e32 v3, 31, v2
	v_lshlrev_b64 v[4:5], 6, v[4:5]
	v_readlane_b32 s1, v254, 32
	v_lshlrev_b64 v[2:3], 2, v[2:3]
	v_cndmask_b32_e32 v0, v76, v75, vcc
	v_lshl_add_u64 v[4:5], s[0:1], 0, v[4:5]
	v_lshl_add_u64 v[4:5], v[4:5], 0, v[2:3]
	global_load_dword v8, v[4:5], off
	global_load_dword v9, v[4:5], off offset:16
	v_or_b32_e32 v4, s4, v7
	v_ashrrev_i32_e32 v5, 31, v4
	v_lshlrev_b64 v[4:5], 6, v[4:5]
	v_lshl_add_u64 v[4:5], s[0:1], 0, v[4:5]
	v_lshl_add_u64 v[2:3], v[4:5], 0, v[2:3]
	global_load_dword v4, v[2:3], off
	s_nop 0
	global_load_dword v2, v[2:3], off offset:16
	v_and_b32_e32 v3, 64, v238
	v_add_u32_e32 v5, -1, v238
	v_cmp_lt_i32_e32 vcc, v5, v3
	v_add_u32_e32 v11, -2, v238
	v_cmp_lt_i32_e64 s[0:1], v11, v3
	v_cndmask_b32_e32 v5, v5, v238, vcc
	v_lshlrev_b32_e32 v5, 2, v5
	v_cmp_eq_u32_e32 vcc, 0, v1
	v_cndmask_b32_e64 v11, v11, v238, s[0:1]
	v_lshlrev_b32_e32 v11, 2, v11
	v_cmp_gt_u32_e64 s[0:1], 2, v1
	v_cmp_gt_u32_e64 s[8:9], 4, v1
	s_waitcnt vmcnt(0) lgkmcnt(0)
	v_add_f32_e32 v2, v9, v2
	ds_bpermute_b32 v10, v5, v2
	s_waitcnt lgkmcnt(0)
	v_add_f32_e32 v10, v2, v10
	v_cndmask_b32_e32 v10, v10, v2, vcc
	ds_bpermute_b32 v12, v11, v10
	s_waitcnt lgkmcnt(0)
	v_add_f32_e32 v12, v10, v12
	v_cndmask_b32_e64 v10, v12, v10, s[0:1]
	v_add_u32_e32 v12, -4, v238
	v_cmp_lt_i32_e64 s[4:5], v12, v3
	s_nop 1
	v_cndmask_b32_e64 v12, v12, v238, s[4:5]
	v_lshlrev_b32_e32 v12, 2, v12
	ds_bpermute_b32 v13, v12, v10
	s_waitcnt lgkmcnt(0)
	v_add_f32_e32 v13, v10, v13
	v_cndmask_b32_e64 v10, v13, v10, s[8:9]
	v_add_u32_e32 v13, -8, v238
	v_cmp_lt_i32_e64 s[4:5], v13, v3
	s_nop 1
	v_cndmask_b32_e64 v13, v13, v238, s[4:5]
	v_lshlrev_b32_e32 v13, 2, v13
	ds_bpermute_b32 v14, v13, v10
	v_cmp_gt_u32_e64 s[4:5], 8, v1
	s_waitcnt lgkmcnt(0)
	v_add_f32_e32 v14, v10, v14
	v_cndmask_b32_e64 v10, v14, v10, s[4:5]
	v_add_u32_e32 v14, -16, v238
	v_cmp_lt_i32_e64 s[6:7], v14, v3
	s_nop 1
	v_cndmask_b32_e64 v14, v14, v238, s[6:7]
	v_lshlrev_b32_e32 v14, 2, v14
	ds_bpermute_b32 v15, v14, v10
	v_cmp_gt_u32_e64 s[6:7], 16, v1
	s_waitcnt lgkmcnt(0)
	v_add_f32_e32 v15, v10, v15
	v_cndmask_b32_e64 v10, v15, v10, s[6:7]
	v_subrev_u32_e32 v15, 32, v238
	v_cmp_lt_i32_e64 s[10:11], v15, v3
	s_nop 1
	v_cndmask_b32_e64 v3, v15, v238, s[10:11]
	v_lshlrev_b32_e32 v3, 2, v3
	ds_bpermute_b32 v15, v3, v10
	v_cmp_gt_u32_e64 s[10:11], 32, v1
	s_waitcnt lgkmcnt(0)
	v_add_f32_e32 v1, v10, v15
	v_cndmask_b32_e64 v10, v1, v10, s[10:11]
	v_sub_f32_e32 v1, v10, v2
	v_add_f32_e32 v2, v9, v1
	v_sub_f32_e32 v8, v8, v2
	v_sub_f32_e32 v4, v4, v10
	v_max_f32_e32 v1, v8, v4
	ds_bpermute_b32 v9, v5, v1
	s_waitcnt lgkmcnt(0)
	v_max_f32_e32 v9, v9, v9
	v_max_f32_e32 v9, v1, v9
	v_cndmask_b32_e32 v1, v9, v1, vcc
	ds_bpermute_b32 v9, v11, v1
	s_waitcnt lgkmcnt(0)
	v_max_f32_e32 v9, v9, v9
	v_max_f32_e32 v9, v1, v9
	v_cndmask_b32_e64 v1, v9, v1, s[0:1]
	ds_bpermute_b32 v9, v12, v1
	v_readlane_b32 s0, v253, 24
	s_waitcnt lgkmcnt(0)
	v_max_f32_e32 v9, v9, v9
	v_max_f32_e32 v9, v1, v9
	v_cndmask_b32_e64 v1, v9, v1, s[8:9]
	ds_bpermute_b32 v9, v13, v1
	s_waitcnt lgkmcnt(0)
	v_max_f32_e32 v9, v9, v9
	v_max_f32_e32 v9, v1, v9
	v_cndmask_b32_e64 v1, v9, v1, s[4:5]
	ds_bpermute_b32 v9, v14, v1
	s_waitcnt lgkmcnt(0)
	v_max_f32_e32 v9, v9, v9
	v_max_f32_e32 v9, v1, v9
	v_cndmask_b32_e64 v1, v9, v1, s[6:7]
	ds_bpermute_b32 v3, v3, v1
	v_max_f32_e32 v9, v1, v1
	s_waitcnt lgkmcnt(0)
	v_max_f32_e32 v3, v3, v3
	v_max_f32_e32 v3, v9, v3
	v_cndmask_b32_e64 v3, v3, v1, s[10:11]
	ds_bpermute_b32 v1, v5, v3
	v_mov_b32_e32 v5, 0xff61b1e6
	v_max_f32_e32 v9, v0, v0
	s_waitcnt lgkmcnt(0)
	v_cndmask_b32_e32 v5, v1, v5, vcc
	v_lshl_or_b32 v1, v238, 2, v233
	ds_bpermute_b32 v1, v1, v3
	v_max3_f32 v5, v5, v8, v0
	v_max_f32_e32 v3, v3, v3
	v_max_f32_e32 v3, v3, v9
	v_add_f32_e32 v2, v2, v5
	s_waitcnt lgkmcnt(0)
	v_max_f32_e32 v1, v1, v1
	v_max_f32_e32 v1, v1, v9
	v_sub_f32_e32 v8, v8, v1
	v_mul_f32_e32 v8, 0x3fb8aa3b, v8
	v_sub_f32_e32 v4, v4, v1
	v_exp_f32_e32 v8, v8
	v_lshlrev_b32_e32 v9, 7, v73
	v_mul_f32_e32 v4, 0x3fb8aa3b, v4
	v_or_b32_e32 v6, v6, v9
	v_exp_f32_e32 v4, v4
	v_lshlrev_b32_e32 v6, 2, v6
	v_or_b32_e32 v7, v7, v9
	v_add_u32_e32 v11, s0, v6
	v_lshlrev_b32_e32 v7, 2, v7
	ds_write_b32 v11, v8
	v_add_u32_e32 v8, s0, v7
	ds_write_b32 v8, v4
	v_sub_f32_e32 v4, v1, v5
	v_mul_f32_e32 v4, 0x3fb8aa3b, v4
	v_exp_f32_e32 v4, v4
	v_readlane_b32 s0, v253, 25
	v_mul_f32_e32 v2, 0xbfb8aa3b, v2
	v_exp_f32_e32 v2, v2
	v_mul_f32_e32 v4, 0x3db504f3, v4
	v_add_u32_e32 v8, s0, v6
	ds_write_b32 v8, v4
	v_sub_f32_e32 v4, v1, v3
	v_mul_f32_e32 v4, 0x3fb8aa3b, v4
	v_exp_f32_e32 v4, v4
	v_add_u32_e32 v8, s0, v7
	v_readlane_b32 s0, v253, 26
	v_mul_f32_e32 v4, 0x3db504f3, v4
	ds_write_b32 v8, v4
	v_add_u32_e32 v4, s0, v6
	ds_write_b32 v4, v2
	v_add_f32_e32 v2, v10, v3
	v_mul_f32_e32 v2, 0xbfb8aa3b, v2
	v_exp_f32_e32 v2, v2
	v_add_u32_e32 v3, s0, v7
	ds_write_b32 v3, v2
	s_and_b64 exec, exec, vcc
	s_cbranch_execz .LBB0_227
	v_sub_f32_e32 v0, v0, v1
	v_mul_f32_e32 v0, 0x3fb8aa3b, v0
	v_exp_f32_e32 v0, v0
	v_lshl_add_u32 v1, v73, 2, 0
	v_add_u32_e32 v1, 0x23800, v1
	ds_write_b32 v1, v0
.LBB0_227:
	s_or_b64 exec, exec, s[12:13]
	s_movk_i32 s0, 0x100
	v_cmp_gt_i32_e32 vcc, s0, v72
	s_and_saveexec_b64 s[0:1], vcc
	s_cbranch_execz .LBB0_229
	v_lshrrev_b32_e32 v0, 5, v72
	v_and_b32_e32 v0, 0x3fffffc, v0
	v_or_b32_e32 v0, s14, v0
	v_lshl_add_u32 v0, v0, 6, s15
	v_ashrrev_i32_e32 v1, 31, v0
	v_readlane_b32 s4, v254, 33
	v_lshlrev_b64 v[0:1], 9, v[0:1]
	v_readlane_b32 s5, v254, 34
	v_lshlrev_b32_e32 v194, 2, v74
	s_nop 0
	v_lshl_add_u64 v[0:1], s[4:5], 0, v[0:1]
	v_lshl_add_u64 v[0:1], v[0:1], 0, v[194:195]
	global_load_dword v0, v[0:1], off
	v_lshl_add_u32 v1, v72, 2, 0
	v_add_u32_e32 v1, 0x22c00, v1
	s_waitcnt vmcnt(0) lgkmcnt(0)
	ds_write_b32 v1, v0

; #define LAS __attribute__((address_space(3)))
; __device__ __forceinline__ void mlstm_out(const Bufs& B, const float* __restrict__ g_out, int item, LAS unsigned char* lds) {
;     ...
;     __syncthreads();
;     f32x4 hacc[4][2]; zero_acc<2>(hacc);
;     u32x4 rc1[4]; ld_N<128, 128>(rc1, B.CST + (size_t)((1 * 4 + h) * 64 + c) * 16384, 128, tid);
; #pragma unroll 1
;     for (int dir = 0; dir < 2; ++dir) {
;         if (dir == 1) st_N<128, 128>(T3, 136, rc1, tid);
;         const float r = vsc[dir];
; #pragma unroll
;         for (int m = 0; m < 4; ++m)
; #pragma unroll
;             for (int n = 0; n < 2; ++n) { const int l = 32 * wc + 16 * n + fr, sb = 64 * wr + 16 * m + 4 * fq;
;                 const f32x4 e4 = *(const LAS f32x4*)(vea + dir * 128 + sb); float v[4];
; #pragma unroll
;                 for (int j = 0; j < 4; ++j) { const int s = sb + j; const bool ok = dir ? (s >= l) : (s <= l); v[j] = ok ? accS[m][n][j] * e4[j] : 0.f; }
.LBB0_233:
	s_or_b64 exec, exec, s[0:1]
	s_lshl_b64 s[0:1], s[2:3], 15
	v_readlane_b32 s2, v254, 19
	v_readlane_b32 s3, v254, 20
	s_add_u32 s0, s2, s0
	s_addc_u32 s1, s3, s1
	s_add_u32 s0, s0, 0x800000
	s_addc_u32 s1, s1, 0
	v_lshl_add_u64 v[32:33], v[32:33], 1, s[0:1]
	v_lshl_add_u64 v[36:37], v[36:37], 1, s[0:1]
	v_lshl_add_u64 v[40:41], v[40:41], 1, s[0:1]
	v_lshl_add_u64 v[44:45], v[44:45], 1, s[0:1]
	v_lshl_add_u64 v[32:33], v[48:49], 1, v[32:33]
	v_lshl_add_u64 v[36:37], v[50:51], 1, v[36:37]
	v_lshl_add_u64 v[40:41], v[52:53], 1, v[40:41]
	v_lshl_add_u64 v[44:45], v[54:55], 1, v[44:45]
	s_waitcnt lgkmcnt(0)
	s_barrier
	global_load_dwordx4 v[32:35], v[32:33], off
	v_and_b32_e32 v61, 0xffffffc0, v119
	global_load_dwordx4 v[36:39], v[36:37], off
	v_lshrrev_b32_e32 v48, 2, v72
	global_load_dwordx4 v[40:43], v[40:41], off
	v_and_or_b32 v125, v48, 12, v61
	global_load_dwordx4 v[44:47], v[44:45], off
	v_readlane_b32 s0, v253, 28
	v_and_b32_e32 v49, 0xffffff00, v72
	v_or_b32_e32 v50, 1, v125
	v_lshl_add_u32 v126, v119, 2, s0
	v_add_u32_e32 v49, s0, v49
	v_cmp_ge_i32_e64 s[0:1], v125, v58
	v_or_b32_e32 v51, 2, v125
	v_or_b32_e32 v52, 3, v125
	v_writelane_b32 v254, s0, 57
	v_or_b32_e32 v53, 16, v58
	v_or_b32_e32 v54, 19, v125
	v_writelane_b32 v254, s1, 58
	v_cmp_le_i32_e64 s[0:1], v125, v58
	v_readlane_b32 s2, v253, 24
	v_cmp_ge_i32_e64 s[52:53], v54, v58
	v_writelane_b32 v254, s0, 59
	v_cmp_le_i32_e64 s[54:55], v54, v58
	v_cmp_ge_i32_e64 s[64:65], v54, v53
	v_writelane_b32 v254, s1, 60
	v_cmp_ge_i32_e64 s[0:1], v50, v58
	v_cmp_le_i32_e64 s[66:67], v54, v53
	v_or_b32_e32 v54, 34, v125
	v_writelane_b32 v254, s0, 61
	v_or_b32_e32 v55, 35, v125
	v_lshl_add_u32 v128, v125, 2, s2
	v_writelane_b32 v254, s1, 62
	v_cmp_lt_i32_e64 s[0:1], v125, v58
	v_readlane_b32 s2, v253, 29
	v_lshlrev_b32_e32 v48, 6, v60
	v_writelane_b32 v254, s0, 63
	v_lshl_add_u32 v127, v125, 1, 0
	v_cmp_ge_i32_e64 s[76:77], v54, v58
	v_writelane_b32 v255, s1, 0
	v_cmp_ge_i32_e64 s[0:1], v51, v58
	v_cmp_le_i32_e64 s[78:79], v54, v58
	v_cmp_ge_i32_e64 s[80:81], v55, v58
	v_writelane_b32 v255, s0, 1
	v_cmp_le_i32_e64 s[82:83], v55, v58
	v_cmp_ge_i32_e64 s[92:93], v54, v53
	v_writelane_b32 v255, s1, 2
	v_cmp_le_i32_e64 s[0:1], v51, v58
	v_cmp_le_i32_e64 s[94:95], v54, v53
	v_cmp_ge_i32_e64 s[96:97], v55, v53
	v_writelane_b32 v255, s0, 3
	v_cmp_le_i32_e64 s[36:37], v55, v53
	v_or_b32_e32 v54, 50, v125
	v_writelane_b32 v255, s1, 4
	v_cmp_ge_i32_e64 s[0:1], v52, v58
	v_or_b32_e32 v55, 51, v125
	v_mov_b32_e32 v80, 0
	v_writelane_b32 v255, s0, 5
	v_lshlrev_b32_e32 v124, 5, v60
	v_cmp_ge_i32_e64 s[10:11], v54, v58
	v_writelane_b32 v255, s1, 6
	v_cmp_le_i32_e64 s[0:1], v52, v58
	v_cmp_le_i32_e64 s[12:13], v54, v58
	v_cmp_ge_i32_e64 s[14:15], v55, v58
	v_writelane_b32 v255, s0, 7
	v_cmp_le_i32_e64 s[16:17], v55, v58
	v_cmp_ge_i32_e64 s[26:27], v54, v53
	v_writelane_b32 v255, s1, 8
	v_cmp_ge_i32_e64 s[0:1], v125, v53
	v_cmp_le_i32_e64 s[28:29], v54, v53
	v_cmp_ge_i32_e64 s[30:31], v55, v53
	v_writelane_b32 v255, s0, 9
	v_cmp_le_i32_e64 s[34:35], v55, v53
	v_add_u32_e32 v130, 0, v57
	v_writelane_b32 v255, s1, 10
	v_cmp_le_i32_e64 s[0:1], v125, v53
	s_mov_b32 s33, 0
	s_mov_b64 s[38:39], 0
	v_writelane_b32 v255, s0, 11
	v_add_u32_e32 v133, v59, v48
	v_add_u32_e32 v134, v49, v56
	v_writelane_b32 v255, s1, 12
	v_cmp_ge_i32_e64 s[0:1], v50, v53
	v_mul_u32_u24_e32 v50, 0x110, v53
	v_add_u32_e32 v132, v127, v50
	v_writelane_b32 v255, s0, 13
	v_mov_b32_e32 v81, v80
	v_mov_b32_e32 v82, v80
	v_writelane_b32 v255, s1, 14
	v_cmp_lt_i32_e64 s[0:1], v125, v53
	v_mov_b32_e32 v83, v80
	v_mov_b32_e32 v86, v80
	v_writelane_b32 v255, s0, 15
	v_mov_b32_e32 v87, v80
	v_mov_b32_e32 v84, v80
	v_writelane_b32 v255, s1, 16
	v_cmp_ge_i32_e64 s[0:1], v51, v53
	v_mov_b32_e32 v85, v80
	v_mov_b32_e32 v106, v80
	v_writelane_b32 v255, s0, 17
	v_mov_b32_e32 v107, v80
	v_mov_b32_e32 v102, v80
	v_writelane_b32 v255, s1, 18
	v_cmp_le_i32_e64 s[0:1], v51, v53
	v_or_b32_e32 v51, 16, v125
	v_cmp_ge_i32_e64 s[40:41], v51, v58
	v_writelane_b32 v255, s0, 19
	v_cmp_le_i32_e64 s[42:43], v51, v58
	v_or_b32_e32 v51, 17, v125
	v_writelane_b32 v255, s1, 20
	v_cmp_ge_i32_e64 s[0:1], v52, v53
	v_cmp_ge_i32_e64 s[44:45], v51, v58
	v_cmp_le_i32_e64 s[46:47], v51, v58
	v_writelane_b32 v255, s0, 21
	v_cmp_ge_i32_e64 s[56:57], v51, v53
	v_cmp_le_i32_e64 s[58:59], v51, v53
	v_writelane_b32 v255, s1, 22
	v_cmp_le_i32_e64 s[0:1], v52, v53
	v_or_b32_e32 v51, 32, v125
	v_or_b32_e32 v52, 18, v125
	v_writelane_b32 v255, s0, 23
	v_cmp_ge_i32_e64 s[68:69], v51, v58
	v_cmp_le_i32_e64 s[70:71], v51, v58
	v_cmp_ge_i32_e64 s[84:85], v51, v53
	v_cmp_le_i32_e64 s[86:87], v51, v53
	v_or_b32_e32 v51, 48, v125
	v_writelane_b32 v255, s1, 24
	v_cmp_ge_i32_e64 s[48:49], v52, v58
	v_cmp_le_i32_e64 s[50:51], v52, v58
	v_cmp_ge_i32_e64 s[60:61], v52, v53
	v_cmp_le_i32_e64 s[62:63], v52, v53
	v_or_b32_e32 v52, 33, v125
	v_cmp_ge_i32_e64 s[0:1], v51, v58
	v_cmp_le_i32_e64 s[4:5], v51, v58
	v_cmp_ge_i32_e64 s[18:19], v51, v53
	v_cmp_le_i32_e64 s[20:21], v51, v53
	v_add_u32_e32 v51, v122, v56
	v_cmp_ge_i32_e64 s[72:73], v52, v58
	v_cmp_le_i32_e64 s[74:75], v52, v58
	v_cmp_ge_i32_e64 s[88:89], v52, v53
	v_cmp_le_i32_e64 s[90:91], v52, v53
	v_or_b32_e32 v52, 49, v125
	v_add_u32_e32 v129, s2, v51
	v_readlane_b32 s2, v253, 30
	v_cmp_ge_i32_e64 s[6:7], v52, v58
	v_cmp_le_i32_e64 s[8:9], v52, v58
	v_cmp_ge_i32_e64 s[22:23], v52, v53
	v_cmp_le_i32_e64 s[24:25], v52, v53
	v_add_u32_e32 v131, s2, v51
	s_mov_b64 s[2:3], -1
	v_mov_b32_e32 v103, v80
	v_mov_b32_e32 v110, v80
	v_mov_b32_e32 v111, v80
	v_mov_b32_e32 v108, v80
	v_mov_b32_e32 v109, v80
	v_mov_b32_e32 v92, v80
	v_mov_b32_e32 v93, v80
	v_mov_b32_e32 v88, v80
	v_mov_b32_e32 v89, v80
	v_mov_b32_e32 v100, v80
	v_mov_b32_e32 v101, v80
	v_mov_b32_e32 v96, v80
	v_mov_b32_e32 v97, v80
	v_mov_b32_e32 v94, v80
	v_mov_b32_e32 v95, v80
	v_mov_b32_e32 v90, v80
	v_mov_b32_e32 v91, v80
	v_mov_b32_e32 v104, v80
	v_mov_b32_e32 v105, v80
	v_mov_b32_e32 v98, v80
	v_mov_b32_e32 v99, v80

; #define LAS __attribute__((address_space(3)))
; __device__ __forceinline__ void mlstm_out(const Bufs& B, const float* __restrict__ g_out, int item, LAS unsigned char* lds) {
;     ...
;         mma_tile<128, 2>(accN, T0, 136, T3, 136, wr, wc, fr, fq);
; #pragma unroll
;         for (int m = 0; m < 4; ++m)
; #pragma unroll
;             for (int n = 0; n < 2; ++n) accN[m][n] *= r;
;         mma_tile<128, 2>(accN, T1, 136, T2, 136, wr, wc, fr, fq);
;         __syncthreads();
; #pragma unroll
;         for (int m = 0; m < 4; ++m) { const f32x4 f4 = *(const LAS f32x4*)(vf + 64 * wr + 16 * m + 4 * fq);
; #pragma unroll
;             for (int n = 0; n < 2; ++n) hacc[m][n] += accN[m][n] * f4; }
;         __syncthreads();
;     }
;     const int erow = tid >> 2, eqd = tid & 3, es = s0 + erow;
;     u32x4 og4[4]; f32x4 gp4[8];
;     { const bf16_t* og = B.PROJ + (size_t)es * NPROJP + PC_MLO + h * 128 + eqd * 32; const float* gp = g_out + h * 128 + eqd * 32;
; #pragma unroll
;         for (int i = 0; i < 4; ++i) og4[i] = *(const u32x4*)(og + i * 8);
; #pragma unroll
;         for (int i = 0; i < 8; ++i) gp4[i] = *(const f32x4*)(gp + i * 4); }
; #pragma unroll
;     for (int m = 0; m < 4; ++m)
; #pragma unroll
;         for (int n = 0; n < 2; ++n)
; #pragma unroll
;             for (int j = 0; j < 4; ++j) HT[(64 * wr + 16 * m + 4 * fq + j) * 132 + 32 * wc + 16 * n + fr] = hacc[m][n][j];
;     __syncthreads();
.LBB0_241:
	ds_read_b128 v[136:139], v135
	v_add_u32_e32 v140, 0xffffef00, v112
	ds_read_b128 v[140:143], v140
	ds_read_b128 v[144:147], v112
	s_add_i32 s2, s2, 32
	s_cmpk_lt_u32 s2, 0x60
	v_add_u32_e32 v112, 64, v112
	s_waitcnt lgkmcnt(0)
	v_mfma_f32_16x16x32_bf16 v[76:79], v[136:139], v[140:143], v[76:79]
	v_mfma_f32_16x16x32_bf16 v[72:75], v[136:139], v[144:147], v[72:75]
	ds_read_b128 v[136:139], v135 offset:4352
	s_waitcnt lgkmcnt(0)
	v_mfma_f32_16x16x32_bf16 v[68:71], v[136:139], v[140:143], v[68:71]
	v_mfma_f32_16x16x32_bf16 v[64:67], v[136:139], v[144:147], v[64:67]
	ds_read_b128 v[136:139], v135 offset:8704
	s_waitcnt lgkmcnt(0)
	v_mfma_f32_16x16x32_bf16 v[60:63], v[136:139], v[140:143], v[60:63]
	v_mfma_f32_16x16x32_bf16 v[56:59], v[136:139], v[144:147], v[56:59]
	ds_read_b128 v[136:139], v135 offset:13056
	v_add_u32_e32 v135, 64, v135
	s_waitcnt lgkmcnt(0)
	v_mfma_f32_16x16x32_bf16 v[52:55], v[136:139], v[140:143], v[52:55]
	v_mfma_f32_16x16x32_bf16 v[48:51], v[136:139], v[144:147], v[48:51]
	s_cbranch_scc1 .LBB0_241
	s_barrier
	ds_read_b128 v[136:139], v134
	ds_read_b128 v[140:143], v134 offset:64
	s_mov_b32 s33, 1
	s_mov_b64 s[2:3], 0
	s_andn2_b64 vcc, exec, s[38:39]
	s_waitcnt lgkmcnt(0)
	v_pk_fma_f32 v[106:107], v[72:73], v[136:137], v[106:107]
	v_pk_fma_f32 v[84:85], v[70:71], v[142:143], v[84:85]
	ds_read_b128 v[70:73], v134 offset:128
	v_pk_fma_f32 v[82:83], v[66:67], v[142:143], v[82:83]
	v_pk_fma_f32 v[80:81], v[64:65], v[140:141], v[80:81]
	ds_read_b128 v[64:67], v134 offset:192
	v_pk_fma_f32 v[108:109], v[78:79], v[138:139], v[108:109]
	v_pk_fma_f32 v[110:111], v[76:77], v[136:137], v[110:111]
	v_pk_fma_f32 v[102:103], v[74:75], v[138:139], v[102:103]
	v_pk_fma_f32 v[86:87], v[68:69], v[140:141], v[86:87]
	s_waitcnt lgkmcnt(0)
	v_pk_fma_f32 v[88:89], v[62:63], v[72:73], v[88:89]
	v_pk_fma_f32 v[92:93], v[60:61], v[70:71], v[92:93]
	v_pk_fma_f32 v[96:97], v[58:59], v[72:73], v[96:97]
	v_pk_fma_f32 v[100:101], v[56:57], v[70:71], v[100:101]
	v_pk_fma_f32 v[90:91], v[54:55], v[66:67], v[90:91]
	v_pk_fma_f32 v[94:95], v[52:53], v[64:65], v[94:95]
	v_pk_fma_f32 v[98:99], v[50:51], v[66:67], v[98:99]
	v_pk_fma_f32 v[104:105], v[48:49], v[64:65], v[104:105]
	s_mov_b64 s[38:39], -1
	s_barrier
	s_cbranch_vccnz .LBB0_234
	v_readlane_b32 s16, v254, 23
	v_readlane_b32 s0, v254, 52
	v_readlane_b32 s17, v254, 24
	v_readlane_b32 s1, v254, 53
	v_add_u32_e32 v60, s0, v119
	v_mov_b64_e32 v[0:1], s[16:17]
	s_movk_i32 s5, 0x2400
	v_mad_i64_i32 v[0:1], s[0:1], v60, s5, v[0:1]
	v_readlane_b32 s4, v254, 54
	v_readlane_b32 s2, v253, 36
	s_lshl_b32 s0, s4, 1
	s_mov_b32 s1, s2
	v_lshl_add_u64 v[0:1], v[0:1], 0, s[0:1]
	v_lshlrev_b32_e32 v194, 1, v124
	v_lshl_add_u64 v[0:1], v[0:1], 0, v[194:195]
	global_load_dwordx4 v[62:65], v[0:1], off offset:3072
	global_load_dwordx4 v[52:55], v[0:1], off offset:3088
	global_load_dwordx4 v[28:31], v[0:1], off offset:3104
	global_load_dwordx4 v[8:11], v[0:1], off offset:3120
	v_readlane_b32 s3, v253, 37
	s_lshl_b32 s2, s4, 2
	v_readlane_b32 s3, v254, 44
	s_add_u32 s2, s3, s2
	v_readlane_b32 s3, v254, 48
	s_addc_u32 s3, s3, 0
	v_lshlrev_b32_e32 v12, 2, v124
	s_nop 2
	global_load_dwordx4 v[36:39], v12, s[2:3] offset:48
	global_load_dwordx4 v[44:47], v12, s[2:3] offset:32
	global_load_dwordx4 v[66:69], v12, s[2:3] offset:16
	global_load_dwordx4 v[70:73], v12, s[2:3]
	global_load_dwordx4 v[0:3], v12, s[2:3] offset:112
	global_load_dwordx4 v[4:7], v12, s[2:3] offset:96
	global_load_dwordx4 v[16:19], v12, s[2:3] offset:80
	global_load_dwordx4 v[20:23], v12, s[2:3] offset:64
	s_movk_i32 s2, 0x210
	v_lshl_add_u32 v13, v120, 7, 0
	v_lshlrev_b32_e32 v14, 2, v121
	v_mul_lo_u32 v15, v125, s2
	v_add3_u32 v13, v13, v14, v15
	v_add_u32_e32 v14, 0x8800, v13
	ds_write2_b32 v14, v110, v106 offset1:16
	ds_write2_b32 v14, v111, v107 offset0:132 offset1:148
	v_add_u32_e32 v14, 0x8c00, v13
	ds_write2_b32 v14, v108, v102 offset0:8 offset1:24
	ds_write2_b32 v14, v109, v103 offset0:140 offset1:156
	v_add_u32_e32 v14, 0xa800, v13
	ds_write2_b32 v14, v86, v80 offset0:64 offset1:80
	ds_write2_b32 v14, v87, v81 offset0:196 offset1:212
	v_add_u32_e32 v14, 0xac00, v13
	ds_write2_b32 v14, v84, v82 offset0:72 offset1:88
	ds_write2_b32 v14, v85, v83 offset0:204 offset1:220
	v_add_u32_e32 v14, 0xc800, v13
	ds_write2_b32 v14, v92, v100 offset0:128 offset1:144
	v_add_u32_e32 v14, 0xcc00, v13
	ds_write2_b32 v14, v93, v101 offset0:4 offset1:20
	ds_write2_b32 v14, v88, v96 offset0:136 offset1:152
	v_add_u32_e32 v14, 0xd000, v13
	ds_write2_b32 v14, v89, v97 offset0:12 offset1:28
	v_add_u32_e32 v14, 0xe800, v13
	ds_write2_b32 v14, v94, v104 offset0:192 offset1:208
	v_add_u32_e32 v14, 0xec00, v13
	v_add_u32_e32 v13, 0xf000, v13
	ds_write2_b32 v14, v95, v105 offset0:68 offset1:84
	ds_write2_b32 v14, v90, v98 offset0:200 offset1:216
	ds_write2_b32 v13, v91, v99 offset0:76 offset1:92
	v_mul_lo_u32 v13, v119, s2
	v_add3_u32 v61, 0, v13, v12
	s_waitcnt lgkmcnt(0)
	s_barrier
; #define LAS __attribute__((address_space(3)))
; __device__ __forceinline__ void unpack8(u32x4 w, float* f) { f[0] = bflo(w.x); f[1] = bfhi(w.x); f[2] = bflo(w.y); f[3] = bfhi(w.y); f[4] = bflo(w.z); f[5] = bfhi(w.z); f[6] = bflo(w.w); f[7] = bfhi(w.w); }
; __device__ __forceinline__ u32x4 pack8(const float* f) { u32x4 w; w.x = cvt_pk_bf16(f[0], f[1]); w.y = cvt_pk_bf16(f[2], f[3]); w.z = cvt_pk_bf16(f[4], f[5]); w.w = cvt_pk_bf16(f[6], f[7]); return w; }
; __device__ __forceinline__ void mlstm_out(const Bufs& B, const float* __restrict__ g_out, int item, LAS unsigned char* lds) {
;     ...
;     { float ssq = 0.f; f32x4 x4[8];
; #pragma unroll
;         for (int i = 0; i < 8; ++i) { x4[i] = *(const LAS f32x4*)(HT + erow * 132 + eqd * 32 + i * 4);
;             ssq += x4[i][0] * x4[i][0] + x4[i][1] * x4[i][1] + x4[i][2] * x4[i][2] + x4[i][3] * x4[i][3]; }
;         ssq += __shfl_xor(ssq, 1); ssq += __shfl_xor(ssq, 2);
;         const float rstd = rsqrtf(ssq * (1.f / 128.f) + EPS_);
;         bf16_t* yo = B.Y + (size_t)es * DM + h * 128 + eqd * 32;
; #pragma unroll
;         for (int i = 0; i < 4; ++i) { float o8[8]; unpack8(og4[i], o8); float r8[8];
; #pragma unroll
;             for (int k = 0; k < 8; ++k) { const float sg = __builtin_amdgcn_rcpf(1.f + __expf(-o8[k])); r8[k] = sg * x4[2 * i + (k >> 2)][k & 3] * rstd * gp4[2 * i + (k >> 2)][k & 3]; }
;             *(u32x4*)(yo + i * 8) = pack8(r8); } }
	ds_read_b128 v[74:77], v61 offset:34816
	ds_read_b128 v[78:81], v61 offset:34832
	ds_read_b128 v[56:59], v61 offset:34848
	ds_read_b128 v[48:51], v61 offset:34864
	s_waitcnt vmcnt(0)
	ds_read_b128 v[40:43], v61 offset:34880
	ds_read_b128 v[32:35], v61 offset:34896
	s_waitcnt lgkmcnt(5)
	v_mov_b32_e32 v14, v75
	s_waitcnt lgkmcnt(4)
	v_mov_b32_e32 v15, v79
	v_mov_b32_e32 v12, v74
	v_mov_b32_e32 v13, v78
	v_pk_mul_f32 v[14:15], v[14:15], v[14:15]
	s_waitcnt lgkmcnt(1)
	v_mov_b32_e32 v88, v43
	v_pk_fma_f32 v[12:13], v[12:13], v[12:13], v[14:15]
	v_mov_b32_e32 v14, v76
	v_mov_b32_e32 v15, v80
	v_pk_fma_f32 v[12:13], v[14:15], v[14:15], v[12:13]
	v_mov_b32_e32 v14, v77
	v_mov_b32_e32 v15, v81
	v_pk_fma_f32 v[82:83], v[14:15], v[14:15], v[12:13]
	v_mov_b32_e32 v14, v57
	v_mov_b32_e32 v15, v49
	v_mov_b32_e32 v12, v56
	v_mov_b32_e32 v13, v48
	v_pk_mul_f32 v[14:15], v[14:15], v[14:15]
	s_waitcnt lgkmcnt(0)
	v_mov_b32_e32 v89, v35
	v_pk_fma_f32 v[12:13], v[12:13], v[12:13], v[14:15]
	v_mov_b32_e32 v14, v58
	v_mov_b32_e32 v15, v50
	v_pk_fma_f32 v[12:13], v[14:15], v[14:15], v[12:13]
	v_mov_b32_e32 v14, v59
	v_mov_b32_e32 v15, v51
	v_pk_fma_f32 v[84:85], v[14:15], v[14:15], v[12:13]
	v_mov_b32_e32 v14, v41
	v_mov_b32_e32 v15, v33
	v_mov_b32_e32 v12, v40
	v_mov_b32_e32 v13, v32
	v_pk_mul_f32 v[14:15], v[14:15], v[14:15]
	s_mov_b32 s2, 0x800000
	v_pk_fma_f32 v[12:13], v[12:13], v[12:13], v[14:15]
	v_mov_b32_e32 v14, v42
	v_mov_b32_e32 v15, v34
	v_pk_fma_f32 v[86:87], v[14:15], v[14:15], v[12:13]
	ds_read_b128 v[24:27], v61 offset:34912
	ds_read_b128 v[12:15], v61 offset:34928
	v_add_f32_e32 v61, v82, v83
	v_pk_fma_f32 v[86:87], v[88:89], v[88:89], v[86:87]
	v_add_f32_e32 v61, v61, v84
	s_waitcnt lgkmcnt(1)
	v_mov_b32_e32 v90, v25
	s_waitcnt lgkmcnt(0)
	v_mov_b32_e32 v91, v13
	v_mov_b32_e32 v88, v24
	v_mov_b32_e32 v89, v12
	v_pk_mul_f32 v[90:91], v[90:91], v[90:91]
	v_add_f32_e32 v61, v61, v85
	v_pk_fma_f32 v[88:89], v[88:89], v[88:89], v[90:91]
	v_mov_b32_e32 v90, v26
	v_mov_b32_e32 v91, v14
	v_pk_fma_f32 v[88:89], v[90:91], v[90:91], v[88:89]
	v_mov_b32_e32 v90, v27
	v_mov_b32_e32 v91, v15
	v_add_f32_e32 v61, v61, v86
	v_pk_fma_f32 v[88:89], v[90:91], v[90:91], v[88:89]
	v_add_f32_e32 v61, v61, v87
	v_add_f32_e32 v61, v61, v88
	v_add_f32_e32 v61, v61, v89
	ds_bpermute_b32 v82, v113, v61
	v_lshlrev_b32_e32 v84, 16, v63
	v_lshlrev_b32_e32 v85, 16, v64
	v_and_b32_e32 v64, 0xffff0000, v64
	v_and_b32_e32 v63, 0xffff0000, v63
	s_waitcnt lgkmcnt(0)
	v_add_f32_e32 v61, v61, v82
	ds_bpermute_b32 v82, v114, v61
	v_lshlrev_b32_e32 v86, 16, v65
	v_and_b32_e32 v65, 0xffff0000, v65
	v_mul_f32_e32 v64, 0xbfb8aa3b, v64
	v_mul_f32_e32 v63, 0xbfb8aa3b, v63
	s_waitcnt lgkmcnt(0)
	v_add_f32_e32 v61, v61, v82
	v_fmamk_f32 v61, v61, 0x3c000000, v242
	v_mul_f32_e32 v82, 0x4b800000, v61
	v_cmp_gt_f32_e32 vcc, s2, v61
	v_exp_f32_e32 v64, v64
	v_mul_f32_e32 v65, 0xbfb8aa3b, v65
	v_cndmask_b32_e32 v61, v61, v82, vcc
	v_rsq_f32_e32 v82, v61
	v_exp_f32_e32 v63, v63
	v_exp_f32_e32 v65, v65
	v_add_f32_e32 v64, 1.0, v64
	v_mul_f32_e32 v83, 0x45800000, v82
	v_cndmask_b32_e32 v82, v82, v83, vcc
	v_lshlrev_b32_e32 v83, 16, v62
	v_mul_f32_e32 v83, 0xbfb8aa3b, v83
	v_exp_f32_e32 v83, v83
	v_and_b32_e32 v62, 0xffff0000, v62
	v_mul_f32_e32 v62, 0xbfb8aa3b, v62
	v_exp_f32_e32 v62, v62
	v_add_f32_e32 v83, 1.0, v83
	v_rcp_f32_e32 v83, v83
	v_add_f32_e32 v63, 1.0, v63
	v_add_f32_e32 v62, 1.0, v62
	v_rcp_f32_e32 v62, v62
	v_mul_f32_e32 v74, v83, v74
	v_mul_f32_e32 v74, v74, v82
	v_mul_f32_e32 v70, v70, v74
	v_mul_f32_e32 v74, 0xbfb8aa3b, v84
	v_exp_f32_e32 v74, v74
	v_mul_f32_e32 v62, v62, v75
	v_mul_f32_e32 v62, v62, v82
	v_mul_f32_e32 v62, v71, v62
	v_add_f32_e32 v74, 1.0, v74
	v_rcp_f32_e32 v74, v74
	v_rcp_f32_e32 v64, v64
	v_add_f32_e32 v65, 1.0, v65
	v_rcp_f32_e32 v63, v63
	v_mul_f32_e32 v71, v74, v76
	v_mul_f32_e32 v71, v71, v82
	v_mul_f32_e32 v71, v72, v71
	v_mul_f32_e32 v72, 0xbfb8aa3b, v85
	v_exp_f32_e32 v72, v72
	v_rcp_f32_e32 v65, v65
	v_ashrrev_i32_e32 v61, 31, v60
	v_readlane_b32 s2, v254, 42
	v_add_f32_e32 v72, 1.0, v72
	v_rcp_f32_e32 v72, v72
	v_lshlrev_b64 v[60:61], 12, v[60:61]
	v_readlane_b32 s3, v254, 43
	v_mul_f32_e32 v64, v64, v79
	v_mul_f32_e32 v72, v72, v78
	v_mul_f32_e32 v72, v72, v82
	v_mul_f32_e32 v66, v66, v72
	v_mul_f32_e32 v72, 0xbfb8aa3b, v86
	v_exp_f32_e32 v72, v72
	v_lshl_add_u64 v[60:61], s[2:3], 0, v[60:61]
	v_mul_f32_e32 v63, v63, v77
	v_mul_f32_e32 v64, v64, v82
	v_add_f32_e32 v72, 1.0, v72
	v_rcp_f32_e32 v72, v72
	v_mul_f32_e32 v65, v65, v81
	v_lshl_add_u64 v[60:61], v[60:61], 0, s[0:1]
	v_mul_f32_e32 v63, v63, v82
	v_mul_f32_e32 v64, v67, v64
	v_mul_f32_e32 v67, v72, v80
	v_mul_f32_e32 v65, v65, v82
	v_lshl_add_u64 v[60:61], v[60:61], 0, v[194:195]
	v_mul_f32_e32 v63, v73, v63
	v_mul_f32_e32 v67, v67, v82
	v_mul_f32_e32 v65, v69, v65
	v_cvt_pk_bf16_f32 v62, v70, v62
	v_mul_f32_e32 v67, v68, v67
	v_cvt_pk_bf16_f32 v63, v71, v63
	v_cvt_pk_bf16_f32 v64, v66, v64
	v_cvt_pk_bf16_f32 v65, v67, v65
	global_store_dwordx4 v[60:61], v[62:65], off
	v_readlane_b32 s0, v252, 9
	v_readlane_b32 s1, v252, 10
	v_lshlrev_b32_e32 v62, 16, v52
	v_mul_f32_e32 v62, 0xbfb8aa3b, v62
	v_exp_f32_e32 v62, v62
	v_and_b32_e32 v52, 0xffff0000, v52
	v_mul_f32_e32 v52, 0xbfb8aa3b, v52
	v_lshlrev_b32_e32 v63, 16, v53
	v_add_f32_e32 v62, 1.0, v62
	v_rcp_f32_e32 v62, v62
	v_exp_f32_e32 v52, v52
	v_and_b32_e32 v53, 0xffff0000, v53
	v_mul_f32_e32 v53, 0xbfb8aa3b, v53
	v_mul_f32_e32 v56, v62, v56
	v_mul_f32_e32 v56, v56, v82
	v_mul_f32_e32 v44, v44, v56
	v_mul_f32_e32 v56, 0xbfb8aa3b, v63
	v_exp_f32_e32 v56, v56
	v_add_f32_e32 v52, 1.0, v52
	v_rcp_f32_e32 v52, v52
	v_exp_f32_e32 v53, v53
; __device__ __forceinline__ void unpack8(u32x4 w, float* f) { f[0] = bflo(w.x); f[1] = bfhi(w.x); f[2] = bflo(w.y); f[3] = bfhi(w.y); f[4] = bflo(w.z); f[5] = bfhi(w.z); f[6] = bflo(w.w); f[7] = bfhi(w.w); }
; __device__ __forceinline__ u32x4 pack8(const float* f) { u32x4 w; w.x = cvt_pk_bf16(f[0], f[1]); w.y = cvt_pk_bf16(f[2], f[3]); w.z = cvt_pk_bf16(f[4], f[5]); w.w = cvt_pk_bf16(f[6], f[7]); return w; }
; __device__ __forceinline__ void mlstm_out(const Bufs& B, const float* __restrict__ g_out, int item, LAS unsigned char* lds) {
;     ...
; #pragma unroll
;         for (int i = 0; i < 4; ++i) { float o8[8]; unpack8(og4[i], o8); float r8[8];
; #pragma unroll
;             for (int k = 0; k < 8; ++k) { const float sg = __builtin_amdgcn_rcpf(1.f + __expf(-o8[k])); r8[k] = sg * x4[2 * i + (k >> 2)][k & 3] * rstd * gp4[2 * i + (k >> 2)][k & 3]; }
;             *(u32x4*)(yo + i * 8) = pack8(r8); } }
;     __syncthreads();
; __global__ void __launch_bounds__(512) mega_fwd(Params p) {
;     ...
;             for (int it = bx; it < 256; it += G) mlstm_out(B, p.g_ml_out + l * 512, it, lds);
	v_add_f32_e32 v56, 1.0, v56
	v_rcp_f32_e32 v56, v56
	v_mul_f32_e32 v52, v52, v57
	v_mul_f32_e32 v52, v52, v82
	v_mul_f32_e32 v45, v45, v52
	v_add_f32_e32 v52, 1.0, v53
	v_mul_f32_e32 v53, v56, v58
	v_lshlrev_b32_e32 v64, 16, v54
	v_mul_f32_e32 v53, v53, v82
	v_mul_f32_e32 v46, v46, v53
	v_mul_f32_e32 v53, 0xbfb8aa3b, v64
	v_and_b32_e32 v54, 0xffff0000, v54
	v_rcp_f32_e32 v52, v52
	v_exp_f32_e32 v53, v53
	v_mul_f32_e32 v54, 0xbfb8aa3b, v54
	v_exp_f32_e32 v54, v54
	v_mul_f32_e32 v52, v52, v59
	v_add_f32_e32 v53, 1.0, v53
	v_mul_f32_e32 v52, v52, v82
	v_rcp_f32_e32 v53, v53
	v_mul_f32_e32 v47, v47, v52
	v_add_f32_e32 v52, 1.0, v54
	v_rcp_f32_e32 v52, v52
	v_mul_f32_e32 v48, v53, v48
	v_lshlrev_b32_e32 v65, 16, v55
	v_and_b32_e32 v55, 0xffff0000, v55
	v_mul_f32_e32 v48, v48, v82
	v_mul_f32_e32 v48, v36, v48
	v_mul_f32_e32 v36, v52, v49
	v_mul_f32_e32 v52, 0xbfb8aa3b, v55
	v_mul_f32_e32 v49, 0xbfb8aa3b, v65
	v_exp_f32_e32 v52, v52
	v_exp_f32_e32 v49, v49
	v_mul_f32_e32 v36, v36, v82
	v_mul_f32_e32 v53, v37, v36
	v_add_f32_e32 v36, 1.0, v52
	v_add_f32_e32 v49, 1.0, v49
	v_rcp_f32_e32 v36, v36
	v_rcp_f32_e32 v49, v49
	v_readlane_b32 s1, v254, 50
	s_add_i32 s0, s1, s0
	v_mul_f32_e32 v36, v36, v51
	v_mul_f32_e32 v37, v49, v50
	v_mul_f32_e32 v36, v36, v82
	v_mul_f32_e32 v37, v37, v82
	v_mul_f32_e32 v39, v39, v36
	v_cvt_pk_bf16_f32 v36, v44, v45
	v_mul_f32_e32 v49, v38, v37
	v_cvt_pk_bf16_f32 v37, v46, v47
	v_cvt_pk_bf16_f32 v38, v48, v53
	v_cvt_pk_bf16_f32 v39, v49, v39
	global_store_dwordx4 v[60:61], v[36:39], off offset:16
	s_cmpk_gt_i32 s0, 0xff
	s_nop 0
	v_lshlrev_b32_e32 v36, 16, v28
	v_mul_f32_e32 v36, 0xbfb8aa3b, v36
	v_exp_f32_e32 v36, v36
	v_and_b32_e32 v28, 0xffff0000, v28
	v_mul_f32_e32 v28, 0xbfb8aa3b, v28
	v_lshlrev_b32_e32 v37, 16, v29
	v_add_f32_e32 v36, 1.0, v36
	v_rcp_f32_e32 v36, v36
	v_exp_f32_e32 v28, v28
	v_and_b32_e32 v29, 0xffff0000, v29
	v_mul_f32_e32 v29, 0xbfb8aa3b, v29
	v_mul_f32_e32 v36, v36, v40
	v_mul_f32_e32 v36, v36, v82
	v_mul_f32_e32 v20, v20, v36
	v_mul_f32_e32 v36, 0xbfb8aa3b, v37
	v_exp_f32_e32 v36, v36
	v_add_f32_e32 v28, 1.0, v28
	v_rcp_f32_e32 v28, v28
	v_exp_f32_e32 v29, v29
	v_add_f32_e32 v36, 1.0, v36
	v_rcp_f32_e32 v36, v36
	v_mul_f32_e32 v28, v28, v41
	v_mul_f32_e32 v28, v28, v82
	v_mul_f32_e32 v21, v21, v28
	v_add_f32_e32 v28, 1.0, v29
	v_mul_f32_e32 v29, v36, v42
	v_lshlrev_b32_e32 v38, 16, v30
	v_mul_f32_e32 v29, v29, v82
	v_mul_f32_e32 v22, v22, v29
	v_mul_f32_e32 v29, 0xbfb8aa3b, v38
	v_and_b32_e32 v30, 0xffff0000, v30
	v_rcp_f32_e32 v28, v28
	v_exp_f32_e32 v29, v29
	v_mul_f32_e32 v30, 0xbfb8aa3b, v30
	v_exp_f32_e32 v30, v30
	v_mul_f32_e32 v28, v28, v43
	v_add_f32_e32 v29, 1.0, v29
	v_mul_f32_e32 v28, v28, v82
	v_rcp_f32_e32 v29, v29
	v_mul_f32_e32 v23, v23, v28
	v_add_f32_e32 v28, 1.0, v30
	v_rcp_f32_e32 v28, v28
	v_lshlrev_b32_e32 v39, 16, v31
	v_and_b32_e32 v31, 0xffff0000, v31
	v_mul_f32_e32 v29, v29, v32
	v_mul_f32_e32 v29, v29, v82
	v_mul_f32_e32 v30, 0xbfb8aa3b, v31
	v_mul_f32_e32 v29, v16, v29
	v_mul_f32_e32 v16, v28, v33
	v_mul_f32_e32 v28, 0xbfb8aa3b, v39
	v_exp_f32_e32 v30, v30
	v_exp_f32_e32 v28, v28
	v_mul_f32_e32 v16, v16, v82
	v_mul_f32_e32 v31, v17, v16
	v_add_f32_e32 v16, 1.0, v30
	v_add_f32_e32 v28, 1.0, v28
	v_rcp_f32_e32 v16, v16
	v_rcp_f32_e32 v28, v28
	v_mul_f32_e32 v16, v16, v35
	v_mul_f32_e32 v17, v28, v34
	v_mul_f32_e32 v16, v16, v82
	v_mul_f32_e32 v17, v17, v82
	v_mul_f32_e32 v19, v19, v16
	v_cvt_pk_bf16_f32 v16, v20, v21
	v_mul_f32_e32 v28, v18, v17
	v_cvt_pk_bf16_f32 v17, v22, v23
	v_cvt_pk_bf16_f32 v18, v29, v31
	v_cvt_pk_bf16_f32 v19, v28, v19
	global_store_dwordx4 v[60:61], v[16:19], off offset:32
	s_nop 1
	v_lshlrev_b32_e32 v16, 16, v8
	v_mul_f32_e32 v16, 0xbfb8aa3b, v16
	v_exp_f32_e32 v16, v16
	v_and_b32_e32 v8, 0xffff0000, v8
	v_mul_f32_e32 v8, 0xbfb8aa3b, v8
	v_lshlrev_b32_e32 v17, 16, v9
	v_add_f32_e32 v16, 1.0, v16
	v_rcp_f32_e32 v16, v16
	v_exp_f32_e32 v8, v8
	v_and_b32_e32 v9, 0xffff0000, v9
	v_mul_f32_e32 v9, 0xbfb8aa3b, v9
	v_mul_f32_e32 v16, v16, v24
	v_mul_f32_e32 v16, v16, v82
	v_mul_f32_e32 v4, v4, v16
	v_mul_f32_e32 v16, 0xbfb8aa3b, v17
	v_exp_f32_e32 v16, v16
	v_add_f32_e32 v8, 1.0, v8
	v_rcp_f32_e32 v8, v8
	v_exp_f32_e32 v9, v9
	v_add_f32_e32 v16, 1.0, v16
	v_rcp_f32_e32 v16, v16
	v_mul_f32_e32 v8, v8, v25
	v_mul_f32_e32 v8, v8, v82
	v_mul_f32_e32 v5, v5, v8
	v_add_f32_e32 v8, 1.0, v9
	v_mul_f32_e32 v9, v16, v26
	v_lshlrev_b32_e32 v18, 16, v10
	v_mul_f32_e32 v9, v9, v82
	v_mul_f32_e32 v6, v6, v9
	v_mul_f32_e32 v9, 0xbfb8aa3b, v18
	v_and_b32_e32 v10, 0xffff0000, v10
	v_rcp_f32_e32 v8, v8
	v_exp_f32_e32 v9, v9
	v_mul_f32_e32 v10, 0xbfb8aa3b, v10
	v_exp_f32_e32 v10, v10
	v_mul_f32_e32 v8, v8, v27
	v_add_f32_e32 v9, 1.0, v9
	v_mul_f32_e32 v8, v8, v82
	v_rcp_f32_e32 v9, v9
	v_mul_f32_e32 v7, v7, v8
	v_add_f32_e32 v8, 1.0, v10
	v_rcp_f32_e32 v8, v8
	v_lshlrev_b32_e32 v19, 16, v11
	v_and_b32_e32 v11, 0xffff0000, v11
	v_mul_f32_e32 v9, v9, v12
	v_mul_f32_e32 v9, v9, v82
	v_mul_f32_e32 v10, 0xbfb8aa3b, v11
	v_mul_f32_e32 v9, v0, v9
	v_mul_f32_e32 v0, v8, v13
	v_mul_f32_e32 v8, 0xbfb8aa3b, v19
	v_exp_f32_e32 v10, v10
	v_exp_f32_e32 v8, v8
	v_mul_f32_e32 v0, v0, v82
	v_mul_f32_e32 v11, v1, v0
	v_add_f32_e32 v0, 1.0, v10
	v_add_f32_e32 v8, 1.0, v8
	v_rcp_f32_e32 v0, v0
	v_rcp_f32_e32 v8, v8
	v_mul_f32_e32 v0, v0, v15
	v_mul_f32_e32 v1, v8, v14
	v_mul_f32_e32 v0, v0, v82
	v_mul_f32_e32 v1, v1, v82
	v_mul_f32_e32 v3, v3, v0
	v_mul_f32_e32 v8, v2, v1
	v_cvt_pk_bf16_f32 v0, v4, v5
	v_cvt_pk_bf16_f32 v1, v6, v7
	v_cvt_pk_bf16_f32 v2, v9, v11
	v_cvt_pk_bf16_f32 v3, v8, v3
	global_store_dwordx4 v[60:61], v[0:3], off offset:48
	s_waitcnt lgkmcnt(0)
	s_barrier
	s_cbranch_scc0 .LBB0_224
	v_readlane_b32 s0, v253, 2
	v_readlane_b32 s1, v253, 3
	v_readlane_b32 s14, v253, 16
	v_readlane_b32 s0, v254, 46
	v_readlane_b32 s15, v253, 17
	v_readlane_b32 s1, v254, 47
	s_add_u32 s0, s14, s0
	v_writelane_b32 v254, s0, 49
	s_addc_u32 s0, s15, s1
	v_writelane_b32 v254, s0, 46
	v_readlane_b32 s2, v253, 4
	v_readlane_b32 s0, v254, 4
	v_readlane_b32 s3, v253, 5
	v_readlane_b32 s4, v253, 6
	v_readlane_b32 s5, v253, 7
	v_readlane_b32 s6, v253, 8
	v_readlane_b32 s7, v253, 9
	v_readlane_b32 s8, v253, 10
	v_readlane_b32 s9, v253, 11
	v_readlane_b32 s10, v253, 12
	v_readlane_b32 s11, v253, 13
	v_readlane_b32 s12, v253, 14
	v_readlane_b32 s13, v253, 15
	v_readlane_b32 s1, v254, 5
; __device__ __forceinline__ void ret_out(const Bufs& B, const float* __restrict__ g_out, int item, LAS unsigned char* lds) {
;     ...
;     u32x4 rr1[2];
;     { u32x4 rq[2], rk[2], rv[4], rr0[2];
;         ld_N<128, 64>(rq, B.RQK + (size_t)s0 * 512 + h * 64, 512, tid);
;         ld_N<128, 64>(rk, B.RQK + (size_t)s0 * 512 + 256 + h * 64, 512, tid);
;         ld_T<128>(rv, B.PROJ + (size_t)s0 * NPROJP + PC_RV + h * 128, NPROJP, tid);
;         ld_N<128, 64>(rr0, B.RST + (size_t)((0 * 4 + h) * 64 + c) * 8192, 64, tid);
;         ld_N<128, 64>(rr1, B.RST + (size_t)((1 * 4 + h) * 64 + c) * 8192, 64, tid);
;         st_N<128, 64>(QB, 72, rq, tid); st_N<128, 64>(KB, 72, rk, tid); st_T<128, false>(VT, 136, rv, HT, tid); st_N<128, 64>(RT, 72, rr0, tid); }
;     if (tid < 256) { const int dir = tid >> 7, p = tid & 127, lp = dir ? 127 - p : p, hd = dir ? 3 - h : h; const float lg = log1pf(-exp2f(-5.f - (float)hd));
.LBB0_245:
	v_mov_b32_e32 v106, v192
	s_ashr_i32 s2, s0, 2
	v_add_u32_e32 v24, 0x200, v106
	s_lshl_b32 s6, s2, 7
	v_ashrrev_i32_e32 v0, 31, v106
	v_ashrrev_i32_e32 v4, 31, v24
	v_writelane_b32 v254, s0, 54
	s_ashr_i32 s7, s6, 31
	v_lshrrev_b32_e32 v0, 29, v0
	v_lshrrev_b32_e32 v4, 29, v4
	s_and_b32 s8, s0, 3
	s_lshl_b64 s[0:1], s[6:7], 10
	v_readlane_b32 s4, v254, 17
	v_add_u32_e32 v0, v106, v0
	v_add_u32_e32 v4, v24, v4
	v_readlane_b32 s5, v254, 18
	s_add_u32 s0, s4, s0
	v_ashrrev_i32_e32 v46, 3, v0
	v_and_b32_e32 v0, -8, v0
	v_ashrrev_i32_e32 v32, 3, v4
	v_and_b32_e32 v4, -8, v4
	s_addc_u32 s1, s5, s1
	s_lshl_b32 s3, s8, 6
	s_lshl_b32 s4, s8, 7
	v_sub_u32_e32 v45, v106, v0
	v_sub_u32_e32 v62, v24, v4
	s_add_u32 s0, s0, s4
	v_lshlrev_b32_e32 v0, 3, v45
	v_ashrrev_i32_e32 v47, 31, v46
	v_lshlrev_b32_e32 v4, 3, v62
	v_ashrrev_i32_e32 v33, 31, v32
	s_addc_u32 s1, s1, 0
	v_lshlrev_b64 v[2:3], 10, v[46:47]
	v_ashrrev_i32_e32 v1, 31, v0
	v_lshlrev_b64 v[6:7], 10, v[32:33]
	v_ashrrev_i32_e32 v5, 31, v4
	v_writelane_b32 v254, s4, 48
	v_lshl_add_u64 v[2:3], s[0:1], 0, v[2:3]
	v_lshlrev_b64 v[0:1], 1, v[0:1]
	v_lshl_add_u64 v[6:7], s[0:1], 0, v[6:7]
	v_lshlrev_b64 v[4:5], 1, v[4:5]
	s_mul_i32 s0, s2, 0x120000
	s_mov_b32 s4, s6
	v_lshl_add_u64 v[2:3], v[2:3], 0, v[0:1]
	v_lshl_add_u64 v[6:7], v[6:7], 0, v[4:5]
	v_writelane_b32 v254, s4, 44
	s_mul_hi_i32 s1, s6, 0x2400
	s_add_u32 s0, s16, s0
	global_load_dwordx4 v[8:11], v[2:3], off
	global_load_dwordx4 v[12:15], v[6:7], off
	global_load_dwordx4 v[16:19], v[2:3], off offset:512
	global_load_dwordx4 v[20:23], v[6:7], off offset:512
	v_writelane_b32 v254, s5, 45
	s_addc_u32 s1, s17, s1
	s_lshl_b32 s4, s8, 8
	v_and_b32_e32 v44, 0x7f, v106
	v_ashrrev_i32_e32 v6, 4, v106
	s_add_u32 s0, s0, s4
	v_mul_u32_u24_e32 v2, 0x1200, v44
	v_and_b32_e32 v40, -8, v6
	v_ashrrev_i32_e32 v6, 4, v24
	s_addc_u32 s1, s1, 0
	v_lshlrev_b32_e32 v194, 1, v2
	v_and_b32_e32 v38, -8, v6
	v_add_u32_e32 v6, 0x400, v106
	v_lshl_add_u64 v[2:3], s[0:1], 0, v[194:195]
	s_mov_b64 s[0:1], 0x1420
	v_ashrrev_i32_e32 v6, 4, v6
	v_lshl_add_u64 v[2:3], v[2:3], 0, s[0:1]
	v_and_b32_e32 v36, -8, v6
	v_add_u32_e32 v6, 0x600, v106
	s_add_i32 s0, s3, s2
	v_ashrrev_i32_e32 v6, 4, v6
	s_ashr_i32 s1, s0, 31
	v_and_b32_e32 v34, -8, v6
	s_lshl_b64 s[0:1], s[0:1], 14
	v_readlane_b32 s2, v254, 21
	v_ashrrev_i32_e32 v41, 31, v40
	v_ashrrev_i32_e32 v39, 31, v38
	v_ashrrev_i32_e32 v37, 31, v36
	v_ashrrev_i32_e32 v35, 31, v34
	v_readlane_b32 s3, v254, 22
	s_add_u32 s0, s2, s0
	v_lshl_add_u64 v[48:49], v[40:41], 1, v[2:3]
	v_lshl_add_u64 v[50:51], v[38:39], 1, v[2:3]
	v_lshl_add_u64 v[54:55], v[36:37], 1, v[2:3]
	v_lshl_add_u64 v[42:43], v[34:35], 1, v[2:3]
	s_addc_u32 s1, s3, s1
	v_lshlrev_b64 v[2:3], 7, v[46:47]
	v_lshl_add_u64 v[6:7], s[0:1], 0, v[2:3]
	v_lshl_add_u64 v[6:7], v[6:7], 0, v[0:1]
	global_load_dwordx4 v[24:27], v[6:7], off
	v_lshlrev_b64 v[6:7], 7, v[32:33]
	v_lshl_add_u64 v[28:29], s[0:1], 0, v[6:7]
	s_add_u32 s0, s0, 0x400000
	s_addc_u32 s1, s1, 0
	v_lshl_add_u64 v[2:3], s[0:1], 0, v[2:3]
	v_lshl_add_u64 v[6:7], s[0:1], 0, v[6:7]
	v_lshl_add_u64 v[28:29], v[28:29], 0, v[4:5]
	v_lshl_add_u64 v[0:1], v[2:3], 0, v[0:1]
	v_lshl_add_u64 v[4:5], v[6:7], 0, v[4:5]
	s_movk_i32 s0, 0x90
	global_load_dwordx4 v[28:31], v[28:29], off
	v_mul_lo_u32 v33, v46, s0
	global_load_dwordx4 v[0:3], v[0:1], off
	v_lshlrev_b32_e32 v35, 4, v45
	global_load_dwordx4 v[4:7], v[4:5], off
	s_nop 0
	global_load_dwordx4 v[46:49], v[48:49], off
	s_nop 0
	global_load_dwordx4 v[50:53], v[50:51], off
	s_nop 0
	global_load_dwordx4 v[54:57], v[54:55], off
	s_nop 0
	global_load_dwordx4 v[58:61], v[42:43], off
	v_add3_u32 v37, 0, v33, v35
	v_readlane_b32 s1, v253, 31
	s_add_i32 s2, 0, 0x1a000
	s_mov_b32 s37, s8
	s_movk_i32 s30, 0x110
	s_waitcnt vmcnt(0) lgkmcnt(0)
	ds_write_b128 v37, v[8:11]
	v_mul_lo_u32 v8, v32, s0
	v_lshlrev_b32_e32 v9, 4, v62
	v_add3_u32 v10, 0, v8, v9
	s_movk_i32 s0, 0x110
	ds_write_b128 v10, v[12:15]
	ds_write_b128 v37, v[16:19] offset:18432
	ds_write_b128 v10, v[20:23] offset:18432
	v_mul_lo_u32 v10, v40, s0
	v_lshlrev_b32_e32 v11, 1, v44
	v_add3_u32 v10, s1, v10, v11
	ds_write_b16 v10, v46
	ds_write_b16_d16_hi v10, v46 offset:272
	ds_write_b16 v10, v47 offset:544
	ds_write_b16_d16_hi v10, v47 offset:816
	ds_write_b16 v10, v48 offset:1088
	ds_write_b16_d16_hi v10, v48 offset:1360
	ds_write_b16 v10, v49 offset:1632
	ds_write_b16_d16_hi v10, v49 offset:1904
	v_mul_lo_u32 v10, v38, s0
	v_add3_u32 v10, s1, v10, v11
	ds_write_b16 v10, v50
	ds_write_b16_d16_hi v10, v50 offset:272
	ds_write_b16 v10, v51 offset:544
	ds_write_b16_d16_hi v10, v51 offset:816
	ds_write_b16 v10, v52 offset:1088
	ds_write_b16_d16_hi v10, v52 offset:1360
	ds_write_b16 v10, v53 offset:1632
	ds_write_b16_d16_hi v10, v53 offset:1904
	v_mul_lo_u32 v10, v36, s0
	v_add3_u32 v10, s1, v10, v11
	ds_write_b16 v10, v54
	ds_write_b16_d16_hi v10, v54 offset:272
	ds_write_b16 v10, v55 offset:544
	ds_write_b16_d16_hi v10, v55 offset:816
	ds_write_b16 v10, v56 offset:1088
	ds_write_b16_d16_hi v10, v56 offset:1360
	ds_write_b16 v10, v57 offset:1632
	ds_write_b16_d16_hi v10, v57 offset:1904
	v_mul_lo_u32 v10, v34, s0
	v_add3_u32 v10, s1, v10, v11
	ds_write_b16 v10, v58
	ds_write_b16_d16_hi v10, v58 offset:272
	ds_write_b16 v10, v59 offset:544
	ds_write_b16_d16_hi v10, v59 offset:816
	ds_write_b16 v10, v60 offset:1088
	ds_write_b16_d16_hi v10, v60 offset:1360
	ds_write_b16 v10, v61 offset:1632
	ds_write_b16_d16_hi v10, v61 offset:1904
	v_add_u32_e32 v10, s2, v33
	v_add_u32_e32 v8, s2, v8
	s_movk_i32 s0, 0x100
	v_add_u32_e32 v107, v10, v35
	v_add_u32_e32 v108, v8, v9
	v_cmp_gt_i32_e32 vcc, s0, v106
	ds_write_b128 v107, v[24:27]
	ds_write_b128 v108, v[28:31]
	s_and_saveexec_b64 s[0:1], vcc
	s_cbranch_execz .LBB0_247
; __device__ __forceinline__ void ret_out(const Bufs& B, const float* __restrict__ g_out, int item, LAS unsigned char* lds) {
;     ...
;     if (tid < 256) { const int dir = tid >> 7, p = tid & 127, lp = dir ? 127 - p : p, hd = dir ? 3 - h : h; const float lg = log1pf(-exp2f(-5.f - (float)hd));
;         vcs[tid] = __expf(-(float)lp * lg); vrw[tid] = __expf((float)lp * lg); }
	s_movk_i32 s3, 0x80
	v_xor_b32_e32 v8, 0x7f, v44
	v_cmp_gt_u32_e32 vcc, s3, v106
	s_xor_b32 s3, s37, 3
	v_mov_b32_e32 v9, s37
	v_cndmask_b32_e32 v10, v8, v44, vcc
	v_mov_b32_e32 v8, s3
	v_cndmask_b32_e32 v8, v8, v9, vcc
	v_cvt_f32_ubyte0_e32 v8, v8
	v_sub_f32_e32 v8, 0xc0a00000, v8
	s_mov_b32 s3, 0xc2fc0000
	v_cmp_gt_f32_e32 vcc, s3, v8
	s_mov_b32 s3, 0x3f2aaaab
	s_nop 0
	v_cndmask_b32_e32 v9, 0, v240, vcc
	v_add_f32_e32 v8, v8, v9
	v_exp_f32_e32 v8, v8
	v_cndmask_b32_e32 v9, 0, v239, vcc
	v_ldexp_f32 v11, v8, v9
	v_sub_f32_e32 v12, 1.0, v11
	v_add_f32_e32 v8, -1.0, v12
	v_sub_f32_e32 v9, v8, v12
	v_add_f32_e32 v9, 1.0, v9
	v_sub_f32_e64 v8, -v11, v8
	v_add_f32_e32 v13, v8, v9
	v_frexp_mant_f32_e32 v14, v12
	v_cvt_f64_f32_e32 v[8:9], v12
	v_frexp_exp_i32_f64_e32 v8, v[8:9]
	v_cmp_gt_f32_e32 vcc, s3, v14
	s_mov_b32 s3, 0x3f317218
	s_nop 0
	v_subbrev_co_u32_e32 v8, vcc, 0, v8, vcc
	v_sub_u32_e32 v9, 0, v8
	v_ldexp_f32 v12, v12, v9
	v_ldexp_f32 v9, v13, v9
	v_add_f32_e32 v13, -1.0, v12
	v_add_f32_e32 v16, 1.0, v12
	v_add_f32_e32 v14, 1.0, v13
	v_add_f32_e32 v17, -1.0, v16
	v_sub_f32_e32 v14, v12, v14
	v_sub_f32_e32 v12, v12, v17
	v_add_f32_e32 v14, v9, v14
	v_add_f32_e32 v9, v9, v12
	v_add_f32_e32 v12, v16, v9
	v_rcp_f32_e32 v17, v12
	v_add_f32_e32 v15, v13, v14
	v_sub_f32_e32 v13, v15, v13
	v_sub_f32_e32 v13, v14, v13
	v_sub_f32_e32 v14, v12, v16
	v_sub_f32_e32 v9, v9, v14
	v_mul_f32_e32 v14, v15, v17
	v_mul_f32_e32 v16, v12, v14
	v_fma_f32 v18, v14, v12, -v16
	v_fmac_f32_e32 v18, v14, v9
	v_add_f32_e32 v19, v16, v18
	v_sub_f32_e32 v20, v15, v19
	v_sub_f32_e32 v15, v15, v20
	v_sub_f32_e32 v16, v19, v16
	v_sub_f32_e32 v15, v15, v19
	v_add_f32_e32 v13, v13, v15
	v_sub_f32_e32 v15, v16, v18
	v_add_f32_e32 v13, v15, v13
	v_add_f32_e32 v15, v20, v13
	v_mul_f32_e32 v16, v17, v15
	v_mul_f32_e32 v18, v12, v16
	v_fma_f32 v12, v16, v12, -v18
	v_fmac_f32_e32 v12, v16, v9
	v_sub_f32_e32 v9, v20, v15
	v_add_f32_e32 v9, v13, v9
	v_add_f32_e32 v13, v18, v12
	v_sub_f32_e32 v19, v15, v13
	v_sub_f32_e32 v15, v15, v19
	v_sub_f32_e32 v18, v13, v18
	v_sub_f32_e32 v13, v15, v13
	v_add_f32_e32 v9, v9, v13
	v_sub_f32_e32 v12, v18, v12
	v_cvt_f32_i32_e32 v8, v8
	v_add_f32_e32 v9, v12, v9
	v_add_f32_e32 v12, v14, v16
	v_add_f32_e32 v9, v19, v9
	v_sub_f32_e32 v13, v12, v14
	v_mul_f32_e32 v9, v17, v9
	v_sub_f32_e32 v13, v16, v13
	v_add_f32_e32 v9, v13, v9
	v_mul_f32_e32 v16, 0x3f317218, v8
	v_add_f32_e32 v13, v12, v9
	v_fma_f32 v17, v8, s3, -v16
	v_mul_f32_e32 v14, v13, v13
	v_fmac_f32_e32 v17, 0xb102e308, v8
	v_sub_f32_e32 v8, v13, v12
	v_fmamk_f32 v15, v14, 0x3e9b6dac, v234
	v_sub_f32_e32 v8, v9, v8
	v_add_f32_e32 v9, v16, v17
	v_fmaak_f32 v15, v14, v15, 0x3f2aaada
	v_sub_f32_e32 v12, v9, v16
	v_ldexp_f32 v16, v13, 1
	v_mul_f32_e32 v13, v13, v14
	v_mul_f32_e32 v13, v13, v15
	v_add_f32_e32 v14, v16, v13
	v_sub_f32_e32 v15, v14, v16
	v_ldexp_f32 v8, v8, 1
	v_sub_f32_e32 v13, v13, v15
	v_add_f32_e32 v8, v8, v13
	v_add_f32_e32 v13, v14, v8
	v_sub_f32_e32 v14, v13, v14
	v_sub_f32_e32 v8, v8, v14
	v_add_f32_e32 v14, v9, v13
	v_sub_f32_e32 v15, v14, v9
	v_sub_f32_e32 v16, v14, v15
	v_sub_f32_e32 v12, v17, v12
	v_sub_f32_e32 v9, v9, v16
	v_sub_f32_e32 v13, v13, v15
	v_add_f32_e32 v9, v13, v9
	v_add_f32_e32 v13, v12, v8
	v_sub_f32_e32 v15, v13, v12
	v_sub_f32_e32 v16, v13, v15
	v_sub_f32_e32 v12, v12, v16
	v_sub_f32_e32 v8, v8, v15
	v_add_f32_e32 v9, v13, v9
	v_add_f32_e32 v8, v8, v12
	v_add_f32_e32 v12, v14, v9
	v_sub_f32_e32 v13, v12, v14
	v_sub_f32_e32 v9, v9, v13
	v_add_f32_e32 v8, v8, v9
	v_add_f32_e32 v8, v12, v8
	v_cmp_nlt_f32_e32 vcc, 1.0, v11
	s_mov_b32 s3, 0x33800000
	v_cvt_f32_ubyte0_e32 v9, v10
	v_cndmask_b32_e32 v8, v251, v8, vcc
	v_cmp_neq_f32_e32 vcc, 1.0, v11
	s_nop 1
	v_cndmask_b32_e32 v8, v241, v8, vcc
	v_cmp_gt_f32_e32 vcc, s3, v11
	s_nop 1
	v_cndmask_b32_e64 v8, v8, -v11, vcc
	v_mul_f32_e64 v10, v8, -v9
	v_mul_f32_e32 v10, 0x3fb8aa3b, v10
	v_mul_f32_e32 v8, v8, v9
	v_exp_f32_e32 v10, v10
	v_mul_f32_e32 v8, 0x3fb8aa3b, v8
	v_exp_f32_e32 v8, v8
	v_lshl_add_u32 v11, v106, 2, 0
	v_add_u32_e32 v9, 0x22000, v11
	ds_write_b32 v9, v10
	v_add_u32_e32 v9, 0x22400, v11
	ds_write_b32 v9, v8

; #define LAS __attribute__((address_space(3)))
; __device__ __forceinline__ void ret_out(const Bufs& B, const float* __restrict__ g_out, int item, LAS unsigned char* lds) {
;     ...
;         mma_tile<128, 2>(accR, ST, 136, VT, 136, wr, wc, fr, fq);
;         __syncthreads();
; #pragma unroll
;         for (int m = 0; m < 4; ++m) { const f32x4 r4 = *(const LAS f32x4*)(vrw + dir * 128 + 64 * wr + 16 * m + 4 * fq);
; #pragma unroll
;             for (int n = 0; n < 2; ++n) yacc[m][n] += accR[m][n] * r4; }
;     }
;     const int erow = tid >> 2, eqd = tid & 3, es = s0 + erow;
;     u32x4 og4[4]; f32x4 gp4[8];
;     { const bf16_t* gg = B.PROJ + (size_t)es * NPROJP + PC_RG + h * 128 + eqd * 32; const float* gp = g_out + h * 128 + eqd * 32;
; #pragma unroll
;         for (int i = 0; i < 4; ++i) og4[i] = *(const u32x4*)(gg + i * 8);
; #pragma unroll
;         for (int i = 0; i < 8; ++i) gp4[i] = *(const f32x4*)(gp + i * 4); }
; #pragma unroll
;     for (int m = 0; m < 4; ++m)
; #pragma unroll
;         for (int n = 0; n < 2; ++n)
; #pragma unroll
;             for (int j = 0; j < 4; ++j) HT[(64 * wr + 16 * m + 4 * fq + j) * 132 + 32 * wc + 16 * n + fr] = yacc[m][n][j];
;     __syncthreads();
.LBB0_255:
	ds_read_b128 v[122:125], v121
	v_add_u32_e32 v126, 0xffffef00, v120
	ds_read_b128 v[126:129], v126
	ds_read_b128 v[130:133], v120
	s_add_i32 s30, s30, 32
	s_cmpk_lt_u32 s30, 0x60
	v_add_u32_e32 v120, 64, v120
	s_waitcnt lgkmcnt(1)
	v_mfma_f32_16x16x32_bf16 v[68:71], v[122:125], v[126:129], v[68:71]
	s_waitcnt lgkmcnt(0)
	v_mfma_f32_16x16x32_bf16 v[64:67], v[122:125], v[130:133], v[64:67]
	ds_read_b128 v[122:125], v121 offset:4352
	s_waitcnt lgkmcnt(0)
	v_mfma_f32_16x16x32_bf16 v[60:63], v[122:125], v[126:129], v[60:63]
	v_mfma_f32_16x16x32_bf16 v[56:59], v[122:125], v[130:133], v[56:59]
	ds_read_b128 v[122:125], v121 offset:8704
	s_waitcnt lgkmcnt(0)
	v_mfma_f32_16x16x32_bf16 v[52:55], v[122:125], v[126:129], v[52:55]
	v_mfma_f32_16x16x32_bf16 v[48:51], v[122:125], v[130:133], v[48:51]
	ds_read_b128 v[122:125], v121 offset:13056
	v_add_u32_e32 v121, 64, v121
	s_waitcnt lgkmcnt(0)
	v_mfma_f32_16x16x32_bf16 v[44:47], v[122:125], v[126:129], v[44:47]
	v_mfma_f32_16x16x32_bf16 v[40:43], v[122:125], v[130:133], v[40:43]
	s_cbranch_scc1 .LBB0_255
	v_add_u32_e32 v128, s33, v115
	s_barrier
	ds_read_b128 v[120:123], v128
	ds_read_b128 v[124:127], v128 offset:64
	s_movk_i32 s33, 0x200
	s_mov_b64 s[34:35], -1
	s_andn2_b64 vcc, exec, s[2:3]
	s_waitcnt lgkmcnt(1)
	v_pk_fma_f32 v[92:93], v[64:65], v[120:121], v[92:93]
	s_waitcnt lgkmcnt(0)
	v_pk_fma_f32 v[78:79], v[62:63], v[126:127], v[78:79]
	ds_read_b128 v[62:65], v128 offset:128
	v_pk_fma_f32 v[94:95], v[58:59], v[126:127], v[94:95]
	v_pk_fma_f32 v[98:99], v[56:57], v[124:125], v[98:99]
	ds_read_b128 v[56:59], v128 offset:192
	v_pk_fma_f32 v[76:77], v[70:71], v[122:123], v[76:77]
	v_pk_fma_f32 v[74:75], v[68:69], v[120:121], v[74:75]
	v_pk_fma_f32 v[88:89], v[66:67], v[122:123], v[88:89]
	v_pk_fma_f32 v[82:83], v[60:61], v[124:125], v[82:83]
	s_waitcnt lgkmcnt(1)
	v_pk_fma_f32 v[80:81], v[54:55], v[64:65], v[80:81]
	v_pk_fma_f32 v[86:87], v[52:53], v[62:63], v[86:87]
	v_pk_fma_f32 v[96:97], v[50:51], v[64:65], v[96:97]
	v_pk_fma_f32 v[102:103], v[48:49], v[62:63], v[102:103]
	s_waitcnt lgkmcnt(0)
	v_pk_fma_f32 v[84:85], v[46:47], v[58:59], v[84:85]
	v_pk_fma_f32 v[90:91], v[44:45], v[56:57], v[90:91]
	v_pk_fma_f32 v[100:101], v[42:43], v[58:59], v[100:101]
	v_pk_fma_f32 v[104:105], v[40:41], v[56:57], v[104:105]
	s_mov_b64 s[30:31], 0
	s_cbranch_vccnz .LBB0_250
	v_readlane_b32 s16, v254, 23
	v_readlane_b32 s0, v254, 44
	v_readlane_b32 s17, v254, 24
	v_readlane_b32 s1, v254, 45
	v_add_u32_e32 v64, s0, v109
	v_mov_b64_e32 v[0:1], s[16:17]
	s_movk_i32 s0, 0x2400
	v_mad_i64_i32 v[0:1], s[0:1], v64, s0, v[0:1]
	v_readlane_b32 s37, v254, 48
	v_readlane_b32 s2, v253, 36
	v_lshlrev_b32_e32 v2, 5, v106
	s_lshl_b32 s0, s37, 1
	s_mov_b32 s1, s2
	v_and_b32_e32 v4, 0x60, v2
	v_readlane_b32 s3, v253, 37
	v_lshl_add_u64 v[0:1], v[0:1], 0, s[0:1]
	v_lshlrev_b32_e32 v194, 1, v4
	v_lshl_add_u64 v[0:1], v[0:1], 0, v[194:195]
	s_mov_b64 s[2:3], 0x1820
	s_movk_i32 s4, 0x1000
	v_lshl_add_u64 v[2:3], v[0:1], 0, s[2:3]
	v_add_co_u32_e32 v0, vcc, s4, v0
	s_lshl_b32 s2, s37, 2
	s_nop 0
	v_addc_co_u32_e32 v1, vcc, 0, v1, vcc
	global_load_dwordx4 v[52:55], v[2:3], off offset:16
	global_load_dwordx4 v[28:31], v[2:3], off offset:32
	global_load_dwordx4 v[66:69], v[0:1], off offset:2080
	global_load_dwordx4 v[8:11], v[2:3], off offset:48
	v_readlane_b32 s3, v254, 49
	s_add_u32 s2, s3, s2
	v_readlane_b32 s3, v254, 46
	s_addc_u32 s3, s3, 0
	v_lshlrev_b32_e32 v12, 2, v4
	s_nop 2
	global_load_dwordx4 v[36:39], v12, s[2:3] offset:48
	global_load_dwordx4 v[44:47], v12, s[2:3] offset:32
	global_load_dwordx4 v[60:63], v12, s[2:3] offset:16
	global_load_dwordx4 v[116:119], v12, s[2:3]
	global_load_dwordx4 v[0:3], v12, s[2:3] offset:112
	global_load_dwordx4 v[4:7], v12, s[2:3] offset:96
	global_load_dwordx4 v[16:19], v12, s[2:3] offset:80
	global_load_dwordx4 v[24:27], v12, s[2:3] offset:64
	s_movk_i32 s2, 0x210
	v_lshl_add_u32 v13, v110, 7, 0
	v_lshlrev_b32_e32 v14, 2, v111
	v_mul_lo_u32 v15, v73, s2
	v_add3_u32 v13, v13, v14, v15
	v_add_u32_e32 v14, 0x9000, v13
	ds_write2_b32 v14, v74, v92 offset1:16
	ds_write2_b32 v14, v75, v93 offset0:132 offset1:148
	v_add_u32_e32 v14, 0x9400, v13
	ds_write2_b32 v14, v76, v88 offset0:8 offset1:24
	ds_write2_b32 v14, v77, v89 offset0:140 offset1:156
	v_add_u32_e32 v14, 0xb000, v13
	ds_write2_b32 v14, v82, v98 offset0:64 offset1:80
	ds_write2_b32 v14, v83, v99 offset0:196 offset1:212
	v_add_u32_e32 v14, 0xb400, v13
	ds_write2_b32 v14, v78, v94 offset0:72 offset1:88
	ds_write2_b32 v14, v79, v95 offset0:204 offset1:220
	v_add_u32_e32 v14, 0xd000, v13
	ds_write2_b32 v14, v86, v102 offset0:128 offset1:144
	v_add_u32_e32 v14, 0xd400, v13
	ds_write2_b32 v14, v87, v103 offset0:4 offset1:20
	ds_write2_b32 v14, v80, v96 offset0:136 offset1:152
	v_add_u32_e32 v14, 0xd800, v13
	ds_write2_b32 v14, v81, v97 offset0:12 offset1:28
	v_add_u32_e32 v14, 0xf000, v13
	ds_write2_b32 v14, v90, v104 offset0:192 offset1:208
	v_add_u32_e32 v14, 0xf400, v13
	v_add_u32_e32 v13, 0xf800, v13
	ds_write2_b32 v14, v91, v105 offset0:68 offset1:84
	ds_write2_b32 v14, v84, v100 offset0:200 offset1:216
	ds_write2_b32 v13, v85, v101 offset0:76 offset1:92
	v_mul_lo_u32 v13, v109, s2
	v_add3_u32 v65, 0, v13, v12
	s_waitcnt lgkmcnt(0)
	s_barrier
; #define LAS __attribute__((address_space(3)))
; __device__ __forceinline__ void unpack8(u32x4 w, float* f) { f[0] = bflo(w.x); f[1] = bfhi(w.x); f[2] = bflo(w.y); f[3] = bfhi(w.y); f[4] = bflo(w.z); f[5] = bfhi(w.z); f[6] = bflo(w.w); f[7] = bfhi(w.w); }
; __device__ __forceinline__ u32x4 pack8(const float* f) { u32x4 w; w.x = cvt_pk_bf16(f[0], f[1]); w.y = cvt_pk_bf16(f[2], f[3]); w.z = cvt_pk_bf16(f[4], f[5]); w.w = cvt_pk_bf16(f[6], f[7]); return w; }
; __device__ __forceinline__ void ret_out(const Bufs& B, const float* __restrict__ g_out, int item, LAS unsigned char* lds) {
;     ...
;     { float ssq = 0.f; f32x4 x4[8];
; #pragma unroll
;         for (int i = 0; i < 8; ++i) { x4[i] = *(const LAS f32x4*)(HT + erow * 132 + eqd * 32 + i * 4);
;             ssq += x4[i][0] * x4[i][0] + x4[i][1] * x4[i][1] + x4[i][2] * x4[i][2] + x4[i][3] * x4[i][3]; }
;         ssq += __shfl_xor(ssq, 1); ssq += __shfl_xor(ssq, 2);
;         const float rstd = rsqrtf(ssq * (1.f / 128.f) + EPS_);
;         bf16_t* yo = B.Y + (size_t)es * DM + 512 + h * 128 + eqd * 32;
; #pragma unroll
;         for (int i = 0; i < 4; ++i) { float o8[8]; unpack8(og4[i], o8); float r8[8];
; #pragma unroll
;             for (int k = 0; k < 8; ++k) { const float sl = o8[k] * __builtin_amdgcn_rcpf(1.f + __expf(-o8[k])); r8[k] = sl * x4[2 * i + (k >> 2)][k & 3] * rstd * gp4[2 * i + (k >> 2)][k & 3]; }
;             *(u32x4*)(yo + i * 8) = pack8(r8); } }
	ds_read_b128 v[70:73], v65 offset:36864
	ds_read_b128 v[74:77], v65 offset:36880
	ds_read_b128 v[56:59], v65 offset:36896
	ds_read_b128 v[48:51], v65 offset:36912
	ds_read_b128 v[40:43], v65 offset:36928
	ds_read_b128 v[32:35], v65 offset:36944
	s_waitcnt lgkmcnt(0)
	v_mov_b32_e32 v14, v71
	v_mov_b32_e32 v15, v75
	v_mov_b32_e32 v12, v70
	v_mov_b32_e32 v13, v74
	v_pk_mul_f32 v[14:15], v[14:15], v[14:15]
	v_mov_b32_e32 v84, v43
	v_pk_fma_f32 v[12:13], v[12:13], v[12:13], v[14:15]
	v_mov_b32_e32 v14, v72
	v_mov_b32_e32 v15, v76
	v_pk_fma_f32 v[12:13], v[14:15], v[14:15], v[12:13]
	v_mov_b32_e32 v14, v73
	v_mov_b32_e32 v15, v77
	v_pk_fma_f32 v[78:79], v[14:15], v[14:15], v[12:13]
	v_mov_b32_e32 v14, v57
	v_mov_b32_e32 v15, v49
	v_mov_b32_e32 v12, v56
	v_mov_b32_e32 v13, v48
	v_pk_mul_f32 v[14:15], v[14:15], v[14:15]
	v_mov_b32_e32 v85, v35
	v_pk_fma_f32 v[12:13], v[12:13], v[12:13], v[14:15]
	v_mov_b32_e32 v14, v58
	v_mov_b32_e32 v15, v50
	v_pk_fma_f32 v[12:13], v[14:15], v[14:15], v[12:13]
	v_mov_b32_e32 v14, v59
	v_mov_b32_e32 v15, v51
	v_pk_fma_f32 v[80:81], v[14:15], v[14:15], v[12:13]
	v_mov_b32_e32 v14, v41
	v_mov_b32_e32 v15, v33
	v_mov_b32_e32 v12, v40
	v_mov_b32_e32 v13, v32
	v_pk_mul_f32 v[14:15], v[14:15], v[14:15]
	s_mov_b32 s2, 0x800000
	v_pk_fma_f32 v[12:13], v[12:13], v[12:13], v[14:15]
	v_mov_b32_e32 v14, v42
	v_mov_b32_e32 v15, v34
	v_pk_fma_f32 v[82:83], v[14:15], v[14:15], v[12:13]
	ds_read_b128 v[20:23], v65 offset:36960
	ds_read_b128 v[12:15], v65 offset:36976
	v_add_f32_e32 v65, v78, v79
	v_pk_fma_f32 v[82:83], v[84:85], v[84:85], v[82:83]
	v_add_f32_e32 v65, v65, v80
	s_waitcnt lgkmcnt(0)
	v_mov_b32_e32 v86, v21
	v_mov_b32_e32 v87, v13
	v_mov_b32_e32 v84, v20
	v_mov_b32_e32 v85, v12
	v_pk_mul_f32 v[86:87], v[86:87], v[86:87]
	v_add_f32_e32 v65, v65, v81
	v_pk_fma_f32 v[84:85], v[84:85], v[84:85], v[86:87]
	v_mov_b32_e32 v86, v22
	v_mov_b32_e32 v87, v14
	v_pk_fma_f32 v[84:85], v[86:87], v[86:87], v[84:85]
	v_mov_b32_e32 v86, v23
	v_mov_b32_e32 v87, v15
	v_add_f32_e32 v65, v65, v82
	v_pk_fma_f32 v[84:85], v[86:87], v[86:87], v[84:85]
	v_add_f32_e32 v65, v65, v83
	v_add_f32_e32 v65, v65, v84
	v_add_f32_e32 v65, v65, v85
	ds_bpermute_b32 v78, v113, v65
	s_waitcnt vmcnt(0)
	v_lshlrev_b32_e32 v80, 16, v67
	v_and_b32_e32 v67, 0xffff0000, v67
	v_lshlrev_b32_e32 v82, 16, v68
	v_and_b32_e32 v68, 0xffff0000, v68
	s_waitcnt lgkmcnt(0)
	v_add_f32_e32 v65, v65, v78
	ds_bpermute_b32 v78, v114, v65
	v_lshlrev_b32_e32 v83, 16, v69
	v_and_b32_e32 v69, 0xffff0000, v69
	v_readlane_b32 s37, v254, 54
	s_waitcnt lgkmcnt(0)
	v_add_f32_e32 v65, v65, v78
	v_fmamk_f32 v65, v65, 0x3c000000, v242
	v_mul_f32_e32 v78, 0x4b800000, v65
	v_cmp_gt_f32_e32 vcc, s2, v65
	v_readlane_b32 s2, v254, 42
	v_readlane_b32 s3, v254, 43
	v_cndmask_b32_e32 v65, v65, v78, vcc
	v_rsq_f32_e32 v78, v65
	v_ashrrev_i32_e32 v65, 31, v64
	v_lshlrev_b64 v[64:65], 12, v[64:65]
	v_lshl_add_u64 v[64:65], s[2:3], 0, v[64:65]
	v_mul_f32_e32 v79, 0x45800000, v78
	v_cndmask_b32_e32 v78, v78, v79, vcc
	v_lshlrev_b32_e32 v79, 16, v66
	v_mul_f32_e32 v81, 0xbfb8aa3b, v79
	v_exp_f32_e32 v81, v81
	v_and_b32_e32 v66, 0xffff0000, v66
	v_mul_f32_e32 v84, 0xbfb8aa3b, v66
	v_exp_f32_e32 v84, v84
	v_add_f32_e32 v81, 1.0, v81
	v_rcp_f32_e32 v81, v81
	v_lshl_add_u64 v[64:65], v[64:65], 0, s[0:1]
	v_lshl_add_u64 v[64:65], v[64:65], 0, v[194:195]
	v_readlane_b32 s0, v252, 9
	v_mul_f32_e32 v79, v81, v79
	v_mul_f32_e32 v70, v79, v70
	v_add_f32_e32 v79, 1.0, v84
	v_rcp_f32_e32 v79, v79
	v_mul_f32_e32 v81, 0xbfb8aa3b, v80
	v_exp_f32_e32 v81, v81
	v_mul_f32_e32 v70, v70, v78
	v_mul_f32_e32 v66, v79, v66
	v_mul_f32_e32 v66, v66, v71
	v_add_f32_e32 v71, 1.0, v81
	v_rcp_f32_e32 v71, v71
	v_mul_f32_e32 v79, 0xbfb8aa3b, v67
	v_exp_f32_e32 v79, v79
	v_mul_f32_e32 v66, v66, v78
	v_mul_f32_e32 v71, v71, v80
	v_mul_f32_e32 v71, v71, v72
	v_add_f32_e32 v72, 1.0, v79
	v_rcp_f32_e32 v72, v72
	v_mul_f32_e32 v79, 0xbfb8aa3b, v82
	v_exp_f32_e32 v79, v79
	v_mul_f32_e32 v70, v116, v70
	v_mul_f32_e32 v67, v72, v67
	v_mul_f32_e32 v67, v67, v73
	v_mul_f32_e32 v73, 0xbfb8aa3b, v68
	v_add_f32_e32 v72, 1.0, v79
	v_exp_f32_e32 v73, v73
	v_rcp_f32_e32 v72, v72
	v_mul_f32_e32 v66, v117, v66
	v_mul_f32_e32 v71, v71, v78
	v_add_f32_e32 v73, 1.0, v73
	v_mul_f32_e32 v72, v72, v82
	v_rcp_f32_e32 v73, v73
	v_mul_f32_e32 v72, v72, v74
	v_mul_f32_e32 v74, 0xbfb8aa3b, v83
	v_exp_f32_e32 v74, v74
	v_mul_f32_e32 v72, v72, v78
	v_mul_f32_e32 v72, v60, v72
	v_mul_f32_e32 v60, v73, v68
	v_mul_f32_e32 v73, 0xbfb8aa3b, v69
	v_exp_f32_e32 v73, v73
	v_add_f32_e32 v68, 1.0, v74
	v_mul_f32_e32 v60, v60, v75
	v_rcp_f32_e32 v68, v68
	v_mul_f32_e32 v60, v60, v78
	v_mul_f32_e32 v74, v61, v60
	v_add_f32_e32 v61, 1.0, v73
	v_rcp_f32_e32 v61, v61
	v_mul_f32_e32 v60, v68, v83
	v_mul_f32_e32 v60, v60, v76
	v_mul_f32_e32 v60, v60, v78
	v_mul_f32_e32 v68, v62, v60
	v_mul_f32_e32 v60, v61, v69
	v_mul_f32_e32 v60, v60, v77
	v_mul_f32_e32 v60, v60, v78
	v_mul_f32_e32 v67, v67, v78
	v_mul_f32_e32 v63, v63, v60
	v_cvt_pk_bf16_f32 v60, v70, v66
	v_mul_f32_e32 v71, v118, v71
	v_mul_f32_e32 v67, v119, v67
	v_cvt_pk_bf16_f32 v61, v71, v67
	v_cvt_pk_bf16_f32 v62, v72, v74
	v_cvt_pk_bf16_f32 v63, v68, v63
	global_store_dwordx4 v[64:65], v[60:63], off offset:1024
	v_lshlrev_b32_e32 v66, 16, v55
	v_and_b32_e32 v55, 0xffff0000, v55
	v_lshlrev_b32_e32 v60, 16, v52
	v_mul_f32_e32 v62, 0xbfb8aa3b, v60
	v_exp_f32_e32 v62, v62
	v_and_b32_e32 v52, 0xffff0000, v52
	v_mul_f32_e32 v67, 0xbfb8aa3b, v52
	v_exp_f32_e32 v67, v67
	v_add_f32_e32 v62, 1.0, v62
	v_rcp_f32_e32 v62, v62
	v_lshlrev_b32_e32 v61, 16, v53
	v_and_b32_e32 v53, 0xffff0000, v53
	v_lshlrev_b32_e32 v63, 16, v54
; __device__ __forceinline__ void unpack8(u32x4 w, float* f) { f[0] = bflo(w.x); f[1] = bfhi(w.x); f[2] = bflo(w.y); f[3] = bfhi(w.y); f[4] = bflo(w.z); f[5] = bfhi(w.z); f[6] = bflo(w.w); f[7] = bfhi(w.w); }
; __device__ __forceinline__ u32x4 pack8(const float* f) { u32x4 w; w.x = cvt_pk_bf16(f[0], f[1]); w.y = cvt_pk_bf16(f[2], f[3]); w.z = cvt_pk_bf16(f[4], f[5]); w.w = cvt_pk_bf16(f[6], f[7]); return w; }
; __device__ __forceinline__ void ret_out(const Bufs& B, const float* __restrict__ g_out, int item, LAS unsigned char* lds) {
;     ...
;         for (int i = 0; i < 4; ++i) { float o8[8]; unpack8(og4[i], o8); float r8[8];
; #pragma unroll
;             for (int k = 0; k < 8; ++k) { const float sl = o8[k] * __builtin_amdgcn_rcpf(1.f + __expf(-o8[k])); r8[k] = sl * x4[2 * i + (k >> 2)][k & 3] * rstd * gp4[2 * i + (k >> 2)][k & 3]; }
;             *(u32x4*)(yo + i * 8) = pack8(r8); } }
;     __syncthreads();
; __global__ void __launch_bounds__(512) mega_fwd(Params p) {
;     ...
;             for (int it = bx; it < 256; it += G) ret_out(B, p.g_ret_out + l * 512, it, lds);
	v_mul_f32_e32 v60, v62, v60
	v_mul_f32_e32 v56, v60, v56
	v_add_f32_e32 v60, 1.0, v67
	v_rcp_f32_e32 v60, v60
	v_mul_f32_e32 v56, v56, v78
	v_mul_f32_e32 v44, v44, v56
	v_mul_f32_e32 v56, 0xbfb8aa3b, v61
	v_exp_f32_e32 v56, v56
	v_mul_f32_e32 v52, v60, v52
	v_mul_f32_e32 v52, v52, v57
	v_mul_f32_e32 v52, v52, v78
	v_mul_f32_e32 v45, v45, v52
	v_mul_f32_e32 v52, 0xbfb8aa3b, v53
	v_add_f32_e32 v56, 1.0, v56
	v_exp_f32_e32 v52, v52
	v_rcp_f32_e32 v56, v56
	v_and_b32_e32 v54, 0xffff0000, v54
	s_add_i32 s0, s37, s0
	v_add_f32_e32 v52, 1.0, v52
	v_mul_f32_e32 v56, v56, v61
	v_rcp_f32_e32 v52, v52
	v_mul_f32_e32 v56, v56, v58
	v_mul_f32_e32 v56, v56, v78
	v_mul_f32_e32 v46, v46, v56
	v_mul_f32_e32 v56, 0xbfb8aa3b, v63
	v_exp_f32_e32 v56, v56
	v_mul_f32_e32 v52, v52, v53
	v_mul_f32_e32 v52, v52, v59
	v_mul_f32_e32 v52, v52, v78
	v_mul_f32_e32 v47, v47, v52
	v_mul_f32_e32 v52, 0xbfb8aa3b, v54
	v_add_f32_e32 v53, 1.0, v56
	v_exp_f32_e32 v52, v52
	v_rcp_f32_e32 v53, v53
	s_cmpk_lt_i32 s0, 0x100
	v_readlane_b32 s1, v252, 10
	v_add_f32_e32 v52, 1.0, v52
	v_mul_f32_e32 v53, v53, v63
	v_rcp_f32_e32 v52, v52
	v_mul_f32_e32 v48, v53, v48
	v_mul_f32_e32 v53, 0xbfb8aa3b, v66
	v_exp_f32_e32 v53, v53
	v_mul_f32_e32 v48, v48, v78
	v_mul_f32_e32 v48, v36, v48
	v_mul_f32_e32 v36, v52, v54
	v_mul_f32_e32 v52, 0xbfb8aa3b, v55
	v_exp_f32_e32 v52, v52
	v_mul_f32_e32 v36, v36, v49
	v_add_f32_e32 v49, 1.0, v53
	v_rcp_f32_e32 v49, v49
	v_mul_f32_e32 v36, v36, v78
	v_mul_f32_e32 v53, v37, v36
	v_add_f32_e32 v37, 1.0, v52
	v_rcp_f32_e32 v37, v37
	v_mul_f32_e32 v36, v49, v66
	v_mul_f32_e32 v36, v36, v50
	v_mul_f32_e32 v36, v36, v78
	v_mul_f32_e32 v49, v38, v36
	v_mul_f32_e32 v36, v37, v55
	v_mul_f32_e32 v36, v36, v51
	v_mul_f32_e32 v36, v36, v78
	v_mul_f32_e32 v39, v39, v36
	v_cvt_pk_bf16_f32 v36, v44, v45
	v_cvt_pk_bf16_f32 v37, v46, v47
	v_cvt_pk_bf16_f32 v38, v48, v53
	v_cvt_pk_bf16_f32 v39, v49, v39
	global_store_dwordx4 v[64:65], v[36:39], off offset:1040
	v_lshlrev_b32_e32 v44, 16, v31
	v_and_b32_e32 v31, 0xffff0000, v31
	v_lshlrev_b32_e32 v36, 16, v28
	v_mul_f32_e32 v38, 0xbfb8aa3b, v36
	v_exp_f32_e32 v38, v38
	v_and_b32_e32 v28, 0xffff0000, v28
	v_mul_f32_e32 v45, 0xbfb8aa3b, v28
	v_exp_f32_e32 v45, v45
	v_add_f32_e32 v38, 1.0, v38
	v_rcp_f32_e32 v38, v38
	v_lshlrev_b32_e32 v37, 16, v29
	v_and_b32_e32 v29, 0xffff0000, v29
	v_lshlrev_b32_e32 v39, 16, v30
	v_mul_f32_e32 v36, v38, v36
	v_add_f32_e32 v38, 1.0, v45
	v_rcp_f32_e32 v38, v38
	v_mul_f32_e32 v36, v36, v40
	v_mul_f32_e32 v36, v36, v78
	v_mul_f32_e32 v24, v24, v36
	v_mul_f32_e32 v36, 0xbfb8aa3b, v37
	v_exp_f32_e32 v36, v36
	v_mul_f32_e32 v28, v38, v28
	v_mul_f32_e32 v28, v28, v41
	v_mul_f32_e32 v28, v28, v78
	v_mul_f32_e32 v25, v25, v28
	v_mul_f32_e32 v28, 0xbfb8aa3b, v29
	v_add_f32_e32 v36, 1.0, v36
	v_exp_f32_e32 v28, v28
	v_rcp_f32_e32 v36, v36
	v_and_b32_e32 v30, 0xffff0000, v30
	v_add_f32_e32 v28, 1.0, v28
	v_mul_f32_e32 v36, v36, v37
	v_rcp_f32_e32 v28, v28
	v_mul_f32_e32 v36, v36, v42
	v_mul_f32_e32 v36, v36, v78
	v_mul_f32_e32 v26, v26, v36
	v_mul_f32_e32 v36, 0xbfb8aa3b, v39
	v_exp_f32_e32 v36, v36
	v_mul_f32_e32 v28, v28, v29
	v_mul_f32_e32 v28, v28, v43
	v_mul_f32_e32 v28, v28, v78
	v_mul_f32_e32 v27, v27, v28
	v_mul_f32_e32 v28, 0xbfb8aa3b, v30
	v_add_f32_e32 v29, 1.0, v36
	v_exp_f32_e32 v28, v28
	v_rcp_f32_e32 v29, v29
	v_add_f32_e32 v28, 1.0, v28
	v_mul_f32_e32 v29, v29, v39
	v_rcp_f32_e32 v28, v28
	v_mul_f32_e32 v29, v29, v32
	v_mul_f32_e32 v32, 0xbfb8aa3b, v44
	v_exp_f32_e32 v32, v32
	v_mul_f32_e32 v29, v29, v78
	v_mul_f32_e32 v29, v16, v29
	v_mul_f32_e32 v16, v28, v30
	v_mul_f32_e32 v30, 0xbfb8aa3b, v31
	v_exp_f32_e32 v30, v30
	v_add_f32_e32 v28, 1.0, v32
	v_mul_f32_e32 v16, v16, v33
	v_rcp_f32_e32 v28, v28
	v_mul_f32_e32 v16, v16, v78
	v_mul_f32_e32 v32, v17, v16
	v_add_f32_e32 v17, 1.0, v30
	v_rcp_f32_e32 v17, v17
	v_mul_f32_e32 v16, v28, v44
	v_mul_f32_e32 v16, v16, v34
	v_mul_f32_e32 v16, v16, v78
	v_mul_f32_e32 v28, v18, v16
	v_mul_f32_e32 v16, v17, v31
	v_mul_f32_e32 v16, v16, v35
	v_mul_f32_e32 v16, v16, v78
	v_mul_f32_e32 v19, v19, v16
	v_cvt_pk_bf16_f32 v16, v24, v25
	v_cvt_pk_bf16_f32 v17, v26, v27
	v_cvt_pk_bf16_f32 v18, v29, v32
	v_cvt_pk_bf16_f32 v19, v28, v19
	global_store_dwordx4 v[64:65], v[16:19], off offset:1056
	v_lshlrev_b32_e32 v24, 16, v11
	v_and_b32_e32 v11, 0xffff0000, v11
	v_lshlrev_b32_e32 v16, 16, v8
	v_mul_f32_e32 v18, 0xbfb8aa3b, v16
	v_exp_f32_e32 v18, v18
	v_and_b32_e32 v8, 0xffff0000, v8
	v_mul_f32_e32 v25, 0xbfb8aa3b, v8
	v_exp_f32_e32 v25, v25
	v_add_f32_e32 v18, 1.0, v18
	v_rcp_f32_e32 v18, v18
	v_lshlrev_b32_e32 v17, 16, v9
	v_and_b32_e32 v9, 0xffff0000, v9
	v_lshlrev_b32_e32 v19, 16, v10
	v_mul_f32_e32 v16, v18, v16
	v_add_f32_e32 v18, 1.0, v25
	v_rcp_f32_e32 v18, v18
	v_mul_f32_e32 v16, v16, v20
	v_mul_f32_e32 v16, v16, v78
	v_mul_f32_e32 v4, v4, v16
	v_mul_f32_e32 v16, 0xbfb8aa3b, v17
	v_exp_f32_e32 v16, v16
	v_mul_f32_e32 v8, v18, v8
	v_mul_f32_e32 v8, v8, v21
	v_mul_f32_e32 v8, v8, v78
	v_mul_f32_e32 v5, v5, v8
	v_mul_f32_e32 v8, 0xbfb8aa3b, v9
	v_add_f32_e32 v16, 1.0, v16
	v_exp_f32_e32 v8, v8
	v_rcp_f32_e32 v16, v16
	v_and_b32_e32 v10, 0xffff0000, v10
	v_add_f32_e32 v8, 1.0, v8
	v_mul_f32_e32 v16, v16, v17
	v_rcp_f32_e32 v8, v8
	v_mul_f32_e32 v16, v16, v22
	v_mul_f32_e32 v16, v16, v78
	v_mul_f32_e32 v6, v6, v16
	v_mul_f32_e32 v16, 0xbfb8aa3b, v19
	v_exp_f32_e32 v16, v16
	v_mul_f32_e32 v8, v8, v9
	v_mul_f32_e32 v8, v8, v23
	v_mul_f32_e32 v8, v8, v78
	v_mul_f32_e32 v7, v7, v8
	v_mul_f32_e32 v8, 0xbfb8aa3b, v10
	v_add_f32_e32 v9, 1.0, v16
	v_exp_f32_e32 v8, v8
	v_rcp_f32_e32 v9, v9
	v_add_f32_e32 v8, 1.0, v8
	v_mul_f32_e32 v9, v9, v19
	v_rcp_f32_e32 v8, v8
	v_mul_f32_e32 v9, v9, v12
	v_mul_f32_e32 v12, 0xbfb8aa3b, v24
	v_exp_f32_e32 v12, v12
	v_mul_f32_e32 v9, v9, v78
	v_mul_f32_e32 v9, v0, v9
	v_mul_f32_e32 v0, v8, v10
	v_mul_f32_e32 v10, 0xbfb8aa3b, v11
	v_exp_f32_e32 v10, v10
	v_add_f32_e32 v8, 1.0, v12
	v_mul_f32_e32 v0, v0, v13
	v_rcp_f32_e32 v8, v8
	v_mul_f32_e32 v0, v0, v78
	v_mul_f32_e32 v12, v1, v0
	v_add_f32_e32 v1, 1.0, v10
	v_rcp_f32_e32 v1, v1
	v_mul_f32_e32 v0, v8, v24
	v_mul_f32_e32 v0, v0, v14
	v_mul_f32_e32 v0, v0, v78
	v_mul_f32_e32 v8, v2, v0
	v_mul_f32_e32 v0, v1, v11
	v_mul_f32_e32 v0, v0, v15
	v_mul_f32_e32 v0, v0, v78
	v_mul_f32_e32 v3, v3, v0
	v_cvt_pk_bf16_f32 v0, v4, v5
	v_cvt_pk_bf16_f32 v1, v6, v7
	v_cvt_pk_bf16_f32 v2, v9, v12
	v_cvt_pk_bf16_f32 v3, v8, v3
	global_store_dwordx4 v[64:65], v[0:3], off offset:1072
	s_waitcnt lgkmcnt(0)
	s_barrier
	s_cbranch_scc1 .LBB0_245
	v_readlane_b32 s0, v254, 4
	v_readlane_b32 s24, v254, 3
	s_mov_b32 s25, s0
	v_readlane_b32 s1, v254, 5
	s_branch .LBB0_260

; __device__ __forceinline__ void scan_phase(const Bufs& B) {
;     ...
;             for (int u = 0; u < 16; ++u) { const int ch = dir ? 63 - (s0 + u) : s0 + u, it = dh * 64 + ch;
;                 cl[u] = B.CLOC[(size_t)it * 16384 + idx]; ml[u] = B.MLOC[it]; bl[u] = B.BLAST[it]; nl[u] = idx < 128 ? B.NLOC[(size_t)it * 128 + idx] : 0.f; }
.LBB0_304:
	s_add_i32 s24, s26, 15
	v_mov_b32_e32 v9, s24
	v_mov_b32_e32 v10, s27
	v_cndmask_b32_e32 v9, v9, v10, vcc
	v_add_u32_e32 v44, v9, v79
	v_ashrrev_i32_e32 v45, 31, v44
	v_lshlrev_b64 v[10:11], 16, v[44:45]
	v_lshl_add_u64 v[10:11], v[0:1], 0, v[10:11]
	global_load_dword v13, v[10:11], off
	v_lshlrev_b64 v[10:11], 2, v[44:45]
	v_lshl_add_u64 v[14:15], s[18:19], 0, v[10:11]
	v_lshl_add_u64 v[10:11], s[20:21], 0, v[10:11]
	global_load_dword v126, v[14:15], off
	global_load_dword v140, v[10:11], off
	v_lshlrev_b64 v[76:77], 9, v[44:45]
	v_mov_b32_e32 v131, 0
	s_and_saveexec_b64 s[24:25], s[4:5]
	s_cbranch_execz .LBB0_306
	v_lshl_add_u64 v[10:11], v[2:3], 0, v[76:77]
	global_load_dword v131, v[10:11], off
.LBB0_306:
	s_or_b64 exec, exec, s[24:25]
	s_add_i32 s24, s26, 14
	s_add_i32 s27, s27, 1
	v_mov_b32_e32 v9, s24
	v_mov_b32_e32 v10, s27
	v_cndmask_b32_e32 v9, v9, v10, vcc
	v_add_u32_e32 v42, v9, v79
	v_ashrrev_i32_e32 v43, 31, v42
	v_lshlrev_b64 v[10:11], 16, v[42:43]
	v_lshl_add_u64 v[10:11], v[0:1], 0, v[10:11]
	global_load_dword v9, v[10:11], off
	v_lshlrev_b64 v[10:11], 2, v[42:43]
	v_lshl_add_u64 v[14:15], s[18:19], 0, v[10:11]
	v_lshl_add_u64 v[10:11], s[20:21], 0, v[10:11]
	global_load_dword v123, v[14:15], off
	global_load_dword v139, v[10:11], off
	v_mov_b32_e32 v87, 0
	v_lshlrev_b64 v[74:75], 9, v[42:43]
	v_mov_b32_e32 v129, 0
	s_and_saveexec_b64 s[24:25], s[4:5]
	s_cbranch_execz .LBB0_308
	v_lshl_add_u64 v[10:11], v[2:3], 0, v[74:75]
	global_load_dword v129, v[10:11], off
.LBB0_308:
	s_or_b64 exec, exec, s[24:25]
	s_add_i32 s24, s26, 13
	s_add_i32 s27, s27, 1
	v_mov_b32_e32 v10, s24
	v_mov_b32_e32 v11, s27
	v_cndmask_b32_e32 v10, v10, v11, vcc
	v_add_u32_e32 v40, v10, v79
	v_ashrrev_i32_e32 v41, 31, v40
	v_lshlrev_b64 v[10:11], 16, v[40:41]
	v_lshl_add_u64 v[10:11], v[0:1], 0, v[10:11]
	global_load_dword v104, v[10:11], off
	v_lshlrev_b64 v[10:11], 2, v[40:41]
	v_lshl_add_u64 v[14:15], s[18:19], 0, v[10:11]
	v_lshl_add_u64 v[10:11], s[20:21], 0, v[10:11]
	global_load_dword v121, v[14:15], off
	global_load_dword v138, v[10:11], off
	v_lshlrev_b64 v[72:73], 9, v[40:41]
	s_and_saveexec_b64 s[24:25], s[4:5]
	s_cbranch_execz .LBB0_310
	v_lshl_add_u64 v[10:11], v[2:3], 0, v[72:73]
	global_load_dword v87, v[10:11], off
.LBB0_310:
	s_or_b64 exec, exec, s[24:25]
	s_add_i32 s24, s26, 12
	s_add_i32 s27, s27, 1
	v_mov_b32_e32 v10, s24
	v_mov_b32_e32 v11, s27
	v_cndmask_b32_e32 v10, v10, v11, vcc
	v_add_u32_e32 v38, v10, v79
	v_ashrrev_i32_e32 v39, 31, v38
	v_lshlrev_b64 v[10:11], 16, v[38:39]
	v_lshl_add_u64 v[10:11], v[0:1], 0, v[10:11]
	global_load_dword v102, v[10:11], off
	v_lshlrev_b64 v[10:11], 2, v[38:39]
	v_lshl_add_u64 v[14:15], s[18:19], 0, v[10:11]
	v_lshl_add_u64 v[10:11], s[20:21], 0, v[10:11]
	global_load_dword v118, v[14:15], off
	global_load_dword v137, v[10:11], off
	v_mov_b32_e32 v86, 0
	v_lshlrev_b64 v[70:71], 9, v[38:39]
	v_mov_b32_e32 v125, 0
	s_and_saveexec_b64 s[24:25], s[4:5]
	s_cbranch_execz .LBB0_312
	v_lshl_add_u64 v[10:11], v[2:3], 0, v[70:71]
	global_load_dword v125, v[10:11], off
.LBB0_312:
	s_or_b64 exec, exec, s[24:25]
	s_add_i32 s24, s26, 11
	s_add_i32 s27, s27, 1
	v_mov_b32_e32 v10, s24
	v_mov_b32_e32 v11, s27
	v_cndmask_b32_e32 v10, v10, v11, vcc
	v_add_u32_e32 v36, v10, v79
	v_ashrrev_i32_e32 v37, 31, v36
	v_lshlrev_b64 v[10:11], 16, v[36:37]
	v_lshl_add_u64 v[10:11], v[0:1], 0, v[10:11]
	global_load_dword v100, v[10:11], off
	v_lshlrev_b64 v[10:11], 2, v[36:37]
	v_lshl_add_u64 v[14:15], s[18:19], 0, v[10:11]
	v_lshl_add_u64 v[10:11], s[20:21], 0, v[10:11]
	global_load_dword v117, v[14:15], off
	global_load_dword v136, v[10:11], off
	v_lshlrev_b64 v[68:69], 9, v[36:37]
	s_and_saveexec_b64 s[24:25], s[4:5]
	s_cbranch_execz .LBB0_314
	v_lshl_add_u64 v[10:11], v[2:3], 0, v[68:69]
	global_load_dword v86, v[10:11], off
.LBB0_314:
	s_or_b64 exec, exec, s[24:25]
	s_add_i32 s24, s26, 10
	s_add_i32 s27, s27, 1
	v_mov_b32_e32 v10, s24
	v_mov_b32_e32 v11, s27
	v_cndmask_b32_e32 v10, v10, v11, vcc
	v_add_u32_e32 v34, v10, v79
	v_ashrrev_i32_e32 v35, 31, v34
	v_lshlrev_b64 v[10:11], 16, v[34:35]
	v_lshl_add_u64 v[10:11], v[0:1], 0, v[10:11]
	global_load_dword v98, v[10:11], off
	v_lshlrev_b64 v[10:11], 2, v[34:35]
	v_lshl_add_u64 v[14:15], s[18:19], 0, v[10:11]
	v_lshl_add_u64 v[10:11], s[20:21], 0, v[10:11]
	global_load_dword v115, v[14:15], off
	global_load_dword v135, v[10:11], off
	v_mov_b32_e32 v85, 0
	v_lshlrev_b64 v[66:67], 9, v[34:35]
	v_mov_b32_e32 v120, 0
	s_and_saveexec_b64 s[24:25], s[4:5]
	s_cbranch_execz .LBB0_316
	v_lshl_add_u64 v[10:11], v[2:3], 0, v[66:67]
	global_load_dword v120, v[10:11], off
.LBB0_316:
	s_or_b64 exec, exec, s[24:25]
	s_add_i32 s24, s26, 9
	s_add_i32 s27, s27, 1
	v_mov_b32_e32 v10, s24
	v_mov_b32_e32 v11, s27
	v_cndmask_b32_e32 v10, v10, v11, vcc
	v_add_u32_e32 v32, v10, v79
	v_ashrrev_i32_e32 v33, 31, v32
	v_lshlrev_b64 v[10:11], 16, v[32:33]
	v_lshl_add_u64 v[10:11], v[0:1], 0, v[10:11]
	global_load_dword v97, v[10:11], off
	v_lshlrev_b64 v[10:11], 2, v[32:33]
	v_lshl_add_u64 v[14:15], s[18:19], 0, v[10:11]
	v_lshl_add_u64 v[10:11], s[20:21], 0, v[10:11]
	global_load_dword v113, v[14:15], off
	global_load_dword v134, v[10:11], off
	v_lshlrev_b64 v[64:65], 9, v[32:33]
	s_and_saveexec_b64 s[24:25], s[4:5]
	s_cbranch_execz .LBB0_318
	v_lshl_add_u64 v[10:11], v[2:3], 0, v[64:65]
	global_load_dword v85, v[10:11], off
; __device__ __forceinline__ void scan_phase(const Bufs& B) {
;     ...
;             for (int u = 0; u < 16; ++u) { const int ch = dir ? 63 - (s0 + u) : s0 + u, it = dh * 64 + ch;
;                 cl[u] = B.CLOC[(size_t)it * 16384 + idx]; ml[u] = B.MLOC[it]; bl[u] = B.BLAST[it]; nl[u] = idx < 128 ? B.NLOC[(size_t)it * 128 + idx] : 0.f; }
.LBB0_318:
	s_or_b64 exec, exec, s[24:25]
	s_add_i32 s24, s26, 8
	s_add_i32 s27, s27, 1
	v_mov_b32_e32 v10, s24
	v_mov_b32_e32 v11, s27
	v_cndmask_b32_e32 v10, v10, v11, vcc
	v_add_u32_e32 v30, v10, v79
	v_ashrrev_i32_e32 v31, 31, v30
	v_lshlrev_b64 v[10:11], 16, v[30:31]
	v_lshl_add_u64 v[10:11], v[0:1], 0, v[10:11]
	global_load_dword v96, v[10:11], off
	v_lshlrev_b64 v[10:11], 2, v[30:31]
	v_lshl_add_u64 v[14:15], s[18:19], 0, v[10:11]
	v_lshl_add_u64 v[10:11], s[20:21], 0, v[10:11]
	global_load_dword v111, v[14:15], off
	global_load_dword v133, v[10:11], off
	v_mov_b32_e32 v83, 0
	v_lshlrev_b64 v[62:63], 9, v[30:31]
	v_mov_b32_e32 v116, 0
	s_and_saveexec_b64 s[24:25], s[4:5]
	s_cbranch_execz .LBB0_320
	v_lshl_add_u64 v[10:11], v[2:3], 0, v[62:63]
	global_load_dword v116, v[10:11], off
.LBB0_320:
	s_or_b64 exec, exec, s[24:25]
	s_add_i32 s24, s26, 7
	s_add_i32 s27, s27, 1
	v_mov_b32_e32 v10, s24
	v_mov_b32_e32 v11, s27
	v_cndmask_b32_e32 v10, v10, v11, vcc
	v_add_u32_e32 v28, v10, v79
	v_ashrrev_i32_e32 v29, 31, v28
	v_lshlrev_b64 v[10:11], 16, v[28:29]
	v_lshl_add_u64 v[10:11], v[0:1], 0, v[10:11]
	global_load_dword v94, v[10:11], off
	v_lshlrev_b64 v[10:11], 2, v[28:29]
	v_lshl_add_u64 v[14:15], s[18:19], 0, v[10:11]
	v_lshl_add_u64 v[10:11], s[20:21], 0, v[10:11]
	global_load_dword v110, v[14:15], off
	global_load_dword v132, v[10:11], off
	v_lshlrev_b64 v[60:61], 9, v[28:29]
	s_and_saveexec_b64 s[24:25], s[4:5]
	s_cbranch_execz .LBB0_322
	v_lshl_add_u64 v[10:11], v[2:3], 0, v[60:61]
	global_load_dword v83, v[10:11], off
.LBB0_322:
	s_or_b64 exec, exec, s[24:25]
	s_add_i32 s24, s26, 6
	s_add_i32 s27, s27, 1
	v_mov_b32_e32 v10, s24
	v_mov_b32_e32 v11, s27
	v_cndmask_b32_e32 v10, v10, v11, vcc
	v_add_u32_e32 v26, v10, v79
	v_ashrrev_i32_e32 v27, 31, v26
	v_lshlrev_b64 v[10:11], 16, v[26:27]
	v_lshl_add_u64 v[10:11], v[0:1], 0, v[10:11]
	global_load_dword v93, v[10:11], off
	v_lshlrev_b64 v[10:11], 2, v[26:27]
	v_lshl_add_u64 v[14:15], s[18:19], 0, v[10:11]
	v_lshl_add_u64 v[10:11], s[20:21], 0, v[10:11]
	global_load_dword v108, v[14:15], off
	global_load_dword v130, v[10:11], off
	v_mov_b32_e32 v82, 0
	v_lshlrev_b64 v[58:59], 9, v[26:27]
	v_mov_b32_e32 v112, 0
	s_and_saveexec_b64 s[24:25], s[4:5]
	s_cbranch_execz .LBB0_324
	v_lshl_add_u64 v[10:11], v[2:3], 0, v[58:59]
	global_load_dword v112, v[10:11], off
.LBB0_324:
	s_or_b64 exec, exec, s[24:25]
	s_add_i32 s24, s26, 5
	s_add_i32 s27, s27, 1
	v_mov_b32_e32 v10, s24
	v_mov_b32_e32 v11, s27
	v_cndmask_b32_e32 v10, v10, v11, vcc
	v_add_u32_e32 v24, v10, v79
	v_ashrrev_i32_e32 v25, 31, v24
	v_lshlrev_b64 v[10:11], 16, v[24:25]
	v_lshl_add_u64 v[10:11], v[0:1], 0, v[10:11]
	global_load_dword v92, v[10:11], off
	v_lshlrev_b64 v[10:11], 2, v[24:25]
	v_lshl_add_u64 v[14:15], s[18:19], 0, v[10:11]
	v_lshl_add_u64 v[10:11], s[20:21], 0, v[10:11]
	global_load_dword v107, v[14:15], off
	global_load_dword v128, v[10:11], off
	v_lshlrev_b64 v[56:57], 9, v[24:25]
	s_and_saveexec_b64 s[24:25], s[4:5]
	s_cbranch_execz .LBB0_326
	v_lshl_add_u64 v[10:11], v[2:3], 0, v[56:57]
	global_load_dword v82, v[10:11], off
.LBB0_326:
	s_or_b64 exec, exec, s[24:25]
	s_add_i32 s24, s26, 4
	s_add_i32 s27, s27, 1
	v_mov_b32_e32 v10, s24
	v_mov_b32_e32 v11, s27
	v_cndmask_b32_e32 v10, v10, v11, vcc
	v_add_u32_e32 v22, v10, v79
	v_ashrrev_i32_e32 v23, 31, v22
	v_lshlrev_b64 v[10:11], 16, v[22:23]
	v_lshl_add_u64 v[10:11], v[0:1], 0, v[10:11]
	global_load_dword v90, v[10:11], off
	v_lshlrev_b64 v[10:11], 2, v[22:23]
	v_lshl_add_u64 v[14:15], s[18:19], 0, v[10:11]
	v_lshl_add_u64 v[10:11], s[20:21], 0, v[10:11]
	global_load_dword v105, v[14:15], off
	global_load_dword v127, v[10:11], off
	v_mov_b32_e32 v80, 0
	v_lshlrev_b64 v[54:55], 9, v[22:23]
	v_mov_b32_e32 v109, 0
	s_and_saveexec_b64 s[24:25], s[4:5]
	s_cbranch_execz .LBB0_328
	v_lshl_add_u64 v[10:11], v[2:3], 0, v[54:55]
	global_load_dword v109, v[10:11], off
.LBB0_328:
	s_or_b64 exec, exec, s[24:25]
	s_add_i32 s24, s26, 3
	s_add_i32 s27, s27, 1
	v_mov_b32_e32 v10, s24
	v_mov_b32_e32 v11, s27
	v_cndmask_b32_e32 v10, v10, v11, vcc
	v_add_u32_e32 v20, v10, v79
	v_ashrrev_i32_e32 v21, 31, v20
	v_lshlrev_b64 v[10:11], 16, v[20:21]
	v_lshl_add_u64 v[10:11], v[0:1], 0, v[10:11]
	global_load_dword v89, v[10:11], off
	v_lshlrev_b64 v[10:11], 2, v[20:21]
	v_lshl_add_u64 v[14:15], s[18:19], 0, v[10:11]
	v_lshl_add_u64 v[10:11], s[20:21], 0, v[10:11]
	global_load_dword v103, v[14:15], off
	global_load_dword v124, v[10:11], off
	v_lshlrev_b64 v[52:53], 9, v[20:21]
	s_and_saveexec_b64 s[24:25], s[4:5]
	s_cbranch_execz .LBB0_330
	v_lshl_add_u64 v[10:11], v[2:3], 0, v[52:53]
	global_load_dword v80, v[10:11], off
.LBB0_330:
	s_or_b64 exec, exec, s[24:25]
	s_add_i32 s24, s26, 2
	s_add_i32 s27, s27, 1
	v_mov_b32_e32 v10, s24
	v_mov_b32_e32 v11, s27
	v_cndmask_b32_e32 v10, v10, v11, vcc
	v_add_u32_e32 v18, v10, v79
	v_ashrrev_i32_e32 v19, 31, v18
	v_lshlrev_b64 v[10:11], 16, v[18:19]
	v_lshl_add_u64 v[10:11], v[0:1], 0, v[10:11]
	global_load_dword v88, v[10:11], off
	v_lshlrev_b64 v[10:11], 2, v[18:19]
	v_lshl_add_u64 v[14:15], s[18:19], 0, v[10:11]
	v_lshl_add_u64 v[10:11], s[20:21], 0, v[10:11]
	global_load_dword v101, v[14:15], off
	global_load_dword v122, v[10:11], off
	v_mov_b32_e32 v81, 0
	v_lshlrev_b64 v[50:51], 9, v[18:19]
	v_mov_b32_e32 v106, 0
	s_and_saveexec_b64 s[24:25], s[4:5]
	s_cbranch_execz .LBB0_332
	v_lshl_add_u64 v[10:11], v[2:3], 0, v[50:51]
	global_load_dword v106, v[10:11], off
; __device__ __forceinline__ bf16_t f2bf(float f) { return (bf16_t)(cvt_pk_bf16(f, 0.f) & 0xffffu); }
; __device__ __forceinline__ void scan_phase(const Bufs& B) {
;     ...
;             for (int u = 0; u < 16; ++u) { const int ch = dir ? 63 - (s0 + u) : s0 + u, it = dh * 64 + ch;
;                 cl[u] = B.CLOC[(size_t)it * 16384 + idx]; ml[u] = B.MLOC[it]; bl[u] = B.BLAST[it]; nl[u] = idx < 128 ? B.NLOC[(size_t)it * 128 + idx] : 0.f; }
; #pragma unroll
;             for (int u = 0; u < 16; ++u) { const int ch = dir ? 63 - (s0 + u) : s0 + u, it = dh * 64 + ch;
;                 B.CST[(size_t)it * 16384 + idx] = f2bf(cst);
;                 if (idx < 128) { B.NST[(size_t)it * 128 + idx] = nst; if (idx == 0) B.MST[it] = m; }
;                 const float mnew = fmaxf(bl[u] + m, ml[u]), a = __expf(bl[u] + m - mnew), g = __expf(ml[u] - mnew);
;                 cst = a * cst + g * cl[u]; nst = a * nst + g * nl[u]; m = mnew; }
.LBB0_332:
	s_or_b64 exec, exec, s[24:25]
	s_add_i32 s24, s26, 1
	s_add_i32 s27, s27, 1
	v_mov_b32_e32 v10, s24
	v_mov_b32_e32 v11, s27
	v_cndmask_b32_e32 v10, v10, v11, vcc
	v_add_u32_e32 v16, v10, v79
	v_ashrrev_i32_e32 v17, 31, v16
	v_lshlrev_b64 v[10:11], 16, v[16:17]
	v_lshl_add_u64 v[10:11], v[0:1], 0, v[10:11]
	global_load_dword v91, v[10:11], off
	v_lshlrev_b64 v[10:11], 2, v[16:17]
	v_lshl_add_u64 v[14:15], s[18:19], 0, v[10:11]
	v_lshl_add_u64 v[10:11], s[20:21], 0, v[10:11]
	global_load_dword v99, v[14:15], off
	global_load_dword v119, v[10:11], off
	v_lshlrev_b64 v[48:49], 9, v[16:17]
	s_and_saveexec_b64 s[24:25], s[4:5]
	s_cbranch_execz .LBB0_334
	v_lshl_add_u64 v[10:11], v[2:3], 0, v[48:49]
	global_load_dword v81, v[10:11], off
.LBB0_334:
	s_or_b64 exec, exec, s[24:25]
	s_add_i32 s27, s27, 1
	v_mov_b32_e32 v10, s26
	v_mov_b32_e32 v11, s27
	v_cndmask_b32_e32 v10, v10, v11, vcc
	v_add_u32_e32 v14, v10, v79
	v_ashrrev_i32_e32 v15, 31, v14
	v_lshlrev_b64 v[10:11], 16, v[14:15]
	v_lshlrev_b64 v[46:47], 2, v[14:15]
	v_lshl_add_u64 v[10:11], v[0:1], 0, v[10:11]
	v_lshl_add_u64 v[142:143], s[18:19], 0, v[46:47]
	v_lshl_add_u64 v[46:47], s[20:21], 0, v[46:47]
	global_load_dword v11, v[10:11], off
	s_nop 0
	global_load_dword v95, v[142:143], off
	global_load_dword v114, v[46:47], off
	v_mov_b32_e32 v10, 0
	v_lshlrev_b64 v[46:47], 9, v[14:15]
	s_and_saveexec_b64 s[24:25], s[4:5]
	s_cbranch_execz .LBB0_336
	v_lshl_add_u64 v[142:143], v[2:3], 0, v[46:47]
	global_load_dword v10, v[142:143], off
.LBB0_336:
	s_or_b64 exec, exec, s[24:25]
	v_lshlrev_b64 v[142:143], 15, v[44:45]
	v_lshl_add_u64 v[142:143], v[4:5], 0, v[142:143]
	v_cvt_pk_bf16_f32 v141, v12, v195
	global_store_short v[142:143], v141, off
	s_and_saveexec_b64 s[24:25], s[4:5]
	s_cbranch_execz .LBB0_339
	v_lshl_add_u64 v[76:77], v[6:7], 0, v[76:77]
	global_store_dword v[76:77], v8, off
	s_and_b64 exec, exec, s[6:7]
	s_cbranch_execz .LBB0_339
	v_readlane_b32 s28, v254, 35
	v_readlane_b32 s29, v254, 36
	s_nop 1
	v_lshl_add_u64 v[44:45], v[44:45], 2, s[28:29]
	global_store_dword v[44:45], v84, off
.LBB0_339:
	s_or_b64 exec, exec, s[24:25]
	s_waitcnt vmcnt(0) lgkmcnt(0)
	v_add_f32_e32 v44, v84, v140
	v_max_f32_e32 v45, v126, v126
	v_max_f32_e32 v45, v44, v45
	v_sub_f32_e32 v76, v126, v45
	v_sub_f32_e32 v44, v44, v45
	v_mul_f32_e32 v76, 0x3fb8aa3b, v76
	v_mul_f32_e32 v44, 0x3fb8aa3b, v44
	v_exp_f32_e32 v77, v76
	v_exp_f32_e32 v76, v44
	v_mul_f32_e32 v44, v13, v77
	v_pk_fma_f32 v[12:13], v[12:13], v[76:77], v[44:45] op_sel_hi:[1,1,0]
	v_mul_f32_e32 v44, v77, v131
	v_fmac_f32_e32 v44, v8, v76
	v_lshlrev_b64 v[76:77], 15, v[42:43]
	v_lshl_add_u64 v[76:77], v[4:5], 0, v[76:77]
	v_cvt_pk_bf16_f32 v8, v12, v195
	global_store_short v[76:77], v8, off
	s_and_saveexec_b64 s[24:25], s[4:5]
	s_cbranch_execz .LBB0_342
	v_lshl_add_u64 v[74:75], v[6:7], 0, v[74:75]
	global_store_dword v[74:75], v44, off
	s_and_b64 exec, exec, s[6:7]
	s_cbranch_execz .LBB0_342
	v_readlane_b32 s28, v254, 35
	v_readlane_b32 s29, v254, 36
	s_nop 1
	v_lshl_add_u64 v[42:43], v[42:43], 2, s[28:29]
	global_store_dword v[42:43], v45, off
.LBB0_342:
	s_or_b64 exec, exec, s[24:25]
	v_add_f32_e32 v8, v45, v139
	v_max_f32_e32 v13, v123, v123
	v_max_f32_e32 v42, v8, v13
	v_sub_f32_e32 v13, v123, v42
	v_sub_f32_e32 v8, v8, v42
	v_mul_f32_e32 v13, 0x3fb8aa3b, v13
	v_mul_f32_e32 v8, 0x3fb8aa3b, v8
	v_exp_f32_e32 v75, v13
	v_exp_f32_e32 v74, v8
	v_mov_b32_e32 v13, v9
	v_mul_f32_e32 v8, v9, v75
	v_pk_fma_f32 v[8:9], v[12:13], v[74:75], v[8:9] op_sel_hi:[1,1,0]
	v_mul_f32_e32 v12, v75, v129
	v_fmac_f32_e32 v12, v44, v74
	v_lshlrev_b64 v[44:45], 15, v[40:41]
	v_lshl_add_u64 v[44:45], v[4:5], 0, v[44:45]
	v_cvt_pk_bf16_f32 v9, v8, v195
	global_store_short v[44:45], v9, off
	s_and_saveexec_b64 s[24:25], s[4:5]
	s_cbranch_execz .LBB0_345
	v_lshl_add_u64 v[44:45], v[6:7], 0, v[72:73]
	global_store_dword v[44:45], v12, off
	s_and_b64 exec, exec, s[6:7]
	s_cbranch_execz .LBB0_345
	v_readlane_b32 s28, v254, 35
	v_readlane_b32 s29, v254, 36
	s_nop 1
	v_lshl_add_u64 v[40:41], v[40:41], 2, s[28:29]
	global_store_dword v[40:41], v42, off
.LBB0_345:
	s_or_b64 exec, exec, s[24:25]
	v_add_f32_e32 v9, v42, v138
	v_max_f32_e32 v13, v121, v121
	v_max_f32_e32 v40, v9, v13
	v_sub_f32_e32 v13, v121, v40
	v_sub_f32_e32 v9, v9, v40
	v_mul_f32_e32 v13, 0x3fb8aa3b, v13
	v_mul_f32_e32 v9, 0x3fb8aa3b, v9
	v_exp_f32_e32 v43, v13
	v_exp_f32_e32 v42, v9
	v_mov_b32_e32 v9, v104
	v_mul_f32_e32 v44, v104, v43
	v_mul_f32_e32 v13, v43, v87
	v_pk_fma_f32 v[8:9], v[8:9], v[42:43], v[44:45] op_sel_hi:[1,1,0]
	v_fmac_f32_e32 v13, v12, v42
	v_lshlrev_b64 v[42:43], 15, v[38:39]
	v_lshl_add_u64 v[42:43], v[4:5], 0, v[42:43]
	v_cvt_pk_bf16_f32 v9, v8, v195
	global_store_short v[42:43], v9, off
	s_and_saveexec_b64 s[24:25], s[4:5]
	s_cbranch_execz .LBB0_348
	v_lshl_add_u64 v[42:43], v[6:7], 0, v[70:71]
	global_store_dword v[42:43], v13, off
	s_and_b64 exec, exec, s[6:7]
	s_cbranch_execz .LBB0_348
	v_readlane_b32 s28, v254, 35
	v_readlane_b32 s29, v254, 36
	s_nop 1
	v_lshl_add_u64 v[38:39], v[38:39], 2, s[28:29]
	global_store_dword v[38:39], v40, off
.LBB0_348:
	s_or_b64 exec, exec, s[24:25]
	v_add_f32_e32 v9, v40, v137
	v_max_f32_e32 v12, v118, v118
	v_max_f32_e32 v38, v9, v12
	v_sub_f32_e32 v12, v118, v38
	v_sub_f32_e32 v9, v9, v38
	v_mul_f32_e32 v12, 0x3fb8aa3b, v12
	v_mul_f32_e32 v9, 0x3fb8aa3b, v9
	v_exp_f32_e32 v41, v12
	v_exp_f32_e32 v40, v9
	v_mov_b32_e32 v9, v102
	v_mul_f32_e32 v12, v102, v41
	v_pk_fma_f32 v[8:9], v[8:9], v[40:41], v[12:13] op_sel_hi:[1,1,0]
	v_mul_f32_e32 v12, v41, v125
	v_fmac_f32_e32 v12, v13, v40
	v_lshlrev_b64 v[40:41], 15, v[36:37]
	v_lshl_add_u64 v[40:41], v[4:5], 0, v[40:41]
	v_cvt_pk_bf16_f32 v9, v8, v195
	global_store_short v[40:41], v9, off
	s_and_saveexec_b64 s[24:25], s[4:5]
	s_cbranch_execz .LBB0_351
	v_lshl_add_u64 v[40:41], v[6:7], 0, v[68:69]
	global_store_dword v[40:41], v12, off
	s_and_b64 exec, exec, s[6:7]
	s_cbranch_execz .LBB0_351
	v_readlane_b32 s28, v254, 35
	v_readlane_b32 s29, v254, 36
	s_nop 1
	v_lshl_add_u64 v[36:37], v[36:37], 2, s[28:29]
	global_store_dword v[36:37], v38, off
; __device__ __forceinline__ bf16_t f2bf(float f) { return (bf16_t)(cvt_pk_bf16(f, 0.f) & 0xffffu); }
; __device__ __forceinline__ void scan_phase(const Bufs& B) {
;     ...
;             for (int u = 0; u < 16; ++u) { const int ch = dir ? 63 - (s0 + u) : s0 + u, it = dh * 64 + ch;
;                 cl[u] = B.CLOC[(size_t)it * 16384 + idx]; ml[u] = B.MLOC[it]; bl[u] = B.BLAST[it]; nl[u] = idx < 128 ? B.NLOC[(size_t)it * 128 + idx] : 0.f; }
; #pragma unroll
;             for (int u = 0; u < 16; ++u) { const int ch = dir ? 63 - (s0 + u) : s0 + u, it = dh * 64 + ch;
;                 B.CST[(size_t)it * 16384 + idx] = f2bf(cst);
;                 if (idx < 128) { B.NST[(size_t)it * 128 + idx] = nst; if (idx == 0) B.MST[it] = m; }
;                 const float mnew = fmaxf(bl[u] + m, ml[u]), a = __expf(bl[u] + m - mnew), g = __expf(ml[u] - mnew);
;                 cst = a * cst + g * cl[u]; nst = a * nst + g * nl[u]; m = mnew; }
.LBB0_351:
	s_or_b64 exec, exec, s[24:25]
	v_add_f32_e32 v9, v38, v136
	v_max_f32_e32 v13, v117, v117
	v_max_f32_e32 v36, v9, v13
	v_sub_f32_e32 v13, v117, v36
	v_sub_f32_e32 v9, v9, v36
	v_mul_f32_e32 v13, 0x3fb8aa3b, v13
	v_mul_f32_e32 v9, 0x3fb8aa3b, v9
	v_exp_f32_e32 v39, v13
	v_exp_f32_e32 v38, v9
	v_mov_b32_e32 v9, v100
	v_mul_f32_e32 v40, v100, v39
	v_mul_f32_e32 v13, v39, v86
	v_pk_fma_f32 v[8:9], v[8:9], v[38:39], v[40:41] op_sel_hi:[1,1,0]
	v_fmac_f32_e32 v13, v12, v38
	v_lshlrev_b64 v[38:39], 15, v[34:35]
	v_lshl_add_u64 v[38:39], v[4:5], 0, v[38:39]
	v_cvt_pk_bf16_f32 v9, v8, v195
	global_store_short v[38:39], v9, off
	s_and_saveexec_b64 s[24:25], s[4:5]
	s_cbranch_execz .LBB0_354
	v_lshl_add_u64 v[38:39], v[6:7], 0, v[66:67]
	global_store_dword v[38:39], v13, off
	s_and_b64 exec, exec, s[6:7]
	s_cbranch_execz .LBB0_354
	v_readlane_b32 s28, v254, 35
	v_readlane_b32 s29, v254, 36
	s_nop 1
	v_lshl_add_u64 v[34:35], v[34:35], 2, s[28:29]
	global_store_dword v[34:35], v36, off
.LBB0_354:
	s_or_b64 exec, exec, s[24:25]
	v_add_f32_e32 v9, v36, v135
	v_max_f32_e32 v12, v115, v115
	v_max_f32_e32 v34, v9, v12
	v_sub_f32_e32 v12, v115, v34
	v_sub_f32_e32 v9, v9, v34
	v_mul_f32_e32 v12, 0x3fb8aa3b, v12
	v_mul_f32_e32 v9, 0x3fb8aa3b, v9
	v_exp_f32_e32 v37, v12
	v_exp_f32_e32 v36, v9
	v_mov_b32_e32 v9, v98
	v_mul_f32_e32 v12, v98, v37
	v_pk_fma_f32 v[8:9], v[8:9], v[36:37], v[12:13] op_sel_hi:[1,1,0]
	v_mul_f32_e32 v12, v37, v120
	v_fmac_f32_e32 v12, v13, v36
	v_lshlrev_b64 v[36:37], 15, v[32:33]
	v_lshl_add_u64 v[36:37], v[4:5], 0, v[36:37]
	v_cvt_pk_bf16_f32 v9, v8, v195
	global_store_short v[36:37], v9, off
	s_and_saveexec_b64 s[24:25], s[4:5]
	s_cbranch_execz .LBB0_357
	v_lshl_add_u64 v[36:37], v[6:7], 0, v[64:65]
	global_store_dword v[36:37], v12, off
	s_and_b64 exec, exec, s[6:7]
	s_cbranch_execz .LBB0_357
	v_readlane_b32 s28, v254, 35
	v_readlane_b32 s29, v254, 36
	s_nop 1
	v_lshl_add_u64 v[32:33], v[32:33], 2, s[28:29]
	global_store_dword v[32:33], v34, off
.LBB0_357:
	s_or_b64 exec, exec, s[24:25]
	v_add_f32_e32 v9, v34, v134
	v_max_f32_e32 v13, v113, v113
	v_max_f32_e32 v32, v9, v13
	v_sub_f32_e32 v13, v113, v32
	v_sub_f32_e32 v9, v9, v32
	v_mul_f32_e32 v13, 0x3fb8aa3b, v13
	v_mul_f32_e32 v9, 0x3fb8aa3b, v9
	v_exp_f32_e32 v35, v13
	v_exp_f32_e32 v34, v9
	v_mov_b32_e32 v9, v97
	v_mul_f32_e32 v36, v97, v35
	v_mul_f32_e32 v13, v35, v85
	v_pk_fma_f32 v[8:9], v[8:9], v[34:35], v[36:37] op_sel_hi:[1,1,0]
	v_fmac_f32_e32 v13, v12, v34
	v_lshlrev_b64 v[34:35], 15, v[30:31]
	v_lshl_add_u64 v[34:35], v[4:5], 0, v[34:35]
	v_cvt_pk_bf16_f32 v9, v8, v195
	global_store_short v[34:35], v9, off
	s_and_saveexec_b64 s[24:25], s[4:5]
	s_cbranch_execz .LBB0_360
	v_lshl_add_u64 v[34:35], v[6:7], 0, v[62:63]
	global_store_dword v[34:35], v13, off
	s_and_b64 exec, exec, s[6:7]
	s_cbranch_execz .LBB0_360
	v_readlane_b32 s28, v254, 35
	v_readlane_b32 s29, v254, 36
	s_nop 1
	v_lshl_add_u64 v[30:31], v[30:31], 2, s[28:29]
	global_store_dword v[30:31], v32, off
.LBB0_360:
	s_or_b64 exec, exec, s[24:25]
	v_add_f32_e32 v9, v32, v133
	v_max_f32_e32 v12, v111, v111
	v_max_f32_e32 v30, v9, v12
	v_sub_f32_e32 v12, v111, v30
	v_sub_f32_e32 v9, v9, v30
	v_mul_f32_e32 v12, 0x3fb8aa3b, v12
	v_mul_f32_e32 v9, 0x3fb8aa3b, v9
	v_exp_f32_e32 v33, v12
	v_exp_f32_e32 v32, v9
	v_mov_b32_e32 v9, v96
	v_mul_f32_e32 v12, v96, v33
	v_pk_fma_f32 v[8:9], v[8:9], v[32:33], v[12:13] op_sel_hi:[1,1,0]
	v_mul_f32_e32 v12, v33, v116
	v_fmac_f32_e32 v12, v13, v32
	v_lshlrev_b64 v[32:33], 15, v[28:29]
	v_lshl_add_u64 v[32:33], v[4:5], 0, v[32:33]
	v_cvt_pk_bf16_f32 v9, v8, v195
	global_store_short v[32:33], v9, off
	s_and_saveexec_b64 s[24:25], s[4:5]
	s_cbranch_execz .LBB0_363
	v_lshl_add_u64 v[32:33], v[6:7], 0, v[60:61]
	global_store_dword v[32:33], v12, off
	s_and_b64 exec, exec, s[6:7]
	s_cbranch_execz .LBB0_363
	v_readlane_b32 s28, v254, 35
	v_readlane_b32 s29, v254, 36
	s_nop 1
	v_lshl_add_u64 v[28:29], v[28:29], 2, s[28:29]
	global_store_dword v[28:29], v30, off
.LBB0_363:
	s_or_b64 exec, exec, s[24:25]
	v_add_f32_e32 v9, v30, v132
	v_max_f32_e32 v13, v110, v110
	v_max_f32_e32 v28, v9, v13
	v_sub_f32_e32 v13, v110, v28
	v_sub_f32_e32 v9, v9, v28
	v_mul_f32_e32 v13, 0x3fb8aa3b, v13
	v_mul_f32_e32 v9, 0x3fb8aa3b, v9
	v_exp_f32_e32 v31, v13
	v_exp_f32_e32 v30, v9
	v_mov_b32_e32 v9, v94
	v_mul_f32_e32 v32, v94, v31
	v_mul_f32_e32 v13, v31, v83
	v_pk_fma_f32 v[8:9], v[8:9], v[30:31], v[32:33] op_sel_hi:[1,1,0]
	v_fmac_f32_e32 v13, v12, v30
	v_lshlrev_b64 v[30:31], 15, v[26:27]
	v_lshl_add_u64 v[30:31], v[4:5], 0, v[30:31]
	v_cvt_pk_bf16_f32 v9, v8, v195
	global_store_short v[30:31], v9, off
	s_and_saveexec_b64 s[24:25], s[4:5]
	s_cbranch_execz .LBB0_366
	v_lshl_add_u64 v[30:31], v[6:7], 0, v[58:59]
	global_store_dword v[30:31], v13, off
	s_and_b64 exec, exec, s[6:7]
	s_cbranch_execz .LBB0_366
	v_readlane_b32 s28, v254, 35
	v_readlane_b32 s29, v254, 36
	s_nop 1
	v_lshl_add_u64 v[26:27], v[26:27], 2, s[28:29]
	global_store_dword v[26:27], v28, off
.LBB0_366:
	s_or_b64 exec, exec, s[24:25]
	v_add_f32_e32 v9, v28, v130
	v_max_f32_e32 v12, v108, v108
	v_max_f32_e32 v26, v9, v12
	v_sub_f32_e32 v12, v108, v26
	v_sub_f32_e32 v9, v9, v26
	v_mul_f32_e32 v12, 0x3fb8aa3b, v12
	v_mul_f32_e32 v9, 0x3fb8aa3b, v9
	v_exp_f32_e32 v29, v12
	v_exp_f32_e32 v28, v9
	v_mov_b32_e32 v9, v93
	v_mul_f32_e32 v12, v93, v29
	v_pk_fma_f32 v[8:9], v[8:9], v[28:29], v[12:13] op_sel_hi:[1,1,0]
	v_mul_f32_e32 v12, v29, v112
	v_fmac_f32_e32 v12, v13, v28
	v_lshlrev_b64 v[28:29], 15, v[24:25]
	v_lshl_add_u64 v[28:29], v[4:5], 0, v[28:29]
	v_cvt_pk_bf16_f32 v9, v8, v195
	global_store_short v[28:29], v9, off
	s_and_saveexec_b64 s[24:25], s[4:5]
	s_cbranch_execz .LBB0_369
	v_lshl_add_u64 v[28:29], v[6:7], 0, v[56:57]
	global_store_dword v[28:29], v12, off
	s_and_b64 exec, exec, s[6:7]
	s_cbranch_execz .LBB0_369
	v_readlane_b32 s28, v254, 35
	v_readlane_b32 s29, v254, 36
	s_nop 1
	v_lshl_add_u64 v[24:25], v[24:25], 2, s[28:29]
	global_store_dword v[24:25], v26, off
; __device__ __forceinline__ bf16_t f2bf(float f) { return (bf16_t)(cvt_pk_bf16(f, 0.f) & 0xffffu); }
; __device__ __forceinline__ void scan_phase(const Bufs& B) {
;     ...
;             for (int u = 0; u < 16; ++u) { const int ch = dir ? 63 - (s0 + u) : s0 + u, it = dh * 64 + ch;
;                 cl[u] = B.CLOC[(size_t)it * 16384 + idx]; ml[u] = B.MLOC[it]; bl[u] = B.BLAST[it]; nl[u] = idx < 128 ? B.NLOC[(size_t)it * 128 + idx] : 0.f; }
; #pragma unroll
;             for (int u = 0; u < 16; ++u) { const int ch = dir ? 63 - (s0 + u) : s0 + u, it = dh * 64 + ch;
;                 B.CST[(size_t)it * 16384 + idx] = f2bf(cst);
;                 if (idx < 128) { B.NST[(size_t)it * 128 + idx] = nst; if (idx == 0) B.MST[it] = m; }
;                 const float mnew = fmaxf(bl[u] + m, ml[u]), a = __expf(bl[u] + m - mnew), g = __expf(ml[u] - mnew);
;                 cst = a * cst + g * cl[u]; nst = a * nst + g * nl[u]; m = mnew; }
.LBB0_369:
	s_or_b64 exec, exec, s[24:25]
	v_add_f32_e32 v9, v26, v128
	v_max_f32_e32 v13, v107, v107
	v_max_f32_e32 v24, v9, v13
	v_sub_f32_e32 v13, v107, v24
	v_sub_f32_e32 v9, v9, v24
	v_mul_f32_e32 v13, 0x3fb8aa3b, v13
	v_mul_f32_e32 v9, 0x3fb8aa3b, v9
	v_exp_f32_e32 v27, v13
	v_exp_f32_e32 v26, v9
	v_mov_b32_e32 v9, v92
	v_mul_f32_e32 v28, v92, v27
	v_mul_f32_e32 v13, v27, v82
	v_pk_fma_f32 v[8:9], v[8:9], v[26:27], v[28:29] op_sel_hi:[1,1,0]
	v_fmac_f32_e32 v13, v12, v26
	v_lshlrev_b64 v[26:27], 15, v[22:23]
	v_lshl_add_u64 v[26:27], v[4:5], 0, v[26:27]
	v_cvt_pk_bf16_f32 v9, v8, v195
	global_store_short v[26:27], v9, off
	s_and_saveexec_b64 s[24:25], s[4:5]
	s_cbranch_execz .LBB0_372
	v_lshl_add_u64 v[26:27], v[6:7], 0, v[54:55]
	global_store_dword v[26:27], v13, off
	s_and_b64 exec, exec, s[6:7]
	s_cbranch_execz .LBB0_372
	v_readlane_b32 s28, v254, 35
	v_readlane_b32 s29, v254, 36
	s_nop 1
	v_lshl_add_u64 v[22:23], v[22:23], 2, s[28:29]
	global_store_dword v[22:23], v24, off
.LBB0_372:
	s_or_b64 exec, exec, s[24:25]
	v_add_f32_e32 v9, v24, v127
	v_max_f32_e32 v12, v105, v105
	v_max_f32_e32 v22, v9, v12
	v_sub_f32_e32 v12, v105, v22
	v_sub_f32_e32 v9, v9, v22
	v_mul_f32_e32 v12, 0x3fb8aa3b, v12
	v_mul_f32_e32 v9, 0x3fb8aa3b, v9
	v_exp_f32_e32 v25, v12
	v_exp_f32_e32 v24, v9
	v_mov_b32_e32 v9, v90
	v_mul_f32_e32 v12, v90, v25
	v_pk_fma_f32 v[8:9], v[8:9], v[24:25], v[12:13] op_sel_hi:[1,1,0]
	v_mul_f32_e32 v12, v25, v109
	v_fmac_f32_e32 v12, v13, v24
	v_lshlrev_b64 v[24:25], 15, v[20:21]
	v_lshl_add_u64 v[24:25], v[4:5], 0, v[24:25]
	v_cvt_pk_bf16_f32 v9, v8, v195
	global_store_short v[24:25], v9, off
	s_and_saveexec_b64 s[24:25], s[4:5]
	s_cbranch_execz .LBB0_375
	v_lshl_add_u64 v[24:25], v[6:7], 0, v[52:53]
	global_store_dword v[24:25], v12, off
	s_and_b64 exec, exec, s[6:7]
	s_cbranch_execz .LBB0_375
	v_readlane_b32 s28, v254, 35
	v_readlane_b32 s29, v254, 36
	s_nop 1
	v_lshl_add_u64 v[20:21], v[20:21], 2, s[28:29]
	global_store_dword v[20:21], v22, off
.LBB0_375:
	s_or_b64 exec, exec, s[24:25]
	v_add_f32_e32 v9, v22, v124
	v_max_f32_e32 v13, v103, v103
	v_max_f32_e32 v20, v9, v13
	v_sub_f32_e32 v13, v103, v20
	v_sub_f32_e32 v9, v9, v20
	v_mul_f32_e32 v13, 0x3fb8aa3b, v13
	v_mul_f32_e32 v9, 0x3fb8aa3b, v9
	v_exp_f32_e32 v23, v13
	v_exp_f32_e32 v22, v9
	v_mov_b32_e32 v9, v89
	v_mul_f32_e32 v24, v89, v23
	v_mul_f32_e32 v13, v23, v80
	v_pk_fma_f32 v[8:9], v[8:9], v[22:23], v[24:25] op_sel_hi:[1,1,0]
	v_fmac_f32_e32 v13, v12, v22
	v_lshlrev_b64 v[22:23], 15, v[18:19]
	v_lshl_add_u64 v[22:23], v[4:5], 0, v[22:23]
	v_cvt_pk_bf16_f32 v9, v8, v195
	global_store_short v[22:23], v9, off
	s_and_saveexec_b64 s[24:25], s[4:5]
	s_cbranch_execz .LBB0_378
	v_lshl_add_u64 v[22:23], v[6:7], 0, v[50:51]
	global_store_dword v[22:23], v13, off
	s_and_b64 exec, exec, s[6:7]
	s_cbranch_execz .LBB0_378
	v_readlane_b32 s28, v254, 35
	v_readlane_b32 s29, v254, 36
	s_nop 1
	v_lshl_add_u64 v[18:19], v[18:19], 2, s[28:29]
	global_store_dword v[18:19], v20, off
.LBB0_378:
	s_or_b64 exec, exec, s[24:25]
	v_add_f32_e32 v9, v20, v122
	v_max_f32_e32 v12, v101, v101
	v_max_f32_e32 v12, v9, v12
	v_sub_f32_e32 v18, v101, v12
	v_sub_f32_e32 v9, v9, v12
	v_mul_f32_e32 v18, 0x3fb8aa3b, v18
	v_mul_f32_e32 v9, 0x3fb8aa3b, v9
	v_exp_f32_e32 v21, v18
	v_exp_f32_e32 v20, v9
	v_mov_b32_e32 v9, v88
	v_mul_f32_e32 v18, v88, v21
	v_pk_fma_f32 v[8:9], v[8:9], v[20:21], v[18:19] op_sel_hi:[1,1,0]
	v_mul_f32_e32 v18, v21, v106
	v_fmac_f32_e32 v18, v13, v20
	v_lshlrev_b64 v[20:21], 15, v[16:17]
	v_lshl_add_u64 v[20:21], v[4:5], 0, v[20:21]
	v_cvt_pk_bf16_f32 v9, v8, v195
	global_store_short v[20:21], v9, off
	s_and_saveexec_b64 s[24:25], s[4:5]
	s_cbranch_execz .LBB0_381
	v_lshl_add_u64 v[20:21], v[6:7], 0, v[48:49]
	global_store_dword v[20:21], v18, off
	s_and_b64 exec, exec, s[6:7]
	s_cbranch_execz .LBB0_381
	v_readlane_b32 s28, v254, 35
	v_readlane_b32 s29, v254, 36
	s_nop 1
	v_lshl_add_u64 v[16:17], v[16:17], 2, s[28:29]
	global_store_dword v[16:17], v12, off
.LBB0_381:
	s_or_b64 exec, exec, s[24:25]
	v_add_f32_e32 v9, v12, v119
	v_max_f32_e32 v12, v99, v99
	v_max_f32_e32 v12, v9, v12
	v_sub_f32_e32 v9, v9, v12
	v_mul_f32_e32 v9, 0x3fb8aa3b, v9
	v_exp_f32_e32 v16, v9
	v_sub_f32_e32 v9, v99, v12
	v_mul_f32_e32 v9, 0x3fb8aa3b, v9
	v_exp_f32_e32 v17, v9
	v_mov_b32_e32 v9, v91
	v_pk_mul_f32 v[8:9], v[8:9], v[16:17]
	v_mul_f32_e32 v16, v18, v16
	v_mul_f32_e32 v18, v17, v81
	v_mov_b32_e32 v17, v8
	v_mov_b32_e32 v19, v9
	v_pk_add_f32 v[8:9], v[16:17], v[18:19]
	v_lshlrev_b64 v[16:17], 15, v[14:15]
	v_lshl_add_u64 v[16:17], v[4:5], 0, v[16:17]
	v_cvt_pk_bf16_f32 v13, v9, v195
	global_store_short v[16:17], v13, off
	s_and_saveexec_b64 s[24:25], s[4:5]
	s_cbranch_execz .LBB0_303
	v_lshl_add_u64 v[16:17], v[6:7], 0, v[46:47]
	global_store_dword v[16:17], v8, off
	s_and_b64 exec, exec, s[6:7]
	s_cbranch_execz .LBB0_303
	v_readlane_b32 s28, v254, 35
	v_readlane_b32 s29, v254, 36
	s_nop 1
	v_lshl_add_u64 v[14:15], v[14:15], 2, s[28:29]
	global_store_dword v[14:15], v12, off
	s_branch .LBB0_303

; __device__ __forceinline__ bf16_t f2bf(float f) { return (bf16_t)(cvt_pk_bf16(f, 0.f) & 0xffffu); }
; __device__ __forceinline__ void scan_phase(const Bufs& B) {
;     ...
; #pragma unroll 1
;         for (int s0 = 0; s0 < 64; s0 += 16) {
;             float rl[16];
; #pragma unroll
;             for (int u = 0; u < 16; ++u) { const int ch = dir ? 63 - (s0 + u) : s0 + u; rl[u] = B.RLOC[(size_t)(dh * 64 + ch) * 8192 + idx]; }
; #pragma unroll
;             for (int u = 0; u < 16; ++u) { const int ch = dir ? 63 - (s0 + u) : s0 + u; B.RST[(size_t)(dh * 64 + ch) * 8192 + idx] = f2bf(r); r = cd * r + rl[u]; }
.LBB0_386:
	s_add_i32 s1, s0, 15
	v_mov_b32_e32 v4, s1
	v_mov_b32_e32 v5, s6
	v_cndmask_b32_e32 v4, v4, v5, vcc
	v_add_u32_e32 v4, v4, v27
	v_ashrrev_i32_e32 v5, 31, v4
	v_lshlrev_b64 v[6:7], 15, v[4:5]
	v_lshl_add_u64 v[6:7], v[0:1], 0, v[6:7]
	s_add_i32 s1, s0, 14
	s_add_i32 s7, s6, 1
	global_load_dword v30, v[6:7], off
	v_mov_b32_e32 v6, s1
	v_mov_b32_e32 v7, s7
	v_cndmask_b32_e32 v6, v6, v7, vcc
	v_add_u32_e32 v6, v6, v27
	v_ashrrev_i32_e32 v7, 31, v6
	v_lshlrev_b64 v[8:9], 15, v[6:7]
	v_lshl_add_u64 v[8:9], v[0:1], 0, v[8:9]
	s_add_i32 s1, s0, 13
	s_add_i32 s7, s6, 2
	global_load_dword v31, v[8:9], off
	v_mov_b32_e32 v8, s1
	v_mov_b32_e32 v9, s7
	v_cndmask_b32_e32 v8, v8, v9, vcc
	v_add_u32_e32 v8, v8, v27
	v_ashrrev_i32_e32 v9, 31, v8
	v_lshlrev_b64 v[10:11], 15, v[8:9]
	v_lshl_add_u64 v[10:11], v[0:1], 0, v[10:11]
	s_add_i32 s1, s0, 12
	s_add_i32 s7, s6, 3
	global_load_dword v32, v[10:11], off
	v_mov_b32_e32 v10, s1
	v_mov_b32_e32 v11, s7
	v_cndmask_b32_e32 v10, v10, v11, vcc
	v_add_u32_e32 v10, v10, v27
	v_ashrrev_i32_e32 v11, 31, v10
	v_lshlrev_b64 v[12:13], 15, v[10:11]
	v_lshl_add_u64 v[12:13], v[0:1], 0, v[12:13]
	s_add_i32 s1, s0, 11
	s_add_i32 s7, s6, 4
	global_load_dword v33, v[12:13], off
	v_mov_b32_e32 v12, s1
	v_mov_b32_e32 v13, s7
	v_cndmask_b32_e32 v12, v12, v13, vcc
	v_add_u32_e32 v12, v12, v27
	v_ashrrev_i32_e32 v13, 31, v12
	v_lshlrev_b64 v[14:15], 15, v[12:13]
	v_lshl_add_u64 v[14:15], v[0:1], 0, v[14:15]
	s_add_i32 s1, s0, 10
	s_add_i32 s7, s6, 5
	global_load_dword v34, v[14:15], off
	v_mov_b32_e32 v14, s1
	v_mov_b32_e32 v15, s7
	v_cndmask_b32_e32 v14, v14, v15, vcc
	v_add_u32_e32 v14, v14, v27
	v_ashrrev_i32_e32 v15, 31, v14
	v_lshlrev_b64 v[16:17], 15, v[14:15]
	v_lshl_add_u64 v[16:17], v[0:1], 0, v[16:17]
	s_add_i32 s1, s0, 9
	s_add_i32 s7, s6, 6
	global_load_dword v35, v[16:17], off
	v_mov_b32_e32 v16, s1
	v_mov_b32_e32 v17, s7
	v_cndmask_b32_e32 v16, v16, v17, vcc
	v_add_u32_e32 v16, v16, v27
	v_ashrrev_i32_e32 v17, 31, v16
	v_lshlrev_b64 v[18:19], 15, v[16:17]
	v_lshl_add_u64 v[18:19], v[0:1], 0, v[18:19]
	s_add_i32 s1, s0, 8
	s_add_i32 s7, s6, 7
	global_load_dword v48, v[18:19], off
	v_mov_b32_e32 v18, s1
	v_mov_b32_e32 v19, s7
	v_cndmask_b32_e32 v18, v18, v19, vcc
	v_add_u32_e32 v18, v18, v27
	v_ashrrev_i32_e32 v19, 31, v18
	v_lshlrev_b64 v[20:21], 15, v[18:19]
	v_lshl_add_u64 v[20:21], v[0:1], 0, v[20:21]
	s_add_i32 s1, s0, 7
	s_add_i32 s7, s6, 8
	global_load_dword v49, v[20:21], off
	v_mov_b32_e32 v20, s1
	v_mov_b32_e32 v21, s7
	v_cndmask_b32_e32 v20, v20, v21, vcc
	v_add_u32_e32 v20, v20, v27
	v_ashrrev_i32_e32 v21, 31, v20
	v_lshlrev_b64 v[22:23], 15, v[20:21]
	v_lshl_add_u64 v[22:23], v[0:1], 0, v[22:23]
	s_add_i32 s1, s0, 6
	s_add_i32 s7, s6, 9
	global_load_dword v50, v[22:23], off
	v_mov_b32_e32 v22, s1
	v_mov_b32_e32 v23, s7
	v_cndmask_b32_e32 v22, v22, v23, vcc
	v_add_u32_e32 v22, v22, v27
	v_ashrrev_i32_e32 v23, 31, v22
	v_lshlrev_b64 v[24:25], 15, v[22:23]
	v_lshl_add_u64 v[24:25], v[0:1], 0, v[24:25]
	s_add_i32 s1, s0, 5
	s_add_i32 s7, s6, 10
	global_load_dword v51, v[24:25], off
	v_mov_b32_e32 v24, s1
	v_mov_b32_e32 v25, s7
	v_cndmask_b32_e32 v24, v24, v25, vcc
	v_add_u32_e32 v24, v24, v27
	v_ashrrev_i32_e32 v25, 31, v24
	v_lshlrev_b64 v[36:37], 15, v[24:25]
	v_lshl_add_u64 v[36:37], v[0:1], 0, v[36:37]
	s_add_i32 s1, s0, 4
	s_add_i32 s7, s6, 11
	global_load_dword v52, v[36:37], off
	v_mov_b32_e32 v28, s1
	v_mov_b32_e32 v36, s7
	v_cndmask_b32_e32 v28, v28, v36, vcc
	v_add_u32_e32 v36, v28, v27
	v_ashrrev_i32_e32 v37, 31, v36
	v_lshlrev_b64 v[38:39], 15, v[36:37]
	v_lshl_add_u64 v[38:39], v[0:1], 0, v[38:39]
	s_add_i32 s1, s0, 3
	s_add_i32 s7, s6, 12
	global_load_dword v53, v[38:39], off
	v_mov_b32_e32 v28, s1
	v_mov_b32_e32 v38, s7
	v_cndmask_b32_e32 v28, v28, v38, vcc
	v_add_u32_e32 v38, v28, v27
	v_ashrrev_i32_e32 v39, 31, v38
	v_lshlrev_b64 v[40:41], 15, v[38:39]
	v_lshl_add_u64 v[40:41], v[0:1], 0, v[40:41]
	s_add_i32 s1, s0, 2
	s_add_i32 s7, s6, 13
	global_load_dword v54, v[40:41], off
	v_mov_b32_e32 v28, s1
	v_mov_b32_e32 v40, s7
	v_cndmask_b32_e32 v28, v28, v40, vcc
	v_add_u32_e32 v40, v28, v27
	v_ashrrev_i32_e32 v41, 31, v40
	v_lshlrev_b64 v[42:43], 15, v[40:41]
	v_lshl_add_u64 v[42:43], v[0:1], 0, v[42:43]
	s_add_i32 s1, s0, 1
	s_add_i32 s7, s6, 14
	global_load_dword v55, v[42:43], off
	v_mov_b32_e32 v28, s1
	v_mov_b32_e32 v42, s7
	v_cndmask_b32_e32 v28, v28, v42, vcc
	v_add_u32_e32 v42, v28, v27
	v_ashrrev_i32_e32 v43, 31, v42
	v_lshlrev_b64 v[44:45], 15, v[42:43]
	v_lshl_add_u64 v[44:45], v[0:1], 0, v[44:45]
	s_add_i32 s1, s6, 15
	global_load_dword v56, v[44:45], off
	v_mov_b32_e32 v28, s0
	v_mov_b32_e32 v44, s1
	v_cndmask_b32_e32 v28, v28, v44, vcc
	v_add_u32_e32 v44, v28, v27
	v_ashrrev_i32_e32 v45, 31, v44
	v_lshlrev_b64 v[46:47], 15, v[44:45]
	v_lshl_add_u64 v[46:47], v[0:1], 0, v[46:47]
	global_load_dword v28, v[46:47], off
	v_lshlrev_b64 v[4:5], 14, v[4:5]
	v_lshl_add_u64 v[4:5], v[2:3], 0, v[4:5]
	v_cvt_pk_bf16_f32 v46, v29, v195
	global_store_short v[4:5], v46, off
	v_lshlrev_b64 v[4:5], 14, v[6:7]
	v_lshl_add_u64 v[4:5], v[2:3], 0, v[4:5]
	s_waitcnt vmcnt(0) lgkmcnt(0)
; __device__ __forceinline__ bf16_t f2bf(float f) { return (bf16_t)(cvt_pk_bf16(f, 0.f) & 0xffffu); }
; __device__ __forceinline__ void scan_phase(const Bufs& B) {
;     ...
;             for (int u = 0; u < 16; ++u) { const int ch = dir ? 63 - (s0 + u) : s0 + u; B.RST[(size_t)(dh * 64 + ch) * 8192 + idx] = f2bf(r); r = cd * r + rl[u]; }
	v_fmac_f32_e32 v30, v26, v29
	v_cvt_pk_bf16_f32 v29, v30, v195
	global_store_short v[4:5], v29, off
	v_lshlrev_b64 v[4:5], 14, v[8:9]
	v_lshl_add_u64 v[4:5], v[2:3], 0, v[4:5]
	v_fmac_f32_e32 v31, v26, v30
	v_cvt_pk_bf16_f32 v6, v31, v195
	global_store_short v[4:5], v6, off
	v_lshlrev_b64 v[4:5], 14, v[10:11]
	v_lshl_add_u64 v[4:5], v[2:3], 0, v[4:5]
	v_fmac_f32_e32 v32, v26, v31
	v_cvt_pk_bf16_f32 v6, v32, v195
	global_store_short v[4:5], v6, off
	v_lshlrev_b64 v[4:5], 14, v[12:13]
	v_lshl_add_u64 v[4:5], v[2:3], 0, v[4:5]
	v_fmac_f32_e32 v33, v26, v32
	v_cvt_pk_bf16_f32 v6, v33, v195
	global_store_short v[4:5], v6, off
	v_lshlrev_b64 v[4:5], 14, v[14:15]
	v_lshl_add_u64 v[4:5], v[2:3], 0, v[4:5]
	v_fmac_f32_e32 v34, v26, v33
	v_cvt_pk_bf16_f32 v6, v34, v195
	global_store_short v[4:5], v6, off
	v_lshlrev_b64 v[4:5], 14, v[16:17]
	v_lshl_add_u64 v[4:5], v[2:3], 0, v[4:5]
	v_fmac_f32_e32 v35, v26, v34
	v_cvt_pk_bf16_f32 v6, v35, v195
	global_store_short v[4:5], v6, off
	v_lshlrev_b64 v[4:5], 14, v[18:19]
	v_lshl_add_u64 v[4:5], v[2:3], 0, v[4:5]
	v_fmac_f32_e32 v48, v26, v35
	v_cvt_pk_bf16_f32 v6, v48, v195
	global_store_short v[4:5], v6, off
	v_lshlrev_b64 v[4:5], 14, v[20:21]
	v_lshl_add_u64 v[4:5], v[2:3], 0, v[4:5]
	v_fmac_f32_e32 v49, v26, v48
	v_cvt_pk_bf16_f32 v6, v49, v195
	global_store_short v[4:5], v6, off
	v_lshlrev_b64 v[4:5], 14, v[22:23]
	v_lshl_add_u64 v[4:5], v[2:3], 0, v[4:5]
	v_fmac_f32_e32 v50, v26, v49
	v_cvt_pk_bf16_f32 v6, v50, v195
	global_store_short v[4:5], v6, off
	v_lshlrev_b64 v[4:5], 14, v[24:25]
	v_lshl_add_u64 v[4:5], v[2:3], 0, v[4:5]
	v_fmac_f32_e32 v51, v26, v50
	v_cvt_pk_bf16_f32 v6, v51, v195
	global_store_short v[4:5], v6, off
	v_lshlrev_b64 v[4:5], 14, v[36:37]
	v_lshl_add_u64 v[4:5], v[2:3], 0, v[4:5]
	v_fmac_f32_e32 v52, v26, v51
	v_cvt_pk_bf16_f32 v6, v52, v195
	global_store_short v[4:5], v6, off
	v_lshlrev_b64 v[4:5], 14, v[38:39]
	v_lshl_add_u64 v[4:5], v[2:3], 0, v[4:5]
	v_fmac_f32_e32 v53, v26, v52
	v_cvt_pk_bf16_f32 v6, v53, v195
	global_store_short v[4:5], v6, off
	v_lshlrev_b64 v[4:5], 14, v[40:41]
	v_fmac_f32_e32 v54, v26, v53
	v_lshl_add_u64 v[4:5], v[2:3], 0, v[4:5]
	v_cvt_pk_bf16_f32 v6, v54, v195
	global_store_short v[4:5], v6, off
	v_fmac_f32_e32 v55, v26, v54
	v_lshlrev_b64 v[4:5], 14, v[42:43]
	v_lshl_add_u64 v[4:5], v[2:3], 0, v[4:5]
	v_fmac_f32_e32 v56, v26, v55
	v_cvt_pk_bf16_f32 v6, v55, v195
	global_store_short v[4:5], v6, off
	v_lshlrev_b64 v[4:5], 14, v[44:45]
	s_add_i32 s0, s0, -16
	s_add_i32 s1, s6, 16
	v_lshl_add_u64 v[4:5], v[2:3], 0, v[4:5]
	v_fmac_f32_e32 v28, v26, v56
	s_cmp_lt_u32 s6, 48
	s_mov_b32 s6, s1
	v_mov_b32_e32 v29, v28
	v_cvt_pk_bf16_f32 v6, v56, v195
	global_store_short v[4:5], v6, off
	s_cbranch_scc1 .LBB0_386

; __device__ __forceinline__ int ltid() { int t = threadIdx.x; asm volatile("" : "+v"(t)); return t; }
; __global__ void __launch_bounds__(512) mega_fwd(Params p) {
;     ...
;             for (int i = bx * 512 + ltid(); i < S_; i += G * 512) { ssqa[i] = 0ull; ssqb[i] = 0ull; } } break;
.LBB0_389:
	v_add_co_u32_e32 v4, vcc, 0xffff0000, v2
	s_mov_b32 s25, s24
	s_nop 0
	v_addc_co_u32_e32 v5, vcc, -1, v3, vcc
	v_add_u32_e32 v0, s6, v0
	v_mov_b64_e32 v[6:7], s[24:25]
	v_cmp_lt_i32_e32 vcc, s7, v0
	global_store_dwordx2 v[4:5], v[6:7], off
	global_store_dwordx2 v[2:3], v[6:7], off
	s_or_b64 s[4:5], vcc, s[4:5]
	v_lshl_add_u64 v[2:3], v[2:3], 0, s[26:27]
	s_andn2_b64 exec, exec, s[4:5]
	s_cbranch_execnz .LBB0_389

; #define LAS __attribute__((address_space(3)))
; template <class Epi>
; __device__ __forceinline__ void gemm_phase(LAS unsigned char* lds, const Gemm g, const StaticOrder& S, const Epi& E) {
;     ...
;     if (Epi::PRE) E.stash(E.prefetch(cur.pm, tid), lds, 0, tid);
;     __device__ __forceinline__ void stash(unsigned long long v, LAS unsigned char* lds, int par, int tid) const { if (tid < 256) *(LAS float*)(lds + 131072 + par * 1024 + tid * 4) = rsqrtf((float)v * (1.f / (1048576.f * DM)) + EPS_); }
; __global__ void __launch_bounds__(512) mega_fwd(Params p) {
;     ...
;             if (bx < 192) { so.init(S_, 1536, 192, bx); pg8::Gemm g{B.CQN, (const bf16_t*)(Wl + WO_Q), S_, 1536, 512}; pg8::EpiQup e{(unsigned char*)B.Q, B.RC, B.RS}; pg8::gemm_phase(lds, g, so, e); }
;             else { so.init(S_, 512, 64, bx - 192, 0, 6); pg8::Gemm g{B.H, (const bf16_t*)(Wl + WO_IN), S_, NPROJP, DM}; pg8::EpiBf16<0> e{B.PROJ, NPROJP, ssqa}; pg8::gemm_phase(lds, g, so, e); }
.LBB0_391:
	s_and_b64 vcc, exec, s[0:1]
	s_cbranch_vccz .LBB0_465
	v_readlane_b32 s4, v254, 3
	s_cmpk_lt_i32 s4, 0xc0
	s_cselect_b64 s[0:1], -1, 0
	s_cmpk_gt_i32 s4, 0xbf
	s_mov_b64 s[4:5], -1
	s_cbranch_scc0 .LBB0_405
	v_readlane_b32 s4, v254, 3
	s_addk_i32 s4, 0xff40
	v_mov_b32_e32 v0, v192
	s_movk_i32 s26, 0x800
	v_readfirstlane_b32 s33, v0
	s_cmp_gt_u32 s4, 63
	s_cbranch_scc1 .LBB0_404
	s_lshr_b32 s30, s4, 3
	v_readlane_b32 s4, v254, 3
	s_lshl_b32 s4, s4, 2
	s_and_b32 s31, s4, 24
	s_movk_i32 s4, 0x100
	s_or_b32 s34, s30, s31
	v_cmp_gt_i32_e32 vcc, s4, v0
	s_and_saveexec_b64 s[4:5], vcc
	s_cbranch_execz .LBB0_396
	v_lshl_add_u32 v2, s34, 8, v0
	v_readlane_b32 s6, v254, 37
	v_ashrrev_i32_e32 v3, 31, v2
	v_readlane_b32 s7, v254, 38
	s_nop 1
	v_lshl_add_u64 v[2:3], v[2:3], 3, s[6:7]
	global_load_dwordx2 v[2:3], v[2:3], off
	s_mov_b32 s6, 0x800000
	s_waitcnt vmcnt(0) lgkmcnt(0)
	v_ffbh_u32_e32 v1, v3
	v_min_u32_e32 v1, 32, v1
	v_lshlrev_b64 v[2:3], v1, v[2:3]
	v_min_u32_e32 v2, 1, v2
	v_or_b32_e32 v2, v3, v2
	v_cvt_f32_u32_e32 v2, v2
	v_sub_u32_e32 v1, 32, v1
	v_ldexp_f32 v1, v2, v1
	v_fmamk_f32 v1, v1, 0x30000000, v242
	v_mul_f32_e32 v2, 0x4b800000, v1
	v_cmp_gt_f32_e32 vcc, s6, v1
	s_nop 1
	v_cndmask_b32_e32 v1, v1, v2, vcc
	v_rsq_f32_e32 v1, v1
	v_lshl_add_u32 v2, v0, 2, 0
	v_add_u32_e32 v2, 0x20000, v2
	v_mul_f32_e32 v3, 0x45800000, v1
	v_cndmask_b32_e32 v1, v1, v3, vcc
	ds_write_b32 v2, v1

; #define LAS __attribute__((address_space(3)))
; __device__ __forceinline__ unsigned cvt_pk_bf16(float lo, float hi) { unsigned r; asm volatile("v_cvt_pk_bf16_f32 %0, %1, %2" : "=v"(r) : "v"(lo), "v"(hi)); return r; }
;     __device__ __forceinline__ void operator()(const f32x4 (&acc)[2][2][4][2], const Unit& u, int wr, int wc, int fr, int fq, LAS unsigned char* lds, int par, int npm, int tid) const {
;     ...
;             for (int m = 0; m < 4; ++m) { const int row = row0 + ai * HALF + m * 16; bf16_t* rowp = O + (size_t)row * ldc + col0;
;                 const float rstd = *(const LAS float*)(lds + 131072 + par * 1024 + (wr * 64 + fr + ai * HALF + m * 16) * 4);
; #pragma unroll
;                 for (int bj = 0; bj < 2; ++bj) { f32x4 v0 = acc[ai][bj][m][0] * rstd, v1 = acc[ai][bj][m][1] * rstd;
;                     if (ACT == 1) {
; #pragma unroll
;                         for (int j = 0; j < 4; ++j) { const float a = fmaxf(v0[j], 0.f), b = fmaxf(v1[j], 0.f); v0[j] = a * a; v1[j] = b * b; } }
;                     u32x4 w; w.x = cvt_pk_bf16(v0[0], v0[1]); w.y = cvt_pk_bf16(v0[2], v0[3]); w.z = cvt_pk_bf16(v1[0], v1[1]); w.w = cvt_pk_bf16(v1[2], v1[3]);
;                     *(u32x4*)(rowp + bj * HALF) = w; } }
.LBB0_401:
	v_lshl_add_u32 v130, v138, 2, 0
	v_add_u32_e32 v137, 0x20000, v130
	ds_read_b32 v130, v137
	v_readlane_b32 s4, v254, 23
	v_lshl_or_b32 v128, s35, 8, v139
	v_readlane_b32 s5, v254, 24
	v_or_b32_e32 v131, s36, v128
	v_lshl_add_u32 v136, s34, 8, v138
	v_mov_b64_e32 v[128:129], s[4:5]
	s_movk_i32 s6, 0x2400
	v_mad_i64_i32 v[132:133], s[4:5], v136, s6, v[128:129]
	v_lshlrev_b32_e32 v194, 1, v131
	v_lshl_add_u64 v[132:133], v[132:133], 0, v[194:195]
	s_waitcnt lgkmcnt(0)
	v_pk_mul_f32 v[126:127], v[126:127], v[130:131] op_sel_hi:[1,0]
	v_pk_mul_f32 v[124:125], v[124:125], v[130:131] op_sel_hi:[1,0]
	v_pk_mul_f32 v[134:135], v[122:123], v[130:131] op_sel_hi:[1,0]
	v_pk_mul_f32 v[122:123], v[120:121], v[130:131] op_sel_hi:[1,0]
	v_cvt_pk_bf16_f32 v120, v124, v125
	v_cvt_pk_bf16_f32 v121, v126, v127
	v_pk_mul_f32 v[118:119], v[118:119], v[130:131] op_sel_hi:[1,0]
	v_cvt_pk_bf16_f32 v122, v122, v123
	v_cvt_pk_bf16_f32 v123, v134, v135
	global_store_dwordx4 v[132:133], v[120:123], off
	v_pk_mul_f32 v[116:117], v[116:117], v[130:131] op_sel_hi:[1,0]
	s_cmpk_lt_u32 s33, 0x100
	v_pk_mul_f32 v[120:121], v[114:115], v[130:131] op_sel_hi:[1,0]
	v_pk_mul_f32 v[114:115], v[112:113], v[130:131] op_sel_hi:[1,0]
	v_cvt_pk_bf16_f32 v112, v116, v117
	v_cvt_pk_bf16_f32 v113, v118, v119
	s_nop 0
	v_cvt_pk_bf16_f32 v114, v114, v115
	v_cvt_pk_bf16_f32 v115, v120, v121
	global_store_dwordx4 v[132:133], v[112:115], off offset:256
	ds_read_b32 v112, v137 offset:64
	s_nop 0
	v_or_b32_e32 v113, 16, v136
	v_mad_i64_i32 v[114:115], s[4:5], v113, s6, v[128:129]
	v_lshl_add_u64 v[114:115], v[114:115], 0, v[194:195]
	s_waitcnt lgkmcnt(0)
	v_pk_mul_f32 v[110:111], v[110:111], v[112:113] op_sel_hi:[1,0]
	v_pk_mul_f32 v[108:109], v[108:109], v[112:113] op_sel_hi:[1,0]
	v_pk_mul_f32 v[116:117], v[106:107], v[112:113] op_sel_hi:[1,0]
	v_pk_mul_f32 v[106:107], v[104:105], v[112:113] op_sel_hi:[1,0]
	v_cvt_pk_bf16_f32 v104, v108, v109
	v_cvt_pk_bf16_f32 v105, v110, v111
	v_pk_mul_f32 v[102:103], v[102:103], v[112:113] op_sel_hi:[1,0]
	v_cvt_pk_bf16_f32 v106, v106, v107
	v_cvt_pk_bf16_f32 v107, v116, v117
	global_store_dwordx4 v[114:115], v[104:107], off
	v_pk_mul_f32 v[100:101], v[100:101], v[112:113] op_sel_hi:[1,0]
	s_nop 0
	v_pk_mul_f32 v[104:105], v[98:99], v[112:113] op_sel_hi:[1,0]
	v_pk_mul_f32 v[98:99], v[96:97], v[112:113] op_sel_hi:[1,0]
	v_cvt_pk_bf16_f32 v96, v100, v101
	v_cvt_pk_bf16_f32 v97, v102, v103
	s_nop 0
	v_cvt_pk_bf16_f32 v98, v98, v99
	v_cvt_pk_bf16_f32 v99, v104, v105
	global_store_dwordx4 v[114:115], v[96:99], off offset:256
	ds_read_b32 v96, v137 offset:128
	s_nop 0
	v_or_b32_e32 v97, 32, v136
	v_mad_i64_i32 v[98:99], s[4:5], v97, s6, v[128:129]
	v_lshl_add_u64 v[98:99], v[98:99], 0, v[194:195]
	s_waitcnt lgkmcnt(0)
	v_pk_mul_f32 v[94:95], v[94:95], v[96:97] op_sel_hi:[1,0]
	v_pk_mul_f32 v[92:93], v[92:93], v[96:97] op_sel_hi:[1,0]
	v_pk_mul_f32 v[100:101], v[90:91], v[96:97] op_sel_hi:[1,0]
	v_pk_mul_f32 v[90:91], v[88:89], v[96:97] op_sel_hi:[1,0]
	v_cvt_pk_bf16_f32 v88, v92, v93
	v_cvt_pk_bf16_f32 v89, v94, v95
	v_pk_mul_f32 v[86:87], v[86:87], v[96:97] op_sel_hi:[1,0]
	v_cvt_pk_bf16_f32 v90, v90, v91
	v_cvt_pk_bf16_f32 v91, v100, v101
	global_store_dwordx4 v[98:99], v[88:91], off
	v_pk_mul_f32 v[84:85], v[84:85], v[96:97] op_sel_hi:[1,0]
	s_nop 0
	v_pk_mul_f32 v[88:89], v[82:83], v[96:97] op_sel_hi:[1,0]
	v_pk_mul_f32 v[82:83], v[80:81], v[96:97] op_sel_hi:[1,0]
	v_cvt_pk_bf16_f32 v80, v84, v85
	v_cvt_pk_bf16_f32 v81, v86, v87
	s_nop 0
	v_cvt_pk_bf16_f32 v82, v82, v83
	v_cvt_pk_bf16_f32 v83, v88, v89
	global_store_dwordx4 v[98:99], v[80:83], off offset:256
	ds_read_b32 v80, v137 offset:192
	s_nop 0
	v_or_b32_e32 v81, 48, v136
	v_mad_i64_i32 v[82:83], s[4:5], v81, s6, v[128:129]
	v_lshl_add_u64 v[82:83], v[82:83], 0, v[194:195]
	s_waitcnt lgkmcnt(0)
	v_pk_mul_f32 v[78:79], v[78:79], v[80:81] op_sel_hi:[1,0]
	v_pk_mul_f32 v[76:77], v[76:77], v[80:81] op_sel_hi:[1,0]
	v_pk_mul_f32 v[84:85], v[74:75], v[80:81] op_sel_hi:[1,0]
	v_pk_mul_f32 v[74:75], v[72:73], v[80:81] op_sel_hi:[1,0]
	v_cvt_pk_bf16_f32 v72, v76, v77
	v_cvt_pk_bf16_f32 v73, v78, v79
	v_pk_mul_f32 v[70:71], v[70:71], v[80:81] op_sel_hi:[1,0]
	v_cvt_pk_bf16_f32 v74, v74, v75
	v_cvt_pk_bf16_f32 v75, v84, v85
	global_store_dwordx4 v[82:83], v[72:75], off
	v_pk_mul_f32 v[68:69], v[68:69], v[80:81] op_sel_hi:[1,0]
	s_nop 0
	v_pk_mul_f32 v[72:73], v[66:67], v[80:81] op_sel_hi:[1,0]
	v_pk_mul_f32 v[66:67], v[64:65], v[80:81] op_sel_hi:[1,0]
	v_cvt_pk_bf16_f32 v64, v68, v69
	v_cvt_pk_bf16_f32 v65, v70, v71
	s_nop 0
	v_cvt_pk_bf16_f32 v66, v66, v67
	v_cvt_pk_bf16_f32 v67, v72, v73
	global_store_dwordx4 v[82:83], v[64:67], off offset:256
	ds_read_b32 v64, v137 offset:512
	s_nop 0
	v_add_u32_e32 v65, 0x80, v136
	v_mad_i64_i32 v[66:67], s[4:5], v65, s6, v[128:129]
	v_lshl_add_u64 v[66:67], v[66:67], 0, v[194:195]
	s_waitcnt lgkmcnt(0)
; #define LAS __attribute__((address_space(3)))
; __device__ __forceinline__ unsigned cvt_pk_bf16(float lo, float hi) { unsigned r; asm volatile("v_cvt_pk_bf16_f32 %0, %1, %2" : "=v"(r) : "v"(lo), "v"(hi)); return r; }
; #define PG8_WAIT_V(n) asm volatile("s_waitcnt vmcnt(" #n ")" ::: "memory")
; #define PG8_BAR __builtin_amdgcn_s_barrier()
; template <class Epi>
; __device__ __forceinline__ void gemm_phase(LAS unsigned char* lds, const Gemm g, const StaticOrder& S, const Epi& E) {
;     ...
;     PG8_WAIT_V(0);
;     if (wr == 0) PG8_BAR;
;     __device__ __forceinline__ void operator()(const f32x4 (&acc)[2][2][4][2], const Unit& u, int wr, int wc, int fr, int fq, LAS unsigned char* lds, int par, int npm, int tid) const {
;     ...
;             for (int m = 0; m < 4; ++m) { const int row = row0 + ai * HALF + m * 16; bf16_t* rowp = O + (size_t)row * ldc + col0;
;                 const float rstd = *(const LAS float*)(lds + 131072 + par * 1024 + (wr * 64 + fr + ai * HALF + m * 16) * 4);
; #pragma unroll
;                 for (int bj = 0; bj < 2; ++bj) { f32x4 v0 = acc[ai][bj][m][0] * rstd, v1 = acc[ai][bj][m][1] * rstd;
;                     if (ACT == 1) {
; #pragma unroll
;                         for (int j = 0; j < 4; ++j) { const float a = fmaxf(v0[j], 0.f), b = fmaxf(v1[j], 0.f); v0[j] = a * a; v1[j] = b * b; } }
;                     u32x4 w; w.x = cvt_pk_bf16(v0[0], v0[1]); w.y = cvt_pk_bf16(v0[2], v0[3]); w.z = cvt_pk_bf16(v1[0], v1[1]); w.w = cvt_pk_bf16(v1[2], v1[3]);
;                     *(u32x4*)(rowp + bj * HALF) = w; } }
	v_pk_mul_f32 v[62:63], v[62:63], v[64:65] op_sel_hi:[1,0]
	v_pk_mul_f32 v[60:61], v[60:61], v[64:65] op_sel_hi:[1,0]
	v_pk_mul_f32 v[68:69], v[58:59], v[64:65] op_sel_hi:[1,0]
	v_pk_mul_f32 v[58:59], v[56:57], v[64:65] op_sel_hi:[1,0]
	v_cvt_pk_bf16_f32 v56, v60, v61
	v_cvt_pk_bf16_f32 v57, v62, v63
	v_pk_mul_f32 v[54:55], v[54:55], v[64:65] op_sel_hi:[1,0]
	v_cvt_pk_bf16_f32 v58, v58, v59
	v_cvt_pk_bf16_f32 v59, v68, v69
	global_store_dwordx4 v[66:67], v[56:59], off
	v_pk_mul_f32 v[52:53], v[52:53], v[64:65] op_sel_hi:[1,0]
	s_nop 0
	v_pk_mul_f32 v[56:57], v[50:51], v[64:65] op_sel_hi:[1,0]
	v_pk_mul_f32 v[50:51], v[48:49], v[64:65] op_sel_hi:[1,0]
	v_cvt_pk_bf16_f32 v48, v52, v53
	v_cvt_pk_bf16_f32 v49, v54, v55
	s_nop 0
	v_cvt_pk_bf16_f32 v50, v50, v51
	v_cvt_pk_bf16_f32 v51, v56, v57
	global_store_dwordx4 v[66:67], v[48:51], off offset:256
	ds_read_b32 v48, v137 offset:576
	s_nop 0
	v_add_u32_e32 v49, 0x90, v136
	v_mad_i64_i32 v[50:51], s[4:5], v49, s6, v[128:129]
	v_lshl_add_u64 v[50:51], v[50:51], 0, v[194:195]
	s_waitcnt lgkmcnt(0)
	v_pk_mul_f32 v[46:47], v[46:47], v[48:49] op_sel_hi:[1,0]
	v_pk_mul_f32 v[44:45], v[44:45], v[48:49] op_sel_hi:[1,0]
	v_pk_mul_f32 v[52:53], v[42:43], v[48:49] op_sel_hi:[1,0]
	v_pk_mul_f32 v[42:43], v[40:41], v[48:49] op_sel_hi:[1,0]
	v_cvt_pk_bf16_f32 v40, v44, v45
	v_cvt_pk_bf16_f32 v41, v46, v47
	v_pk_mul_f32 v[38:39], v[38:39], v[48:49] op_sel_hi:[1,0]
	v_cvt_pk_bf16_f32 v42, v42, v43
	v_cvt_pk_bf16_f32 v43, v52, v53
	global_store_dwordx4 v[50:51], v[40:43], off
	v_pk_mul_f32 v[36:37], v[36:37], v[48:49] op_sel_hi:[1,0]
	s_nop 0
	v_pk_mul_f32 v[40:41], v[34:35], v[48:49] op_sel_hi:[1,0]
	v_pk_mul_f32 v[34:35], v[32:33], v[48:49] op_sel_hi:[1,0]
	v_cvt_pk_bf16_f32 v32, v36, v37
	v_cvt_pk_bf16_f32 v33, v38, v39
	s_nop 0
	v_cvt_pk_bf16_f32 v34, v34, v35
	v_cvt_pk_bf16_f32 v35, v40, v41
	global_store_dwordx4 v[50:51], v[32:35], off offset:256
	ds_read_b32 v32, v137 offset:640
	s_nop 0
	v_add_u32_e32 v33, 0xa0, v136
	v_mad_i64_i32 v[34:35], s[4:5], v33, s6, v[128:129]
	v_lshl_add_u64 v[34:35], v[34:35], 0, v[194:195]
	s_waitcnt lgkmcnt(0)
	v_pk_mul_f32 v[30:31], v[30:31], v[32:33] op_sel_hi:[1,0]
	v_pk_mul_f32 v[28:29], v[28:29], v[32:33] op_sel_hi:[1,0]
	v_pk_mul_f32 v[36:37], v[26:27], v[32:33] op_sel_hi:[1,0]
	v_pk_mul_f32 v[26:27], v[24:25], v[32:33] op_sel_hi:[1,0]
	v_cvt_pk_bf16_f32 v24, v28, v29
	v_cvt_pk_bf16_f32 v25, v30, v31
	v_pk_mul_f32 v[22:23], v[22:23], v[32:33] op_sel_hi:[1,0]
	v_cvt_pk_bf16_f32 v26, v26, v27
	v_cvt_pk_bf16_f32 v27, v36, v37
	global_store_dwordx4 v[34:35], v[24:27], off
	v_pk_mul_f32 v[20:21], v[20:21], v[32:33] op_sel_hi:[1,0]
	s_nop 0
	v_pk_mul_f32 v[24:25], v[18:19], v[32:33] op_sel_hi:[1,0]
	v_pk_mul_f32 v[18:19], v[16:17], v[32:33] op_sel_hi:[1,0]
	v_cvt_pk_bf16_f32 v16, v20, v21
	v_cvt_pk_bf16_f32 v17, v22, v23
	s_nop 0
	v_cvt_pk_bf16_f32 v18, v18, v19
	v_cvt_pk_bf16_f32 v19, v24, v25
	global_store_dwordx4 v[34:35], v[16:19], off offset:256
	ds_read_b32 v16, v137 offset:704
	s_nop 0
	v_add_u32_e32 v17, 0xb0, v136
	v_mad_i64_i32 v[18:19], s[4:5], v17, s6, v[128:129]
	v_lshl_add_u64 v[18:19], v[18:19], 0, v[194:195]
	s_waitcnt lgkmcnt(0)
	v_pk_mul_f32 v[14:15], v[14:15], v[16:17] op_sel_hi:[1,0]
	v_pk_mul_f32 v[12:13], v[12:13], v[16:17] op_sel_hi:[1,0]
	v_pk_mul_f32 v[20:21], v[10:11], v[16:17] op_sel_hi:[1,0]
	v_pk_mul_f32 v[10:11], v[8:9], v[16:17] op_sel_hi:[1,0]
	v_cvt_pk_bf16_f32 v8, v12, v13
	v_cvt_pk_bf16_f32 v9, v14, v15
	v_pk_mul_f32 v[6:7], v[6:7], v[16:17] op_sel_hi:[1,0]
	v_cvt_pk_bf16_f32 v10, v10, v11
	v_cvt_pk_bf16_f32 v11, v20, v21
	global_store_dwordx4 v[18:19], v[8:11], off
	v_pk_mul_f32 v[4:5], v[4:5], v[16:17] op_sel_hi:[1,0]
	s_nop 0
	v_pk_mul_f32 v[8:9], v[2:3], v[16:17] op_sel_hi:[1,0]
	v_pk_mul_f32 v[2:3], v[0:1], v[16:17] op_sel_hi:[1,0]
	v_cvt_pk_bf16_f32 v0, v4, v5
	v_cvt_pk_bf16_f32 v1, v6, v7
	s_nop 0
	v_cvt_pk_bf16_f32 v2, v2, v3
	v_cvt_pk_bf16_f32 v3, v8, v9
	global_store_dwordx4 v[18:19], v[0:3], off offset:256
	s_waitcnt vmcnt(0)
	s_cbranch_scc0 .LBB0_403
	s_barrier

;     __device__ __forceinline__ void operator()(const f32x4 (&acc)[2][2][4][2], const Unit& u, int wr, int wc, int fr, int fq, LAS unsigned char* lds, int par, int npm, int tid) const {
;     ...
;             const int jj0 = (wc & 1) * 32 + 8 * fq, j0 = jj0 >> 1;
;             unsigned char* d0 = Q + ((size_t)((u.pn - 4) * 4 + (wc >> 1)) * S_ + row0) * 192 + 128 + jj0;
;             const float* c0 = rc + (size_t)row0 * 32 + j0; const float* s0 = rs + (size_t)row0 * 32 + j0;
;             f32x4 cv[2][4], sv[2][4];
; #pragma unroll
;             for (int ai = 0; ai < 2; ++ai)
; #pragma unroll
;                 for (int m = 0; m < 4; ++m) { const int ro = ai * HALF + m * 16; cv[ai][m] = *(const f32x4*)(c0 + ro * 32); sv[ai][m] = *(const f32x4*)(s0 + ro * 32); }
; #pragma unroll
;             for (int ai = 0; ai < 2; ++ai)
; #pragma unroll
;                 for (int m = 0; m < 4; ++m) { const int ro = ai * HALF + m * 16; const f32x4 c = cv[ai][m], s = sv[ai][m];
; #pragma unroll
;                     for (int bj = 0; bj < 2; ++bj) { const f32x4 v0 = acc[ai][bj][m][0], v1 = acc[ai][bj][m][1];
;                         const float f[8] = {v0[0] * c[0] - v0[1] * s[0], v0[1] * c[0] + v0[0] * s[0], v0[2] * c[1] - v0[3] * s[1], v0[3] * c[1] + v0[2] * s[1],
;                                             v1[0] * c[2] - v1[1] * s[2], v1[1] * c[2] + v1[0] * s[2], v1[2] * c[3] - v1[3] * s[3], v1[3] * c[3] + v1[2] * s[3]};
;                         *(u32x2*)(d0 + (size_t)ro * 192 + (size_t)bj * 2 * S_ * 192) = pack8_fp8(f); } }
.LBB0_420:
	v_lshl_add_u32 v220, s57, 8, v201
	s_mov_b64 s[34:35], -1
	s_cmp_gt_i32 s33, 3
	v_ashrrev_i32_e32 v221, 31, v220
	s_cbranch_scc0 .LBB0_422
	v_lshlrev_b64 v[128:129], 7, v[220:221]
	v_lshl_add_u64 v[130:131], v[208:209], 0, v[128:129]
	v_lshl_add_u64 v[128:129], v[210:211], 0, v[128:129]
	global_load_dwordx4 v[184:187], v[130:131], off
	global_load_dwordx4 v[188:191], v[128:129], off
	global_load_dwordx4 v[176:179], v[130:131], off offset:2048
	global_load_dwordx4 v[180:183], v[128:129], off offset:2048
	v_add_co_u32_e32 v132, vcc, 0x1000, v130
	s_lshl_b32 s34, s33, 2
	s_nop 0
	v_addc_co_u32_e32 v133, vcc, 0, v131, vcc
	global_load_dwordx4 v[168:171], v[132:133], off
	v_add_co_u32_e32 v134, vcc, 0x1000, v128
	v_readlane_b32 s36, v253, 36
	s_nop 0
	v_addc_co_u32_e32 v135, vcc, 0, v129, vcc
	global_load_dwordx4 v[172:175], v[134:135], off
	global_load_dwordx4 v[160:163], v[132:133], off offset:2048
	global_load_dwordx4 v[164:167], v[134:135], off offset:2048
	s_add_i32 s34, s53, s34
	s_mov_b32 s35, s36
	s_lshl_b64 s[34:35], s[34:35], 13
	v_lshl_add_u64 v[224:225], s[34:35], 0, v[220:221]
	s_movk_i32 s34, 0x4000
	v_add_co_u32_e32 v132, vcc, s34, v130
	s_movk_i32 s36, 0xc0
	s_nop 0
	v_addc_co_u32_e32 v133, vcc, 0, v131, vcc
	v_add_co_u32_e32 v134, vcc, s34, v128
	s_movk_i32 s34, 0x5000
	s_nop 0
	v_addc_co_u32_e32 v135, vcc, 0, v129, vcc
	v_add_co_u32_e32 v130, vcc, s34, v130
	global_load_dwordx4 v[152:155], v[132:133], off
	s_nop 0
	v_addc_co_u32_e32 v131, vcc, 0, v131, vcc
	global_load_dwordx4 v[156:159], v[134:135], off
	global_load_dwordx4 v[144:147], v[132:133], off offset:2048
	global_load_dwordx4 v[148:151], v[134:135], off offset:2048
	v_add_co_u32_e32 v132, vcc, s34, v128
	v_mad_u64_u32 v[222:223], s[34:35], v224, s36, v[214:215]
	v_mad_i32_i24 v223, v225, s36, v223
	v_addc_co_u32_e32 v133, vcc, 0, v129, vcc
	s_mov_b32 s34, 0x300000
	global_load_dwordx4 v[136:139], v[130:131], off
	global_load_dwordx4 v[140:143], v[132:133], off
	s_nop 0
	global_load_dwordx4 v[128:131], v[130:131], off offset:2048
	s_nop 0
	global_load_dwordx4 v[132:135], v[132:133], off offset:2048
	v_readlane_b32 s37, v253, 37
	s_waitcnt vmcnt(0) lgkmcnt(0)
	v_mov_b32_e32 v230, v184
	v_mov_b32_e32 v231, v188
	v_pk_mul_f32 v[224:225], v[124:125], v[230:231]
	v_mov_b32_e32 v226, v188
	v_mov_b32_e32 v227, v184
	v_sub_f32_e32 v243, v224, v225
	v_pk_mul_f32 v[224:225], v[124:125], v[226:227]
	v_mov_b32_e32 v188, v185
	v_add_f32_e32 v193, v225, v224
	v_pk_mul_f32 v[224:225], v[126:127], v[188:189]
	v_mov_b32_e32 v184, v189
	v_sub_f32_e32 v239, v224, v225
	v_pk_mul_f32 v[224:225], v[126:127], v[184:185]
	v_pk_mul_f32 v[188:189], v[118:119], v[188:189]
	v_add_f32_e32 v244, v225, v224
	v_mov_b32_e32 v224, v186
	v_mov_b32_e32 v225, v190
	v_pk_mul_f32 v[228:229], v[120:121], v[224:225]
	v_pk_mul_f32 v[184:185], v[118:119], v[184:185]
	v_sub_f32_e32 v249, v228, v229
	v_mov_b32_e32 v228, v190
	v_mov_b32_e32 v229, v186
	v_pk_mul_f32 v[232:233], v[120:121], v[228:229]
	v_mov_b32_e32 v190, v187
	v_sub_f32_e32 v188, v188, v189
	v_add_f32_e32 v189, v185, v184
	v_pk_mul_f32 v[184:185], v[112:113], v[224:225]
	v_add_f32_e32 v250, v233, v232
	v_pk_mul_f32 v[232:233], v[122:123], v[190:191]
	v_mov_b32_e32 v186, v191
	v_sub_f32_e32 v224, v184, v185
	v_pk_mul_f32 v[184:185], v[112:113], v[228:229]
	v_sub_f32_e32 v247, v232, v233
	v_pk_mul_f32 v[232:233], v[122:123], v[186:187]
	v_add_f32_e32 v225, v185, v184
	v_pk_mul_f32 v[184:185], v[114:115], v[190:191]
	v_add_f32_e32 v248, v233, v232
	v_mov_b32_e32 v232, v195
	v_pk_mul_f32 v[230:231], v[116:117], v[230:231]
	v_pk_mul_f32 v[226:227], v[116:117], v[226:227]
	v_sub_f32_e32 v190, v184, v185
	v_pk_mul_f32 v[184:185], v[114:115], v[186:187]
	v_cvt_pk_fp8_f32 v232, v243, v193
	v_sub_f32_e32 v193, v230, v231
	v_add_f32_e32 v226, v227, v226
	v_add_f32_e32 v186, v185, v184
	v_mov_b32_e32 v184, v195
	v_mov_b32_e32 v185, v195
	v_cvt_pk_fp8_f32 v184, v193, v226
	v_cvt_pk_fp8_f32 v185, v224, v225
	v_mov_b32_e32 v233, v195
	v_cvt_pk_fp8_f32 v233, v249, v250
	v_cvt_pk_fp8_f32 v184, v188, v189 op_sel:[0,0,1]
	v_cvt_pk_fp8_f32 v185, v190, v186 op_sel:[0,0,1]
	v_add_co_u32_e32 v186, vcc, s34, v222
	v_cvt_pk_fp8_f32 v232, v239, v244 op_sel:[0,0,1]
	s_nop 0
	v_addc_co_u32_e32 v187, vcc, 0, v223, vcc
	global_store_dwordx2 v[186:187], v[184:185], off offset:128
	v_mov_b32_e32 v184, v176
	v_mov_b32_e32 v185, v180
	v_pk_mul_f32 v[188:189], v[108:109], v[184:185]
	v_cvt_pk_fp8_f32 v233, v247, v248 op_sel:[0,0,1]
	v_sub_f32_e32 v193, v188, v189
	v_mov_b32_e32 v188, v180
	v_mov_b32_e32 v189, v176
	v_pk_mul_f32 v[190:191], v[108:109], v[188:189]
	v_mov_b32_e32 v180, v177
	v_add_f32_e32 v228, v191, v190
	v_pk_mul_f32 v[190:191], v[110:111], v[180:181]
	v_mov_b32_e32 v176, v181
	v_sub_f32_e32 v229, v190, v191
	v_pk_mul_f32 v[190:191], v[110:111], v[176:177]
	global_store_dwordx2 v[222:223], v[232:233], off offset:128
	v_add_f32_e32 v230, v191, v190
	v_mov_b32_e32 v190, v178
	v_mov_b32_e32 v191, v182
	v_pk_mul_f32 v[224:225], v[104:105], v[190:191]
	v_pk_mul_f32 v[184:185], v[100:101], v[184:185]
	v_sub_f32_e32 v231, v224, v225
	v_mov_b32_e32 v224, v182
	v_mov_b32_e32 v225, v178
	v_pk_mul_f32 v[226:227], v[104:105], v[224:225]
	v_mov_b32_e32 v182, v179
	v_add_f32_e32 v232, v227, v226
	v_pk_mul_f32 v[226:227], v[106:107], v[182:183]
	v_mov_b32_e32 v178, v183
	v_sub_f32_e32 v233, v226, v227
	v_pk_mul_f32 v[226:227], v[106:107], v[178:179]
	v_pk_mul_f32 v[180:181], v[102:103], v[180:181]
	v_add_f32_e32 v239, v227, v226
	v_mov_b32_e32 v226, v195
	v_pk_mul_f32 v[176:177], v[102:103], v[176:177]
	v_cvt_pk_fp8_f32 v226, v193, v228
	v_sub_f32_e32 v193, v184, v185
;     __device__ __forceinline__ void operator()(const f32x4 (&acc)[2][2][4][2], const Unit& u, int wr, int wc, int fr, int fq, LAS unsigned char* lds, int par, int npm, int tid) const {
;     ...
;                     for (int bj = 0; bj < 2; ++bj) { const f32x4 v0 = acc[ai][bj][m][0], v1 = acc[ai][bj][m][1];
;                         const float f[8] = {v0[0] * c[0] - v0[1] * s[0], v0[1] * c[0] + v0[0] * s[0], v0[2] * c[1] - v0[3] * s[1], v0[3] * c[1] + v0[2] * s[1],
;                                             v1[0] * c[2] - v1[1] * s[2], v1[1] * c[2] + v1[0] * s[2], v1[2] * c[3] - v1[3] * s[3], v1[3] * c[3] + v1[2] * s[3]};
;                         *(u32x2*)(d0 + (size_t)ro * 192 + (size_t)bj * 2 * S_ * 192) = pack8_fp8(f); } }
	v_pk_mul_f32 v[184:185], v[100:101], v[188:189]
	v_sub_f32_e32 v180, v180, v181
	v_add_f32_e32 v181, v177, v176
	v_pk_mul_f32 v[176:177], v[96:97], v[190:191]
	v_add_f32_e32 v184, v185, v184
	v_sub_f32_e32 v185, v176, v177
	v_pk_mul_f32 v[176:177], v[96:97], v[224:225]
	s_movk_i32 s34, 0x1000
	v_add_f32_e32 v188, v177, v176
	v_pk_mul_f32 v[176:177], v[98:99], v[182:183]
	v_mov_b32_e32 v227, v195
	v_sub_f32_e32 v182, v176, v177
	v_pk_mul_f32 v[176:177], v[98:99], v[178:179]
	v_cvt_pk_fp8_f32 v227, v231, v232
	v_add_f32_e32 v178, v177, v176
	v_mov_b32_e32 v176, v195
	v_mov_b32_e32 v177, v195
	v_cvt_pk_fp8_f32 v176, v193, v184
	v_cvt_pk_fp8_f32 v177, v185, v188
	v_cvt_pk_fp8_f32 v226, v229, v230 op_sel:[0,0,1]
	v_cvt_pk_fp8_f32 v227, v233, v239 op_sel:[0,0,1]
	v_cvt_pk_fp8_f32 v176, v180, v181 op_sel:[0,0,1]
	v_cvt_pk_fp8_f32 v177, v182, v178 op_sel:[0,0,1]
	global_store_dwordx2 v[222:223], v[226:227], off offset:3200
	global_store_dwordx2 v[186:187], v[176:177], off offset:3200
	v_mov_b32_e32 v176, v168
	v_mov_b32_e32 v177, v172
	v_pk_mul_f32 v[178:179], v[92:93], v[176:177]
	v_pk_mul_f32 v[176:177], v[84:85], v[176:177]
	v_sub_f32_e32 v186, v178, v179
	v_mov_b32_e32 v178, v172
	v_mov_b32_e32 v179, v168
	v_pk_mul_f32 v[180:181], v[92:93], v[178:179]
	v_mov_b32_e32 v172, v169
	v_add_f32_e32 v187, v181, v180
	v_pk_mul_f32 v[180:181], v[94:95], v[172:173]
	v_mov_b32_e32 v168, v173
	v_sub_f32_e32 v188, v180, v181
	v_pk_mul_f32 v[180:181], v[94:95], v[168:169]
	v_pk_mul_f32 v[172:173], v[86:87], v[172:173]
	v_add_f32_e32 v189, v181, v180
	v_mov_b32_e32 v180, v170
	v_mov_b32_e32 v181, v174
	v_pk_mul_f32 v[182:183], v[88:89], v[180:181]
	v_pk_mul_f32 v[168:169], v[86:87], v[168:169]
	v_sub_f32_e32 v190, v182, v183
	v_mov_b32_e32 v182, v174
	v_mov_b32_e32 v183, v170
	v_pk_mul_f32 v[184:185], v[88:89], v[182:183]
	v_mov_b32_e32 v174, v171
	v_add_f32_e32 v191, v185, v184
	v_pk_mul_f32 v[184:185], v[90:91], v[174:175]
	v_mov_b32_e32 v170, v175
	v_sub_f32_e32 v193, v184, v185
	v_pk_mul_f32 v[184:185], v[90:91], v[170:171]
	v_sub_f32_e32 v172, v172, v173
	v_add_f32_e32 v224, v185, v184
	v_mov_b32_e32 v184, v195
	v_mov_b32_e32 v185, v195
	v_cvt_pk_fp8_f32 v184, v186, v187
	v_cvt_pk_fp8_f32 v185, v190, v191
	v_add_co_u32_e32 v186, vcc, s34, v222
	v_cvt_pk_fp8_f32 v184, v188, v189 op_sel:[0,0,1]
	v_cvt_pk_fp8_f32 v185, v193, v224 op_sel:[0,0,1]
	v_addc_co_u32_e32 v187, vcc, 0, v223, vcc
	v_add_f32_e32 v173, v169, v168
	global_store_dwordx2 v[186:187], v[184:185], off offset:2176
	v_sub_f32_e32 v184, v176, v177
	v_pk_mul_f32 v[176:177], v[84:85], v[178:179]
	v_pk_mul_f32 v[168:169], v[80:81], v[180:181]
	v_add_f32_e32 v176, v177, v176
	v_sub_f32_e32 v177, v168, v169
	v_pk_mul_f32 v[168:169], v[80:81], v[182:183]
	s_mov_b32 s34, 0x301000
	v_add_f32_e32 v178, v169, v168
	v_pk_mul_f32 v[168:169], v[82:83], v[174:175]
	s_nop 0
	v_sub_f32_e32 v174, v168, v169
	v_pk_mul_f32 v[168:169], v[82:83], v[170:171]
	s_nop 0
	v_add_f32_e32 v170, v169, v168
	v_mov_b32_e32 v168, v195
	v_mov_b32_e32 v169, v195
	v_cvt_pk_fp8_f32 v168, v184, v176
	v_cvt_pk_fp8_f32 v169, v177, v178
	v_cvt_pk_fp8_f32 v168, v172, v173 op_sel:[0,0,1]
	v_cvt_pk_fp8_f32 v169, v174, v170 op_sel:[0,0,1]
	v_add_co_u32_e32 v170, vcc, s34, v222
	s_movk_i32 s34, 0x2000
	s_nop 0
	v_addc_co_u32_e32 v171, vcc, 0, v223, vcc
	global_store_dwordx2 v[170:171], v[168:169], off offset:2176
	v_mov_b32_e32 v168, v160
	v_mov_b32_e32 v169, v164
	v_pk_mul_f32 v[170:171], v[76:77], v[168:169]
	v_pk_mul_f32 v[168:169], v[68:69], v[168:169]
	v_sub_f32_e32 v178, v170, v171
	v_mov_b32_e32 v170, v164
	v_mov_b32_e32 v171, v160
	v_pk_mul_f32 v[172:173], v[76:77], v[170:171]
	v_mov_b32_e32 v164, v161
	v_add_f32_e32 v179, v173, v172
	v_pk_mul_f32 v[172:173], v[78:79], v[164:165]
	v_mov_b32_e32 v160, v165
	v_sub_f32_e32 v180, v172, v173
	v_pk_mul_f32 v[172:173], v[78:79], v[160:161]
	v_pk_mul_f32 v[164:165], v[70:71], v[164:165]
	v_add_f32_e32 v181, v173, v172
	v_mov_b32_e32 v172, v162
	v_mov_b32_e32 v173, v166
	v_pk_mul_f32 v[174:175], v[72:73], v[172:173]
	v_pk_mul_f32 v[160:161], v[70:71], v[160:161]
	v_sub_f32_e32 v182, v174, v175
	v_mov_b32_e32 v174, v166
	v_mov_b32_e32 v175, v162
	v_pk_mul_f32 v[176:177], v[72:73], v[174:175]
	v_mov_b32_e32 v166, v163
	v_add_f32_e32 v183, v177, v176
	v_pk_mul_f32 v[176:177], v[74:75], v[166:167]
	v_mov_b32_e32 v162, v167
	v_sub_f32_e32 v184, v176, v177
	v_pk_mul_f32 v[176:177], v[74:75], v[162:163]
	v_sub_f32_e32 v164, v164, v165
	v_add_f32_e32 v185, v177, v176
	v_mov_b32_e32 v176, v195
	v_mov_b32_e32 v177, v195
	v_cvt_pk_fp8_f32 v176, v178, v179
	v_cvt_pk_fp8_f32 v177, v182, v183
	v_add_co_u32_e32 v178, vcc, s34, v222
	v_cvt_pk_fp8_f32 v176, v180, v181 op_sel:[0,0,1]
	v_cvt_pk_fp8_f32 v177, v184, v185 op_sel:[0,0,1]
	v_addc_co_u32_e32 v179, vcc, 0, v223, vcc
	v_add_f32_e32 v165, v161, v160
	global_store_dwordx2 v[178:179], v[176:177], off offset:1152
	v_sub_f32_e32 v176, v168, v169
	v_pk_mul_f32 v[168:169], v[68:69], v[170:171]
	v_pk_mul_f32 v[160:161], v[64:65], v[172:173]
	v_add_f32_e32 v168, v169, v168
	v_sub_f32_e32 v169, v160, v161
	v_pk_mul_f32 v[160:161], v[64:65], v[174:175]
	s_mov_b32 s34, 0x302000
	v_add_f32_e32 v170, v161, v160
	v_pk_mul_f32 v[160:161], v[66:67], v[166:167]
	s_nop 0
	v_sub_f32_e32 v166, v160, v161
	v_pk_mul_f32 v[160:161], v[66:67], v[162:163]
	s_nop 0
	v_add_f32_e32 v162, v161, v160
	v_mov_b32_e32 v160, v195
	v_mov_b32_e32 v161, v195
	v_cvt_pk_fp8_f32 v160, v176, v168
	v_cvt_pk_fp8_f32 v161, v169, v170
	v_cvt_pk_fp8_f32 v160, v164, v165 op_sel:[0,0,1]
	v_cvt_pk_fp8_f32 v161, v166, v162 op_sel:[0,0,1]
	v_add_co_u32_e32 v162, vcc, s34, v222
	s_movk_i32 s34, 0x6000
;     __device__ __forceinline__ void operator()(const f32x4 (&acc)[2][2][4][2], const Unit& u, int wr, int wc, int fr, int fq, LAS unsigned char* lds, int par, int npm, int tid) const {
;     ...
;                     for (int bj = 0; bj < 2; ++bj) { const f32x4 v0 = acc[ai][bj][m][0], v1 = acc[ai][bj][m][1];
;                         const float f[8] = {v0[0] * c[0] - v0[1] * s[0], v0[1] * c[0] + v0[0] * s[0], v0[2] * c[1] - v0[3] * s[1], v0[3] * c[1] + v0[2] * s[1],
;                                             v1[0] * c[2] - v1[1] * s[2], v1[1] * c[2] + v1[0] * s[2], v1[2] * c[3] - v1[3] * s[3], v1[3] * c[3] + v1[2] * s[3]};
;                         *(u32x2*)(d0 + (size_t)ro * 192 + (size_t)bj * 2 * S_ * 192) = pack8_fp8(f); } }
	s_nop 0
	v_addc_co_u32_e32 v163, vcc, 0, v223, vcc
	global_store_dwordx2 v[162:163], v[160:161], off offset:1152
	v_mov_b32_e32 v160, v152
	v_mov_b32_e32 v161, v156
	v_pk_mul_f32 v[162:163], v[60:61], v[160:161]
	v_pk_mul_f32 v[160:161], v[52:53], v[160:161]
	v_sub_f32_e32 v170, v162, v163
	v_mov_b32_e32 v162, v156
	v_mov_b32_e32 v163, v152
	v_pk_mul_f32 v[164:165], v[60:61], v[162:163]
	v_mov_b32_e32 v156, v153
	v_add_f32_e32 v171, v165, v164
	v_pk_mul_f32 v[164:165], v[62:63], v[156:157]
	v_mov_b32_e32 v152, v157
	v_sub_f32_e32 v172, v164, v165
	v_pk_mul_f32 v[164:165], v[62:63], v[152:153]
	v_pk_mul_f32 v[156:157], v[54:55], v[156:157]
	v_add_f32_e32 v173, v165, v164
	v_mov_b32_e32 v164, v154
	v_mov_b32_e32 v165, v158
	v_pk_mul_f32 v[166:167], v[56:57], v[164:165]
	v_pk_mul_f32 v[152:153], v[54:55], v[152:153]
	v_sub_f32_e32 v174, v166, v167
	v_mov_b32_e32 v166, v158
	v_mov_b32_e32 v167, v154
	v_pk_mul_f32 v[168:169], v[56:57], v[166:167]
	v_mov_b32_e32 v158, v155
	v_add_f32_e32 v175, v169, v168
	v_pk_mul_f32 v[168:169], v[58:59], v[158:159]
	v_mov_b32_e32 v154, v159
	v_sub_f32_e32 v176, v168, v169
	v_pk_mul_f32 v[168:169], v[58:59], v[154:155]
	v_sub_f32_e32 v156, v156, v157
	v_add_f32_e32 v177, v169, v168
	v_mov_b32_e32 v168, v195
	v_mov_b32_e32 v169, v195
	v_cvt_pk_fp8_f32 v168, v170, v171
	v_cvt_pk_fp8_f32 v169, v174, v175
	v_add_co_u32_e32 v170, vcc, s34, v222
	v_cvt_pk_fp8_f32 v168, v172, v173 op_sel:[0,0,1]
	v_cvt_pk_fp8_f32 v169, v176, v177 op_sel:[0,0,1]
	v_addc_co_u32_e32 v171, vcc, 0, v223, vcc
	v_add_f32_e32 v157, v153, v152
	global_store_dwordx2 v[170:171], v[168:169], off offset:128
	v_sub_f32_e32 v168, v160, v161
	v_pk_mul_f32 v[160:161], v[52:53], v[162:163]
	v_pk_mul_f32 v[152:153], v[48:49], v[164:165]
	v_add_f32_e32 v160, v161, v160
	v_sub_f32_e32 v161, v152, v153
	v_pk_mul_f32 v[152:153], v[48:49], v[166:167]
	s_mov_b32 s34, 0x306000
	v_add_f32_e32 v162, v153, v152
	v_pk_mul_f32 v[152:153], v[50:51], v[158:159]
	s_nop 0
	v_sub_f32_e32 v158, v152, v153
	v_pk_mul_f32 v[152:153], v[50:51], v[154:155]
	s_nop 0
	v_add_f32_e32 v154, v153, v152
	v_mov_b32_e32 v152, v195
	v_mov_b32_e32 v153, v195
	v_cvt_pk_fp8_f32 v152, v168, v160
	v_cvt_pk_fp8_f32 v153, v161, v162
	v_cvt_pk_fp8_f32 v152, v156, v157 op_sel:[0,0,1]
	v_cvt_pk_fp8_f32 v153, v158, v154 op_sel:[0,0,1]
	v_add_co_u32_e32 v154, vcc, s34, v222
	s_movk_i32 s34, 0x7000
	s_nop 0
	v_addc_co_u32_e32 v155, vcc, 0, v223, vcc
	global_store_dwordx2 v[154:155], v[152:153], off offset:128
	v_mov_b32_e32 v152, v144
	v_mov_b32_e32 v153, v148
	v_pk_mul_f32 v[156:157], v[44:45], v[152:153]
	v_pk_mul_f32 v[152:153], v[36:37], v[152:153]
	v_sub_f32_e32 v164, v156, v157
	v_mov_b32_e32 v156, v148
	v_mov_b32_e32 v157, v144
	v_pk_mul_f32 v[158:159], v[44:45], v[156:157]
	v_mov_b32_e32 v148, v145
	v_add_f32_e32 v165, v159, v158
	v_pk_mul_f32 v[158:159], v[46:47], v[148:149]
	v_mov_b32_e32 v144, v149
	v_sub_f32_e32 v166, v158, v159
	v_pk_mul_f32 v[158:159], v[46:47], v[144:145]
	v_pk_mul_f32 v[148:149], v[38:39], v[148:149]
	v_add_f32_e32 v167, v159, v158
	v_mov_b32_e32 v158, v146
	v_mov_b32_e32 v159, v150
	v_pk_mul_f32 v[160:161], v[40:41], v[158:159]
	v_pk_mul_f32 v[144:145], v[38:39], v[144:145]
	v_sub_f32_e32 v168, v160, v161
	v_mov_b32_e32 v160, v150
	v_mov_b32_e32 v161, v146
	v_pk_mul_f32 v[162:163], v[40:41], v[160:161]
	v_mov_b32_e32 v150, v147
	v_add_f32_e32 v169, v163, v162
	v_pk_mul_f32 v[162:163], v[42:43], v[150:151]
	v_mov_b32_e32 v146, v151
	v_sub_f32_e32 v172, v162, v163
	v_pk_mul_f32 v[162:163], v[42:43], v[146:147]
	v_sub_f32_e32 v148, v148, v149
	v_add_f32_e32 v173, v163, v162
	v_mov_b32_e32 v162, v195
	v_mov_b32_e32 v163, v195
	v_cvt_pk_fp8_f32 v162, v164, v165
	v_cvt_pk_fp8_f32 v163, v168, v169
	v_add_f32_e32 v149, v145, v144
	v_pk_mul_f32 v[144:145], v[32:33], v[158:159]
	v_cvt_pk_fp8_f32 v162, v166, v167 op_sel:[0,0,1]
	v_cvt_pk_fp8_f32 v163, v172, v173 op_sel:[0,0,1]
	global_store_dwordx2 v[170:171], v[162:163], off offset:3200
	v_sub_f32_e32 v162, v152, v153
	v_pk_mul_f32 v[152:153], v[36:37], v[156:157]
	s_nop 0
	v_add_f32_e32 v152, v153, v152
	v_sub_f32_e32 v153, v144, v145
	v_pk_mul_f32 v[144:145], v[32:33], v[160:161]
	s_nop 0
	v_add_f32_e32 v156, v145, v144
	v_pk_mul_f32 v[144:145], v[34:35], v[150:151]
	s_nop 0
	v_sub_f32_e32 v150, v144, v145
	v_pk_mul_f32 v[144:145], v[34:35], v[146:147]
	s_nop 0
	v_add_f32_e32 v146, v145, v144
	v_mov_b32_e32 v144, v195
	v_mov_b32_e32 v145, v195
	v_cvt_pk_fp8_f32 v144, v162, v152
	v_cvt_pk_fp8_f32 v145, v153, v156
	v_cvt_pk_fp8_f32 v144, v148, v149 op_sel:[0,0,1]
	v_cvt_pk_fp8_f32 v145, v150, v146 op_sel:[0,0,1]
	global_store_dwordx2 v[154:155], v[144:145], off offset:3200
	v_mov_b32_e32 v144, v136
	v_mov_b32_e32 v145, v140
	v_pk_mul_f32 v[146:147], v[28:29], v[144:145]
	v_pk_mul_f32 v[144:145], v[20:21], v[144:145]
	v_sub_f32_e32 v154, v146, v147
	v_mov_b32_e32 v146, v140
	v_mov_b32_e32 v147, v136
	v_pk_mul_f32 v[148:149], v[28:29], v[146:147]
	v_mov_b32_e32 v140, v137
	v_add_f32_e32 v155, v149, v148
	v_pk_mul_f32 v[148:149], v[30:31], v[140:141]
	v_mov_b32_e32 v136, v141
	v_sub_f32_e32 v156, v148, v149
	v_pk_mul_f32 v[148:149], v[30:31], v[136:137]
	v_pk_mul_f32 v[140:141], v[22:23], v[140:141]
	v_add_f32_e32 v157, v149, v148
	v_mov_b32_e32 v148, v138
	v_mov_b32_e32 v149, v142
	v_pk_mul_f32 v[150:151], v[24:25], v[148:149]
	v_pk_mul_f32 v[136:137], v[22:23], v[136:137]
	v_sub_f32_e32 v158, v150, v151
	v_mov_b32_e32 v150, v142
	v_mov_b32_e32 v151, v138
	v_pk_mul_f32 v[152:153], v[24:25], v[150:151]
	v_mov_b32_e32 v142, v139
	v_add_f32_e32 v159, v153, v152
	v_pk_mul_f32 v[152:153], v[26:27], v[142:143]
	v_mov_b32_e32 v138, v143
;     __device__ __forceinline__ void operator()(const f32x4 (&acc)[2][2][4][2], const Unit& u, int wr, int wc, int fr, int fq, LAS unsigned char* lds, int par, int npm, int tid) const {
;     ...
;                     for (int bj = 0; bj < 2; ++bj) { const f32x4 v0 = acc[ai][bj][m][0], v1 = acc[ai][bj][m][1];
;                         const float f[8] = {v0[0] * c[0] - v0[1] * s[0], v0[1] * c[0] + v0[0] * s[0], v0[2] * c[1] - v0[3] * s[1], v0[3] * c[1] + v0[2] * s[1],
;                                             v1[0] * c[2] - v1[1] * s[2], v1[1] * c[2] + v1[0] * s[2], v1[2] * c[3] - v1[3] * s[3], v1[3] * c[3] + v1[2] * s[3]};
;                         *(u32x2*)(d0 + (size_t)ro * 192 + (size_t)bj * 2 * S_ * 192) = pack8_fp8(f); } }
	v_sub_f32_e32 v160, v152, v153
	v_pk_mul_f32 v[152:153], v[26:27], v[138:139]
	v_sub_f32_e32 v140, v140, v141
	v_add_f32_e32 v161, v153, v152
	v_mov_b32_e32 v152, v195
	v_mov_b32_e32 v153, v195
	v_cvt_pk_fp8_f32 v152, v154, v155
	v_cvt_pk_fp8_f32 v153, v158, v159
	v_add_co_u32_e32 v154, vcc, s34, v222
	v_cvt_pk_fp8_f32 v152, v156, v157 op_sel:[0,0,1]
	v_cvt_pk_fp8_f32 v153, v160, v161 op_sel:[0,0,1]
	v_addc_co_u32_e32 v155, vcc, 0, v223, vcc
	v_add_f32_e32 v141, v137, v136
	global_store_dwordx2 v[154:155], v[152:153], off offset:2176
	v_sub_f32_e32 v152, v144, v145
	v_pk_mul_f32 v[144:145], v[20:21], v[146:147]
	v_pk_mul_f32 v[136:137], v[16:17], v[148:149]
	v_add_f32_e32 v144, v145, v144
	v_sub_f32_e32 v145, v136, v137
	v_pk_mul_f32 v[136:137], v[16:17], v[150:151]
	s_mov_b32 s34, 0x307000
	v_add_f32_e32 v146, v137, v136
	v_pk_mul_f32 v[136:137], v[18:19], v[142:143]
	s_nop 0
	v_sub_f32_e32 v142, v136, v137
	v_pk_mul_f32 v[136:137], v[18:19], v[138:139]
	s_nop 0
	v_add_f32_e32 v138, v137, v136
	v_mov_b32_e32 v136, v195
	v_mov_b32_e32 v137, v195
	v_cvt_pk_fp8_f32 v136, v152, v144
	v_cvt_pk_fp8_f32 v137, v145, v146
	v_cvt_pk_fp8_f32 v136, v140, v141 op_sel:[0,0,1]
	v_cvt_pk_fp8_f32 v137, v142, v138 op_sel:[0,0,1]
	v_add_co_u32_e32 v138, vcc, s34, v222
	s_mov_b32 s34, 0x8000
	s_nop 0
	v_addc_co_u32_e32 v139, vcc, 0, v223, vcc
	global_store_dwordx2 v[138:139], v[136:137], off offset:2176
	v_mov_b32_e32 v136, v128
	v_mov_b32_e32 v137, v132
	v_pk_mul_f32 v[138:139], v[12:13], v[136:137]
	v_pk_mul_f32 v[136:137], v[4:5], v[136:137]
	v_sub_f32_e32 v146, v138, v139
	v_mov_b32_e32 v138, v132
	v_mov_b32_e32 v139, v128
	v_pk_mul_f32 v[140:141], v[12:13], v[138:139]
	v_mov_b32_e32 v132, v129
	v_add_f32_e32 v147, v141, v140
	v_pk_mul_f32 v[140:141], v[14:15], v[132:133]
	v_mov_b32_e32 v128, v133
	v_sub_f32_e32 v148, v140, v141
	v_pk_mul_f32 v[140:141], v[14:15], v[128:129]
	v_pk_mul_f32 v[132:133], v[6:7], v[132:133]
	v_add_f32_e32 v149, v141, v140
	v_mov_b32_e32 v140, v130
	v_mov_b32_e32 v141, v134
	v_pk_mul_f32 v[142:143], v[8:9], v[140:141]
	v_pk_mul_f32 v[128:129], v[6:7], v[128:129]
	v_sub_f32_e32 v150, v142, v143
	v_mov_b32_e32 v142, v134
	v_mov_b32_e32 v143, v130
	v_pk_mul_f32 v[144:145], v[8:9], v[142:143]
	v_mov_b32_e32 v134, v131
	v_add_f32_e32 v151, v145, v144
	v_pk_mul_f32 v[144:145], v[10:11], v[134:135]
	v_mov_b32_e32 v130, v135
	v_sub_f32_e32 v152, v144, v145
	v_pk_mul_f32 v[144:145], v[10:11], v[130:131]
	v_sub_f32_e32 v132, v132, v133
	v_add_f32_e32 v153, v145, v144
	v_mov_b32_e32 v144, v195
	v_mov_b32_e32 v145, v195
	v_cvt_pk_fp8_f32 v144, v146, v147
	v_cvt_pk_fp8_f32 v145, v150, v151
	v_add_co_u32_e32 v146, vcc, s34, v222
	v_cvt_pk_fp8_f32 v144, v148, v149 op_sel:[0,0,1]
	v_cvt_pk_fp8_f32 v145, v152, v153 op_sel:[0,0,1]
	v_addc_co_u32_e32 v147, vcc, 0, v223, vcc
	v_add_f32_e32 v133, v129, v128
	global_store_dwordx2 v[146:147], v[144:145], off offset:1152
	v_sub_f32_e32 v144, v136, v137
	v_pk_mul_f32 v[136:137], v[4:5], v[138:139]
	v_pk_mul_f32 v[128:129], v[0:1], v[140:141]
	v_add_f32_e32 v136, v137, v136
	v_sub_f32_e32 v137, v128, v129
	v_pk_mul_f32 v[128:129], v[0:1], v[142:143]
	s_mov_b64 s[34:35], 0
	v_add_f32_e32 v138, v129, v128
	v_pk_mul_f32 v[128:129], v[2:3], v[134:135]
	s_nop 0
	v_sub_f32_e32 v134, v128, v129
	v_pk_mul_f32 v[128:129], v[2:3], v[130:131]
	s_nop 0
	v_add_f32_e32 v130, v129, v128
	v_mov_b32_e32 v128, v195
	v_mov_b32_e32 v129, v195
	v_cvt_pk_fp8_f32 v128, v144, v136
	v_cvt_pk_fp8_f32 v129, v137, v138
	v_cvt_pk_fp8_f32 v128, v132, v133 op_sel:[0,0,1]
	v_cvt_pk_fp8_f32 v129, v134, v130 op_sel:[0,0,1]
	v_add_co_u32_e32 v130, vcc, 0x308000, v222
	s_nop 1
	v_addc_co_u32_e32 v131, vcc, 0, v223, vcc
	global_store_dwordx2 v[130:131], v[128:129], off offset:1152
;     __device__ __forceinline__ void operator()(const f32x4 (&acc)[2][2][4][2], const Unit& u, int wr, int wc, int fr, int fq, LAS unsigned char* lds, int par, int npm, int tid) const {
;     ...
;         if (u.pn < 4) {
;             unsigned char* d0 = Q + ((size_t)(u.pn * 2) * S_ + row0) * 192 + wc * 32 + 8 * fq;
; #pragma unroll
;             for (int ai = 0; ai < 2; ++ai)
; #pragma unroll
;                 for (int m = 0; m < 4; ++m)
; #pragma unroll
;                     for (int bj = 0; bj < 2; ++bj) { const f32x4 v0 = acc[ai][bj][m][0], v1 = acc[ai][bj][m][1];
;                         const float f[8] = {v0[0], v0[1], v0[2], v0[3], v1[0], v1[1], v1[2], v1[3]};
;                         *(u32x2*)(d0 + (size_t)(ai * HALF + m * 16) * 192 + (size_t)bj * S_ * 192) = pack8_fp8(f); }
.LBB0_422:
	s_andn2_b64 vcc, exec, s[34:35]
	s_cbranch_vccnz .LBB0_409
	s_lshl_b32 s34, s33, 1
	s_ashr_i32 s35, s34, 31
	s_lshl_b64 s[34:35], s[34:35], 13
	v_lshl_add_u64 v[130:131], s[34:35], 0, v[220:221]
	s_movk_i32 s33, 0xc0
	v_mad_u64_u32 v[128:129], s[34:35], v130, s33, v[212:213]
	v_mad_i32_i24 v129, v131, s33, v129
	v_mov_b32_e32 v131, v195
	v_cvt_pk_fp8_f32 v131, v120, v121
	v_mov_b32_e32 v121, v195
	v_cvt_pk_fp8_f32 v121, v112, v113
	s_mov_b32 s33, 0x180000
	v_add_co_u32_e32 v112, vcc, s33, v128
	v_cvt_pk_fp8_f32 v121, v114, v115 op_sel:[0,0,1]
	v_mov_b32_e32 v115, v195
	v_cvt_pk_fp8_f32 v115, v104, v105
	v_mov_b32_e32 v105, v195
	v_cvt_pk_fp8_f32 v105, v96, v97
	v_mov_b32_e32 v96, v195
	v_mov_b32_e32 v97, v195
	v_cvt_pk_fp8_f32 v96, v92, v93
	v_cvt_pk_fp8_f32 v97, v88, v89
	v_addc_co_u32_e32 v113, vcc, 0, v129, vcc
	v_cvt_pk_fp8_f32 v96, v94, v95 op_sel:[0,0,1]
	v_cvt_pk_fp8_f32 v97, v90, v91 op_sel:[0,0,1]
	s_movk_i32 s33, 0x1000
	v_add_co_u32_e32 v88, vcc, s33, v128
	s_mov_b32 s33, 0x181000
	s_nop 0
	v_addc_co_u32_e32 v89, vcc, 0, v129, vcc
	global_store_dwordx2 v[88:89], v[96:97], off offset:2048
	v_mov_b32_e32 v88, v195
	v_mov_b32_e32 v89, v195
	v_cvt_pk_fp8_f32 v88, v84, v85
	v_cvt_pk_fp8_f32 v89, v80, v81
	v_add_co_u32_e32 v80, vcc, s33, v128
	v_cvt_pk_fp8_f32 v88, v86, v87 op_sel:[0,0,1]
	v_cvt_pk_fp8_f32 v89, v82, v83 op_sel:[0,0,1]
	v_addc_co_u32_e32 v81, vcc, 0, v129, vcc
	s_movk_i32 s33, 0x2000
	global_store_dwordx2 v[80:81], v[88:89], off offset:2048
	v_mov_b32_e32 v80, v195
	v_mov_b32_e32 v81, v195
	v_cvt_pk_fp8_f32 v80, v76, v77
	v_cvt_pk_fp8_f32 v81, v72, v73
	v_add_co_u32_e32 v72, vcc, s33, v128
	v_cvt_pk_fp8_f32 v80, v78, v79 op_sel:[0,0,1]
	v_cvt_pk_fp8_f32 v81, v74, v75 op_sel:[0,0,1]
	v_addc_co_u32_e32 v73, vcc, 0, v129, vcc
	s_mov_b32 s33, 0x182000
	global_store_dwordx2 v[72:73], v[80:81], off offset:1024
	v_mov_b32_e32 v72, v195
	v_mov_b32_e32 v73, v195
	v_cvt_pk_fp8_f32 v72, v68, v69
	v_cvt_pk_fp8_f32 v73, v64, v65
	v_add_co_u32_e32 v64, vcc, s33, v128
	v_cvt_pk_fp8_f32 v72, v70, v71 op_sel:[0,0,1]
	v_cvt_pk_fp8_f32 v73, v66, v67 op_sel:[0,0,1]
	v_addc_co_u32_e32 v65, vcc, 0, v129, vcc
	s_movk_i32 s33, 0x6000
	global_store_dwordx2 v[64:65], v[72:73], off offset:1024
	v_mov_b32_e32 v65, v195
	v_cvt_pk_fp8_f32 v65, v56, v57
	v_add_co_u32_e32 v56, vcc, s33, v128
	s_mov_b32 s33, 0x186000
	v_cvt_pk_fp8_f32 v65, v58, v59 op_sel:[0,0,1]
	v_mov_b32_e32 v59, v195
	v_cvt_pk_fp8_f32 v59, v48, v49
	v_addc_co_u32_e32 v57, vcc, 0, v129, vcc
	v_add_co_u32_e32 v48, vcc, s33, v128
	v_cvt_pk_fp8_f32 v59, v50, v51 op_sel:[0,0,1]
	v_mov_b32_e32 v51, v195
	v_cvt_pk_fp8_f32 v51, v40, v41
	v_mov_b32_e32 v41, v195
	v_cvt_pk_fp8_f32 v41, v32, v33
	v_mov_b32_e32 v32, v195
	v_mov_b32_e32 v33, v195
	v_cvt_pk_fp8_f32 v32, v28, v29
	v_cvt_pk_fp8_f32 v33, v24, v25
	v_addc_co_u32_e32 v49, vcc, 0, v129, vcc
	v_cvt_pk_fp8_f32 v32, v30, v31 op_sel:[0,0,1]
	v_cvt_pk_fp8_f32 v33, v26, v27 op_sel:[0,0,1]
	s_movk_i32 s33, 0x7000
	v_add_co_u32_e32 v24, vcc, s33, v128
	v_mov_b32_e32 v130, v195
	s_nop 0
	v_addc_co_u32_e32 v25, vcc, 0, v129, vcc
	global_store_dwordx2 v[24:25], v[32:33], off offset:2048
	v_mov_b32_e32 v24, v195
	v_mov_b32_e32 v25, v195
	v_cvt_pk_fp8_f32 v24, v20, v21
	v_cvt_pk_fp8_f32 v25, v16, v17
	v_add_co_u32_e32 v16, vcc, 0x187000, v128
	v_cvt_pk_fp8_f32 v24, v22, v23 op_sel:[0,0,1]
	v_cvt_pk_fp8_f32 v25, v18, v19 op_sel:[0,0,1]
	v_addc_co_u32_e32 v17, vcc, 0, v129, vcc
	v_mov_b32_e32 v120, v195
	global_store_dwordx2 v[16:17], v[24:25], off offset:2048
	v_mov_b32_e32 v16, v195
	v_mov_b32_e32 v17, v195
	v_cvt_pk_fp8_f32 v16, v12, v13
	v_cvt_pk_fp8_f32 v17, v8, v9
	v_add_co_u32_e32 v8, vcc, 0x8000, v128
	v_cvt_pk_fp8_f32 v16, v14, v15 op_sel:[0,0,1]
	v_cvt_pk_fp8_f32 v17, v10, v11 op_sel:[0,0,1]
	v_addc_co_u32_e32 v9, vcc, 0, v129, vcc
	v_mov_b32_e32 v114, v195
	v_mov_b32_e32 v104, v195
	v_mov_b32_e32 v64, v195
	v_mov_b32_e32 v58, v195
	v_mov_b32_e32 v50, v195
	v_mov_b32_e32 v40, v195
	global_store_dwordx2 v[8:9], v[16:17], off offset:1024
	v_mov_b32_e32 v8, v195
	v_mov_b32_e32 v9, v195
	v_cvt_pk_fp8_f32 v130, v124, v125
	v_cvt_pk_fp8_f32 v120, v116, v117
	v_cvt_pk_fp8_f32 v114, v108, v109
	v_cvt_pk_fp8_f32 v104, v100, v101
	v_cvt_pk_fp8_f32 v64, v60, v61
	v_cvt_pk_fp8_f32 v58, v52, v53
	v_cvt_pk_fp8_f32 v50, v44, v45
	v_cvt_pk_fp8_f32 v40, v36, v37
	v_cvt_pk_fp8_f32 v8, v4, v5
	v_cvt_pk_fp8_f32 v9, v0, v1
	v_cvt_pk_fp8_f32 v130, v126, v127 op_sel:[0,0,1]
	v_cvt_pk_fp8_f32 v131, v122, v123 op_sel:[0,0,1]
	v_cvt_pk_fp8_f32 v120, v118, v119 op_sel:[0,0,1]
	v_cvt_pk_fp8_f32 v114, v110, v111 op_sel:[0,0,1]
	v_cvt_pk_fp8_f32 v115, v106, v107 op_sel:[0,0,1]
	v_cvt_pk_fp8_f32 v104, v102, v103 op_sel:[0,0,1]
	v_cvt_pk_fp8_f32 v105, v98, v99 op_sel:[0,0,1]
	v_cvt_pk_fp8_f32 v64, v62, v63 op_sel:[0,0,1]
	v_cvt_pk_fp8_f32 v58, v54, v55 op_sel:[0,0,1]
	v_cvt_pk_fp8_f32 v50, v46, v47 op_sel:[0,0,1]
	v_cvt_pk_fp8_f32 v51, v42, v43 op_sel:[0,0,1]
	v_cvt_pk_fp8_f32 v40, v38, v39 op_sel:[0,0,1]
	v_cvt_pk_fp8_f32 v41, v34, v35 op_sel:[0,0,1]
	v_cvt_pk_fp8_f32 v8, v6, v7 op_sel:[0,0,1]
	v_cvt_pk_fp8_f32 v9, v2, v3 op_sel:[0,0,1]
	v_add_co_u32_e32 v0, vcc, 0x188000, v128
	global_store_dwordx2 v[128:129], v[130:131], off
	s_nop 0
	v_addc_co_u32_e32 v1, vcc, 0, v129, vcc
	global_store_dwordx2 v[112:113], v[120:121], off
	global_store_dwordx2 v[128:129], v[114:115], off offset:3072
	global_store_dwordx2 v[112:113], v[104:105], off offset:3072
	global_store_dwordx2 v[56:57], v[64:65], off
	global_store_dwordx2 v[48:49], v[58:59], off
	global_store_dwordx2 v[56:57], v[50:51], off offset:3072
	global_store_dwordx2 v[48:49], v[40:41], off offset:3072
	global_store_dwordx2 v[0:1], v[8:9], off offset:1024
	s_branch .LBB0_409

; #define PG8_WAIT_V(n) asm volatile("s_waitcnt vmcnt(" #n ")" ::: "memory")
; #define PG8_BAR __builtin_amdgcn_s_barrier()
; template <class Epi>
; __device__ __forceinline__ void gemm_phase(LAS unsigned char* lds, const Gemm g, const StaticOrder& S, const Epi& E) {
;     ...
;     PG8_WAIT_V(0);
;     if (wr == 0) PG8_BAR;
;     __device__ __forceinline__ void operator()(const f32x4 (&acc)[2][2][4][2], const Unit& u, int wr, int wc, int fr, int fq, LAS unsigned char* lds, int par, int npm, int tid) const {
;         const int row0 = u.pm * BM + wr * 64 + fr, col0 = u.pn * BM + wc * 32 + 8 * fq;
; #pragma unroll
;         for (int ai = 0; ai < 2; ++ai)
; #pragma unroll
;             for (int m = 0; m < 4; ++m)
; #pragma unroll
;                 for (int bj = 0; bj < 2; ++bj) { const f32x4 v0 = acc[ai][bj][m][0], v1 = acc[ai][bj][m][1];
;                     const float f[8] = {v0[0], v0[1], v0[2], v0[3], v1[0], v1[1], v1[2], v1[3]};
;                     *(u32x2*)(Vt + (size_t)(row0 + ai * HALF + m * 16) * S_ + col0 + bj * HALF) = pack8_fp8(f); }
.LBB0_434:
	v_mov_b32_e32 v133, v195
	v_cvt_pk_fp8_f32 v133, v120, v121
	v_lshl_add_u32 v128, s37, 8, v138
	v_lshl_or_b32 v129, s36, 8, v139
	v_or_b32_e32 v194, s38, v129
	v_cvt_pk_fp8_f32 v133, v122, v123 op_sel:[0,0,1]
	v_mov_b32_e32 v123, v195
	v_cvt_pk_fp8_f32 v123, v112, v113
	v_ashrrev_i32_e32 v129, 31, v128
	v_readlane_b32 s4, v254, 29
	v_or_b32_e32 v112, 16, v128
	v_cvt_pk_fp8_f32 v123, v114, v115 op_sel:[0,0,1]
	v_mov_b32_e32 v115, v195
	v_cvt_pk_fp8_f32 v115, v104, v105
	v_lshlrev_b64 v[130:131], 13, v[128:129]
	v_readlane_b32 s5, v254, 30
	v_ashrrev_i32_e32 v113, 31, v112
	v_cvt_pk_fp8_f32 v115, v106, v107 op_sel:[0,0,1]
	v_mov_b32_e32 v107, v195
	v_cvt_pk_fp8_f32 v107, v96, v97
	v_or_b32_e32 v96, 32, v128
	v_ashrrev_i32_e32 v97, 31, v96
	v_lshl_add_u64 v[120:121], s[4:5], 0, v[130:131]
	v_cvt_pk_fp8_f32 v107, v98, v99 op_sel:[0,0,1]
	v_mov_b32_e32 v99, v195
	v_cvt_pk_fp8_f32 v99, v88, v89
	v_lshlrev_b64 v[112:113], 13, v[112:113]
	v_lshlrev_b64 v[96:97], 13, v[96:97]
	v_lshl_add_u64 v[120:121], v[120:121], 0, v[194:195]
	v_cvt_pk_fp8_f32 v99, v90, v91 op_sel:[0,0,1]
	v_mov_b32_e32 v91, v195
	v_cvt_pk_fp8_f32 v91, v80, v81
	v_or_b32_e32 v80, 48, v128
	v_ashrrev_i32_e32 v81, 31, v80
	v_lshlrev_b64 v[80:81], 13, v[80:81]
	v_cvt_pk_fp8_f32 v91, v82, v83 op_sel:[0,0,1]
	v_mov_b32_e32 v83, v195
	v_cvt_pk_fp8_f32 v83, v72, v73
	v_lshl_add_u64 v[104:105], s[4:5], 0, v[112:113]
	v_lshl_add_u64 v[88:89], s[4:5], 0, v[96:97]
	v_lshl_add_u64 v[72:73], s[4:5], 0, v[80:81]
	v_cvt_pk_fp8_f32 v83, v74, v75 op_sel:[0,0,1]
	v_mov_b32_e32 v75, v195
	v_cvt_pk_fp8_f32 v75, v64, v65
	v_mov_b32_e32 v64, v195
	v_mov_b32_e32 v65, v195
	v_cvt_pk_fp8_f32 v64, v60, v61
	v_cvt_pk_fp8_f32 v65, v56, v57
	s_mov_b64 s[4:5], 0x100000
	v_lshl_add_u64 v[56:57], v[120:121], 0, s[4:5]
	v_cvt_pk_fp8_f32 v64, v62, v63 op_sel:[0,0,1]
	v_cvt_pk_fp8_f32 v65, v58, v59 op_sel:[0,0,1]
	s_mov_b32 s4, 0x100000
	v_add_co_u32_e32 v58, vcc, s4, v120
	s_mov_b64 s[4:5], 0x120000
	s_nop 0
	v_addc_co_u32_e32 v59, vcc, 0, v121, vcc
	global_store_dwordx2 v[58:59], v[64:65], off
	v_mov_b32_e32 v59, v195
	v_cvt_pk_fp8_f32 v59, v48, v49
	v_mov_b32_e32 v48, v195
	v_mov_b32_e32 v49, v195
	v_cvt_pk_fp8_f32 v48, v44, v45
	v_cvt_pk_fp8_f32 v49, v40, v41
	v_lshl_add_u64 v[40:41], v[120:121], 0, s[4:5]
	s_mov_b32 s4, 0x120000
	v_cvt_pk_fp8_f32 v48, v46, v47 op_sel:[0,0,1]
	v_cvt_pk_fp8_f32 v49, v42, v43 op_sel:[0,0,1]
	v_add_co_u32_e32 v42, vcc, s4, v120
	s_mov_b64 s[4:5], 0x140000
	s_nop 0
	v_addc_co_u32_e32 v43, vcc, 0, v121, vcc
	global_store_dwordx2 v[42:43], v[48:49], off
	v_mov_b32_e32 v43, v195
	v_cvt_pk_fp8_f32 v43, v32, v33
	v_mov_b32_e32 v32, v195
	v_mov_b32_e32 v33, v195
	v_cvt_pk_fp8_f32 v32, v28, v29
	v_cvt_pk_fp8_f32 v33, v24, v25
	v_lshl_add_u64 v[24:25], v[120:121], 0, s[4:5]
	s_mov_b32 s4, 0x140000
	v_cvt_pk_fp8_f32 v32, v30, v31 op_sel:[0,0,1]
	v_cvt_pk_fp8_f32 v33, v26, v27 op_sel:[0,0,1]
	v_add_co_u32_e32 v26, vcc, s4, v120
	v_mov_b32_e32 v132, v195
	s_nop 0
	v_addc_co_u32_e32 v27, vcc, 0, v121, vcc
	global_store_dwordx2 v[26:27], v[32:33], off
	v_mov_b32_e32 v27, v195
	v_cvt_pk_fp8_f32 v27, v16, v17
	v_mov_b32_e32 v16, v195
	v_mov_b32_e32 v17, v195
	v_cvt_pk_fp8_f32 v16, v12, v13
	v_cvt_pk_fp8_f32 v17, v8, v9
	v_mov_b32_e32 v122, v195
	v_mov_b32_e32 v114, v195
	v_cvt_pk_fp8_f32 v16, v14, v15 op_sel:[0,0,1]
	v_cvt_pk_fp8_f32 v17, v10, v11 op_sel:[0,0,1]
	v_add_co_u32_e32 v10, vcc, 0x160000, v120
	v_mov_b32_e32 v106, v195
	s_nop 0
	v_addc_co_u32_e32 v11, vcc, 0, v121, vcc
	v_mov_b32_e32 v98, v195
	v_mov_b32_e32 v90, v195
	v_mov_b32_e32 v82, v195
	v_mov_b32_e32 v74, v195
	v_mov_b32_e32 v58, v195
	v_mov_b32_e32 v42, v195
	v_mov_b32_e32 v26, v195
	global_store_dwordx2 v[10:11], v[16:17], off
	v_mov_b32_e32 v10, v195
	v_mov_b32_e32 v11, v195
	v_cvt_pk_fp8_f32 v132, v124, v125
	v_cvt_pk_fp8_f32 v122, v116, v117
	v_cvt_pk_fp8_f32 v114, v108, v109
	v_cvt_pk_fp8_f32 v106, v100, v101
	v_cvt_pk_fp8_f32 v98, v92, v93
	v_cvt_pk_fp8_f32 v90, v84, v85
	v_cvt_pk_fp8_f32 v82, v76, v77
	v_cvt_pk_fp8_f32 v74, v68, v69
	v_cvt_pk_fp8_f32 v58, v52, v53
	v_cvt_pk_fp8_f32 v42, v36, v37
	v_cvt_pk_fp8_f32 v26, v20, v21
	v_cvt_pk_fp8_f32 v10, v4, v5
	v_cvt_pk_fp8_f32 v11, v0, v1
	v_cvt_pk_fp8_f32 v132, v126, v127 op_sel:[0,0,1]
	v_cvt_pk_fp8_f32 v122, v118, v119 op_sel:[0,0,1]
	v_cvt_pk_fp8_f32 v114, v110, v111 op_sel:[0,0,1]
	v_cvt_pk_fp8_f32 v106, v102, v103 op_sel:[0,0,1]
	v_cvt_pk_fp8_f32 v98, v94, v95 op_sel:[0,0,1]
	v_cvt_pk_fp8_f32 v90, v86, v87 op_sel:[0,0,1]
	v_cvt_pk_fp8_f32 v82, v78, v79 op_sel:[0,0,1]
	v_cvt_pk_fp8_f32 v74, v70, v71 op_sel:[0,0,1]
	v_cvt_pk_fp8_f32 v75, v66, v67 op_sel:[0,0,1]
	v_cvt_pk_fp8_f32 v58, v54, v55 op_sel:[0,0,1]
	v_cvt_pk_fp8_f32 v59, v50, v51 op_sel:[0,0,1]
	v_cvt_pk_fp8_f32 v42, v38, v39 op_sel:[0,0,1]
	v_cvt_pk_fp8_f32 v43, v34, v35 op_sel:[0,0,1]
	v_cvt_pk_fp8_f32 v26, v22, v23 op_sel:[0,0,1]
	v_cvt_pk_fp8_f32 v27, v18, v19 op_sel:[0,0,1]
	v_cvt_pk_fp8_f32 v10, v6, v7 op_sel:[0,0,1]
	v_cvt_pk_fp8_f32 v11, v2, v3 op_sel:[0,0,1]
	s_mov_b64 s[4:5], 0x160000
	v_lshl_add_u64 v[104:105], v[104:105], 0, v[194:195]
	v_lshl_add_u64 v[88:89], v[88:89], 0, v[194:195]
	v_lshl_add_u64 v[72:73], v[72:73], 0, v[194:195]
	v_lshl_add_u64 v[8:9], v[120:121], 0, s[4:5]
	global_store_dwordx2 v[120:121], v[132:133], off
	global_store_dwordx2 v[120:121], v[122:123], off offset:128
	global_store_dwordx2 v[104:105], v[114:115], off
	global_store_dwordx2 v[104:105], v[106:107], off offset:128
	global_store_dwordx2 v[88:89], v[98:99], off
	global_store_dwordx2 v[88:89], v[90:91], off offset:128
	global_store_dwordx2 v[72:73], v[82:83], off
	global_store_dwordx2 v[72:73], v[74:75], off offset:128
	global_store_dwordx2 v[56:57], v[58:59], off offset:128
	global_store_dwordx2 v[40:41], v[42:43], off offset:128
	global_store_dwordx2 v[24:25], v[26:27], off offset:128
	global_store_dwordx2 v[8:9], v[10:11], off offset:128
	s_waitcnt vmcnt(0)
	s_cmpk_lt_u32 s33, 0x100
	s_cbranch_scc0 .LBB0_436
	s_barrier

;     __device__ __forceinline__ void operator()(const f32x4 (&acc)[2][2][4][2], const Unit& u, int wr, int wc, int fr, int fq, LAS unsigned char* lds, int par, int npm, int tid) const {
;         const int row0 = u.pm * BM + wr * 64 + fr;
;         unsigned char* d0 = Kb + ((size_t)(u.pn * 2) * S_ + row0) * 192 + wc * 32 + 8 * fq;
; #pragma unroll
;         for (int ai = 0; ai < 2; ++ai)
; #pragma unroll
;             for (int m = 0; m < 4; ++m)
; #pragma unroll
;                 for (int bj = 0; bj < 2; ++bj) { const f32x4 v0 = acc[ai][bj][m][0], v1 = acc[ai][bj][m][1];
;                     const float f[8] = {v0[0], v0[1], v0[2], v0[3], v1[0], v1[1], v1[2], v1[3]};
;                     *(u32x2*)(d0 + (size_t)(ai * HALF + m * 16) * 192 + (size_t)bj * S_ * 192) = pack8_fp8(f); }
.LBB0_446:
	s_lshl_b32 s34, s56, 1
	v_lshl_add_u32 v140, s55, 8, v142
	s_ashr_i32 s35, s34, 31
	s_lshl_b64 s[34:35], s[34:35], 13
	v_ashrrev_i32_e32 v141, 31, v140
	v_lshl_add_u64 v[146:147], s[34:35], 0, v[140:141]
	s_movk_i32 s36, 0xc0
	v_mad_u64_u32 v[140:141], s[34:35], v146, s36, v[134:135]
	v_mad_i32_i24 v141, v147, s36, v141
	v_mov_b32_e32 v147, v195
	v_cvt_pk_fp8_f32 v147, v120, v121
	v_mov_b32_e32 v121, v195
	v_cvt_pk_fp8_f32 v121, v112, v113
	s_mov_b32 s34, 0x180000
	v_add_co_u32_e32 v112, vcc, s34, v140
	v_cvt_pk_fp8_f32 v121, v114, v115 op_sel:[0,0,1]
	v_mov_b32_e32 v115, v195
	v_cvt_pk_fp8_f32 v115, v104, v105
	v_mov_b32_e32 v105, v195
	v_cvt_pk_fp8_f32 v105, v96, v97
	v_mov_b32_e32 v96, v195
	v_mov_b32_e32 v97, v195
	v_cvt_pk_fp8_f32 v96, v92, v93
	v_cvt_pk_fp8_f32 v97, v88, v89
	v_addc_co_u32_e32 v113, vcc, 0, v141, vcc
	v_cvt_pk_fp8_f32 v96, v94, v95 op_sel:[0,0,1]
	v_cvt_pk_fp8_f32 v97, v90, v91 op_sel:[0,0,1]
	s_movk_i32 s34, 0x1000
	v_add_co_u32_e32 v88, vcc, s34, v140
	s_mov_b32 s34, 0x181000
	s_nop 0
	v_addc_co_u32_e32 v89, vcc, 0, v141, vcc
	global_store_dwordx2 v[88:89], v[96:97], off offset:2048
	v_mov_b32_e32 v88, v195
	v_mov_b32_e32 v89, v195
	v_cvt_pk_fp8_f32 v88, v84, v85
	v_cvt_pk_fp8_f32 v89, v80, v81
	v_add_co_u32_e32 v80, vcc, s34, v140
	v_cvt_pk_fp8_f32 v88, v86, v87 op_sel:[0,0,1]
	v_cvt_pk_fp8_f32 v89, v82, v83 op_sel:[0,0,1]
	v_addc_co_u32_e32 v81, vcc, 0, v141, vcc
	s_movk_i32 s34, 0x2000
	global_store_dwordx2 v[80:81], v[88:89], off offset:2048
	v_mov_b32_e32 v80, v195
	v_mov_b32_e32 v81, v195
	v_cvt_pk_fp8_f32 v80, v76, v77
	v_cvt_pk_fp8_f32 v81, v72, v73
	v_add_co_u32_e32 v72, vcc, s34, v140
	v_cvt_pk_fp8_f32 v80, v78, v79 op_sel:[0,0,1]
	v_cvt_pk_fp8_f32 v81, v74, v75 op_sel:[0,0,1]
	v_addc_co_u32_e32 v73, vcc, 0, v141, vcc
	s_mov_b32 s34, 0x182000
	global_store_dwordx2 v[72:73], v[80:81], off offset:1024
	v_mov_b32_e32 v72, v195
	v_mov_b32_e32 v73, v195
	v_cvt_pk_fp8_f32 v72, v68, v69
	v_cvt_pk_fp8_f32 v73, v64, v65
	v_add_co_u32_e32 v64, vcc, s34, v140
	v_cvt_pk_fp8_f32 v72, v70, v71 op_sel:[0,0,1]
	v_cvt_pk_fp8_f32 v73, v66, v67 op_sel:[0,0,1]
	v_addc_co_u32_e32 v65, vcc, 0, v141, vcc
	s_movk_i32 s34, 0x6000
	global_store_dwordx2 v[64:65], v[72:73], off offset:1024
	v_mov_b32_e32 v65, v195
	v_cvt_pk_fp8_f32 v65, v56, v57
	v_add_co_u32_e32 v56, vcc, s34, v140
	s_mov_b32 s34, 0x186000
	v_cvt_pk_fp8_f32 v65, v58, v59 op_sel:[0,0,1]
	v_mov_b32_e32 v59, v195
	v_cvt_pk_fp8_f32 v59, v48, v49
	v_addc_co_u32_e32 v57, vcc, 0, v141, vcc
	v_add_co_u32_e32 v48, vcc, s34, v140
	v_cvt_pk_fp8_f32 v59, v50, v51 op_sel:[0,0,1]
	v_mov_b32_e32 v51, v195
	v_cvt_pk_fp8_f32 v51, v40, v41
	v_mov_b32_e32 v41, v195
	v_cvt_pk_fp8_f32 v41, v32, v33
	v_mov_b32_e32 v32, v195
	v_mov_b32_e32 v33, v195
	v_cvt_pk_fp8_f32 v32, v28, v29
	v_cvt_pk_fp8_f32 v33, v24, v25
	v_addc_co_u32_e32 v49, vcc, 0, v141, vcc
	v_cvt_pk_fp8_f32 v32, v30, v31 op_sel:[0,0,1]
	v_cvt_pk_fp8_f32 v33, v26, v27 op_sel:[0,0,1]
	s_movk_i32 s34, 0x7000
	v_add_co_u32_e32 v24, vcc, s34, v140
	s_mov_b32 s34, 0x187000
	s_nop 0
	v_addc_co_u32_e32 v25, vcc, 0, v141, vcc
	global_store_dwordx2 v[24:25], v[32:33], off offset:2048
	v_mov_b32_e32 v24, v195
	v_mov_b32_e32 v25, v195
	v_cvt_pk_fp8_f32 v24, v20, v21
	v_cvt_pk_fp8_f32 v25, v16, v17
	v_add_co_u32_e32 v16, vcc, s34, v140
	v_cvt_pk_fp8_f32 v24, v22, v23 op_sel:[0,0,1]
	v_cvt_pk_fp8_f32 v25, v18, v19 op_sel:[0,0,1]
	v_addc_co_u32_e32 v17, vcc, 0, v141, vcc
	s_mov_b32 s34, 0x8000
	global_store_dwordx2 v[16:17], v[24:25], off offset:2048
	v_mov_b32_e32 v16, v195
	v_mov_b32_e32 v17, v195
	v_cvt_pk_fp8_f32 v16, v12, v13
	v_cvt_pk_fp8_f32 v17, v8, v9
	v_add_co_u32_e32 v8, vcc, s34, v140
	v_cvt_pk_fp8_f32 v16, v14, v15 op_sel:[0,0,1]
	v_cvt_pk_fp8_f32 v17, v10, v11 op_sel:[0,0,1]
	v_addc_co_u32_e32 v9, vcc, 0, v141, vcc
	v_mov_b32_e32 v146, v195
	v_mov_b32_e32 v120, v195
	v_mov_b32_e32 v114, v195
	v_mov_b32_e32 v104, v195
	v_mov_b32_e32 v64, v195
	v_mov_b32_e32 v58, v195
	v_mov_b32_e32 v50, v195
	v_mov_b32_e32 v40, v195
	global_store_dwordx2 v[8:9], v[16:17], off offset:1024
	v_mov_b32_e32 v8, v195
	v_mov_b32_e32 v9, v195
	v_cvt_pk_fp8_f32 v146, v124, v125
	v_cvt_pk_fp8_f32 v120, v116, v117
	v_cvt_pk_fp8_f32 v114, v108, v109
	v_cvt_pk_fp8_f32 v104, v100, v101
	v_cvt_pk_fp8_f32 v64, v60, v61
	v_cvt_pk_fp8_f32 v58, v52, v53
	v_cvt_pk_fp8_f32 v50, v44, v45
	v_cvt_pk_fp8_f32 v40, v36, v37
	v_cvt_pk_fp8_f32 v8, v4, v5
	v_cvt_pk_fp8_f32 v9, v0, v1
	v_cvt_pk_fp8_f32 v146, v126, v127 op_sel:[0,0,1]
	v_cvt_pk_fp8_f32 v147, v122, v123 op_sel:[0,0,1]
	v_cvt_pk_fp8_f32 v120, v118, v119 op_sel:[0,0,1]
	v_cvt_pk_fp8_f32 v114, v110, v111 op_sel:[0,0,1]
	v_cvt_pk_fp8_f32 v115, v106, v107 op_sel:[0,0,1]
	v_cvt_pk_fp8_f32 v104, v102, v103 op_sel:[0,0,1]
	v_cvt_pk_fp8_f32 v105, v98, v99 op_sel:[0,0,1]
	v_cvt_pk_fp8_f32 v64, v62, v63 op_sel:[0,0,1]
	v_cvt_pk_fp8_f32 v58, v54, v55 op_sel:[0,0,1]
	v_cvt_pk_fp8_f32 v50, v46, v47 op_sel:[0,0,1]
	v_cvt_pk_fp8_f32 v51, v42, v43 op_sel:[0,0,1]
	v_cvt_pk_fp8_f32 v40, v38, v39 op_sel:[0,0,1]
	v_cvt_pk_fp8_f32 v41, v34, v35 op_sel:[0,0,1]
	v_cvt_pk_fp8_f32 v8, v6, v7 op_sel:[0,0,1]
	v_cvt_pk_fp8_f32 v9, v2, v3 op_sel:[0,0,1]
	v_add_co_u32_e32 v0, vcc, 0x188000, v140
	s_mov_b32 s56, s54
	s_nop 0
	v_addc_co_u32_e32 v1, vcc, 0, v141, vcc
	s_and_b64 vcc, exec, s[26:27]
	s_mov_b32 s55, s53
	s_mov_b64 s[34:35], s[30:31]
	s_mov_b64 s[36:37], s[28:29]
	global_store_dwordx2 v[140:141], v[146:147], off
	global_store_dwordx2 v[112:113], v[120:121], off
	global_store_dwordx2 v[140:141], v[114:115], off offset:3072
	global_store_dwordx2 v[112:113], v[104:105], off offset:3072
	global_store_dwordx2 v[56:57], v[64:65], off
	global_store_dwordx2 v[48:49], v[58:59], off
	global_store_dwordx2 v[56:57], v[50:51], off offset:3072
	global_store_dwordx2 v[48:49], v[40:41], off offset:3072
	global_store_dwordx2 v[0:1], v[8:9], off offset:1024
	s_cbranch_vccnz .LBB0_461

; #define LAS __attribute__((address_space(3)))
; __device__ __forceinline__ int ltid() { int t = threadIdx.x; asm volatile("" : "+v"(t)); return t; }
; __device__ __forceinline__ void ret_local(const Bufs& B, int item, LAS unsigned char* lds) {
;     const int tid = ltid(), wid = tid >> 6, lane = tid & 63, wr = wid >> 2, wc = wid & 3, fr = lane & 15, fq = lane >> 4;
;     const int c = item & 63, h = (item >> 6) & 3, dir = item >> 8, s0 = c * 128, hd = dir ? 3 - h : h;
;     const float lg = log1pf(-exp2f(-5.f - (float)hd));
;     LAS bf16_t* T0 = (LAS bf16_t*)(lds + CB0); LAS bf16_t* T1 = (LAS bf16_t*)(lds + CB1); LAS float* vz = (LAS float*)(lds + CVEC);
;     u32x4 rk[2], rv[4];
;     ld_T<64>(rk, B.RQK + (size_t)s0 * 512 + 256 + h * 64, 512, tid);
;     ld_T<128>(rv, B.PROJ + (size_t)s0 * NPROJP + PC_RV + h * 128, NPROJP, tid);
;     if (tid < 128) { const int lp = dir ? 127 - tid : tid; vz[tid] = __expf((float)(127 - lp) * lg); }
; __global__ void __launch_bounds__(512) mega_fwd(Params p) {
;     ...
;             if (bx < 192) for (int it = bx; it < 1024; it += 192) { if (it < 512) mlstm_local(B, it, lds); else ret_local(B, it - 512, lds); }
.LBB0_472:
	s_mov_b32 s26, s0
	s_cmpk_gt_i32 s0, 0x1ff
	s_mov_b64 s[0:1], -1
	s_cbranch_scc0 .LBB0_478
	s_add_i32 s4, s26, 0xfffffe00
	s_lshl_b32 s0, s4, 7
	v_mov_b32_e32 v32, v192
	s_and_b32 s6, s0, 0x1f80
	s_bfe_u32 s5, s26, 0x20006
	s_lshl_b32 s0, s6, 10
	v_readlane_b32 s24, v254, 17
	v_ashrrev_i32_e32 v33, 4, v32
	v_readlane_b32 s25, v254, 18
	s_add_u32 s0, s24, s0
	v_and_b32_e32 v30, -8, v33
	s_addc_u32 s1, s25, 0
	s_lshl_b32 s7, s5, 7
	v_ashrrev_i32_e32 v31, 31, v30
	v_add_u32_e32 v6, 0x200, v32
	s_add_u32 s0, s0, s7
	v_lshlrev_b32_e32 v0, 10, v32
	v_lshlrev_b64 v[2:3], 1, v[30:31]
	v_ashrrev_i32_e32 v31, 4, v6
	s_addc_u32 s1, s1, 0
	v_and_b32_e32 v194, 0x1fc00, v0
	v_and_b32_e32 v28, -8, v31
	s_waitcnt lgkmcnt(0)
	v_lshl_add_u64 v[0:1], s[0:1], 0, v[194:195]
	v_ashrrev_i32_e32 v29, 31, v28
	s_mulk_i32 s6, 0x2400
	v_readlane_b32 s0, v254, 23
	v_lshlrev_b64 v[6:7], 1, v[28:29]
	v_readlane_b32 s1, v254, 24
	s_add_u32 s0, s0, s6
	v_lshl_add_u64 v[4:5], v[0:1], 0, v[2:3]
	v_lshl_add_u64 v[0:1], v[0:1], 0, v[6:7]
	s_addc_u32 s1, s1, 0
	s_lshl_b32 s6, s5, 8
	v_and_b32_e32 v34, 0x7f, v32
	global_load_dwordx4 v[20:23], v[4:5], off offset:512
	global_load_dwordx4 v[12:15], v[0:1], off offset:512
	s_add_u32 s0, s0, s6
	v_mul_u32_u24_e32 v0, 0x1200, v34
	s_addc_u32 s1, s1, 0
	v_lshlrev_b32_e32 v194, 1, v0
	v_lshl_add_u64 v[0:1], s[0:1], 0, v[194:195]
	s_mov_b64 s[0:1], 0x1420
	v_lshl_add_u64 v[0:1], v[0:1], 0, s[0:1]
	v_lshl_add_u64 v[2:3], v[0:1], 0, v[2:3]
	v_lshl_add_u64 v[4:5], v[0:1], 0, v[6:7]
	global_load_dwordx4 v[16:19], v[2:3], off
	global_load_dwordx4 v[8:11], v[4:5], off
	v_add_u32_e32 v2, 0x400, v32
	v_ashrrev_i32_e32 v29, 4, v2
	v_and_b32_e32 v26, -8, v29
	v_ashrrev_i32_e32 v27, 31, v26
	v_add_u32_e32 v4, 0x600, v32
	v_lshl_add_u64 v[2:3], v[26:27], 1, v[0:1]
	v_ashrrev_i32_e32 v27, 4, v4
	v_and_b32_e32 v24, -8, v27
	v_ashrrev_i32_e32 v25, 31, v24
	v_lshl_add_u64 v[0:1], v[24:25], 1, v[0:1]
	global_load_dwordx4 v[4:7], v[2:3], off
	s_nop 0
	global_load_dwordx4 v[0:3], v[0:1], off
	s_movk_i32 s0, 0x80
	v_cmp_gt_i32_e32 vcc, s0, v32
	s_and_saveexec_b64 s[0:1], vcc
	s_cbranch_execz .LBB0_475
	s_xor_b32 s24, s5, 3
	s_cmpk_lt_u32 s4, 0x100
	s_cselect_b64 vcc, -1, 0
	s_and_b64 s[6:7], vcc, exec
	s_cselect_b32 s5, s5, s24
	v_cvt_f32_ubyte0_e32 v35, s5
	v_sub_u32_e32 v25, 0x7f, v32
	v_sub_f32_e32 v35, 0xc0a00000, v35
	s_mov_b32 s5, 0xc2fc0000
	v_cndmask_b32_e32 v25, v32, v25, vcc
	v_cmp_gt_f32_e32 vcc, s5, v35
	s_and_b64 s[6:7], vcc, exec
	s_cselect_b32 s5, 0xffffffc0, 0
	v_cndmask_b32_e32 v36, 0, v240, vcc
	v_add_f32_e32 v35, v35, v36
	v_exp_f32_e32 v35, v35
	v_cvt_f32_i32_e32 v25, v25
	v_ldexp_f32 v35, v35, s5
	v_sub_f32_e32 v38, 1.0, v35
	v_cvt_f64_f32_e32 v[36:37], v38
	v_frexp_exp_i32_f64_e32 v36, v[36:37]
	v_frexp_mant_f32_e32 v37, v38
	s_mov_b32 s5, 0x3f2aaaab
	v_cmp_gt_f32_e32 vcc, s5, v37
	v_add_f32_e32 v40, -1.0, v38
	v_sub_f32_e64 v41, -v35, v40
	v_subbrev_co_u32_e32 v37, vcc, 0, v36, vcc
	v_cvt_f32_i32_e32 v36, v37
	v_sub_u32_e32 v37, 0, v37
	v_ldexp_f32 v39, v38, v37
	v_sub_f32_e32 v38, v40, v38
	v_add_f32_e32 v38, 1.0, v38
	v_add_f32_e32 v43, -1.0, v39
	v_add_f32_e32 v38, v41, v38
	v_ldexp_f32 v37, v38, v37
	v_add_f32_e32 v38, 1.0, v43
	v_sub_f32_e32 v38, v39, v38
	v_add_f32_e32 v44, v37, v38
	v_add_f32_e32 v38, 1.0, v39
	v_add_f32_e32 v40, -1.0, v38
	v_sub_f32_e32 v39, v39, v40
	v_add_f32_e32 v37, v37, v39
	v_add_f32_e32 v46, v38, v37
	v_rcp_f32_e32 v47, v46
	v_add_f32_e32 v39, v43, v44
	v_sub_f32_e32 v38, v46, v38
	v_sub_f32_e32 v37, v37, v38
	v_mul_f32_e32 v48, v39, v47
	v_mul_f32_e32 v40, v46, v48
	v_fma_f32 v42, v48, v46, -v40
	v_fmac_f32_e32 v42, v48, v37
	v_add_f32_e32 v38, v40, v42
	v_sub_f32_e32 v41, v39, v38
	v_sub_f32_e32 v43, v39, v43
	v_sub_f32_e32 v49, v44, v43
	v_pk_add_f32 v[44:45], v[38:39], v[40:41] neg_lo:[0,1] neg_hi:[0,1]
	v_mov_b32_e32 v43, v38
	v_pk_add_f32 v[38:39], v[44:45], v[42:43] neg_lo:[0,1] neg_hi:[0,1]
	s_mov_b32 s5, 0x3f317218
	v_add_f32_e32 v39, v49, v39
	v_add_f32_e32 v44, v38, v39
	v_add_f32_e32 v39, v41, v44
	v_mul_f32_e32 v38, v47, v39
	v_add_f32_e32 v49, v48, v38
	v_sub_f32_e32 v40, v49, v48
	v_mul_f32_e32 v42, v46, v38
	v_sub_f32_e32 v48, v38, v40
	v_fma_f32 v40, v38, v46, -v42
	v_fmac_f32_e32 v40, v38, v37
	v_add_f32_e32 v38, v42, v40
	v_sub_f32_e32 v43, v39, v38
	v_sub_f32_e32 v37, v41, v39
	v_add_f32_e32 v37, v44, v37
	v_pk_add_f32 v[44:45], v[38:39], v[42:43] neg_lo:[0,1] neg_hi:[0,1]
	v_mov_b32_e32 v41, v38
	v_pk_add_f32 v[38:39], v[44:45], v[40:41] neg_lo:[0,1] neg_hi:[0,1]
	v_cmp_nlt_f32_e32 vcc, 1.0, v35
	v_add_f32_e32 v37, v37, v39
	v_add_f32_e32 v37, v38, v37
	v_add_f32_e32 v37, v43, v37
	v_mul_f32_e32 v37, v47, v37
	v_add_f32_e32 v38, v48, v37
	v_add_f32_e32 v40, v49, v38
	v_mul_f32_e32 v41, v40, v40
	v_fmamk_f32 v42, v41, 0x3e9b6dac, v234
	v_ldexp_f32 v39, v40, 1
	v_mul_f32_e32 v37, v40, v41
	v_fmaak_f32 v201, v41, v42, 0x3f2aaada
	v_sub_f32_e32 v40, v40, v49
	v_sub_f32_e32 v38, v38, v40
	v_pk_mul_f32 v[40:41], v[36:37], v[200:201]
	v_ldexp_f32 v42, v38, 1
	v_fma_f32 v38, v36, s5, -v40
	v_fmac_f32_e32 v38, 0xb102e308, v36
	v_pk_add_f32 v[36:37], v[40:41], v[38:39]
	s_mov_b32 s5, 0x33800000
	v_sub_f32_e32 v39, v37, v39
	v_sub_f32_e32 v39, v41, v39
	v_add_f32_e32 v43, v42, v39
	v_mov_b32_e32 v42, v40
	v_pk_add_f32 v[40:41], v[36:37], v[40:41] neg_lo:[0,1] neg_hi:[0,1]
	v_pk_add_f32 v[44:45], v[36:37], v[42:43]
	v_mov_b32_e32 v39, v36
	v_mov_b32_e32 v41, v45
	v_pk_add_f32 v[46:47], v[38:39], v[40:41] neg_lo:[0,1] neg_hi:[0,1]
	v_pk_add_f32 v[38:39], v[38:39], v[40:41]
	v_mov_b32_e32 v50, v37
	v_pk_add_f32 v[40:41], v[38:39], v[36:37] op_sel:[1,0] op_sel_hi:[0,1] neg_lo:[0,1] neg_hi:[0,1]
	v_pk_add_f32 v[48:49], v[44:45], v[40:41] op_sel_hi:[1,0] neg_lo:[0,1] neg_hi:[0,1]
	v_mov_b32_e32 v44, v45
	v_mov_b32_e32 v45, v39
	v_mov_b32_e32 v51, v40
	v_pk_add_f32 v[40:41], v[44:45], v[50:51] neg_lo:[0,1] neg_hi:[0,1]
	v_mov_b32_e32 v42, v43
	v_mov_b32_e32 v43, v36
	v_pk_add_f32 v[36:37], v[42:43], v[40:41] neg_lo:[0,1] neg_hi:[0,1]
	v_mov_b32_e32 v48, v46
	v_pk_add_f32 v[40:41], v[48:49], v[36:37]
	v_mov_b32_e32 v47, v39
	v_pk_add_f32 v[42:43], v[40:41], v[40:41] op_sel:[0,1] op_sel_hi:[1,0]
	s_nop 0
	v_pk_add_f32 v[38:39], v[38:39], v[42:43] op_sel:[1,0] op_sel_hi:[0,1]
	v_mov_b32_e32 v41, v38
	v_pk_add_f32 v[44:45], v[40:41], v[46:47] neg_lo:[0,1] neg_hi:[0,1]
	v_mov_b32_e32 v37, v42
	v_sub_f32_e32 v39, v40, v44
	v_pk_add_f32 v[36:37], v[36:37], v[44:45] neg_lo:[0,1] neg_hi:[0,1]
	v_sub_f32_e32 v39, v46, v39
	v_add_f32_e32 v36, v36, v39
	v_add_f32_e32 v36, v36, v37
	v_add_f32_e32 v36, v38, v36
	v_cndmask_b32_e32 v36, v251, v36, vcc
	v_cmp_neq_f32_e32 vcc, 1.0, v35
	s_nop 1
	v_cndmask_b32_e32 v36, v241, v36, vcc
	v_cmp_gt_f32_e32 vcc, s5, v35
	s_nop 1
	v_cndmask_b32_e64 v35, v36, -v35, vcc
	v_mul_f32_e32 v25, v35, v25
	v_mul_f32_e32 v25, 0x3fb8aa3b, v25
	v_exp_f32_e32 v25, v25
	v_lshl_add_u32 v35, v32, 2, 0
	v_add_u32_e32 v35, 0x22000, v35
	ds_write_b32 v35, v25

; #define LAS __attribute__((address_space(3)))
; __device__ __forceinline__ void mlstm_local(const Bufs& B, int item, LAS unsigned char* lds) {
;     ...
;     const int c = item & 63, h = (item >> 6) & 3, dir = item >> 8, s0 = c * 128;
;     LAS bf16_t* T0 = (LAS bf16_t*)(lds + CB0); LAS bf16_t* T1 = (LAS bf16_t*)(lds + CB1); LAS float* ve = (LAS float*)(lds + CVEC);
;     u32x4 rk[4], rv[4];
;     ld_T<128>(rk, B.QKML + (size_t)s0 * 1024 + 512 + h * 128, 1024, tid);
;     ld_T<128>(rv, B.PROJ + (size_t)s0 * NPROJP + PC_MLV + h * 128, NPROJP, tid);
;     if (wid == 0) {
;         const int l0 = 2 * lane, l1 = l0 + 1, p0 = dir ? 127 - l0 : l0, p1 = dir ? 127 - l1 : l1, gi = 8 * dir + h, gf = gi + 4;
;         const float li0 = B.G[(size_t)(s0 + p0) * 16 + gi], lf0 = B.G[(size_t)(s0 + p0) * 16 + gf], li1 = B.G[(size_t)(s0 + p1) * 16 + gi], lf1 = B.G[(size_t)(s0 + p1) * 16 + gf];
; __device__ __forceinline__ void ret_local(const Bufs& B, int item, LAS unsigned char* lds) {
;     ...
;     mma_tile<128, 1>(acc, T1, 136, T0, 136, wr, wc, fr, fq);
;     float* dst = B.RLOC + (size_t)item * 8192;
; #pragma unroll
;     for (int m = 0; m < 4; ++m)
; #pragma unroll
;         for (int j = 0; j < 4; ++j) dst[(64 * wr + 16 * m + 4 * fq + j) * 64 + 16 * wc + fr] = acc[m][0][j];
;     __syncthreads();
.LBB0_476:
	ds_read_b128 v[20:23], v19
	ds_read_b128 v[26:29], v18
	s_add_i32 s0, s0, 32
	s_cmpk_lt_u32 s0, 0x60
	v_add_u32_e32 v18, 64, v18
	s_waitcnt lgkmcnt(0)
	v_mfma_f32_16x16x32_bf16 v[12:15], v[20:23], v[26:29], v[12:15]
	ds_read_b128 v[20:23], v19 offset:4352
	s_waitcnt lgkmcnt(0)
	v_mfma_f32_16x16x32_bf16 v[8:11], v[20:23], v[26:29], v[8:11]
	ds_read_b128 v[20:23], v19 offset:8704
	s_waitcnt lgkmcnt(0)
	v_mfma_f32_16x16x32_bf16 v[4:7], v[20:23], v[26:29], v[4:7]
	ds_read_b128 v[20:23], v19 offset:13056
	v_add_u32_e32 v19, 64, v19
	s_waitcnt lgkmcnt(0)
	v_mfma_f32_16x16x32_bf16 v[0:3], v[20:23], v[26:29], v[0:3]
	s_cbranch_scc1 .LBB0_476
	s_lshl_b32 s0, s4, 13
	v_readlane_b32 s4, v253, 36
	v_and_b32_e32 v17, 0x3ffffc0, v17
	s_mov_b32 s1, s4
	s_lshl_b64 s[0:1], s[0:1], 2
	v_lshlrev_b32_e32 v18, 8, v25
	v_lshlrev_b32_e32 v17, 6, v17
	s_add_u32 s0, s22, s0
	v_or3_b32 v16, v18, v17, v16
	s_addc_u32 s1, s23, s1
	v_ashrrev_i32_e32 v17, 31, v16
	v_lshl_add_u64 v[16:17], v[16:17], 2, s[0:1]
	s_movk_i32 s0, 0x1000
	global_store_dword v[16:17], v12, off
	global_store_dword v[16:17], v13, off offset:256
	global_store_dword v[16:17], v14, off offset:512
	global_store_dword v[16:17], v15, off offset:768
	v_add_co_u32_e32 v12, vcc, s0, v16
	s_movk_i32 s0, 0x2000
	s_nop 0
	v_addc_co_u32_e32 v13, vcc, 0, v17, vcc
	global_store_dword v[12:13], v8, off
	global_store_dword v[12:13], v9, off offset:256
	global_store_dword v[12:13], v10, off offset:512
	global_store_dword v[12:13], v11, off offset:768
	v_add_co_u32_e32 v8, vcc, s0, v16
	s_mov_b64 s[0:1], 0
	s_nop 0
	v_addc_co_u32_e32 v9, vcc, 0, v17, vcc
	global_store_dword v[8:9], v4, off
	global_store_dword v[8:9], v5, off offset:256
	global_store_dword v[8:9], v6, off offset:512
	global_store_dword v[8:9], v7, off offset:768
	v_add_co_u32_e32 v4, vcc, 0x3000, v16
	v_readlane_b32 s5, v253, 37
	s_nop 0
	v_addc_co_u32_e32 v5, vcc, 0, v17, vcc
	global_store_dword v[4:5], v0, off
	global_store_dword v[4:5], v1, off offset:256
	global_store_dword v[4:5], v2, off offset:512
	global_store_dword v[4:5], v3, off offset:768
	s_waitcnt lgkmcnt(0)
	s_barrier
.LBB0_478:
	s_and_b64 vcc, exec, s[0:1]
	s_cbranch_vccz .LBB0_471
	s_lshl_b32 s0, s26, 7
	s_and_b32 s0, s0, 0x1f80
	s_bfe_u32 s1, s26, 0x20006
	s_lshl_b32 s4, s0, 11
	v_readlane_b32 s6, v254, 15
	v_mov_b32_e32 v40, v192
	v_readlane_b32 s7, v254, 16
	s_add_u32 s4, s6, s4
	s_addc_u32 s5, s7, 0
	s_lshl_b32 s6, s1, 8
	v_ashrrev_i32_e32 v42, 4, v40
	v_add_u32_e32 v6, 0x200, v40
	s_add_u32 s4, s4, s6
	v_and_b32_e32 v43, 0x7f, v40
	v_and_b32_e32 v38, -8, v42
	v_ashrrev_i32_e32 v41, 4, v6
	s_addc_u32 s5, s5, 0
	v_lshlrev_b32_e32 v194, 11, v43
	v_ashrrev_i32_e32 v39, 31, v38
	v_and_b32_e32 v34, -8, v41
	s_waitcnt lgkmcnt(0)
	v_lshl_add_u64 v[0:1], s[4:5], 0, v[194:195]
	v_lshlrev_b64 v[2:3], 1, v[38:39]
	v_ashrrev_i32_e32 v35, 31, v34
	v_lshl_add_u64 v[4:5], v[0:1], 0, v[2:3]
	v_lshlrev_b64 v[6:7], 1, v[34:35]
	v_lshl_add_u64 v[8:9], v[0:1], 0, v[6:7]
	global_load_dwordx4 v[28:31], v[4:5], off offset:1024
	global_load_dwordx4 v[20:23], v[8:9], off offset:1024
	v_add_u32_e32 v4, 0x400, v40
	v_add_u32_e32 v10, 0x600, v40
	v_ashrrev_i32_e32 v39, 4, v4
	v_ashrrev_i32_e32 v35, 4, v10
	s_mul_i32 s4, s0, 0x2400
	v_readlane_b32 s24, v254, 23
	v_and_b32_e32 v36, -8, v39
	v_and_b32_e32 v32, -8, v35
	v_readlane_b32 s25, v254, 24
	s_add_u32 s4, s24, s4
	v_ashrrev_i32_e32 v37, 31, v36
	v_ashrrev_i32_e32 v33, 31, v32
	s_addc_u32 s5, s25, 0
	v_lshlrev_b64 v[4:5], 1, v[36:37]
	v_lshlrev_b64 v[44:45], 1, v[32:33]
	s_add_u32 s4, s4, s6
	v_lshl_add_u64 v[8:9], v[0:1], 0, v[4:5]
	v_lshl_add_u64 v[0:1], v[0:1], 0, v[44:45]
	s_addc_u32 s5, s5, 0
	global_load_dwordx4 v[24:27], v[8:9], off offset:1024
	global_load_dwordx4 v[16:19], v[0:1], off offset:1024
	v_mov_b64_e32 v[0:1], s[4:5]
	s_movk_i32 s4, 0x2400
	v_mad_u64_u32 v[0:1], s[4:5], v43, s4, v[0:1]
	v_lshl_add_u64 v[2:3], v[0:1], 0, v[2:3]
	v_lshl_add_u64 v[6:7], v[0:1], 0, v[6:7]
	global_load_dwordx4 v[12:15], v[2:3], off offset:2048
	global_load_dwordx4 v[8:11], v[6:7], off offset:2048
	v_lshl_add_u64 v[2:3], v[0:1], 0, v[4:5]
	v_lshl_add_u64 v[0:1], v[0:1], 0, v[44:45]
	global_load_dwordx4 v[4:7], v[2:3], off offset:2048
	s_nop 0
	global_load_dwordx4 v[0:3], v[0:1], off offset:2048
	v_cmp_gt_u32_e32 vcc, 64, v40
	s_and_saveexec_b64 s[4:5], vcc
	s_cbranch_execz .LBB0_482
; __device__ __forceinline__ float wave_max(float v) { for (int o = 32; o > 0; o >>= 1) v = fmaxf(v, __shfl_xor(v, o)); return v; }
; __device__ __forceinline__ void mlstm_local(const Bufs& B, int item, LAS unsigned char* lds) {
;     ...
;         const int l0 = 2 * lane, l1 = l0 + 1, p0 = dir ? 127 - l0 : l0, p1 = dir ? 127 - l1 : l1, gi = 8 * dir + h, gf = gi + 4;
;         const float li0 = B.G[(size_t)(s0 + p0) * 16 + gi], lf0 = B.G[(size_t)(s0 + p0) * 16 + gf], li1 = B.G[(size_t)(s0 + p1) * 16 + gi], lf1 = B.G[(size_t)(s0 + p1) * 16 + gf];
;         const float t = lf0 + lf1, incl = scan_add64(t, lane), b0 = incl - t + lf0, b1 = incl, btot = __shfl(incl, 63);
;         const float w0 = btot - b0 + li0, w1 = btot - b1 + li1, mloc = wave_max(fmaxf(w0, w1));
;         ve[p0] = __expf(w0 - mloc); ve[p1] = __expf(w1 - mloc);
;         if (lane == 0) { B.MLOC[item] = mloc; B.BLAST[item] = btot; }
	v_lshlrev_b32_e32 v33, 1, v40
	s_cmpk_lt_u32 s26, 0x100
	v_or_b32_e32 v37, 1, v33
	s_cselect_b64 vcc, -1, 0
	v_sub_u32_e32 v44, 0x7f, v33
	s_ashr_i32 s6, s26, 5
	v_cndmask_b32_e32 v46, v44, v33, vcc
	v_sub_u32_e32 v33, 0x7f, v37
	s_and_b32 s6, s6, -8
	v_cndmask_b32_e32 v33, v33, v37, vcc
	s_or_b32 s6, s6, s1
	v_or_b32_e32 v37, s0, v46
	v_readlane_b32 s24, v254, 31
	v_lshlrev_b32_e32 v194, 4, v37
	s_ashr_i32 s7, s6, 31
	v_readlane_b32 s25, v254, 32
	s_lshl_b64 s[6:7], s[6:7], 2
	v_add_u32_e32 v49, -1, v238
	v_lshl_add_u64 v[44:45], v[194:195], 2, s[24:25]
	v_lshl_add_u64 v[44:45], v[44:45], 0, s[6:7]
	global_load_dword v47, v[44:45], off
	global_load_dword v37, v[44:45], off offset:16
	v_or_b32_e32 v44, s0, v33
	v_lshlrev_b32_e32 v194, 4, v44
	v_lshl_add_u64 v[44:45], v[194:195], 2, s[24:25]
	v_lshl_add_u64 v[44:45], v[44:45], 0, s[6:7]
	global_load_dword v48, v[44:45], off
	s_nop 0
	global_load_dword v44, v[44:45], off offset:16
	v_and_b32_e32 v45, 64, v238
	v_cmp_lt_i32_e32 vcc, v49, v45
	v_add_u32_e32 v50, -2, v238
	v_cmp_lt_i32_e64 s[0:1], v50, v45
	v_cndmask_b32_e32 v49, v49, v238, vcc
	v_lshlrev_b32_e32 v49, 2, v49
	v_cmp_eq_u32_e32 vcc, 0, v40
	v_cndmask_b32_e64 v50, v50, v238, s[0:1]
	v_lshlrev_b32_e32 v50, 2, v50
	v_cmp_gt_u32_e64 s[0:1], 2, v40
	s_waitcnt vmcnt(0) lgkmcnt(0)
	v_add_f32_e32 v44, v37, v44
	ds_bpermute_b32 v49, v49, v44
	s_waitcnt lgkmcnt(0)
	v_add_f32_e32 v49, v44, v49
	v_cndmask_b32_e32 v49, v49, v44, vcc
	ds_bpermute_b32 v50, v50, v49
	s_waitcnt lgkmcnt(0)
	v_add_f32_e32 v50, v49, v50
	v_cndmask_b32_e64 v49, v50, v49, s[0:1]
	v_add_u32_e32 v50, -4, v238
	v_cmp_lt_i32_e64 s[0:1], v50, v45
	s_nop 1
	v_cndmask_b32_e64 v50, v50, v238, s[0:1]
	v_lshlrev_b32_e32 v50, 2, v50
	ds_bpermute_b32 v50, v50, v49
	v_cmp_gt_u32_e64 s[0:1], 4, v40
	s_waitcnt lgkmcnt(0)
	v_add_f32_e32 v50, v49, v50
	v_cndmask_b32_e64 v49, v50, v49, s[0:1]
	v_add_u32_e32 v50, -8, v238
	v_cmp_lt_i32_e64 s[0:1], v50, v45
	s_nop 1
	v_cndmask_b32_e64 v50, v50, v238, s[0:1]
	v_lshlrev_b32_e32 v50, 2, v50
	ds_bpermute_b32 v50, v50, v49
	v_cmp_gt_u32_e64 s[0:1], 8, v40
	s_waitcnt lgkmcnt(0)
	v_add_f32_e32 v50, v49, v50
	v_cndmask_b32_e64 v49, v50, v49, s[0:1]
	v_add_u32_e32 v50, -16, v238
	v_cmp_lt_i32_e64 s[0:1], v50, v45
	s_nop 1
	v_cndmask_b32_e64 v50, v50, v238, s[0:1]
	v_lshlrev_b32_e32 v50, 2, v50
	ds_bpermute_b32 v50, v50, v49
	v_cmp_gt_u32_e64 s[0:1], 16, v40
	s_waitcnt lgkmcnt(0)
	v_add_f32_e32 v50, v49, v50
	v_cndmask_b32_e64 v49, v50, v49, s[0:1]
	v_subrev_u32_e32 v50, 32, v238
	v_cmp_lt_i32_e64 s[0:1], v50, v45
	v_add_u32_e32 v45, 64, v45
	s_nop 0
	v_cndmask_b32_e64 v50, v50, v238, s[0:1]
	v_lshlrev_b32_e32 v50, 2, v50
	ds_bpermute_b32 v50, v50, v49
	v_cmp_gt_u32_e64 s[0:1], 32, v40
	s_waitcnt lgkmcnt(0)
	v_add_f32_e32 v50, v49, v50
	v_cndmask_b32_e64 v49, v50, v49, s[0:1]
	v_sub_f32_e32 v44, v49, v44
	v_add_f32_e32 v44, v37, v44
	v_lshl_or_b32 v37, v238, 2, v233
	ds_bpermute_b32 v37, v37, v49
	s_waitcnt lgkmcnt(0)
	v_sub_f32_e32 v44, v37, v44
	v_add_f32_e32 v47, v47, v44
	v_sub_f32_e32 v44, v37, v49
	v_xor_b32_e32 v49, 32, v238
	v_cmp_lt_i32_e64 s[0:1], v49, v45
	v_add_f32_e32 v48, v48, v44
	v_max_f32_e32 v44, v47, v48
	v_cndmask_b32_e64 v49, v238, v49, s[0:1]
	v_lshlrev_b32_e32 v49, 2, v49
	ds_bpermute_b32 v49, v49, v44
	s_waitcnt lgkmcnt(0)
	v_max_f32_e32 v49, v49, v49
	v_max_f32_e32 v44, v44, v49
	v_xor_b32_e32 v49, 16, v238
	v_cmp_lt_i32_e64 s[0:1], v49, v45
	s_nop 1
	v_cndmask_b32_e64 v49, v238, v49, s[0:1]
	v_lshlrev_b32_e32 v49, 2, v49
	ds_bpermute_b32 v49, v49, v44
	s_waitcnt lgkmcnt(0)
	v_max_f32_e32 v49, v49, v49
	v_max_f32_e32 v44, v44, v49
	v_xor_b32_e32 v49, 8, v238
	v_cmp_lt_i32_e64 s[0:1], v49, v45
	s_nop 1
	v_cndmask_b32_e64 v49, v238, v49, s[0:1]
	v_lshlrev_b32_e32 v49, 2, v49
	ds_bpermute_b32 v49, v49, v44
	s_waitcnt lgkmcnt(0)
	v_max_f32_e32 v49, v49, v49
	v_max_f32_e32 v44, v44, v49
	v_xor_b32_e32 v49, 4, v238
	v_cmp_lt_i32_e64 s[0:1], v49, v45
	s_nop 1
	v_cndmask_b32_e64 v49, v238, v49, s[0:1]
	v_lshlrev_b32_e32 v49, 2, v49
	ds_bpermute_b32 v49, v49, v44
	s_waitcnt lgkmcnt(0)
	v_max_f32_e32 v49, v49, v49
	v_max_f32_e32 v44, v44, v49
	v_xor_b32_e32 v49, 2, v238
	v_cmp_lt_i32_e64 s[0:1], v49, v45
	s_nop 1
	v_cndmask_b32_e64 v49, v238, v49, s[0:1]
	v_lshlrev_b32_e32 v49, 2, v49
	ds_bpermute_b32 v49, v49, v44
	s_waitcnt lgkmcnt(0)
	v_max_f32_e32 v49, v49, v49
	v_max_f32_e32 v44, v44, v49
	v_xor_b32_e32 v49, 1, v238
	v_cmp_lt_i32_e64 s[0:1], v49, v45
	s_nop 1
	v_cndmask_b32_e64 v45, v238, v49, s[0:1]
	v_lshlrev_b32_e32 v45, 2, v45
	ds_bpermute_b32 v45, v45, v44
	v_readlane_b32 s0, v253, 24
	s_waitcnt lgkmcnt(0)
	v_max_f32_e32 v45, v45, v45
	v_max_f32_e32 v44, v44, v45
	v_sub_f32_e32 v45, v47, v44
	v_mul_f32_e32 v45, 0x3fb8aa3b, v45
	v_exp_f32_e32 v45, v45
	v_lshl_add_u32 v46, v46, 2, s0
	v_lshl_add_u32 v33, v33, 2, s0
	ds_write_b32 v46, v45
	v_sub_f32_e32 v45, v48, v44
	v_mul_f32_e32 v45, 0x3fb8aa3b, v45
	v_exp_f32_e32 v45, v45
	ds_write_b32 v33, v45
	s_and_b64 exec, exec, vcc
	s_cbranch_execz .LBB0_482
	s_ashr_i32 s27, s26, 31
	s_lshl_b64 s[0:1], s[26:27], 2
	s_add_u32 s6, s20, s0
	s_addc_u32 s7, s21, s1
	s_add_u32 s0, s18, s0
	s_addc_u32 s1, s19, s1
	v_mov_b64_e32 v[46:47], s[0:1]
	global_store_dword v[46:47], v44, off
	v_mov_b64_e32 v[44:45], s[6:7]
	global_store_dword v[44:45], v37, off

; #define LAS __attribute__((address_space(3)))
; __device__ __forceinline__ void unpack8(u32x4 w, float* f) { f[0] = bflo(w.x); f[1] = bfhi(w.x); f[2] = bflo(w.y); f[3] = bfhi(w.y); f[4] = bflo(w.z); f[5] = bfhi(w.z); f[6] = bflo(w.w); f[7] = bfhi(w.w); }
; __device__ __forceinline__ void mlstm_local(const Bufs& B, int item, LAS unsigned char* lds) {
;     ...
;     mma_tile<128, 2>(acc, T1, 136, T0, 136, wr, wc, fr, fq);
;     float* dst = B.CLOC + (size_t)item * 16384;
; #pragma unroll
;     for (int m = 0; m < 4; ++m)
; #pragma unroll
;         for (int n = 0; n < 2; ++n)
; #pragma unroll
;             for (int j = 0; j < 4; ++j) dst[(64 * wr + 16 * m + 4 * fq + j) * 128 + 32 * wc + 16 * n + fr] = acc[m][n][j];
;     { const int dk = tid >> 2, qd = tid & 3; float s = 0.f;
; #pragma unroll
;         for (int i = 0; i < 4; ++i) { float kv[8]; unpack8(*(const LAS u32x4*)(T0 + dk * 136 + qd * 32 + i * 8), kv);
.LBB0_483:
	ds_read_b128 v[36:39], v35
	ds_read_b128 v[42:45], v34
	ds_read_b128 v[46:49], v34 offset:4352
	s_add_i32 s0, s0, 32
	s_cmpk_lt_u32 s0, 0x60
	v_add_u32_e32 v34, 64, v34
	s_waitcnt lgkmcnt(1)
	v_mfma_f32_16x16x32_bf16 v[28:31], v[36:39], v[42:45], v[28:31]
	s_waitcnt lgkmcnt(0)
	v_mfma_f32_16x16x32_bf16 v[24:27], v[36:39], v[46:49], v[24:27]
	ds_read_b128 v[36:39], v35 offset:4352
	s_waitcnt lgkmcnt(0)
	v_mfma_f32_16x16x32_bf16 v[20:23], v[36:39], v[42:45], v[20:23]
	v_mfma_f32_16x16x32_bf16 v[16:19], v[36:39], v[46:49], v[16:19]
	ds_read_b128 v[36:39], v35 offset:8704
	s_waitcnt lgkmcnt(0)
	v_mfma_f32_16x16x32_bf16 v[12:15], v[36:39], v[42:45], v[12:15]
	v_mfma_f32_16x16x32_bf16 v[8:11], v[36:39], v[46:49], v[8:11]
	ds_read_b128 v[36:39], v35 offset:13056
	v_add_u32_e32 v35, 64, v35
	s_waitcnt lgkmcnt(0)
	v_mfma_f32_16x16x32_bf16 v[4:7], v[36:39], v[42:45], v[4:7]
	v_mfma_f32_16x16x32_bf16 v[0:3], v[36:39], v[46:49], v[0:3]
	s_cbranch_scc1 .LBB0_483
	v_and_b32_e32 v34, 0x1ffffc0, v32
	v_lshrrev_b32_e32 v35, 2, v40
	s_mov_b32 s0, s26
	s_ashr_i32 s1, s26, 31
	v_and_or_b32 v34, v35, 12, v34
	s_mov_b64 s[26:27], s[0:1]
	s_lshl_b64 s[0:1], s[0:1], 16
	v_lshlrev_b32_e32 v38, 7, v34
	s_add_u32 s0, s8, s0
	v_or_b32_e32 v34, v38, v33
	s_addc_u32 s1, s9, s1
	v_ashrrev_i32_e32 v35, 31, v34
	v_lshl_add_u64 v[36:37], v[34:35], 2, s[0:1]
	v_ashrrev_i32_e32 v35, 31, v38
	global_store_dword v[36:37], v28, off
	v_lshl_add_u64 v[36:37], v[34:35], 2, s[0:1]
	global_store_dword v[36:37], v29, off offset:512
	global_store_dword v[36:37], v30, off offset:1024
	global_store_dword v[36:37], v31, off offset:1536
	v_or_b32_e32 v30, 16, v33
	v_or_b32_e32 v34, v38, v30
	v_lshl_add_u64 v[28:29], v[34:35], 2, s[0:1]
	global_store_dword v[36:37], v24, off offset:64
	global_store_dword v[28:29], v25, off offset:512
	global_store_dword v[28:29], v26, off offset:1024
	global_store_dword v[28:29], v27, off offset:1536
	v_or_b32_e32 v26, 0x800, v38
	v_or_b32_e32 v24, v26, v33
	v_ashrrev_i32_e32 v25, 31, v24
	v_lshl_add_u64 v[24:25], v[24:25], 2, s[0:1]
	v_or_b32_e32 v27, 0x880, v38
	global_store_dword v[24:25], v20, off
	v_or_b32_e32 v24, v27, v33
	v_ashrrev_i32_e32 v25, 31, v24
	v_lshl_add_u64 v[24:25], v[24:25], 2, s[0:1]
	global_store_dword v[24:25], v21, off
	v_or_b32_e32 v24, 0x900, v38
	v_or_b32_e32 v20, v24, v33
	v_ashrrev_i32_e32 v21, 31, v20
	v_lshl_add_u64 v[20:21], v[20:21], 2, s[0:1]
	global_store_dword v[20:21], v22, off
	v_or_b32_e32 v22, 0x980, v38
	v_or_b32_e32 v20, v22, v33
	v_ashrrev_i32_e32 v21, 31, v20
	v_lshl_add_u64 v[20:21], v[20:21], 2, s[0:1]
	global_store_dword v[20:21], v23, off
	v_or_b32_e32 v20, v26, v30
	v_ashrrev_i32_e32 v21, 31, v20
	v_lshl_add_u64 v[20:21], v[20:21], 2, s[0:1]
	global_store_dword v[20:21], v16, off
	v_or_b32_e32 v20, v27, v30
	v_ashrrev_i32_e32 v21, 31, v20
	v_lshl_add_u64 v[20:21], v[20:21], 2, s[0:1]
	v_or_b32_e32 v16, v24, v30
	global_store_dword v[20:21], v17, off
	v_ashrrev_i32_e32 v17, 31, v16
	v_lshl_add_u64 v[16:17], v[16:17], 2, s[0:1]
	global_store_dword v[16:17], v18, off
	v_or_b32_e32 v16, v22, v30
	v_ashrrev_i32_e32 v17, 31, v16
	v_lshl_add_u64 v[16:17], v[16:17], 2, s[0:1]
	v_or_b32_e32 v18, 0x1000, v38
	global_store_dword v[16:17], v19, off
	v_or_b32_e32 v16, v18, v33
	v_ashrrev_i32_e32 v17, 31, v16
	v_lshl_add_u64 v[16:17], v[16:17], 2, s[0:1]
	v_or_b32_e32 v19, 0x1080, v38
	global_store_dword v[16:17], v12, off
	v_or_b32_e32 v16, v19, v33
	v_ashrrev_i32_e32 v17, 31, v16
	v_lshl_add_u64 v[16:17], v[16:17], 2, s[0:1]
	global_store_dword v[16:17], v13, off
	v_or_b32_e32 v16, 0x1100, v38
	v_or_b32_e32 v12, v16, v33
	v_ashrrev_i32_e32 v13, 31, v12
	v_lshl_add_u64 v[12:13], v[12:13], 2, s[0:1]
	global_store_dword v[12:13], v14, off
	v_or_b32_e32 v14, 0x1180, v38
	v_or_b32_e32 v12, v14, v33
	v_ashrrev_i32_e32 v13, 31, v12
	v_lshl_add_u64 v[12:13], v[12:13], 2, s[0:1]
	global_store_dword v[12:13], v15, off
	v_or_b32_e32 v12, v18, v30
	v_ashrrev_i32_e32 v13, 31, v12
	v_lshl_add_u64 v[12:13], v[12:13], 2, s[0:1]
	global_store_dword v[12:13], v8, off
	v_or_b32_e32 v12, v19, v30
	v_ashrrev_i32_e32 v13, 31, v12
	v_lshl_add_u64 v[12:13], v[12:13], 2, s[0:1]
	v_or_b32_e32 v8, v16, v30
	global_store_dword v[12:13], v9, off
	v_ashrrev_i32_e32 v9, 31, v8
	v_lshl_add_u64 v[8:9], v[8:9], 2, s[0:1]
	global_store_dword v[8:9], v10, off
	v_or_b32_e32 v8, v14, v30
	v_ashrrev_i32_e32 v9, 31, v8
	v_lshl_add_u64 v[8:9], v[8:9], 2, s[0:1]
	v_or_b32_e32 v10, 0x1800, v38
	global_store_dword v[8:9], v11, off
	v_or_b32_e32 v8, v10, v33
	v_ashrrev_i32_e32 v9, 31, v8
	v_lshl_add_u64 v[8:9], v[8:9], 2, s[0:1]
	v_or_b32_e32 v11, 0x1880, v38
	global_store_dword v[8:9], v4, off
	v_or_b32_e32 v8, v11, v33
	v_ashrrev_i32_e32 v9, 31, v8
	v_lshl_add_u64 v[8:9], v[8:9], 2, s[0:1]
	global_store_dword v[8:9], v5, off
	v_or_b32_e32 v8, 0x1900, v38
	v_or_b32_e32 v4, v8, v33
	v_ashrrev_i32_e32 v5, 31, v4
	v_lshl_add_u64 v[4:5], v[4:5], 2, s[0:1]
	global_store_dword v[4:5], v6, off
	v_or_b32_e32 v6, 0x1980, v38
	v_or_b32_e32 v4, v6, v33
	v_ashrrev_i32_e32 v5, 31, v4
	v_lshl_add_u64 v[4:5], v[4:5], 2, s[0:1]
	global_store_dword v[4:5], v7, off
	v_or_b32_e32 v4, v10, v30
	v_ashrrev_i32_e32 v5, 31, v4
	v_lshl_add_u64 v[4:5], v[4:5], 2, s[0:1]
	global_store_dword v[4:5], v0, off
	v_or_b32_e32 v4, v11, v30
	v_ashrrev_i32_e32 v5, 31, v4
	v_lshl_add_u64 v[4:5], v[4:5], 2, s[0:1]
	v_or_b32_e32 v0, v8, v30
	global_store_dword v[4:5], v1, off
	v_ashrrev_i32_e32 v1, 31, v0
	v_lshl_add_u64 v[0:1], v[0:1], 2, s[0:1]
	global_store_dword v[0:1], v2, off
	v_or_b32_e32 v0, v6, v30
	v_ashrrev_i32_e32 v1, 31, v0
	v_lshl_add_u64 v[0:1], v[0:1], 2, s[0:1]
	v_and_b32_e32 v28, 3, v40
	global_store_dword v[0:1], v3, off
	v_mul_lo_u32 v0, v32, s4
	v_lshlrev_b32_e32 v1, 6, v28
	v_add3_u32 v12, 0, v0, v1
	v_lshl_add_u32 v4, v28, 7, 0
	ds_read_b128 v[0:3], v12
	v_add_u32_e32 v29, 0x22000, v4
	ds_read_b128 v[4:7], v12 offset:16
	ds_read_b128 v[8:11], v12 offset:32
	ds_read_b128 v[12:15], v12 offset:48
	ds_read_b128 v[16:19], v29
	s_waitcnt lgkmcnt(0)
; #define LAS __attribute__((address_space(3)))
; __device__ __forceinline__ float bf2f(bf16_t b) { return __uint_as_float(((unsigned)b) << 16); }
; __device__ __forceinline__ void unpack8(u32x4 w, float* f) { f[0] = bflo(w.x); f[1] = bfhi(w.x); f[2] = bflo(w.y); f[3] = bfhi(w.y); f[4] = bflo(w.z); f[5] = bfhi(w.z); f[6] = bflo(w.w); f[7] = bfhi(w.w); }
; __device__ __forceinline__ void mlstm_local(const Bufs& B, int item, LAS unsigned char* lds) {
;     ...
;     { const int dk = tid >> 2, qd = tid & 3; float s = 0.f;
; #pragma unroll
;         for (int i = 0; i < 4; ++i) { float kv[8]; unpack8(*(const LAS u32x4*)(T0 + dk * 136 + qd * 32 + i * 8), kv);
; #pragma unroll
;             for (int k = 0; k < 8; ++k) s += kv[k] * ve[qd * 32 + i * 8 + k]; }
;         s += __shfl_xor(s, 1); s += __shfl_xor(s, 2);
;         if (qd == 0) B.NLOC[(size_t)item * 128 + dk] = s; }
; __device__ __forceinline__ void prep_phase(const Params& p, const Bufs& B, int l) {
;     ...
;         if (lane < 16) { float v = bf2f(gt) + bgl;
;             if ((lane >> 2) & 1) v = fminf(v, 0.f) - log1pf(__expf(-fabsf(v)));
;             B.G[(size_t)s * 16 + lane] = v; }
	v_lshlrev_b32_e32 v30, 16, v0
	v_and_b32_e32 v31, 0xffff0000, v0
	v_lshlrev_b32_e32 v33, 16, v1
	v_fma_f32 v16, v16, v30, 0
	v_and_b32_e32 v34, 0xffff0000, v1
	v_lshlrev_b32_e32 v35, 16, v2
	v_and_b32_e32 v36, 0xffff0000, v2
	v_lshlrev_b32_e32 v37, 16, v3
	v_and_b32_e32 v38, 0xffff0000, v3
	ds_read_b128 v[0:3], v29 offset:16
	ds_read_b128 v[20:23], v29 offset:32
	ds_read_b128 v[24:27], v29 offset:48
	v_fmac_f32_e32 v16, v17, v31
	v_fmac_f32_e32 v16, v18, v33
	v_fmac_f32_e32 v16, v19, v34
	s_waitcnt lgkmcnt(0)
	v_fmac_f32_e32 v16, v0, v35
	v_fmac_f32_e32 v16, v1, v36
	v_fmac_f32_e32 v16, v2, v37
	v_fmac_f32_e32 v16, v3, v38
	v_lshlrev_b32_e32 v0, 16, v4
	v_and_b32_e32 v1, 0xffff0000, v4
	v_fmac_f32_e32 v16, v20, v0
	v_lshlrev_b32_e32 v2, 16, v5
	v_fmac_f32_e32 v16, v21, v1
	v_and_b32_e32 v3, 0xffff0000, v5
	v_fmac_f32_e32 v16, v22, v2
	v_lshlrev_b32_e32 v4, 16, v6
	v_fmac_f32_e32 v16, v23, v3
	ds_read_b128 v[0:3], v29 offset:64
	v_and_b32_e32 v5, 0xffff0000, v6
	v_fmac_f32_e32 v16, v24, v4
	v_lshlrev_b32_e32 v6, 16, v7
	v_fmac_f32_e32 v16, v25, v5
	v_and_b32_e32 v7, 0xffff0000, v7
	v_fmac_f32_e32 v16, v26, v6
	v_fmac_f32_e32 v16, v27, v7
	v_lshlrev_b32_e32 v17, 16, v8
	ds_read_b128 v[4:7], v29 offset:80
	v_and_b32_e32 v8, 0xffff0000, v8
	s_waitcnt lgkmcnt(0)
	v_fmac_f32_e32 v16, v0, v17
	v_lshlrev_b32_e32 v18, 16, v9
	v_fmac_f32_e32 v16, v1, v8
	v_and_b32_e32 v9, 0xffff0000, v9
	v_fmac_f32_e32 v16, v2, v18
	v_lshlrev_b32_e32 v19, 16, v10
	v_fmac_f32_e32 v16, v3, v9
	ds_read_b128 v[0:3], v29 offset:96
	v_and_b32_e32 v10, 0xffff0000, v10
	v_fmac_f32_e32 v16, v4, v19
	v_lshlrev_b32_e32 v20, 16, v11
	v_fmac_f32_e32 v16, v5, v10
	v_and_b32_e32 v11, 0xffff0000, v11
	v_fmac_f32_e32 v16, v6, v20
	v_fmac_f32_e32 v16, v7, v11
	v_lshlrev_b32_e32 v8, 16, v12
	ds_read_b128 v[4:7], v29 offset:112
	v_and_b32_e32 v9, 0xffff0000, v12
	s_waitcnt lgkmcnt(0)
	v_fmac_f32_e32 v16, v0, v8
	v_lshlrev_b32_e32 v10, 16, v13
	v_fmac_f32_e32 v16, v1, v9
	v_and_b32_e32 v11, 0xffff0000, v13
	v_fmac_f32_e32 v16, v2, v10
	v_lshlrev_b32_e32 v12, 16, v14
	v_fmac_f32_e32 v16, v3, v11
	v_and_b32_e32 v1, 64, v238
	v_and_b32_e32 v13, 0xffff0000, v14
	v_fmac_f32_e32 v16, v4, v12
	v_xor_b32_e32 v0, 1, v238
	v_add_u32_e32 v1, 64, v1
	v_lshlrev_b32_e32 v14, 16, v15
	v_fmac_f32_e32 v16, v5, v13
	v_cmp_lt_i32_e32 vcc, v0, v1
	v_and_b32_e32 v15, 0xffff0000, v15
	v_fmac_f32_e32 v16, v6, v14
	v_cndmask_b32_e32 v0, v238, v0, vcc
	v_fmac_f32_e32 v16, v7, v15
	v_lshlrev_b32_e32 v0, 2, v0
	ds_bpermute_b32 v0, v0, v16
	v_xor_b32_e32 v2, 2, v238
	v_cmp_lt_i32_e32 vcc, v2, v1
	s_waitcnt lgkmcnt(0)
	v_add_f32_e32 v0, v16, v0
	v_cndmask_b32_e32 v1, v238, v2, vcc
	v_lshlrev_b32_e32 v1, 2, v1
	ds_bpermute_b32 v1, v1, v0
	v_cmp_eq_u32_e32 vcc, 0, v28
	s_and_saveexec_b64 s[0:1], vcc
	s_cbranch_execz .LBB0_470
	s_lshl_b64 s[4:5], s[26:27], 9
	s_add_u32 s4, s16, s4
	s_addc_u32 s5, s17, s5
	v_ashrrev_i32_e32 v33, 31, v32
	v_lshl_add_u64 v[2:3], v[32:33], 2, s[4:5]
	s_waitcnt lgkmcnt(0)
	v_add_f32_e32 v0, v0, v1
	global_store_dword v[2:3], v0, off
	s_branch .LBB0_470
.LBB0_486:
	s_or_b64 exec, exec, s[14:15]
	v_lshlrev_b64 v[2:3], 6, v[56:57]
	v_lshl_add_u64 v[2:3], v[88:89], 0, v[2:3]
	global_store_dword v[2:3], v0, off

; __device__ __forceinline__ void prep_phase(const Params& p, const Bufs& B, int l) {
;     ...
;         const bf16_t* pr = B.PROJ + (size_t)s * NPROJP;
;         const u32x4 z4 = (u32x4){0u, 0u, 0u, 0u};
;         u32x4 cm[2], cc[2], cp[2];
; #pragma unroll
;         for (int hf = 0; hf < 2; ++hf) { const int c0 = lane * 16 + hf * 8;
;             cm[hf] = s > 0 ? *(const u32x4*)(pr - NPROJP + c0) : z4; cc[hf] = *(const u32x4*)(pr + c0); cp[hf] = s < S_ - 1 ? *(const u32x4*)(pr + NPROJP + c0) : z4; }
;         const int tensor = lane >> 5, head = (lane & 31) >> 3, j0 = (lane & 7) * 4, base = PC_RQ + tensor * 256 + head * 64;
;         const u32x2 w1 = *(const u32x2*)(pr + base + j0), w2 = *(const u32x2*)(pr + base + 32 + j0);
;         const f32x4 rc4 = *(const f32x4*)(B.RC + (size_t)s * 32 + j0), rs4 = *(const f32x4*)(B.RS + (size_t)s * 32 + j0);
;         const u32x4 cqv = *(const u32x4*)(pr + PC_CQ + lane * 8); const u32x2 ckvv = *(const u32x2*)(pr + PC_CKV + lane * 4);
;         const int l32 = lane & 31, l16 = lane & 15;
;         const bf16_t kr1 = pr[PC_KR + l32], kr2 = pr[PC_KR + 32 + l32]; const float krc = B.RC[(size_t)s * 32 + l32], krs = B.RS[(size_t)s * 32 + l32];
;         const bf16_t gt = pr[PC_GATE + l16]; const float bgl = bg[l16];
.LBB0_488:
	v_readlane_b32 s0, v254, 23
	v_readlane_b32 s1, v254, 24
	v_mov_b32_e32 v20, 0
	v_cmp_lt_i32_e32 vcc, 0, v56
	v_mov_b64_e32 v[0:1], s[0:1]
	s_movk_i32 s0, 0x2400
	v_mad_i64_i32 v[36:37], s[0:1], v56, s0, v[0:1]
	s_movk_i32 s0, 0xdc00
	s_mov_b32 s1, -1
	v_lshl_add_u64 v[0:1], v[36:37], 0, s[0:1]
	v_lshlrev_b32_e32 v194, 1, v58
	v_mov_b32_e32 v24, 0
	v_mov_b32_e32 v25, 0
	v_mov_b32_e32 v26, 0
	v_mov_b32_e32 v27, 0
	s_and_saveexec_b64 s[0:1], vcc
	s_cbranch_execz .LBB0_490
	v_lshl_add_u64 v[2:3], v[0:1], 0, v[194:195]
	global_load_dwordx4 v[24:27], v[2:3], off
.LBB0_490:
	s_or_b64 exec, exec, s[0:1]
	v_lshl_add_u64 v[4:5], v[36:37], 0, v[194:195]
	global_load_dwordx4 v[32:35], v[4:5], off
	s_movk_i32 s0, 0x1fff
	s_mov_b64 s[14:15], 0x2400
	v_cmp_ne_u32_e64 s[0:1], s0, v56
	v_lshl_add_u64 v[2:3], v[36:37], 0, s[14:15]
	v_mov_b32_e32 v21, 0
	v_mov_b32_e32 v22, 0
	v_mov_b32_e32 v23, 0
	s_and_saveexec_b64 s[14:15], s[0:1]
	s_cbranch_execz .LBB0_492
	v_lshl_add_u64 v[6:7], v[2:3], 0, v[194:195]
	global_load_dwordx4 v[20:23], v[6:7], off
.LBB0_492:
	s_or_b64 exec, exec, s[14:15]
	v_mov_b32_e32 v12, 0
	v_lshlrev_b32_e32 v194, 1, v66
	v_mov_b32_e32 v16, 0
	v_mov_b32_e32 v17, 0
	v_mov_b32_e32 v18, 0
	v_mov_b32_e32 v19, 0
	s_and_saveexec_b64 s[14:15], vcc
	s_cbranch_execz .LBB0_494
	v_lshl_add_u64 v[0:1], v[0:1], 0, v[194:195]
	global_load_dwordx4 v[16:19], v[0:1], off
.LBB0_494:
	s_or_b64 exec, exec, s[14:15]
	global_load_dwordx4 v[28:31], v[4:5], off offset:16
	v_mov_b32_e32 v13, 0
	v_mov_b32_e32 v14, 0
	v_mov_b32_e32 v15, 0
	s_and_saveexec_b64 s[14:15], s[0:1]
	s_cbranch_execz .LBB0_496
	v_lshl_add_u64 v[0:1], v[2:3], 0, v[194:195]
	global_load_dwordx4 v[12:15], v[0:1], off
.LBB0_496:
	s_or_b64 exec, exec, s[14:15]
	v_mov_b32_e32 v97, v195
	v_lshl_add_u64 v[0:1], v[36:37], 0, v[96:97]
	v_mov_b32_e32 v99, v195
	v_lshl_add_u64 v[0:1], v[0:1], 0, v[98:99]
	v_ashrrev_i32_e32 v57, 31, v56
	v_add_co_u32_e32 v0, vcc, 0x1000, v0
	v_lshlrev_b64 v[38:39], 7, v[56:57]
	s_nop 0
	v_addc_co_u32_e32 v1, vcc, 0, v1, vcc
	global_load_dwordx2 v[108:109], v[0:1], off offset:32
	global_load_dwordx2 v[110:111], v[0:1], off offset:96
	v_lshl_add_u64 v[0:1], v[74:75], 0, v[38:39]
	global_load_dwordx4 v[4:7], v[0:1], off
	v_lshl_add_u64 v[0:1], v[76:77], 0, v[38:39]
	v_mov_b32_e32 v101, v195
	global_load_dwordx4 v[8:11], v[0:1], off
	v_lshl_add_u64 v[0:1], v[36:37], 0, v[100:101]
	s_movk_i32 s1, 0x1000
	v_add_co_u32_e32 v0, vcc, s1, v0
	v_mov_b32_e32 v103, v195
	s_nop 0
	v_addc_co_u32_e32 v1, vcc, 0, v1, vcc
	v_lshl_add_u64 v[40:41], v[36:37], 0, v[102:103]
	s_movk_i32 s0, 0x2000
	v_add_co_u32_e32 v40, vcc, s0, v40
	v_lshlrev_b32_e32 v194, 1, v60
	s_nop 0
	v_addc_co_u32_e32 v41, vcc, 0, v41, vcc
	global_load_dwordx4 v[0:3], v[0:1], off offset:3104
	v_mov_b32_e32 v105, v195
	global_load_dwordx2 v[106:107], v[40:41], off offset:32
	v_lshl_add_u64 v[40:41], v[36:37], 0, v[194:195]
	v_add_co_u32_e32 v40, vcc, s0, v40
	v_lshl_add_u64 v[36:37], v[36:37], 0, v[104:105]
	s_nop 0
	v_addc_co_u32_e32 v41, vcc, 0, v41, vcc
	v_lshl_or_b32 v38, v60, 2, v38
	v_add_co_u32_e32 v36, vcc, s1, v36
	global_load_ushort v97, v[40:41], off offset:544
	global_load_ushort v99, v[40:41], off offset:608
	v_lshl_add_u64 v[40:41], s[2:3], 0, v[38:39]
	v_lshl_add_u64 v[38:39], s[10:11], 0, v[38:39]
	v_addc_co_u32_e32 v37, vcc, 0, v37, vcc
	global_load_dword v101, v[40:41], off
	global_load_dword v103, v[38:39], off
	global_load_ushort v59, v[36:37], off
	global_load_dword v67, v[62:63], off
	s_waitcnt vmcnt(0) lgkmcnt(0)
	v_lshlrev_b32_e32 v119, 16, v32
	v_and_b32_e32 v124, 0xffff0000, v32
	v_lshlrev_b32_e32 v118, 16, v33
	v_and_b32_e32 v117, 0xffff0000, v33
	v_lshlrev_b32_e32 v116, 16, v34
	v_and_b32_e32 v115, 0xffff0000, v34
	v_lshlrev_b32_e32 v114, 16, v35
	v_and_b32_e32 v105, 0xffff0000, v35
	v_mov_b64_e32 v[32:33], v[128:129]
	v_mov_b64_e32 v[34:35], v[130:131]
	v_mov_b64_e32 v[48:49], v[132:133]
	v_mov_b64_e32 v[50:51], v[134:135]
	v_mov_b64_e32 v[36:37], v[136:137]
	v_mov_b64_e32 v[38:39], v[138:139]
	v_mov_b64_e32 v[44:45], v[140:141]
	v_mov_b64_e32 v[46:47], v[142:143]
	v_mov_b64_e32 v[40:41], v[144:145]
	v_mov_b64_e32 v[42:43], v[146:147]
	v_mov_b64_e32 v[52:53], v[148:149]
	v_mov_b64_e32 v[54:55], v[150:151]
	v_lshlrev_b32_e32 v121, 16, v20
	v_lshlrev_b32_e32 v120, 16, v24
	v_lshlrev_b64 v[112:113], 11, v[56:57]
	s_waitcnt vmcnt(4)
	v_mov_b32_e32 v122, v48
	s_waitcnt vmcnt(0)
; __device__ __forceinline__ void unpack8(u32x4 w, float* f) { f[0] = bflo(w.x); f[1] = bfhi(w.x); f[2] = bflo(w.y); f[3] = bfhi(w.y); f[4] = bflo(w.z); f[5] = bfhi(w.z); f[6] = bflo(w.w); f[7] = bfhi(w.w); }
; __device__ __forceinline__ u32x4 pack8(const float* f) { u32x4 w; w.x = cvt_pk_bf16(f[0], f[1]); w.y = cvt_pk_bf16(f[2], f[3]); w.z = cvt_pk_bf16(f[4], f[5]); w.w = cvt_pk_bf16(f[6], f[7]); return w; }
; __device__ __forceinline__ void prep_phase(const Params& p, const Bufs& B, int l) {
;     ...
;         for (int hf = 0; hf < 2; ++hf) { const int c0 = lane * 16 + hf * 8; float xm[8], x0[8], xp[8], r[8];
;             unpack8(cm[hf], xm); unpack8(cc[hf], x0); unpack8(cp[hf], xp);
; #pragma unroll
;             for (int i = 0; i < 8; ++i) { const float v = xm[i] * wconv[c0 + i] + x0[i] * wconv[1024 + c0 + i] + xp[i] * wconv[2048 + c0 + i]; r[i] = v * __builtin_amdgcn_rcpf(1.f + __expf(-v)); }
;             *(u32x4*)(B.QKML + (size_t)s * 1024 + c0) = pack8(r); }
	v_mov_b32_e32 v123, v52
	v_pk_mul_f32 v[120:121], v[122:123], v[120:121]
	v_mov_b32_e32 v52, v49
	v_fma_f32 v44, v44, v119, v120
	v_add_f32_e32 v44, v44, v121
	v_mul_f32_e32 v48, 0xbfb8aa3b, v44
	v_exp_f32_e32 v48, v48
	v_and_b32_e32 v121, 0xffff0000, v20
	v_and_b32_e32 v120, 0xffff0000, v24
	v_add_f32_e32 v48, 1.0, v48
	v_rcp_f32_e32 v48, v48
	s_nop 0
	v_mul_f32_e32 v119, v44, v48
	v_pk_mul_f32 v[48:49], v[52:53], v[120:121]
	v_lshlrev_b32_e32 v44, 16, v25
	v_fma_f32 v20, v45, v124, v48
	v_add_f32_e32 v20, v20, v49
	v_mul_f32_e32 v24, 0xbfb8aa3b, v20
	v_exp_f32_e32 v24, v24
	v_lshlrev_b32_e32 v45, 16, v21
	v_mov_b32_e32 v48, v50
	v_mov_b32_e32 v49, v54
	v_add_f32_e32 v24, 1.0, v24
	v_rcp_f32_e32 v24, v24
	v_pk_mul_f32 v[44:45], v[48:49], v[44:45]
	v_and_b32_e32 v21, 0xffff0000, v21
	v_mov_b32_e32 v54, v51
	v_mul_f32_e32 v52, v20, v24
	v_fma_f32 v20, v46, v118, v44
	v_add_f32_e32 v20, v20, v45
	v_mul_f32_e32 v24, 0xbfb8aa3b, v20
	v_exp_f32_e32 v24, v24
	v_lshlrev_b32_e32 v50, 16, v28
	v_and_b32_e32 v51, 0xffff0000, v28
	v_and_b32_e32 v53, 0xffff0000, v29
	v_add_f32_e32 v24, 1.0, v24
	v_rcp_f32_e32 v24, v24
	v_lshlrev_b32_e32 v46, 16, v16
	v_mul_f32_e32 v44, v20, v24
	v_and_b32_e32 v20, 0xffff0000, v25
	v_pk_mul_f32 v[20:21], v[54:55], v[20:21]
	v_mov_b32_e32 v24, v32
	v_fma_f32 v20, v47, v117, v20
	v_add_f32_e32 v20, v20, v21
	v_mul_f32_e32 v21, 0xbfb8aa3b, v20
	v_exp_f32_e32 v21, v21
	v_mov_b32_e32 v25, v40
	v_mov_b32_e32 v40, v33
	v_lshlrev_b32_e32 v54, 16, v30
	v_add_f32_e32 v21, 1.0, v21
	v_rcp_f32_e32 v21, v21
	v_and_b32_e32 v55, 0xffff0000, v30
	v_lshlrev_b32_e32 v47, 16, v12
	v_mul_f32_e32 v45, v20, v21
	v_lshlrev_b32_e32 v21, 16, v22
	v_lshlrev_b32_e32 v20, 16, v26
	v_pk_mul_f32 v[20:21], v[24:25], v[20:21]
	v_mov_b32_e32 v24, v34
	v_fma_f32 v20, v36, v116, v20
	v_add_f32_e32 v20, v20, v21
	v_mul_f32_e32 v21, 0xbfb8aa3b, v20
	v_exp_f32_e32 v21, v21
	v_mov_b32_e32 v25, v42
	v_mov_b32_e32 v42, v35
	v_add_f32_e32 v21, 1.0, v21
	v_rcp_f32_e32 v21, v21
	s_nop 0
	v_mul_f32_e32 v32, v20, v21
	v_and_b32_e32 v21, 0xffff0000, v22
	v_and_b32_e32 v20, 0xffff0000, v26
	v_pk_mul_f32 v[20:21], v[40:41], v[20:21]
	s_nop 0
	v_fma_f32 v20, v37, v115, v20
	v_add_f32_e32 v20, v20, v21
	v_mul_f32_e32 v21, 0xbfb8aa3b, v20
	v_exp_f32_e32 v21, v21
	s_nop 0
	v_add_f32_e32 v21, 1.0, v21
	v_rcp_f32_e32 v21, v21
	s_nop 0
	v_mul_f32_e32 v22, v20, v21
	v_lshlrev_b32_e32 v20, 16, v27
	v_lshlrev_b32_e32 v21, 16, v23
	v_pk_mul_f32 v[20:21], v[24:25], v[20:21]
	s_nop 0
	v_fma_f32 v20, v38, v114, v20
	v_add_f32_e32 v20, v20, v21
	v_mul_f32_e32 v21, 0xbfb8aa3b, v20
	v_exp_f32_e32 v21, v21
	s_nop 0
	v_add_f32_e32 v21, 1.0, v21
	v_rcp_f32_e32 v21, v21
	s_nop 0
	v_mul_f32_e32 v24, v20, v21
	v_and_b32_e32 v21, 0xffff0000, v23
	v_and_b32_e32 v20, 0xffff0000, v27
	v_pk_mul_f32 v[20:21], v[42:43], v[20:21]
	s_nop 0
	v_fma_f32 v20, v39, v105, v20
	v_add_f32_e32 v20, v20, v21
	v_mul_f32_e32 v21, 0xbfb8aa3b, v20
	v_exp_f32_e32 v21, v21
	v_lshlrev_b32_e32 v105, 16, v31
	v_add_f32_e32 v21, 1.0, v21
	v_rcp_f32_e32 v21, v21
	s_nop 0
	v_mul_f32_e32 v23, v20, v21
	v_cvt_pk_bf16_f32 v20, v119, v52
	v_cvt_pk_bf16_f32 v21, v44, v45
	v_cvt_pk_bf16_f32 v22, v32, v22
	v_lshl_add_u64 v[32:33], v[94:95], 0, v[112:113]
	v_cvt_pk_bf16_f32 v23, v24, v23
	global_store_dwordx4 v[32:33], v[20:23], off
	v_lshlrev_b32_e32 v52, 16, v29
	v_and_b32_e32 v112, 0xffff0000, v31
	s_nop 1
	v_mov_b64_e32 v[20:21], v[152:153]
	v_mov_b64_e32 v[22:23], v[154:155]
	v_mov_b64_e32 v[34:35], v[156:157]
	v_mov_b64_e32 v[36:37], v[158:159]
	v_mov_b64_e32 v[24:25], v[160:161]
	v_mov_b64_e32 v[26:27], v[162:163]
	v_mov_b64_e32 v[38:39], v[164:165]
	v_mov_b64_e32 v[40:41], v[166:167]
	v_mov_b64_e32 v[28:29], v[168:169]
	v_mov_b64_e32 v[30:31], v[170:171]
	v_mov_b64_e32 v[42:43], v[172:173]
	v_mov_b64_e32 v[44:45], v[174:175]
	s_waitcnt vmcnt(0)
	v_mov_b32_e32 v48, v34
	v_mov_b32_e32 v49, v42
	v_pk_mul_f32 v[46:47], v[48:49], v[46:47]
	v_mov_b32_e32 v42, v35
	v_fma_f32 v34, v38, v50, v46
	v_add_f32_e32 v34, v34, v47
	v_mul_f32_e32 v38, 0xbfb8aa3b, v34
	v_exp_f32_e32 v38, v38
	v_and_b32_e32 v47, 0xffff0000, v12
	v_and_b32_e32 v46, 0xffff0000, v16
	v_add_f32_e32 v38, 1.0, v38
	v_rcp_f32_e32 v38, v38
	s_nop 0
	v_mul_f32_e32 v48, v34, v38
	v_pk_mul_f32 v[34:35], v[42:43], v[46:47]
	v_mov_b32_e32 v38, v36
	v_fma_f32 v12, v39, v51, v34
	v_add_f32_e32 v12, v12, v35
	v_mul_f32_e32 v16, 0xbfb8aa3b, v12
	v_exp_f32_e32 v16, v16
	v_lshlrev_b32_e32 v34, 16, v17
	v_lshlrev_b32_e32 v35, 16, v13
	v_mov_b32_e32 v39, v44
	v_add_f32_e32 v16, 1.0, v16
	v_rcp_f32_e32 v16, v16
	v_pk_mul_f32 v[34:35], v[38:39], v[34:35]
	v_and_b32_e32 v13, 0xffff0000, v13
	v_mov_b32_e32 v44, v37
	v_mul_f32_e32 v42, v12, v16
	v_fma_f32 v12, v40, v52, v34
	v_add_f32_e32 v12, v12, v35
	v_mul_f32_e32 v16, 0xbfb8aa3b, v12
	v_exp_f32_e32 v16, v16
	s_nop 0
	v_add_f32_e32 v16, 1.0, v16
	v_rcp_f32_e32 v16, v16
	s_nop 0
	v_mul_f32_e32 v34, v12, v16
	v_and_b32_e32 v12, 0xffff0000, v17
	v_pk_mul_f32 v[12:13], v[44:45], v[12:13]
	v_mov_b32_e32 v16, v20
	v_fma_f32 v12, v41, v53, v12
	v_add_f32_e32 v12, v12, v13
	v_mul_f32_e32 v13, 0xbfb8aa3b, v12
	v_exp_f32_e32 v13, v13
	v_mov_b32_e32 v17, v28
	v_mov_b32_e32 v28, v21
	v_and_b32_e32 v21, s0, v3
	v_add_f32_e32 v13, 1.0, v13
	v_rcp_f32_e32 v13, v13
	s_mov_b32 s0, 0x3b800000
	s_mov_b32 s1, 0x3b000000
	v_mul_f32_e32 v35, v12, v13
	v_lshlrev_b32_e32 v13, 16, v14
	v_lshlrev_b32_e32 v12, 16, v18
	v_pk_mul_f32 v[12:13], v[16:17], v[12:13]
	v_mov_b32_e32 v16, v22
	v_fma_f32 v12, v24, v54, v12
	v_add_f32_e32 v12, v12, v13
	v_mul_f32_e32 v13, 0xbfb8aa3b, v12
	v_exp_f32_e32 v13, v13
	v_mov_b32_e32 v17, v30
	v_mov_b32_e32 v30, v23
; __device__ __forceinline__ unsigned cvt_pk_bf16(float lo, float hi) { unsigned r; asm volatile("v_cvt_pk_bf16_f32 %0, %1, %2" : "=v"(r) : "v"(lo), "v"(hi)); return r; }
; __device__ __forceinline__ float bflo(unsigned w) { return __uint_as_float(w << 16); }
; __device__ __forceinline__ float bfhi(unsigned w) { return __uint_as_float(w & 0xffff0000u); }
; __device__ __forceinline__ void unpack8(u32x4 w, float* f) { f[0] = bflo(w.x); f[1] = bfhi(w.x); f[2] = bflo(w.y); f[3] = bfhi(w.y); f[4] = bflo(w.z); f[5] = bfhi(w.z); f[6] = bflo(w.w); f[7] = bfhi(w.w); }
; __device__ __forceinline__ void prep_phase(const Params& p, const Bufs& B, int l) {
;     ...
;         for (int hf = 0; hf < 2; ++hf) { const int c0 = lane * 16 + hf * 8; float xm[8], x0[8], xp[8], r[8];
;             unpack8(cm[hf], xm); unpack8(cc[hf], x0); unpack8(cp[hf], xp);
; #pragma unroll
;             for (int i = 0; i < 8; ++i) { const float v = xm[i] * wconv[c0 + i] + x0[i] * wconv[1024 + c0 + i] + xp[i] * wconv[2048 + c0 + i]; r[i] = v * __builtin_amdgcn_rcpf(1.f + __expf(-v)); }
;             *(u32x4*)(B.QKML + (size_t)s * 1024 + c0) = pack8(r); }
;         { const float x1[4] = {bflo(w1.x), bfhi(w1.x), bflo(w1.y), bfhi(w1.y)}, x2[4] = {bflo(w2.x), bfhi(w2.x), bflo(w2.y), bfhi(w2.y)};
;             const float sc = tensor ? 0.125f : 1.f; float o1[4], o2[4];
; #pragma unroll
;             for (int i = 0; i < 4; ++i) { o1[i] = (x1[i] * rc4[i] - x2[i] * rs4[i]) * sc; o2[i] = (x2[i] * rc4[i] + x1[i] * rs4[i]) * sc; }
;             u32x2 a, b2; a.x = cvt_pk_bf16(o1[0], o1[1]); a.y = cvt_pk_bf16(o1[2], o1[3]); b2.x = cvt_pk_bf16(o2[0], o2[1]); b2.y = cvt_pk_bf16(o2[2], o2[3]);
;             bf16_t* d = B.RQK + (size_t)s * 512 + tensor * 256 + head * 64 + j0; *(u32x2*)d = a; *(u32x2*)(d + 32) = b2; }
;         { float f[8]; unpack8(cqv, f); float g4[4] = {bflo(ckvv.x), bfhi(ckvv.x), bflo(ckvv.y), bfhi(ckvv.y)};
;             float ssq = 0.f, ssk = g4[0] * g4[0] + g4[1] * g4[1] + g4[2] * g4[2] + g4[3] * g4[3];
; #pragma unroll
;             for (int i = 0; i < 8; ++i) ssq += f[i] * f[i];
; #pragma unroll
;             for (int o = 32; o > 0; o >>= 1) { ssq += __shfl_xor(ssq, o); ssk += __shfl_xor(ssk, o); }
;             const float rstd = rsqrtf(ssq * (1.f / 512.f) + EPS_), rstk = rsqrtf(ssk * (1.f / 256.f) + EPS_);
	v_lshlrev_b32_e32 v23, 16, v2
	v_add_f32_e32 v13, 1.0, v13
	v_rcp_f32_e32 v13, v13
	v_and_b32_e32 v24, 0xffff0000, v3
	v_mul_f32_e32 v20, v12, v13
	v_and_b32_e32 v13, 0xffff0000, v14
	v_and_b32_e32 v12, 0xffff0000, v18
	v_pk_mul_f32 v[12:13], v[28:29], v[12:13]
	v_and_b32_e32 v18, 0xffff0000, v1
	v_fma_f32 v12, v25, v55, v12
	v_add_f32_e32 v12, v12, v13
	v_mul_f32_e32 v13, 0xbfb8aa3b, v12
	v_exp_f32_e32 v13, v13
	v_xor_b32_e32 v28, 4, v238
	v_lshlrev_b32_e32 v25, 16, v3
	v_add_f32_e32 v13, 1.0, v13
	v_rcp_f32_e32 v13, v13
	s_nop 0
	v_mul_f32_e32 v14, v12, v13
	v_lshlrev_b32_e32 v12, 16, v19
	v_lshlrev_b32_e32 v13, 16, v15
	v_pk_mul_f32 v[12:13], v[16:17], v[12:13]
	s_nop 0
	v_fma_f32 v12, v26, v105, v12
	v_add_f32_e32 v12, v12, v13
	v_mul_f32_e32 v13, 0xbfb8aa3b, v12
	v_exp_f32_e32 v13, v13
	s_nop 0
	v_add_f32_e32 v13, 1.0, v13
	v_rcp_f32_e32 v13, v13
	s_nop 0
	v_mul_f32_e32 v16, v12, v13
	v_and_b32_e32 v13, 0xffff0000, v15
	v_and_b32_e32 v12, 0xffff0000, v19
	v_pk_mul_f32 v[12:13], v[30:31], v[12:13]
	v_lshlrev_b32_e32 v19, 16, v1
	v_fma_f32 v12, v27, v112, v12
	v_add_f32_e32 v12, v12, v13
	v_mul_f32_e32 v13, 0xbfb8aa3b, v12
	v_exp_f32_e32 v13, v13
	s_nop 0
	v_add_f32_e32 v13, 1.0, v13
	v_rcp_f32_e32 v13, v13
	s_nop 0
	v_mul_f32_e32 v15, v12, v13
	v_cvt_pk_bf16_f32 v12, v48, v42
	v_cvt_pk_bf16_f32 v13, v34, v35
	v_cvt_pk_bf16_f32 v14, v20, v14
	v_cvt_pk_bf16_f32 v15, v16, v15
	global_store_dwordx4 v[32:33], v[12:15], off offset:16
	v_and_b32_e32 v20, 0xffff0000, v2
	v_mov_b32_e32 v22, v20
	v_lshlrev_b32_e32 v13, 16, v110
	v_lshlrev_b32_e32 v12, 16, v108
	v_mov_b32_e32 v14, v4
	v_mov_b32_e32 v15, v8
	v_pk_mul_f32 v[14:15], v[14:15], v[12:13]
	v_pk_mul_f32 v[26:27], v[20:21], v[20:21]
	v_sub_f32_e32 v14, v14, v15
	v_mul_f32_e32 v16, v61, v14
	v_mov_b32_e32 v14, v8
	v_mov_b32_e32 v15, v4
	v_pk_mul_f32 v[12:13], v[14:15], v[12:13]
	v_mov_b32_e32 v8, v5
	v_add_f32_e32 v4, v12, v13
	v_and_b32_e32 v13, 0xffff0000, v110
	v_and_b32_e32 v12, 0xffff0000, v108
	v_pk_mul_f32 v[14:15], v[8:9], v[12:13]
	v_mul_f32_e32 v17, v61, v4
	v_sub_f32_e32 v4, v14, v15
	v_mul_f32_e32 v14, v61, v4
	v_mov_b32_e32 v4, v9
	v_pk_mul_f32 v[4:5], v[4:5], v[12:13]
	v_mov_b32_e32 v8, v6
	v_add_f32_e32 v4, v4, v5
	v_mul_f32_e32 v12, v61, v4
	v_lshlrev_b32_e32 v5, 16, v111
	v_lshlrev_b32_e32 v4, 16, v109
	v_mov_b32_e32 v9, v10
	v_pk_mul_f32 v[8:9], v[8:9], v[4:5]
	v_xor_b32_e32 v21, 32, v238
	v_sub_f32_e32 v8, v8, v9
	v_mul_f32_e32 v13, v61, v8
	v_mov_b32_e32 v8, v10
	v_mov_b32_e32 v9, v6
	v_pk_mul_f32 v[4:5], v[8:9], v[4:5]
	v_mov_b32_e32 v10, v7
	v_add_f32_e32 v4, v4, v5
	v_mul_f32_e32 v15, v61, v4
	v_and_b32_e32 v5, 0xffff0000, v111
	v_and_b32_e32 v4, 0xffff0000, v109
	v_pk_mul_f32 v[8:9], v[10:11], v[4:5]
	v_xor_b32_e32 v27, 8, v238
	v_sub_f32_e32 v6, v8, v9
	v_mul_f32_e32 v8, v61, v6
	v_mov_b32_e32 v6, v11
	v_pk_mul_f32 v[4:5], v[6:7], v[4:5]
	v_mov_b32_e32 v29, v26
	v_add_f32_e32 v4, v4, v5
	v_mul_f32_e32 v7, v61, v4
	v_cvt_pk_bf16_f32 v4, v16, v14
	v_cvt_pk_bf16_f32 v5, v13, v8
	v_cvt_pk_bf16_f32 v6, v17, v12
	v_cvt_pk_bf16_f32 v7, v15, v7
	v_lshlrev_b64 v[14:15], 10, v[56:57]
	v_lshl_add_u64 v[10:11], v[82:83], 0, v[14:15]
	v_lshlrev_b32_e32 v16, 16, v0
	v_and_b32_e32 v17, 0xffff0000, v0
	global_store_dwordx2 v[10:11], v[4:5], off
	global_store_dwordx2 v[10:11], v[6:7], off offset:64
	v_pk_mul_f32 v[6:7], v[16:17], v[16:17]
	v_pk_mul_f32 v[0:1], v[18:19], v[18:19]
	v_add_f32_e32 v2, v6, v7
	v_add_f32_e32 v1, v1, v2
	v_add_f32_e32 v0, v0, v1
	v_pk_fma_f32 v[0:1], v[22:23], v[22:23], v[0:1] op_sel_hi:[1,1,0]
	v_xor_b32_e32 v22, 16, v238
	v_and_b32_e32 v0, 64, v238
	v_add_u32_e32 v0, 64, v0
	v_cmp_lt_i32_e32 vcc, v21, v0
	v_lshlrev_b32_e32 v12, 16, v106
	v_and_b32_e32 v13, 0xffff0000, v106
	v_cndmask_b32_e32 v21, v238, v21, vcc
	v_cmp_lt_i32_e32 vcc, v22, v0
	v_and_b32_e32 v10, 0xffff0000, v107
	v_lshlrev_b32_e32 v11, 16, v107
	v_cndmask_b32_e32 v22, v238, v22, vcc
	v_cmp_lt_i32_e32 vcc, v27, v0
	v_pk_mul_f32 v[6:7], v[12:13], v[12:13]
	v_pk_mul_f32 v[4:5], v[10:11], v[10:11]
	v_cndmask_b32_e32 v27, v238, v27, vcc
	v_cmp_lt_i32_e32 vcc, v28, v0
	v_pk_mul_f32 v[2:3], v[24:25], v[24:25]
	v_lshlrev_b32_e32 v21, 2, v21
	v_cndmask_b32_e32 v28, v238, v28, vcc
	v_lshlrev_b32_e32 v30, 2, v28
	v_xor_b32_e32 v28, 2, v238
	v_cmp_lt_i32_e32 vcc, v28, v0
	v_lshlrev_b32_e32 v22, 2, v22
	v_lshlrev_b32_e32 v27, 2, v27
	v_cndmask_b32_e32 v28, v238, v28, vcc
	v_lshlrev_b32_e32 v31, 2, v28
	v_xor_b32_e32 v28, 1, v238
	v_cmp_lt_i32_e32 vcc, v28, v0
	v_lshlrev_b64 v[8:9], 9, v[56:57]
	s_nop 0
	v_cndmask_b32_e32 v0, v238, v28, vcc
	v_lshlrev_b32_e32 v32, 2, v0
	v_mov_b32_e32 v28, v6
	v_mov_b32_e32 v0, v7
	v_pk_add_f32 v[0:1], v[28:29], v[0:1]
	v_mov_b32_e32 v6, v5
	v_mov_b32_e32 v7, v3
	v_pk_add_f32 v[0:1], v[6:7], v[0:1]
	v_mov_b32_e32 v5, v2
	v_pk_add_f32 v[0:1], v[4:5], v[0:1]
	ds_bpermute_b32 v3, v21, v1
	ds_bpermute_b32 v2, v21, v0
	s_waitcnt lgkmcnt(0)
; __device__ __forceinline__ unsigned cvt_pk_bf16(float lo, float hi) { unsigned r; asm volatile("v_cvt_pk_bf16_f32 %0, %1, %2" : "=v"(r) : "v"(lo), "v"(hi)); return r; }
; __device__ __forceinline__ float bf2f(bf16_t b) { return __uint_as_float(((unsigned)b) << 16); }
; __device__ __forceinline__ u32x4 pack8(const float* f) { u32x4 w; w.x = cvt_pk_bf16(f[0], f[1]); w.y = cvt_pk_bf16(f[2], f[3]); w.z = cvt_pk_bf16(f[4], f[5]); w.w = cvt_pk_bf16(f[6], f[7]); return w; }
; __device__ __forceinline__ void prep_phase(const Params& p, const Bufs& B, int l) {
;     ...
;             for (int o = 32; o > 0; o >>= 1) { ssq += __shfl_xor(ssq, o); ssk += __shfl_xor(ssk, o); }
;             const float rstd = rsqrtf(ssq * (1.f / 512.f) + EPS_), rstk = rsqrtf(ssk * (1.f / 256.f) + EPS_);
; #pragma unroll
;             for (int i = 0; i < 8; ++i) f[i] = f[i] * rstd * gq[lane * 8 + i];
;             *(u32x4*)(B.CQN + (size_t)s * 512 + lane * 8) = pack8(f);
; #pragma unroll
;             for (int i = 0; i < 4; ++i) g4[i] = g4[i] * rstk * gkv[lane * 4 + i];
;             u32x2 o; o.x = cvt_pk_bf16(g4[0], g4[1]); o.y = cvt_pk_bf16(g4[2], g4[3]); *(u32x2*)(B.CKVN + (size_t)s * 256 + lane * 4) = o; }
;         if (lane < 32) { const float x1 = bf2f(kr1), x2 = bf2f(kr2);
;             const unsigned short w = (unsigned short)(__builtin_amdgcn_cvt_pk_fp8_f32(x1 * krc - x2 * krs, x2 * krc + x1 * krs, 0, false) & 0xffff);
; #pragma unroll
;             for (int h = 0; h < 8; ++h) *(unsigned short*)((unsigned char*)B.K + ((size_t)h * S_ + s) * 192 + 128 + 2 * lane) = w; }
	v_pk_add_f32 v[0:1], v[0:1], v[2:3]
	ds_bpermute_b32 v3, v22, v1
	ds_bpermute_b32 v2, v22, v0
	s_waitcnt lgkmcnt(0)
	v_pk_add_f32 v[0:1], v[0:1], v[2:3]
	ds_bpermute_b32 v3, v27, v1
	ds_bpermute_b32 v2, v27, v0
	s_waitcnt lgkmcnt(0)
	v_pk_add_f32 v[0:1], v[0:1], v[2:3]
	ds_bpermute_b32 v3, v30, v1
	ds_bpermute_b32 v2, v30, v0
	s_waitcnt lgkmcnt(0)
	v_pk_add_f32 v[0:1], v[0:1], v[2:3]
	ds_bpermute_b32 v3, v31, v1
	ds_bpermute_b32 v2, v31, v0
	s_waitcnt lgkmcnt(0)
	v_pk_add_f32 v[0:1], v[0:1], v[2:3]
	ds_bpermute_b32 v3, v32, v1
	ds_bpermute_b32 v2, v32, v0
	s_waitcnt lgkmcnt(0)
	v_pk_add_f32 v[0:1], v[0:1], v[2:3]
	s_nop 0
	v_pk_fma_f32 v[0:1], v[0:1], s[0:1], v[242:243] op_sel_hi:[1,1,0]
	s_mov_b32 s0, 0x800000
	v_mul_f32_e32 v2, 0x4b800000, v1
	v_cmp_gt_f32_e32 vcc, s0, v0
	v_cmp_gt_f32_e64 s[0:1], s0, v1
	s_nop 1
	v_cndmask_b32_e64 v1, v1, v2, s[0:1]
	v_rsq_f32_e32 v1, v1
	s_nop 0
	v_mul_f32_e32 v2, 0x45800000, v1
	v_cndmask_b32_e64 v21, v1, v2, s[0:1]
	v_mul_f32_e32 v21, 0x3f553b94, v21
	v_mul_f32_e32 v1, 0x4b800000, v0
	v_cndmask_b32_e32 v0, v0, v1, vcc
	v_rsq_f32_e32 v22, v0
	v_mov_b64_e32 v[0:1], v[176:177]
	v_mov_b64_e32 v[2:3], v[178:179]
	v_mov_b64_e32 v[4:5], v[180:181]
	v_mov_b64_e32 v[6:7], v[182:183]
	v_mul_f32_e32 v16, v21, v16
	v_mul_f32_e32 v26, 0x45800000, v22
	s_waitcnt vmcnt(0)
	v_mul_f32_e32 v4, v4, v16
	v_mul_f32_e32 v16, v21, v17
	v_mul_f32_e32 v5, v5, v16
	v_mul_f32_e32 v16, v21, v19
	v_mul_f32_e32 v6, v6, v16
	v_mul_f32_e32 v16, v21, v18
	v_mul_f32_e32 v7, v7, v16
	v_mul_f32_e32 v16, v21, v23
	v_mul_f32_e32 v16, v0, v16
	v_mul_f32_e32 v0, v21, v20
	v_mul_f32_e32 v17, v1, v0
	v_mul_f32_e32 v0, v21, v25
	v_mul_f32_e32 v18, v2, v0
	v_mul_f32_e32 v0, v21, v24
	v_mul_f32_e32 v3, v3, v0
	v_cvt_pk_bf16_f32 v0, v4, v5
	v_lshl_add_u64 v[4:5], v[84:85], 0, v[14:15]
	v_cvt_pk_bf16_f32 v1, v6, v7
	v_cvt_pk_bf16_f32 v2, v16, v17
	v_cvt_pk_bf16_f32 v3, v18, v3
	global_store_dwordx4 v[4:5], v[0:3], off
	s_nop 1
	v_mov_b64_e32 v[0:1], v[184:185]
	v_mov_b64_e32 v[2:3], v[186:187]
	v_cndmask_b32_e32 v19, v22, v26, vcc
	v_mul_f32_e32 v4, v19, v12
	s_waitcnt vmcnt(0)
	v_mul_f32_e32 v0, v4, v0
	v_mul_f32_e32 v4, v19, v13
	v_mul_f32_e32 v1, v4, v1
	v_mul_f32_e32 v4, v19, v11
	v_mul_f32_e32 v2, v4, v2
	v_mul_f32_e32 v4, v19, v10
	v_mul_f32_e32 v3, v4, v3
	v_cvt_pk_bf16_f32 v0, v0, v1
	v_cvt_pk_bf16_f32 v1, v2, v3
	v_lshl_add_u64 v[2:3], v[86:87], 0, v[8:9]
	global_store_dwordx2 v[2:3], v[0:1], off
	s_and_saveexec_b64 s[0:1], s[4:5]
	s_cbranch_execz .LBB0_498
	v_lshlrev_b32_e32 v1, 16, v99
	v_lshlrev_b32_e32 v0, 16, v97
	v_mul_f32_e32 v2, v103, v1
	v_mul_f32_e32 v1, v101, v1
	v_readlane_b32 s14, v254, 27
	v_fma_f32 v2, v101, v0, -v2
	v_fmac_f32_e32 v1, v103, v0
	v_mov_b32_e32 v4, v195
	v_readlane_b32 s15, v254, 28
	v_cvt_pk_fp8_f32 v4, v2, v1
	s_nop 0
	v_mov_b64_e32 v[0:1], s[14:15]
	s_movk_i32 s14, 0xc0
	v_mad_i64_i32 v[0:1], s[14:15], v56, s14, v[0:1]
	v_lshl_add_u64 v[0:1], v[0:1], 0, v[64:65]
	v_add_co_u32_e32 v2, vcc, 0x180000, v0
	global_store_short v[0:1], v4, off offset:128
	s_nop 0
	v_addc_co_u32_e32 v3, vcc, 0, v1, vcc
	global_store_short v[2:3], v4, off offset:128
	v_add_co_u32_e32 v2, vcc, 0x300000, v0
	s_nop 1
	v_addc_co_u32_e32 v3, vcc, 0, v1, vcc
	global_store_short v[2:3], v4, off offset:128
	v_add_co_u32_e32 v2, vcc, 0x480000, v0
	s_nop 1
	v_addc_co_u32_e32 v3, vcc, 0, v1, vcc
	global_store_short v[2:3], v4, off offset:128
	v_add_co_u32_e32 v2, vcc, 0x600000, v0
	s_nop 1
	v_addc_co_u32_e32 v3, vcc, 0, v1, vcc
	global_store_short v[2:3], v4, off offset:128
	v_add_co_u32_e32 v2, vcc, 0x780000, v0
	s_nop 1
	v_addc_co_u32_e32 v3, vcc, 0, v1, vcc
	global_store_short v[2:3], v4, off offset:128
	v_add_co_u32_e32 v2, vcc, 0x900000, v0
	s_nop 1
	v_addc_co_u32_e32 v3, vcc, 0, v1, vcc
	v_add_co_u32_e32 v0, vcc, 0xa80000, v0
	global_store_short v[2:3], v4, off offset:128
	s_nop 0
	v_addc_co_u32_e32 v1, vcc, 0, v1, vcc
	global_store_short v[0:1], v4, off offset:128

; #define LAS __attribute__((address_space(3)))
;     __device__ bool next(int i, Unit& u) const {
;     ...
;         int wgid = (int)L; { const int q = nwg / NXCD, r = nwg % NXCD, xcd = wgid % NXCD, off = wgid / NXCD; wgid = (xcd < r ? xcd * (q + 1) : r * (q + 1) + (xcd - r) * q) + off; }
;         const int nig = WGM * nN, gid = wgid / nig, fm = gid * WGM, gsz = (nM - fm) < WGM ? (nM - fm) : WGM;
;         u.pm = fm + ((wgid % nig) % gsz); u.pn = (wgid % nig) / gsz; if (u.pn >= skip_lo) u.pn += skip_n; return true;
;     __device__ __forceinline__ void stash(unsigned long long v, LAS unsigned char* lds, int par, int tid) const { if (tid < 256) *(LAS float*)(lds + 131072 + par * 1024 + tid * 4) = rsqrtf((float)v * (1.f / (1048576.f * DM)) + EPS_); }
.LBB0_509:
	s_ashr_i32 s0, s2, 3
	s_add_i32 s0, s4, s0
	s_ashr_i32 s1, s0, 31
	s_lshr_b32 s1, s1, 25
	s_add_i32 s1, s0, s1
	s_ashr_i32 s2, s1, 7
	s_and_b32 s1, s1, 0xffffff80
	s_lshl_b32 s4, s2, 3
	s_sub_i32 s2, s0, s1
	s_bfe_i32 s0, s2, 0x80000
	s_bfe_u32 s0, s0, 0x3000c
	s_add_i32 s3, s2, s0
	s_and_b32 s0, s3, 0xf8
	s_sub_i32 s0, s2, s0
	s_sext_i32_i8 s0, s0
	s_add_i32 s37, s4, s0
	s_movk_i32 s0, 0x100
	v_cmp_gt_i32_e64 s[4:5], s0, v142
	s_and_saveexec_b64 s[0:1], s[4:5]
	s_cbranch_execz .LBB0_511
	v_lshl_add_u32 v0, s37, 8, v142
	v_readlane_b32 s8, v254, 37
	s_waitcnt lgkmcnt(0)
	v_ashrrev_i32_e32 v1, 31, v0
	v_readlane_b32 s9, v254, 38
	s_mov_b32 s7, 0x800000
	s_nop 0
	v_lshl_add_u64 v[0:1], v[0:1], 3, s[8:9]
	global_load_dwordx2 v[0:1], v[0:1], off
	s_waitcnt vmcnt(0) lgkmcnt(0)
	v_ffbh_u32_e32 v2, v1
	v_min_u32_e32 v2, 32, v2
	v_lshlrev_b64 v[0:1], v2, v[0:1]
	v_min_u32_e32 v0, 1, v0
	v_or_b32_e32 v0, v1, v0
	v_cvt_f32_u32_e32 v0, v0
	v_sub_u32_e32 v1, 32, v2
	v_ldexp_f32 v0, v0, v1
	v_fmamk_f32 v0, v0, 0x30000000, v242
	v_mul_f32_e32 v1, 0x4b800000, v0
	v_cmp_gt_f32_e32 vcc, s7, v0
	s_nop 1
	v_cndmask_b32_e32 v0, v0, v1, vcc
	v_rsq_f32_e32 v0, v0
	v_lshl_add_u32 v1, v142, 2, 0
	v_add_u32_e32 v1, 0x20000, v1
	v_mul_f32_e32 v2, 0x45800000, v0
	v_cndmask_b32_e32 v0, v0, v2, vcc
	ds_write_b32 v1, v0

; #define LAS __attribute__((address_space(3)))
; __device__ __forceinline__ unsigned cvt_pk_bf16(float lo, float hi) { unsigned r; asm volatile("v_cvt_pk_bf16_f32 %0, %1, %2" : "=v"(r) : "v"(lo), "v"(hi)); return r; }
;     __device__ __forceinline__ void stash(unsigned long long v, LAS unsigned char* lds, int par, int tid) const { if (tid < 256) *(LAS float*)(lds + 131072 + par * 1024 + tid * 4) = rsqrtf((float)v * (1.f / (1048576.f * DM)) + EPS_); }
;     __device__ __forceinline__ void operator()(const f32x4 (&acc)[2][2][4][2], const Unit& u, int wr, int wc, int fr, int fq, LAS unsigned char* lds, int par, int npm, int tid) const {
;         const int row0 = u.pm * BM + wr * 64 + fr, col0 = u.pn * BM + wc * 32 + 8 * fq;
;         unsigned long long nx = 0ull; if (npm >= 0) nx = prefetch(npm, tid);
; #pragma unroll
;         for (int ai = 0; ai < 2; ++ai)
; #pragma unroll
;             for (int m = 0; m < 4; ++m) { const int row = row0 + ai * HALF + m * 16; bf16_t* rowp = O + (size_t)row * ldc + col0;
;                 const float rstd = *(const LAS float*)(lds + 131072 + par * 1024 + (wr * 64 + fr + ai * HALF + m * 16) * 4);
; #pragma unroll
;                 for (int bj = 0; bj < 2; ++bj) { f32x4 v0 = acc[ai][bj][m][0] * rstd, v1 = acc[ai][bj][m][1] * rstd;
;                     if (ACT == 1) {
; #pragma unroll
;                         for (int j = 0; j < 4; ++j) { const float a = fmaxf(v0[j], 0.f), b = fmaxf(v1[j], 0.f); v0[j] = a * a; v1[j] = b * b; } }
;                     u32x4 w; w.x = cvt_pk_bf16(v0[0], v0[1]); w.y = cvt_pk_bf16(v0[2], v0[3]); w.z = cvt_pk_bf16(v1[0], v1[1]); w.w = cvt_pk_bf16(v1[2], v1[3]);
;                     *(u32x4*)(rowp + bj * HALF) = w; } }
;         if (npm >= 0) stash(nx, lds, par ^ 1, tid);
.LBB0_529:
	s_and_b64 s[14:15], s[14:15], exec
	s_cselect_b32 s18, s35, -1
	s_cmp_gt_i32 s18, -1
	s_cselect_b64 s[14:15], -1, 0
	s_and_b64 s[14:15], s[4:5], s[14:15]
	v_mov_b32_e32 v149, 0x358637bd
	s_and_saveexec_b64 s[16:17], s[14:15]
	s_cbranch_execz .LBB0_531
	v_lshl_add_u32 v138, s18, 8, v142
	v_readlane_b32 s18, v254, 37
	v_ashrrev_i32_e32 v139, 31, v138
	v_readlane_b32 s19, v254, 38
	s_nop 1
	v_lshl_add_u64 v[138:139], v[138:139], 3, s[18:19]
	global_load_dwordx2 v[138:139], v[138:139], off
	s_waitcnt vmcnt(0) lgkmcnt(0)
	v_ffbh_u32_e32 v140, v139
	v_min_u32_e32 v140, 32, v140
	v_lshlrev_b64 v[138:139], v140, v[138:139]
	v_min_u32_e32 v138, 1, v138
	v_or_b32_e32 v138, v139, v138
	v_cvt_f32_u32_e32 v138, v138
	v_sub_u32_e32 v139, 32, v140
	v_ldexp_f32 v138, v138, v139
	v_fmamk_f32 v149, v138, 0x30000000, v242
.LBB0_531:
	s_or_b64 exec, exec, s[16:17]
	s_lshl_b32 s16, s39, 10
	s_and_b32 s18, s16, 0x400
	v_add_u32_e32 v156, s18, v145
	ds_read_b32 v150, v156
	v_readlane_b32 s16, v254, 23
	v_lshl_or_b32 v140, s38, 8, v147
	v_readlane_b32 s17, v254, 24
	v_lshl_add_u32 v151, s37, 8, v143
	v_ashrrev_i32_e32 v141, 31, v140
	v_mov_b64_e32 v[138:139], s[16:17]
	s_movk_i32 s19, 0x2400
	v_mad_i64_i32 v[152:153], s[16:17], v151, s19, v[138:139]
	v_lshlrev_b64 v[140:141], 1, v[140:141]
	v_lshl_add_u64 v[152:153], v[152:153], 0, v[140:141]
	s_waitcnt lgkmcnt(0)
	v_pk_mul_f32 v[126:127], v[126:127], v[150:151] op_sel_hi:[1,0]
	v_pk_mul_f32 v[124:125], v[124:125], v[150:151] op_sel_hi:[1,0]
	v_pk_mul_f32 v[154:155], v[122:123], v[150:151] op_sel_hi:[1,0]
	v_pk_mul_f32 v[122:123], v[120:121], v[150:151] op_sel_hi:[1,0]
	v_cvt_pk_bf16_f32 v120, v124, v125
	v_cvt_pk_bf16_f32 v121, v126, v127
	v_pk_mul_f32 v[118:119], v[118:119], v[150:151] op_sel_hi:[1,0]
	v_cvt_pk_bf16_f32 v122, v122, v123
	v_cvt_pk_bf16_f32 v123, v154, v155
	global_store_dwordx4 v[152:153], v[120:123], off
	v_pk_mul_f32 v[116:117], v[116:117], v[150:151] op_sel_hi:[1,0]
	s_nop 0
	v_pk_mul_f32 v[120:121], v[114:115], v[150:151] op_sel_hi:[1,0]
	v_pk_mul_f32 v[114:115], v[112:113], v[150:151] op_sel_hi:[1,0]
	v_cvt_pk_bf16_f32 v112, v116, v117
	v_cvt_pk_bf16_f32 v113, v118, v119
	s_nop 0
	v_cvt_pk_bf16_f32 v114, v114, v115
	v_cvt_pk_bf16_f32 v115, v120, v121
	global_store_dwordx4 v[152:153], v[112:115], off offset:256
	ds_read_b32 v112, v156 offset:64
	s_nop 0
	v_or_b32_e32 v113, 16, v151
	v_mad_i64_i32 v[114:115], s[16:17], v113, s19, v[138:139]
	v_lshl_add_u64 v[114:115], v[114:115], 0, v[140:141]
	s_waitcnt lgkmcnt(0)
	v_pk_mul_f32 v[110:111], v[110:111], v[112:113] op_sel_hi:[1,0]
	v_pk_mul_f32 v[108:109], v[108:109], v[112:113] op_sel_hi:[1,0]
	v_pk_mul_f32 v[116:117], v[106:107], v[112:113] op_sel_hi:[1,0]
	v_pk_mul_f32 v[106:107], v[104:105], v[112:113] op_sel_hi:[1,0]
	v_cvt_pk_bf16_f32 v104, v108, v109
	v_cvt_pk_bf16_f32 v105, v110, v111
	v_pk_mul_f32 v[102:103], v[102:103], v[112:113] op_sel_hi:[1,0]
	v_cvt_pk_bf16_f32 v106, v106, v107
	v_cvt_pk_bf16_f32 v107, v116, v117
	global_store_dwordx4 v[114:115], v[104:107], off
	v_pk_mul_f32 v[100:101], v[100:101], v[112:113] op_sel_hi:[1,0]
	s_nop 0
	v_pk_mul_f32 v[104:105], v[98:99], v[112:113] op_sel_hi:[1,0]
	v_pk_mul_f32 v[98:99], v[96:97], v[112:113] op_sel_hi:[1,0]
	v_cvt_pk_bf16_f32 v96, v100, v101
	v_cvt_pk_bf16_f32 v97, v102, v103
	s_nop 0
	v_cvt_pk_bf16_f32 v98, v98, v99
	v_cvt_pk_bf16_f32 v99, v104, v105
	global_store_dwordx4 v[114:115], v[96:99], off offset:256
	ds_read_b32 v96, v156 offset:128
	s_nop 0
	v_or_b32_e32 v97, 32, v151
	v_mad_i64_i32 v[98:99], s[16:17], v97, s19, v[138:139]
	v_lshl_add_u64 v[98:99], v[98:99], 0, v[140:141]
	s_waitcnt lgkmcnt(0)
	v_pk_mul_f32 v[94:95], v[94:95], v[96:97] op_sel_hi:[1,0]
	v_pk_mul_f32 v[92:93], v[92:93], v[96:97] op_sel_hi:[1,0]
	v_pk_mul_f32 v[100:101], v[90:91], v[96:97] op_sel_hi:[1,0]
	v_pk_mul_f32 v[90:91], v[88:89], v[96:97] op_sel_hi:[1,0]
	v_cvt_pk_bf16_f32 v88, v92, v93
	v_cvt_pk_bf16_f32 v89, v94, v95
	v_pk_mul_f32 v[86:87], v[86:87], v[96:97] op_sel_hi:[1,0]
	v_cvt_pk_bf16_f32 v90, v90, v91
	v_cvt_pk_bf16_f32 v91, v100, v101
	global_store_dwordx4 v[98:99], v[88:91], off
	v_pk_mul_f32 v[84:85], v[84:85], v[96:97] op_sel_hi:[1,0]
	s_nop 0
	v_pk_mul_f32 v[88:89], v[82:83], v[96:97] op_sel_hi:[1,0]
	v_pk_mul_f32 v[82:83], v[80:81], v[96:97] op_sel_hi:[1,0]
	v_cvt_pk_bf16_f32 v80, v84, v85
	v_cvt_pk_bf16_f32 v81, v86, v87
	s_nop 0
	v_cvt_pk_bf16_f32 v82, v82, v83
	v_cvt_pk_bf16_f32 v83, v88, v89
	global_store_dwordx4 v[98:99], v[80:83], off offset:256
	ds_read_b32 v80, v156 offset:192
	s_nop 0
	v_or_b32_e32 v81, 48, v151
	v_mad_i64_i32 v[82:83], s[16:17], v81, s19, v[138:139]
	v_lshl_add_u64 v[82:83], v[82:83], 0, v[140:141]
	s_waitcnt lgkmcnt(0)
; #define LAS __attribute__((address_space(3)))
; __device__ __forceinline__ unsigned cvt_pk_bf16(float lo, float hi) { unsigned r; asm volatile("v_cvt_pk_bf16_f32 %0, %1, %2" : "=v"(r) : "v"(lo), "v"(hi)); return r; }
;     __device__ __forceinline__ void stash(unsigned long long v, LAS unsigned char* lds, int par, int tid) const { if (tid < 256) *(LAS float*)(lds + 131072 + par * 1024 + tid * 4) = rsqrtf((float)v * (1.f / (1048576.f * DM)) + EPS_); }
;     __device__ __forceinline__ void operator()(const f32x4 (&acc)[2][2][4][2], const Unit& u, int wr, int wc, int fr, int fq, LAS unsigned char* lds, int par, int npm, int tid) const {
;     ...
;             for (int m = 0; m < 4; ++m) { const int row = row0 + ai * HALF + m * 16; bf16_t* rowp = O + (size_t)row * ldc + col0;
;                 const float rstd = *(const LAS float*)(lds + 131072 + par * 1024 + (wr * 64 + fr + ai * HALF + m * 16) * 4);
; #pragma unroll
;                 for (int bj = 0; bj < 2; ++bj) { f32x4 v0 = acc[ai][bj][m][0] * rstd, v1 = acc[ai][bj][m][1] * rstd;
;                     if (ACT == 1) {
; #pragma unroll
;                         for (int j = 0; j < 4; ++j) { const float a = fmaxf(v0[j], 0.f), b = fmaxf(v1[j], 0.f); v0[j] = a * a; v1[j] = b * b; } }
;                     u32x4 w; w.x = cvt_pk_bf16(v0[0], v0[1]); w.y = cvt_pk_bf16(v0[2], v0[3]); w.z = cvt_pk_bf16(v1[0], v1[1]); w.w = cvt_pk_bf16(v1[2], v1[3]);
;                     *(u32x4*)(rowp + bj * HALF) = w; } }
;         if (npm >= 0) stash(nx, lds, par ^ 1, tid);
	v_pk_mul_f32 v[78:79], v[78:79], v[80:81] op_sel_hi:[1,0]
	v_pk_mul_f32 v[76:77], v[76:77], v[80:81] op_sel_hi:[1,0]
	v_pk_mul_f32 v[84:85], v[74:75], v[80:81] op_sel_hi:[1,0]
	v_pk_mul_f32 v[74:75], v[72:73], v[80:81] op_sel_hi:[1,0]
	v_cvt_pk_bf16_f32 v72, v76, v77
	v_cvt_pk_bf16_f32 v73, v78, v79
	v_pk_mul_f32 v[70:71], v[70:71], v[80:81] op_sel_hi:[1,0]
	v_cvt_pk_bf16_f32 v74, v74, v75
	v_cvt_pk_bf16_f32 v75, v84, v85
	global_store_dwordx4 v[82:83], v[72:75], off
	v_pk_mul_f32 v[68:69], v[68:69], v[80:81] op_sel_hi:[1,0]
	s_nop 0
	v_pk_mul_f32 v[72:73], v[66:67], v[80:81] op_sel_hi:[1,0]
	v_pk_mul_f32 v[66:67], v[64:65], v[80:81] op_sel_hi:[1,0]
	v_cvt_pk_bf16_f32 v64, v68, v69
	v_cvt_pk_bf16_f32 v65, v70, v71
	s_nop 0
	v_cvt_pk_bf16_f32 v66, v66, v67
	v_cvt_pk_bf16_f32 v67, v72, v73
	global_store_dwordx4 v[82:83], v[64:67], off offset:256
	ds_read_b32 v64, v156 offset:512
	s_nop 0
	v_add_u32_e32 v65, 0x80, v151
	v_mad_i64_i32 v[66:67], s[16:17], v65, s19, v[138:139]
	v_lshl_add_u64 v[66:67], v[66:67], 0, v[140:141]
	s_waitcnt lgkmcnt(0)
	v_pk_mul_f32 v[62:63], v[62:63], v[64:65] op_sel_hi:[1,0]
	v_pk_mul_f32 v[60:61], v[60:61], v[64:65] op_sel_hi:[1,0]
	v_pk_mul_f32 v[68:69], v[58:59], v[64:65] op_sel_hi:[1,0]
	v_pk_mul_f32 v[58:59], v[56:57], v[64:65] op_sel_hi:[1,0]
	v_cvt_pk_bf16_f32 v56, v60, v61
	v_cvt_pk_bf16_f32 v57, v62, v63
	v_pk_mul_f32 v[54:55], v[54:55], v[64:65] op_sel_hi:[1,0]
	v_cvt_pk_bf16_f32 v58, v58, v59
	v_cvt_pk_bf16_f32 v59, v68, v69
	global_store_dwordx4 v[66:67], v[56:59], off
	v_pk_mul_f32 v[52:53], v[52:53], v[64:65] op_sel_hi:[1,0]
	s_nop 0
	v_pk_mul_f32 v[56:57], v[50:51], v[64:65] op_sel_hi:[1,0]
	v_pk_mul_f32 v[50:51], v[48:49], v[64:65] op_sel_hi:[1,0]
	v_cvt_pk_bf16_f32 v48, v52, v53
	v_cvt_pk_bf16_f32 v49, v54, v55
	s_nop 0
	v_cvt_pk_bf16_f32 v50, v50, v51
	v_cvt_pk_bf16_f32 v51, v56, v57
	global_store_dwordx4 v[66:67], v[48:51], off offset:256
	ds_read_b32 v48, v156 offset:576
	s_nop 0
	v_add_u32_e32 v49, 0x90, v151
	v_mad_i64_i32 v[50:51], s[16:17], v49, s19, v[138:139]
	v_lshl_add_u64 v[50:51], v[50:51], 0, v[140:141]
	s_waitcnt lgkmcnt(0)
	v_pk_mul_f32 v[46:47], v[46:47], v[48:49] op_sel_hi:[1,0]
	v_pk_mul_f32 v[44:45], v[44:45], v[48:49] op_sel_hi:[1,0]
	v_pk_mul_f32 v[52:53], v[42:43], v[48:49] op_sel_hi:[1,0]
	v_pk_mul_f32 v[42:43], v[40:41], v[48:49] op_sel_hi:[1,0]
	v_cvt_pk_bf16_f32 v40, v44, v45
	v_cvt_pk_bf16_f32 v41, v46, v47
	v_pk_mul_f32 v[38:39], v[38:39], v[48:49] op_sel_hi:[1,0]
	v_cvt_pk_bf16_f32 v42, v42, v43
	v_cvt_pk_bf16_f32 v43, v52, v53
	global_store_dwordx4 v[50:51], v[40:43], off
	v_pk_mul_f32 v[36:37], v[36:37], v[48:49] op_sel_hi:[1,0]
	s_nop 0
	v_pk_mul_f32 v[40:41], v[34:35], v[48:49] op_sel_hi:[1,0]
	v_pk_mul_f32 v[34:35], v[32:33], v[48:49] op_sel_hi:[1,0]
	v_cvt_pk_bf16_f32 v32, v36, v37
	v_cvt_pk_bf16_f32 v33, v38, v39
	s_nop 0
	v_cvt_pk_bf16_f32 v34, v34, v35
	v_cvt_pk_bf16_f32 v35, v40, v41
	global_store_dwordx4 v[50:51], v[32:35], off offset:256
	ds_read_b32 v32, v156 offset:640
	s_nop 0
	v_add_u32_e32 v33, 0xa0, v151
	v_mad_i64_i32 v[34:35], s[16:17], v33, s19, v[138:139]
	v_lshl_add_u64 v[34:35], v[34:35], 0, v[140:141]
	s_waitcnt lgkmcnt(0)
	v_pk_mul_f32 v[30:31], v[30:31], v[32:33] op_sel_hi:[1,0]
	v_pk_mul_f32 v[28:29], v[28:29], v[32:33] op_sel_hi:[1,0]
	v_pk_mul_f32 v[36:37], v[26:27], v[32:33] op_sel_hi:[1,0]
	v_pk_mul_f32 v[26:27], v[24:25], v[32:33] op_sel_hi:[1,0]
	v_cvt_pk_bf16_f32 v24, v28, v29
	v_cvt_pk_bf16_f32 v25, v30, v31
	v_pk_mul_f32 v[22:23], v[22:23], v[32:33] op_sel_hi:[1,0]
	v_cvt_pk_bf16_f32 v26, v26, v27
	v_cvt_pk_bf16_f32 v27, v36, v37
	global_store_dwordx4 v[34:35], v[24:27], off
	v_pk_mul_f32 v[20:21], v[20:21], v[32:33] op_sel_hi:[1,0]
	s_nop 0
	v_pk_mul_f32 v[24:25], v[18:19], v[32:33] op_sel_hi:[1,0]
	v_pk_mul_f32 v[18:19], v[16:17], v[32:33] op_sel_hi:[1,0]
	v_cvt_pk_bf16_f32 v16, v20, v21
	v_cvt_pk_bf16_f32 v17, v22, v23
	s_nop 0
	v_cvt_pk_bf16_f32 v18, v18, v19
	v_cvt_pk_bf16_f32 v19, v24, v25
	global_store_dwordx4 v[34:35], v[16:19], off offset:256
	ds_read_b32 v16, v156 offset:704
	s_nop 0
	v_add_u32_e32 v17, 0xb0, v151
	v_mad_i64_i32 v[18:19], s[16:17], v17, s19, v[138:139]
	v_lshl_add_u64 v[18:19], v[18:19], 0, v[140:141]
	s_waitcnt lgkmcnt(0)
	v_pk_mul_f32 v[14:15], v[14:15], v[16:17] op_sel_hi:[1,0]
	v_pk_mul_f32 v[12:13], v[12:13], v[16:17] op_sel_hi:[1,0]
	v_pk_mul_f32 v[20:21], v[10:11], v[16:17] op_sel_hi:[1,0]
	v_pk_mul_f32 v[10:11], v[8:9], v[16:17] op_sel_hi:[1,0]
	v_cvt_pk_bf16_f32 v8, v12, v13
	v_cvt_pk_bf16_f32 v9, v14, v15
	v_pk_mul_f32 v[6:7], v[6:7], v[16:17] op_sel_hi:[1,0]
	v_cvt_pk_bf16_f32 v10, v10, v11
	v_cvt_pk_bf16_f32 v11, v20, v21
	global_store_dwordx4 v[18:19], v[8:11], off
	v_pk_mul_f32 v[4:5], v[4:5], v[16:17] op_sel_hi:[1,0]
	s_nop 0
	v_pk_mul_f32 v[8:9], v[2:3], v[16:17] op_sel_hi:[1,0]
	v_pk_mul_f32 v[2:3], v[0:1], v[16:17] op_sel_hi:[1,0]
	v_cvt_pk_bf16_f32 v0, v4, v5
	v_cvt_pk_bf16_f32 v1, v6, v7
	s_nop 0
	v_cvt_pk_bf16_f32 v2, v2, v3
	v_cvt_pk_bf16_f32 v3, v8, v9
	global_store_dwordx4 v[18:19], v[0:3], off offset:256
	s_and_saveexec_b64 s[16:17], s[14:15]
	s_cbranch_execz .LBB0_514
	s_xor_b32 s14, s18, 0x400
	v_add_u32_e32 v0, s14, v146
	s_mov_b32 s14, 0x800000
	v_cmp_gt_f32_e32 vcc, s14, v149
	v_mul_f32_e32 v1, 0x4b800000, v149
	s_nop 0
	v_cndmask_b32_e32 v1, v149, v1, vcc
	v_rsq_f32_e32 v1, v1
	s_nop 0
	v_mul_f32_e32 v2, 0x45800000, v1
	v_cndmask_b32_e32 v1, v1, v2, vcc
	ds_write_b32 v0, v1
	s_branch .LBB0_514
